# GEMM epilogue output stores write-through (sc1) so the XCD L2 writeback at each phase seam has little left to flush
# baseline (speedup 1.0000x reference)
;     DI void operator()(f4 (&acc)[2][2][4][2], const Unit& u, int wr, int wc, int fr, int fq) const {
;     ...
;         } else if (wc == 2 && fq < 2) {
; #pragma unroll
;             for (int ai = 0; ai < 2; ++ai)
; #pragma unroll
;                 for (int m = 0; m < 4; ++m) { const int row = row0 + ai * HALF + m * 16; const float rs = rsv[ai][m] * 0.25f;
;                     *(f4*)(wi + (size_t)row * 16 + 8 * fq) = acc[ai][0][m][0] * rs; *(f4*)(wi + (size_t)row * 16 + 8 * fq + 4) = acc[ai][0][m][1] * rs; }
.LBB0_312:
	v_add_u32_e32 v186, 0x80, v188
	v_add_u32_e32 v180, 0x90, v188
	v_add_u32_e32 v174, 0xa0, v188
	v_add_u32_e32 v168, 0xb0, v188
	s_mov_b64 s[64:65], -1
	v_ashrrev_i32_e32 v187, 31, v186
	v_ashrrev_i32_e32 v181, 31, v180
	v_ashrrev_i32_e32 v175, 31, v174
	v_ashrrev_i32_e32 v169, 31, v168
	s_andn2_b64 vcc, exec, s[66:67]
	v_ashrrev_i32_e32 v173, 4, v128
	s_cbranch_vccz .LBB0_325
	s_xor_b64 s[66:67], s[68:69], -1
	s_and_b64 vcc, exec, s[66:67]
	s_cbranch_vccz .LBB0_321
	s_xor_b64 s[66:67], s[70:71], -1
	s_and_b64 vcc, exec, s[66:67]
	s_cbranch_vccz .LBB0_318
	v_cmp_gt_i32_e32 vcc, 2, v173
	s_and_b64 s[66:67], s[46:47], vcc
	s_and_saveexec_b64 s[64:65], s[66:67]
	s_cbranch_execz .LBB0_317
	v_lshlrev_b32_e32 v132, 3, v173
	v_ashrrev_i32_e32 v133, 31, v132
	v_lshlrev_b64 v[136:137], 6, v[188:189]
	s_waitcnt vmcnt(0)
	v_mul_f32_e32 v134, 0x3e800000, v190
	v_lshl_add_u64 v[136:137], s[30:31], 0, v[136:137]
	v_lshlrev_b64 v[132:133], 2, v[132:133]
	v_pk_mul_f32 v[130:131], v[126:127], v[134:135] op_sel_hi:[1,0]
	v_pk_mul_f32 v[128:129], v[124:125], v[134:135] op_sel_hi:[1,0]
	v_lshl_add_u64 v[136:137], v[136:137], 0, v[132:133]
	global_store_dwordx4 v[136:137], v[128:131], off sc1
	s_nop 1
	v_pk_mul_f32 v[130:131], v[122:123], v[134:135] op_sel_hi:[1,0]
	v_pk_mul_f32 v[128:129], v[120:121], v[134:135] op_sel_hi:[1,0]
	global_store_dwordx4 v[136:137], v[128:131], off offset:16 sc1
	v_lshlrev_b64 v[136:137], 6, v[182:183]
	v_mul_f32_e32 v134, 0x3e800000, v184
	v_lshl_add_u64 v[136:137], s[30:31], 0, v[136:137]
	v_pk_mul_f32 v[130:131], v[110:111], v[134:135] op_sel_hi:[1,0]
	v_pk_mul_f32 v[128:129], v[108:109], v[134:135] op_sel_hi:[1,0]
	v_lshl_add_u64 v[136:137], v[136:137], 0, v[132:133]
	global_store_dwordx4 v[136:137], v[128:131], off sc1
	s_nop 1
	v_pk_mul_f32 v[130:131], v[106:107], v[134:135] op_sel_hi:[1,0]
	v_pk_mul_f32 v[128:129], v[104:105], v[134:135] op_sel_hi:[1,0]
	global_store_dwordx4 v[136:137], v[128:131], off offset:16 sc1
	v_lshlrev_b64 v[136:137], 6, v[176:177]
	v_mul_f32_e32 v134, 0x3e800000, v178
	v_lshl_add_u64 v[136:137], s[30:31], 0, v[136:137]
	v_pk_mul_f32 v[130:131], v[94:95], v[134:135] op_sel_hi:[1,0]
	v_pk_mul_f32 v[128:129], v[92:93], v[134:135] op_sel_hi:[1,0]
	v_lshl_add_u64 v[136:137], v[136:137], 0, v[132:133]
	global_store_dwordx4 v[136:137], v[128:131], off sc1
	s_nop 1
	v_pk_mul_f32 v[130:131], v[90:91], v[134:135] op_sel_hi:[1,0]
	v_pk_mul_f32 v[128:129], v[88:89], v[134:135] op_sel_hi:[1,0]
	global_store_dwordx4 v[136:137], v[128:131], off offset:16 sc1
	v_lshlrev_b64 v[136:137], 6, v[170:171]
	v_mul_f32_e32 v134, 0x3e800000, v172
	v_lshl_add_u64 v[136:137], s[30:31], 0, v[136:137]
	v_pk_mul_f32 v[130:131], v[78:79], v[134:135] op_sel_hi:[1,0]
	v_pk_mul_f32 v[128:129], v[76:77], v[134:135] op_sel_hi:[1,0]
	v_lshl_add_u64 v[136:137], v[136:137], 0, v[132:133]
	global_store_dwordx4 v[136:137], v[128:131], off sc1
	s_nop 1
	v_pk_mul_f32 v[130:131], v[74:75], v[134:135] op_sel_hi:[1,0]
	v_pk_mul_f32 v[128:129], v[72:73], v[134:135] op_sel_hi:[1,0]
	global_store_dwordx4 v[136:137], v[128:131], off offset:16 sc1
	v_lshlrev_b64 v[136:137], 6, v[186:187]
	v_mul_f32_e32 v134, 0x3e800000, v166
	v_lshl_add_u64 v[136:137], s[30:31], 0, v[136:137]
	v_pk_mul_f32 v[130:131], v[62:63], v[134:135] op_sel_hi:[1,0]
	v_pk_mul_f32 v[128:129], v[60:61], v[134:135] op_sel_hi:[1,0]
	v_lshl_add_u64 v[136:137], v[136:137], 0, v[132:133]
	global_store_dwordx4 v[136:137], v[128:131], off sc1
	s_nop 1
	v_pk_mul_f32 v[130:131], v[58:59], v[134:135] op_sel_hi:[1,0]
	v_pk_mul_f32 v[128:129], v[56:57], v[134:135] op_sel_hi:[1,0]
	global_store_dwordx4 v[136:137], v[128:131], off offset:16 sc1
	v_lshlrev_b64 v[136:137], 6, v[180:181]
	v_mul_f32_e32 v134, 0x3e800000, v164
	v_lshl_add_u64 v[136:137], s[30:31], 0, v[136:137]
	v_pk_mul_f32 v[130:131], v[46:47], v[134:135] op_sel_hi:[1,0]
	v_pk_mul_f32 v[128:129], v[44:45], v[134:135] op_sel_hi:[1,0]
	v_lshl_add_u64 v[136:137], v[136:137], 0, v[132:133]
	global_store_dwordx4 v[136:137], v[128:131], off sc1
	s_nop 1
	v_pk_mul_f32 v[130:131], v[42:43], v[134:135] op_sel_hi:[1,0]
	v_pk_mul_f32 v[128:129], v[40:41], v[134:135] op_sel_hi:[1,0]
	global_store_dwordx4 v[136:137], v[128:131], off offset:16 sc1
	v_lshlrev_b64 v[136:137], 6, v[174:175]
	v_mul_f32_e32 v134, 0x3e800000, v162
	v_lshl_add_u64 v[136:137], s[30:31], 0, v[136:137]
	v_pk_mul_f32 v[130:131], v[30:31], v[134:135] op_sel_hi:[1,0]
	v_pk_mul_f32 v[128:129], v[28:29], v[134:135] op_sel_hi:[1,0]
	v_lshl_add_u64 v[136:137], v[136:137], 0, v[132:133]
	global_store_dwordx4 v[136:137], v[128:131], off sc1
	s_nop 1
	v_pk_mul_f32 v[130:131], v[26:27], v[134:135] op_sel_hi:[1,0]
	v_pk_mul_f32 v[128:129], v[24:25], v[134:135] op_sel_hi:[1,0]
	global_store_dwordx4 v[136:137], v[128:131], off offset:16 sc1
	v_lshlrev_b64 v[136:137], 6, v[168:169]
	v_mul_f32_e32 v134, 0x3e800000, v160
	v_lshl_add_u64 v[136:137], s[30:31], 0, v[136:137]
	v_pk_mul_f32 v[130:131], v[14:15], v[134:135] op_sel_hi:[1,0]
	v_pk_mul_f32 v[128:129], v[12:13], v[134:135] op_sel_hi:[1,0]
	v_lshl_add_u64 v[132:133], v[136:137], 0, v[132:133]
	global_store_dwordx4 v[132:133], v[128:131], off sc1
	s_nop 1
	v_pk_mul_f32 v[130:131], v[10:11], v[134:135] op_sel_hi:[1,0]
	v_pk_mul_f32 v[128:129], v[8:9], v[134:135] op_sel_hi:[1,0]
	global_store_dwordx4 v[132:133], v[128:131], off offset:16 sc1

; DI v4u pack8(const f4& a, const f4& b) { v4u w; w.x = cvt_pk_bf16(a[0], a[1]); w.y = cvt_pk_bf16(a[2], a[3]); w.z = cvt_pk_bf16(b[0], b[1]); w.w = cvt_pk_bf16(b[2], b[3]); return w; }
;     DI void operator()(f4 (&acc)[2][2][4][2], const Unit& u, int wr, int wc, int fr, int fq) const {
;     ...
;         } else if (kind == 1 || wc < 2) {
;             const int hb = cb + (wc >> 1) * 128, dd0 = (wc & 1) * 32 + 8 * fq;
; #pragma unroll
;             for (int ai = 0; ai < 2; ++ai)
; #pragma unroll
;               for (int mp = 0; mp < 2; ++mp) {
;                 f4 cv[2][2], sv[2][2];
; #pragma unroll
;                 for (int mm = 0; mm < 2; ++mm) { const size_t to = (size_t)(row0 + ai * HALF + (2 * mp + mm) * 16) * 64 + dd0; cv[mm][0] = *(const f4*)(rcos + to); cv[mm][1] = *(const f4*)(rcos + to + 4); sv[mm][0] = *(const f4*)(rsin + to); sv[mm][1] = *(const f4*)(rsin + to + 4); }
;                 asm volatile("" ::: "memory");
; #pragma unroll
;                 for (int mm = 0; mm < 2; ++mm) { const int m = 2 * mp + mm, row = row0 + ai * HALF + m * 16; const float rs = rsv[ai][m];
;                     const f4 c0 = cv[mm][0], c1 = cv[mm][1], s0 = sv[mm][0], s1 = sv[mm][1];
;                     const f4 a0 = acc[ai][0][m][0] * rs, a1 = acc[ai][0][m][1] * rs, b0 = acc[ai][1][m][0] * rs, b1 = acc[ai][1][m][1] * rs;
;                     bf16* p = dst + (size_t)row * ld + hb + dd0;
;                     *(v4u*)(p)      = pack8(a0 * c0 - b0 * s0, a1 * c1 - b1 * s1);
;                     *(v4u*)(p + 64) = pack8(a0 * s0 + b0 * c0, a1 * s1 + b1 * c1); }
.LBB0_318:
	s_andn2_b64 vcc, exec, s[64:65]
	s_cbranch_vccnz .LBB0_320
	v_lshl_add_u32 v194, v173, 3, s86
	v_ashrrev_i32_e32 v195, 31, v194
	v_lshlrev_b64 v[128:129], 6, v[188:189]
	v_lshl_add_u64 v[128:129], v[128:129], 0, v[194:195]
	v_lshlrev_b64 v[128:129], 2, v[128:129]
	v_lshl_add_u64 v[130:131], s[36:37], 0, v[128:129]
	v_lshl_add_u64 v[128:129], s[38:39], 0, v[128:129]
	global_load_dwordx4 v[196:199], v[130:131], off offset:16
	global_load_dwordx4 v[200:203], v[130:131], off
	global_load_dwordx4 v[204:207], v[128:129], off offset:16
	global_load_dwordx4 v[208:211], v[128:129], off
	v_lshlrev_b64 v[128:129], 6, v[182:183]
	v_lshl_add_u64 v[128:129], v[128:129], 0, v[194:195]
	v_lshlrev_b64 v[136:137], 2, v[128:129]
	v_lshl_add_u64 v[132:133], s[36:37], 0, v[136:137]
	v_lshl_add_u64 v[140:141], s[38:39], 0, v[136:137]
	global_load_dwordx4 v[128:131], v[132:133], off offset:16
	s_nop 0
	global_load_dwordx4 v[132:135], v[132:133], off
	s_nop 0
	global_load_dwordx4 v[136:139], v[140:141], off offset:16
	s_nop 0
	global_load_dwordx4 v[140:143], v[140:141], off
	s_add_i32 s64, s58, s85
	s_ashr_i32 s65, s64, 31
	s_lshl_b64 s[64:65], s[64:65], 1
	s_add_u32 s64, s60, s64
	s_addc_u32 s65, s61, s65
	v_lshl_add_u64 v[192:193], v[194:195], 1, s[64:65]
	v_mul_lo_u32 v179, s63, v188
	v_mul_lo_u32 v185, s62, v189
	v_mad_u64_u32 v[212:213], s[64:65], s62, v188, 0
	s_waitcnt vmcnt(0)
	v_pk_mul_f32 v[224:225], v[118:119], v[190:191] op_sel_hi:[1,0]
	v_pk_mul_f32 v[226:227], v[116:117], v[190:191] op_sel_hi:[1,0]
	v_add3_u32 v213, v213, v185, v179
	v_pk_mul_f32 v[216:217], v[126:127], v[190:191] op_sel_hi:[1,0]
	v_pk_mul_f32 v[218:219], v[124:125], v[190:191] op_sel_hi:[1,0]
	v_pk_mul_f32 v[228:229], v[114:115], v[190:191] op_sel_hi:[1,0]
	v_pk_mul_f32 v[230:231], v[112:113], v[190:191] op_sel_hi:[1,0]
	v_lshl_add_u64 v[232:233], v[212:213], 1, v[192:193]
	v_pk_mul_f32 v[220:221], v[122:123], v[190:191] op_sel_hi:[1,0]
	v_pk_mul_f32 v[222:223], v[120:121], v[190:191] op_sel_hi:[1,0]
	v_mul_lo_u32 v179, s63, v182
	v_pk_mul_f32 v[236:237], v[230:231], v[204:205]
	v_pk_mul_f32 v[212:213], v[224:225], v[210:211]
	v_pk_mul_f32 v[214:215], v[226:227], v[208:209]
	v_pk_fma_f32 v[234:235], v[216:217], v[202:203], v[212:213] neg_lo:[0,0,1] neg_hi:[0,0,1]
	v_pk_fma_f32 v[212:213], v[218:219], v[200:201], v[214:215] neg_lo:[0,0,1] neg_hi:[0,0,1]
	v_pk_mul_f32 v[214:215], v[228:229], v[206:207]
	v_pk_mul_f32 v[210:211], v[216:217], v[210:211]
	v_pk_fma_f32 v[238:239], v[220:221], v[198:199], v[214:215] neg_lo:[0,0,1] neg_hi:[0,0,1]
	v_pk_fma_f32 v[214:215], v[222:223], v[196:197], v[236:237] neg_lo:[0,0,1] neg_hi:[0,0,1]
	v_pk_mul_f32 v[208:209], v[218:219], v[208:209]
	v_pk_mul_f32 v[206:207], v[220:221], v[206:207]
	v_pk_mul_f32 v[204:205], v[222:223], v[204:205]
	v_cvt_pk_bf16_f32 v212, v212, v213
	v_cvt_pk_bf16_f32 v213, v234, v235
	v_cvt_pk_bf16_f32 v214, v214, v215
	v_cvt_pk_bf16_f32 v215, v238, v239
	global_store_dwordx4 v[232:233], v[212:215], off sc1
	v_pk_fma_f32 v[202:203], v[224:225], v[202:203], v[210:211]
	v_pk_fma_f32 v[200:201], v[226:227], v[200:201], v[208:209]
	v_pk_fma_f32 v[206:207], v[228:229], v[198:199], v[206:207]
	v_pk_fma_f32 v[198:199], v[230:231], v[196:197], v[204:205]
	v_cvt_pk_bf16_f32 v196, v200, v201
	v_cvt_pk_bf16_f32 v197, v202, v203
	v_pk_mul_f32 v[200:201], v[110:111], v[184:185] op_sel_hi:[1,0]
	v_cvt_pk_bf16_f32 v198, v198, v199
	v_cvt_pk_bf16_f32 v199, v206, v207
	global_store_dwordx4 v[232:233], v[196:199], off offset:128 sc1
	v_pk_mul_f32 v[202:203], v[108:109], v[184:185] op_sel_hi:[1,0]
	v_pk_mul_f32 v[204:205], v[106:107], v[184:185] op_sel_hi:[1,0]
	v_pk_mul_f32 v[206:207], v[104:105], v[184:185] op_sel_hi:[1,0]
	v_pk_mul_f32 v[208:209], v[102:103], v[184:185] op_sel_hi:[1,0]
	v_pk_mul_f32 v[210:211], v[100:101], v[184:185] op_sel_hi:[1,0]
	v_pk_mul_f32 v[212:213], v[98:99], v[184:185] op_sel_hi:[1,0]
	v_pk_mul_f32 v[214:215], v[96:97], v[184:185] op_sel_hi:[1,0]
	v_mul_lo_u32 v185, s62, v183
	v_mad_u64_u32 v[196:197], s[64:65], s62, v182, 0
	v_add3_u32 v197, v197, v185, v179
	v_lshl_add_u64 v[216:217], v[196:197], 1, v[192:193]
	v_pk_mul_f32 v[196:197], v[208:209], v[142:143]
	v_pk_mul_f32 v[198:199], v[210:211], v[140:141]
	v_pk_fma_f32 v[218:219], v[200:201], v[134:135], v[196:197] neg_lo:[0,0,1] neg_hi:[0,0,1]
	v_pk_fma_f32 v[196:197], v[202:203], v[132:133], v[198:199] neg_lo:[0,0,1] neg_hi:[0,0,1]
	v_pk_mul_f32 v[198:199], v[212:213], v[138:139]
	v_pk_mul_f32 v[220:221], v[214:215], v[136:137]
	v_pk_fma_f32 v[222:223], v[204:205], v[130:131], v[198:199] neg_lo:[0,0,1] neg_hi:[0,0,1]
	v_pk_fma_f32 v[198:199], v[206:207], v[128:129], v[220:221] neg_lo:[0,0,1] neg_hi:[0,0,1]
	v_pk_mul_f32 v[142:143], v[200:201], v[142:143]
	v_pk_mul_f32 v[140:141], v[202:203], v[140:141]
	v_pk_mul_f32 v[138:139], v[204:205], v[138:139]
	v_pk_mul_f32 v[136:137], v[206:207], v[136:137]
	v_cvt_pk_bf16_f32 v196, v196, v197
	v_cvt_pk_bf16_f32 v197, v218, v219
	v_cvt_pk_bf16_f32 v198, v198, v199
	v_cvt_pk_bf16_f32 v199, v222, v223
	global_store_dwordx4 v[216:217], v[196:199], off sc1
	v_pk_fma_f32 v[134:135], v[208:209], v[134:135], v[142:143]
	v_pk_fma_f32 v[132:133], v[210:211], v[132:133], v[140:141]
	v_pk_fma_f32 v[138:139], v[212:213], v[130:131], v[138:139]
	v_pk_fma_f32 v[130:131], v[214:215], v[128:129], v[136:137]
	v_cvt_pk_bf16_f32 v128, v132, v133
	v_cvt_pk_bf16_f32 v129, v134, v135
	v_pk_mul_f32 v[218:219], v[92:93], v[178:179] op_sel_hi:[1,0]
	v_cvt_pk_bf16_f32 v130, v130, v131
	v_cvt_pk_bf16_f32 v131, v138, v139
	global_store_dwordx4 v[216:217], v[128:131], off offset:128 sc1
	v_pk_mul_f32 v[216:217], v[94:95], v[178:179] op_sel_hi:[1,0]
; DI v4u pack8(const f4& a, const f4& b) { v4u w; w.x = cvt_pk_bf16(a[0], a[1]); w.y = cvt_pk_bf16(a[2], a[3]); w.z = cvt_pk_bf16(b[0], b[1]); w.w = cvt_pk_bf16(b[2], b[3]); return w; }
;     DI void operator()(f4 (&acc)[2][2][4][2], const Unit& u, int wr, int wc, int fr, int fq) const {
;     ...
;         } else if (kind == 1 || wc < 2) {
;             const int hb = cb + (wc >> 1) * 128, dd0 = (wc & 1) * 32 + 8 * fq;
; #pragma unroll
;             for (int ai = 0; ai < 2; ++ai)
; #pragma unroll
;               for (int mp = 0; mp < 2; ++mp) {
;                 f4 cv[2][2], sv[2][2];
; #pragma unroll
;                 for (int mm = 0; mm < 2; ++mm) { const size_t to = (size_t)(row0 + ai * HALF + (2 * mp + mm) * 16) * 64 + dd0; cv[mm][0] = *(const f4*)(rcos + to); cv[mm][1] = *(const f4*)(rcos + to + 4); sv[mm][0] = *(const f4*)(rsin + to); sv[mm][1] = *(const f4*)(rsin + to + 4); }
;                 asm volatile("" ::: "memory");
; #pragma unroll
;                 for (int mm = 0; mm < 2; ++mm) { const int m = 2 * mp + mm, row = row0 + ai * HALF + m * 16; const float rs = rsv[ai][m];
;                     const f4 c0 = cv[mm][0], c1 = cv[mm][1], s0 = sv[mm][0], s1 = sv[mm][1];
;                     const f4 a0 = acc[ai][0][m][0] * rs, a1 = acc[ai][0][m][1] * rs, b0 = acc[ai][1][m][0] * rs, b1 = acc[ai][1][m][1] * rs;
;                     bf16* p = dst + (size_t)row * ld + hb + dd0;
;                     *(v4u*)(p)      = pack8(a0 * c0 - b0 * s0, a1 * c1 - b1 * s1);
;                     *(v4u*)(p + 64) = pack8(a0 * s0 + b0 * c0, a1 * s1 + b1 * c1); }
;                 asm volatile("" ::: "memory"); }
	v_pk_mul_f32 v[220:221], v[90:91], v[178:179] op_sel_hi:[1,0]
	v_lshlrev_b64 v[128:129], 6, v[176:177]
	v_lshl_add_u64 v[128:129], v[128:129], 0, v[194:195]
	v_lshlrev_b64 v[128:129], 2, v[128:129]
	v_lshl_add_u64 v[130:131], s[36:37], 0, v[128:129]
	v_lshl_add_u64 v[128:129], s[38:39], 0, v[128:129]
	global_load_dwordx4 v[196:199], v[130:131], off offset:16
	global_load_dwordx4 v[200:203], v[130:131], off
	global_load_dwordx4 v[204:207], v[128:129], off offset:16
	global_load_dwordx4 v[208:211], v[128:129], off
	v_lshlrev_b64 v[128:129], 6, v[170:171]
	v_lshl_add_u64 v[128:129], v[128:129], 0, v[194:195]
	v_lshlrev_b64 v[136:137], 2, v[128:129]
	v_lshl_add_u64 v[132:133], s[36:37], 0, v[136:137]
	v_lshl_add_u64 v[140:141], s[38:39], 0, v[136:137]
	global_load_dwordx4 v[128:131], v[132:133], off offset:16
	s_nop 0
	global_load_dwordx4 v[132:135], v[132:133], off
	s_nop 0
	global_load_dwordx4 v[136:139], v[140:141], off offset:16
	s_nop 0
	global_load_dwordx4 v[140:143], v[140:141], off
	v_pk_mul_f32 v[222:223], v[88:89], v[178:179] op_sel_hi:[1,0]
	v_pk_mul_f32 v[224:225], v[86:87], v[178:179] op_sel_hi:[1,0]
	v_pk_mul_f32 v[226:227], v[84:85], v[178:179] op_sel_hi:[1,0]
	v_pk_mul_f32 v[228:229], v[82:83], v[178:179] op_sel_hi:[1,0]
	v_pk_mul_f32 v[230:231], v[80:81], v[178:179] op_sel_hi:[1,0]
	v_mul_lo_u32 v179, s63, v176
	v_mul_lo_u32 v185, s62, v177
	v_mad_u64_u32 v[212:213], s[64:65], s62, v176, 0
	v_add3_u32 v213, v213, v185, v179
	v_lshl_add_u64 v[232:233], v[212:213], 1, v[192:193]
	v_mul_lo_u32 v179, s63, v170
	v_mul_lo_u32 v185, s62, v171
	s_waitcnt vmcnt(5)
	v_pk_mul_f32 v[236:237], v[230:231], v[204:205]
	s_waitcnt vmcnt(4)
	v_pk_mul_f32 v[212:213], v[224:225], v[210:211]
	v_pk_mul_f32 v[214:215], v[226:227], v[208:209]
	v_pk_fma_f32 v[234:235], v[216:217], v[202:203], v[212:213] neg_lo:[0,0,1] neg_hi:[0,0,1]
	v_pk_fma_f32 v[212:213], v[218:219], v[200:201], v[214:215] neg_lo:[0,0,1] neg_hi:[0,0,1]
	v_pk_mul_f32 v[214:215], v[228:229], v[206:207]
	v_pk_mul_f32 v[210:211], v[216:217], v[210:211]
	v_pk_fma_f32 v[238:239], v[220:221], v[198:199], v[214:215] neg_lo:[0,0,1] neg_hi:[0,0,1]
	v_pk_fma_f32 v[214:215], v[222:223], v[196:197], v[236:237] neg_lo:[0,0,1] neg_hi:[0,0,1]
	v_pk_mul_f32 v[208:209], v[218:219], v[208:209]
	v_pk_mul_f32 v[206:207], v[220:221], v[206:207]
	v_pk_mul_f32 v[204:205], v[222:223], v[204:205]
	v_cvt_pk_bf16_f32 v212, v212, v213
	v_cvt_pk_bf16_f32 v213, v234, v235
	v_cvt_pk_bf16_f32 v214, v214, v215
	v_cvt_pk_bf16_f32 v215, v238, v239
	global_store_dwordx4 v[232:233], v[212:215], off sc1
	v_pk_fma_f32 v[202:203], v[224:225], v[202:203], v[210:211]
	v_pk_fma_f32 v[200:201], v[226:227], v[200:201], v[208:209]
	v_pk_fma_f32 v[206:207], v[228:229], v[198:199], v[206:207]
	v_pk_fma_f32 v[198:199], v[230:231], v[196:197], v[204:205]
	v_cvt_pk_bf16_f32 v196, v200, v201
	v_cvt_pk_bf16_f32 v197, v202, v203
	v_pk_mul_f32 v[208:209], v[70:71], v[172:173] op_sel_hi:[1,0]
	v_cvt_pk_bf16_f32 v198, v198, v199
	v_cvt_pk_bf16_f32 v199, v206, v207
	global_store_dwordx4 v[232:233], v[196:199], off offset:128 sc1
	v_pk_mul_f32 v[210:211], v[68:69], v[172:173] op_sel_hi:[1,0]
	v_pk_mul_f32 v[200:201], v[78:79], v[172:173] op_sel_hi:[1,0]
	v_mad_u64_u32 v[196:197], s[64:65], s62, v170, 0
	v_add3_u32 v197, v197, v185, v179
	v_pk_mul_f32 v[202:203], v[76:77], v[172:173] op_sel_hi:[1,0]
	v_pk_mul_f32 v[212:213], v[66:67], v[172:173] op_sel_hi:[1,0]
	v_pk_mul_f32 v[214:215], v[64:65], v[172:173] op_sel_hi:[1,0]
	v_lshl_add_u64 v[216:217], v[196:197], 1, v[192:193]
	s_waitcnt vmcnt(2)
	v_pk_mul_f32 v[196:197], v[208:209], v[142:143]
	v_pk_mul_f32 v[198:199], v[210:211], v[140:141]
	v_pk_mul_f32 v[204:205], v[74:75], v[172:173] op_sel_hi:[1,0]
	v_pk_mul_f32 v[206:207], v[72:73], v[172:173] op_sel_hi:[1,0]
	v_pk_fma_f32 v[218:219], v[200:201], v[134:135], v[196:197] neg_lo:[0,0,1] neg_hi:[0,0,1]
	v_pk_fma_f32 v[196:197], v[202:203], v[132:133], v[198:199] neg_lo:[0,0,1] neg_hi:[0,0,1]
	v_pk_mul_f32 v[198:199], v[212:213], v[138:139]
	v_pk_mul_f32 v[220:221], v[214:215], v[136:137]
	v_pk_fma_f32 v[222:223], v[204:205], v[130:131], v[198:199] neg_lo:[0,0,1] neg_hi:[0,0,1]
	v_pk_fma_f32 v[198:199], v[206:207], v[128:129], v[220:221] neg_lo:[0,0,1] neg_hi:[0,0,1]
	v_pk_mul_f32 v[142:143], v[200:201], v[142:143]
	v_pk_mul_f32 v[140:141], v[202:203], v[140:141]
	v_pk_mul_f32 v[138:139], v[204:205], v[138:139]
	v_pk_mul_f32 v[136:137], v[206:207], v[136:137]
	v_cvt_pk_bf16_f32 v196, v196, v197
	v_cvt_pk_bf16_f32 v197, v218, v219
	v_cvt_pk_bf16_f32 v198, v198, v199
	v_cvt_pk_bf16_f32 v199, v222, v223
	global_store_dwordx4 v[216:217], v[196:199], off sc1
	v_pk_fma_f32 v[134:135], v[208:209], v[134:135], v[142:143]
	v_pk_fma_f32 v[132:133], v[210:211], v[132:133], v[140:141]
	v_pk_fma_f32 v[138:139], v[212:213], v[130:131], v[138:139]
	v_pk_fma_f32 v[130:131], v[214:215], v[128:129], v[136:137]
	v_cvt_pk_bf16_f32 v128, v132, v133
	v_cvt_pk_bf16_f32 v129, v134, v135
	v_mul_lo_u32 v179, s63, v186
	v_cvt_pk_bf16_f32 v130, v130, v131
	v_cvt_pk_bf16_f32 v131, v138, v139
	global_store_dwordx4 v[216:217], v[128:131], off offset:128 sc1
	v_mul_lo_u32 v185, s62, v187
	v_mad_u64_u32 v[212:213], s[64:65], s62, v186, 0
	v_lshlrev_b64 v[128:129], 6, v[186:187]
	v_lshl_add_u64 v[128:129], v[128:129], 0, v[194:195]
	v_lshlrev_b64 v[128:129], 2, v[128:129]
	v_lshl_add_u64 v[130:131], s[36:37], 0, v[128:129]
	v_lshl_add_u64 v[128:129], s[38:39], 0, v[128:129]
	global_load_dwordx4 v[196:199], v[130:131], off offset:16
	global_load_dwordx4 v[200:203], v[130:131], off
	global_load_dwordx4 v[204:207], v[128:129], off offset:16
	global_load_dwordx4 v[208:211], v[128:129], off
	v_lshlrev_b64 v[128:129], 6, v[180:181]
	v_lshl_add_u64 v[128:129], v[128:129], 0, v[194:195]
	v_lshlrev_b64 v[136:137], 2, v[128:129]
	v_lshl_add_u64 v[132:133], s[36:37], 0, v[136:137]
	v_lshl_add_u64 v[140:141], s[38:39], 0, v[136:137]
	global_load_dwordx4 v[128:131], v[132:133], off offset:16
	s_nop 0
	global_load_dwordx4 v[132:135], v[132:133], off
	s_nop 0
	global_load_dwordx4 v[136:139], v[140:141], off offset:16
	s_nop 0
	global_load_dwordx4 v[140:143], v[140:141], off
	v_pk_mul_f32 v[224:225], v[54:55], v[166:167] op_sel_hi:[1,0]
	v_pk_mul_f32 v[226:227], v[52:53], v[166:167] op_sel_hi:[1,0]
	v_add3_u32 v213, v213, v185, v179
	v_pk_mul_f32 v[216:217], v[62:63], v[166:167] op_sel_hi:[1,0]
	v_pk_mul_f32 v[218:219], v[60:61], v[166:167] op_sel_hi:[1,0]
	v_pk_mul_f32 v[228:229], v[50:51], v[166:167] op_sel_hi:[1,0]
	v_pk_mul_f32 v[230:231], v[48:49], v[166:167] op_sel_hi:[1,0]
	v_lshl_add_u64 v[232:233], v[212:213], 1, v[192:193]
	v_pk_mul_f32 v[220:221], v[58:59], v[166:167] op_sel_hi:[1,0]
	v_pk_mul_f32 v[222:223], v[56:57], v[166:167] op_sel_hi:[1,0]
	v_mul_lo_u32 v179, s63, v180
	v_mul_lo_u32 v185, s62, v181
	s_waitcnt vmcnt(5)
; DI v4u pack8(const f4& a, const f4& b) { v4u w; w.x = cvt_pk_bf16(a[0], a[1]); w.y = cvt_pk_bf16(a[2], a[3]); w.z = cvt_pk_bf16(b[0], b[1]); w.w = cvt_pk_bf16(b[2], b[3]); return w; }
;     DI void operator()(f4 (&acc)[2][2][4][2], const Unit& u, int wr, int wc, int fr, int fq) const {
;     ...
;         } else if (kind == 1 || wc < 2) {
;             const int hb = cb + (wc >> 1) * 128, dd0 = (wc & 1) * 32 + 8 * fq;
; #pragma unroll
;             for (int ai = 0; ai < 2; ++ai)
; #pragma unroll
;               for (int mp = 0; mp < 2; ++mp) {
;                 f4 cv[2][2], sv[2][2];
; #pragma unroll
;                 for (int mm = 0; mm < 2; ++mm) { const size_t to = (size_t)(row0 + ai * HALF + (2 * mp + mm) * 16) * 64 + dd0; cv[mm][0] = *(const f4*)(rcos + to); cv[mm][1] = *(const f4*)(rcos + to + 4); sv[mm][0] = *(const f4*)(rsin + to); sv[mm][1] = *(const f4*)(rsin + to + 4); }
;                 asm volatile("" ::: "memory");
; #pragma unroll
;                 for (int mm = 0; mm < 2; ++mm) { const int m = 2 * mp + mm, row = row0 + ai * HALF + m * 16; const float rs = rsv[ai][m];
;                     const f4 c0 = cv[mm][0], c1 = cv[mm][1], s0 = sv[mm][0], s1 = sv[mm][1];
;                     const f4 a0 = acc[ai][0][m][0] * rs, a1 = acc[ai][0][m][1] * rs, b0 = acc[ai][1][m][0] * rs, b1 = acc[ai][1][m][1] * rs;
;                     bf16* p = dst + (size_t)row * ld + hb + dd0;
;                     *(v4u*)(p)      = pack8(a0 * c0 - b0 * s0, a1 * c1 - b1 * s1);
;                     *(v4u*)(p + 64) = pack8(a0 * s0 + b0 * c0, a1 * s1 + b1 * c1); }
;                 asm volatile("" ::: "memory"); }
	v_pk_mul_f32 v[236:237], v[230:231], v[204:205]
	s_waitcnt vmcnt(4)
	v_pk_mul_f32 v[212:213], v[224:225], v[210:211]
	v_pk_mul_f32 v[214:215], v[226:227], v[208:209]
	v_pk_fma_f32 v[234:235], v[216:217], v[202:203], v[212:213] neg_lo:[0,0,1] neg_hi:[0,0,1]
	v_pk_fma_f32 v[212:213], v[218:219], v[200:201], v[214:215] neg_lo:[0,0,1] neg_hi:[0,0,1]
	v_pk_mul_f32 v[214:215], v[228:229], v[206:207]
	v_pk_mul_f32 v[210:211], v[216:217], v[210:211]
	v_pk_fma_f32 v[238:239], v[220:221], v[198:199], v[214:215] neg_lo:[0,0,1] neg_hi:[0,0,1]
	v_pk_fma_f32 v[214:215], v[222:223], v[196:197], v[236:237] neg_lo:[0,0,1] neg_hi:[0,0,1]
	v_pk_mul_f32 v[208:209], v[218:219], v[208:209]
	v_pk_mul_f32 v[206:207], v[220:221], v[206:207]
	v_pk_mul_f32 v[204:205], v[222:223], v[204:205]
	v_cvt_pk_bf16_f32 v212, v212, v213
	v_cvt_pk_bf16_f32 v213, v234, v235
	v_cvt_pk_bf16_f32 v214, v214, v215
	v_cvt_pk_bf16_f32 v215, v238, v239
	global_store_dwordx4 v[232:233], v[212:215], off sc1
	v_pk_fma_f32 v[202:203], v[224:225], v[202:203], v[210:211]
	v_pk_fma_f32 v[200:201], v[226:227], v[200:201], v[208:209]
	v_pk_fma_f32 v[206:207], v[228:229], v[198:199], v[206:207]
	v_pk_fma_f32 v[198:199], v[230:231], v[196:197], v[204:205]
	v_cvt_pk_bf16_f32 v196, v200, v201
	v_cvt_pk_bf16_f32 v197, v202, v203
	v_pk_mul_f32 v[208:209], v[38:39], v[164:165] op_sel_hi:[1,0]
	v_cvt_pk_bf16_f32 v198, v198, v199
	v_cvt_pk_bf16_f32 v199, v206, v207
	global_store_dwordx4 v[232:233], v[196:199], off offset:128 sc1
	v_pk_mul_f32 v[210:211], v[36:37], v[164:165] op_sel_hi:[1,0]
	v_pk_mul_f32 v[200:201], v[46:47], v[164:165] op_sel_hi:[1,0]
	v_mad_u64_u32 v[196:197], s[64:65], s62, v180, 0
	v_add3_u32 v197, v197, v185, v179
	v_pk_mul_f32 v[202:203], v[44:45], v[164:165] op_sel_hi:[1,0]
	v_pk_mul_f32 v[212:213], v[34:35], v[164:165] op_sel_hi:[1,0]
	v_pk_mul_f32 v[214:215], v[32:33], v[164:165] op_sel_hi:[1,0]
	v_lshl_add_u64 v[216:217], v[196:197], 1, v[192:193]
	s_waitcnt vmcnt(2)
	v_pk_mul_f32 v[196:197], v[208:209], v[142:143]
	v_pk_mul_f32 v[198:199], v[210:211], v[140:141]
	v_pk_mul_f32 v[204:205], v[42:43], v[164:165] op_sel_hi:[1,0]
	v_pk_mul_f32 v[206:207], v[40:41], v[164:165] op_sel_hi:[1,0]
	v_pk_fma_f32 v[218:219], v[200:201], v[134:135], v[196:197] neg_lo:[0,0,1] neg_hi:[0,0,1]
	v_pk_fma_f32 v[196:197], v[202:203], v[132:133], v[198:199] neg_lo:[0,0,1] neg_hi:[0,0,1]
	v_pk_mul_f32 v[198:199], v[212:213], v[138:139]
	v_pk_mul_f32 v[220:221], v[214:215], v[136:137]
	v_pk_fma_f32 v[222:223], v[204:205], v[130:131], v[198:199] neg_lo:[0,0,1] neg_hi:[0,0,1]
	v_pk_fma_f32 v[198:199], v[206:207], v[128:129], v[220:221] neg_lo:[0,0,1] neg_hi:[0,0,1]
	v_pk_mul_f32 v[142:143], v[200:201], v[142:143]
	v_pk_mul_f32 v[140:141], v[202:203], v[140:141]
	v_pk_mul_f32 v[138:139], v[204:205], v[138:139]
	v_pk_mul_f32 v[136:137], v[206:207], v[136:137]
	v_cvt_pk_bf16_f32 v196, v196, v197
	v_cvt_pk_bf16_f32 v197, v218, v219
	v_cvt_pk_bf16_f32 v198, v198, v199
	v_cvt_pk_bf16_f32 v199, v222, v223
	global_store_dwordx4 v[216:217], v[196:199], off sc1
	v_pk_fma_f32 v[134:135], v[208:209], v[134:135], v[142:143]
	v_pk_fma_f32 v[132:133], v[210:211], v[132:133], v[140:141]
	v_pk_fma_f32 v[138:139], v[212:213], v[130:131], v[138:139]
	v_pk_fma_f32 v[130:131], v[214:215], v[128:129], v[136:137]
	v_cvt_pk_bf16_f32 v128, v132, v133
	v_cvt_pk_bf16_f32 v129, v134, v135
	v_lshlrev_b64 v[196:197], 6, v[168:169]
	v_cvt_pk_bf16_f32 v130, v130, v131
	v_cvt_pk_bf16_f32 v131, v138, v139
	global_store_dwordx4 v[216:217], v[128:131], off offset:128 sc1
	v_mul_lo_u32 v179, s63, v174
	v_mul_lo_u32 v185, s62, v175
	v_lshlrev_b64 v[128:129], 6, v[174:175]
	v_lshl_add_u64 v[128:129], v[128:129], 0, v[194:195]
	v_lshlrev_b64 v[136:137], 2, v[128:129]
	v_lshl_add_u64 v[132:133], s[36:37], 0, v[136:137]
	v_lshl_add_u64 v[140:141], s[38:39], 0, v[136:137]
	global_load_dwordx4 v[128:131], v[132:133], off offset:16
	s_nop 0
	global_load_dwordx4 v[132:135], v[132:133], off
	s_nop 0
	global_load_dwordx4 v[136:139], v[140:141], off offset:16
	s_nop 0
	global_load_dwordx4 v[140:143], v[140:141], off
	v_lshl_add_u64 v[194:195], v[196:197], 0, v[194:195]
	v_lshlrev_b64 v[202:203], 2, v[194:195]
	v_lshl_add_u64 v[198:199], s[36:37], 0, v[202:203]
	v_lshl_add_u64 v[206:207], s[38:39], 0, v[202:203]
	global_load_dwordx4 v[194:197], v[198:199], off offset:16
	s_nop 0
	global_load_dwordx4 v[198:201], v[198:199], off
	s_nop 0
	global_load_dwordx4 v[202:205], v[206:207], off offset:16
	s_nop 0
	global_load_dwordx4 v[206:209], v[206:207], off
	v_mad_u64_u32 v[210:211], s[64:65], s62, v174, 0
	v_pk_mul_f32 v[222:223], v[22:23], v[162:163] op_sel_hi:[1,0]
	v_pk_mul_f32 v[224:225], v[20:21], v[162:163] op_sel_hi:[1,0]
	v_add3_u32 v211, v211, v185, v179
	v_pk_mul_f32 v[214:215], v[30:31], v[162:163] op_sel_hi:[1,0]
	v_pk_mul_f32 v[216:217], v[28:29], v[162:163] op_sel_hi:[1,0]
	v_pk_mul_f32 v[218:219], v[26:27], v[162:163] op_sel_hi:[1,0]
	v_pk_mul_f32 v[220:221], v[24:25], v[162:163] op_sel_hi:[1,0]
	v_pk_mul_f32 v[226:227], v[18:19], v[162:163] op_sel_hi:[1,0]
	v_pk_mul_f32 v[228:229], v[16:17], v[162:163] op_sel_hi:[1,0]
	v_lshl_add_u64 v[230:231], v[210:211], 1, v[192:193]
	s_waitcnt vmcnt(5)
; DI v4u pack8(const f4& a, const f4& b) { v4u w; w.x = cvt_pk_bf16(a[0], a[1]); w.y = cvt_pk_bf16(a[2], a[3]); w.z = cvt_pk_bf16(b[0], b[1]); w.w = cvt_pk_bf16(b[2], b[3]); return w; }
;     DI void operator()(f4 (&acc)[2][2][4][2], const Unit& u, int wr, int wc, int fr, int fq) const {
;     ...
;         } else if (kind == 1 || wc < 2) {
;             const int hb = cb + (wc >> 1) * 128, dd0 = (wc & 1) * 32 + 8 * fq;
; #pragma unroll
;             for (int ai = 0; ai < 2; ++ai)
; #pragma unroll
;               for (int mp = 0; mp < 2; ++mp) {
;                 f4 cv[2][2], sv[2][2];
; #pragma unroll
;                 for (int mm = 0; mm < 2; ++mm) { const size_t to = (size_t)(row0 + ai * HALF + (2 * mp + mm) * 16) * 64 + dd0; cv[mm][0] = *(const f4*)(rcos + to); cv[mm][1] = *(const f4*)(rcos + to + 4); sv[mm][0] = *(const f4*)(rsin + to); sv[mm][1] = *(const f4*)(rsin + to + 4); }
;                 asm volatile("" ::: "memory");
; #pragma unroll
;                 for (int mm = 0; mm < 2; ++mm) { const int m = 2 * mp + mm, row = row0 + ai * HALF + m * 16; const float rs = rsv[ai][m];
;                     const f4 c0 = cv[mm][0], c1 = cv[mm][1], s0 = sv[mm][0], s1 = sv[mm][1];
;                     const f4 a0 = acc[ai][0][m][0] * rs, a1 = acc[ai][0][m][1] * rs, b0 = acc[ai][1][m][0] * rs, b1 = acc[ai][1][m][1] * rs;
;                     bf16* p = dst + (size_t)row * ld + hb + dd0;
;                     *(v4u*)(p)      = pack8(a0 * c0 - b0 * s0, a1 * c1 - b1 * s1);
;                     *(v4u*)(p + 64) = pack8(a0 * s0 + b0 * c0, a1 * s1 + b1 * c1); }
;                 asm volatile("" ::: "memory"); }
	v_pk_mul_f32 v[234:235], v[228:229], v[136:137]
	s_waitcnt vmcnt(4)
	v_pk_mul_f32 v[210:211], v[222:223], v[142:143]
	v_pk_mul_f32 v[212:213], v[224:225], v[140:141]
	v_pk_fma_f32 v[232:233], v[214:215], v[134:135], v[210:211] neg_lo:[0,0,1] neg_hi:[0,0,1]
	v_pk_fma_f32 v[210:211], v[216:217], v[132:133], v[212:213] neg_lo:[0,0,1] neg_hi:[0,0,1]
	v_pk_mul_f32 v[212:213], v[226:227], v[138:139]
	v_pk_mul_f32 v[138:139], v[218:219], v[138:139]
	v_pk_mul_f32 v[136:137], v[220:221], v[136:137]
	v_pk_fma_f32 v[236:237], v[218:219], v[130:131], v[212:213] neg_lo:[0,0,1] neg_hi:[0,0,1]
	v_pk_fma_f32 v[212:213], v[220:221], v[128:129], v[234:235] neg_lo:[0,0,1] neg_hi:[0,0,1]
	v_pk_mul_f32 v[142:143], v[214:215], v[142:143]
	v_pk_mul_f32 v[140:141], v[216:217], v[140:141]
	v_pk_fma_f32 v[138:139], v[226:227], v[130:131], v[138:139]
	v_pk_fma_f32 v[130:131], v[228:229], v[128:129], v[136:137]
	v_cvt_pk_bf16_f32 v210, v210, v211
	v_cvt_pk_bf16_f32 v211, v232, v233
	v_cvt_pk_bf16_f32 v212, v212, v213
	v_cvt_pk_bf16_f32 v213, v236, v237
	global_store_dwordx4 v[230:231], v[210:213], off sc1
	v_pk_fma_f32 v[134:135], v[222:223], v[134:135], v[142:143]
	v_pk_fma_f32 v[132:133], v[224:225], v[132:133], v[140:141]
	v_pk_mul_f32 v[140:141], v[6:7], v[160:161] op_sel_hi:[1,0]
	v_cvt_pk_bf16_f32 v128, v132, v133
	v_cvt_pk_bf16_f32 v129, v134, v135
	v_cvt_pk_bf16_f32 v130, v130, v131
	v_cvt_pk_bf16_f32 v131, v138, v139
	global_store_dwordx4 v[230:231], v[128:131], off offset:128 sc1
	v_pk_mul_f32 v[142:143], v[4:5], v[160:161] op_sel_hi:[1,0]
	v_pk_mul_f32 v[132:133], v[14:15], v[160:161] op_sel_hi:[1,0]
	v_mul_lo_u32 v130, s63, v168
	v_mul_lo_u32 v131, s62, v169
	v_mad_u64_u32 v[128:129], s[64:65], s62, v168, 0
	v_add3_u32 v129, v129, v131, v130
	v_pk_mul_f32 v[134:135], v[12:13], v[160:161] op_sel_hi:[1,0]
	v_pk_mul_f32 v[210:211], v[2:3], v[160:161] op_sel_hi:[1,0]
	v_pk_mul_f32 v[212:213], v[0:1], v[160:161] op_sel_hi:[1,0]
	v_lshl_add_u64 v[192:193], v[128:129], 1, v[192:193]
	s_waitcnt vmcnt(2)
	v_pk_mul_f32 v[128:129], v[140:141], v[208:209]
	v_pk_mul_f32 v[130:131], v[142:143], v[206:207]
	v_pk_mul_f32 v[136:137], v[10:11], v[160:161] op_sel_hi:[1,0]
	v_pk_mul_f32 v[138:139], v[8:9], v[160:161] op_sel_hi:[1,0]
	v_pk_fma_f32 v[214:215], v[132:133], v[200:201], v[128:129] neg_lo:[0,0,1] neg_hi:[0,0,1]
	v_pk_fma_f32 v[128:129], v[134:135], v[198:199], v[130:131] neg_lo:[0,0,1] neg_hi:[0,0,1]
	v_pk_mul_f32 v[130:131], v[210:211], v[204:205]
	v_pk_mul_f32 v[216:217], v[212:213], v[202:203]
	v_pk_fma_f32 v[218:219], v[136:137], v[196:197], v[130:131] neg_lo:[0,0,1] neg_hi:[0,0,1]
	v_pk_fma_f32 v[130:131], v[138:139], v[194:195], v[216:217] neg_lo:[0,0,1] neg_hi:[0,0,1]
	v_cvt_pk_bf16_f32 v128, v128, v129
	v_cvt_pk_bf16_f32 v129, v214, v215
	s_nop 0
	v_cvt_pk_bf16_f32 v130, v130, v131
	v_cvt_pk_bf16_f32 v131, v218, v219
	global_store_dwordx4 v[192:193], v[128:131], off sc1
	s_nop 1
	v_pk_mul_f32 v[128:129], v[132:133], v[208:209]
	v_pk_mul_f32 v[130:131], v[134:135], v[206:207]
	v_pk_fma_f32 v[132:133], v[140:141], v[200:201], v[128:129]
	v_pk_fma_f32 v[128:129], v[142:143], v[198:199], v[130:131]
	v_pk_mul_f32 v[130:131], v[136:137], v[204:205]
	v_pk_mul_f32 v[134:135], v[138:139], v[202:203]
	v_pk_fma_f32 v[136:137], v[210:211], v[196:197], v[130:131]
	v_pk_fma_f32 v[130:131], v[212:213], v[194:195], v[134:135]
	v_cvt_pk_bf16_f32 v128, v128, v129
	v_cvt_pk_bf16_f32 v129, v132, v133
	s_nop 0
	v_cvt_pk_bf16_f32 v130, v130, v131
	v_cvt_pk_bf16_f32 v131, v136, v137
	global_store_dwordx4 v[192:193], v[128:131], off offset:128 sc1

; DI v4u pack8(const f4& a, const f4& b) { v4u w; w.x = cvt_pk_bf16(a[0], a[1]); w.y = cvt_pk_bf16(a[2], a[3]); w.z = cvt_pk_bf16(b[0], b[1]); w.w = cvt_pk_bf16(b[2], b[3]); return w; }
;     DI void operator()(f4 (&acc)[2][2][4][2], const Unit& u, int wr, int wc, int fr, int fq) const {
;     ...
;         } else if (kind == 0) {
; #pragma unroll
;             for (int ai = 0; ai < 2; ++ai)
; #pragma unroll
;                 for (int m = 0; m < 4; ++m) { const int row = row0 + ai * HALF + m * 16; const float rs = rsv[ai][m];
; #pragma unroll
;                     for (int bj = 0; bj < 2; ++bj) *(v4u*)(dst + (size_t)row * ld + cb + bj * HALF + wc * 32 + 8 * fq) = pack8(acc[ai][bj][m][0] * rs, acc[ai][bj][m][1] * rs); }
.LBB0_321:
	s_andn2_b64 vcc, exec, s[64:65]
	s_cbranch_vccnz .LBB0_323
	s_ashr_i32 s59, s58, 31
	s_lshl_b64 s[64:65], s[58:59], 1
	s_add_u32 s51, s60, s64
	s_addc_u32 s53, s61, s65
	s_add_u32 s64, s51, s91
	v_lshlrev_b32_e32 v128, 3, v173
	s_addc_u32 s65, s53, 0
	v_ashrrev_i32_e32 v129, 31, v128
	v_lshl_add_u64 v[128:129], v[128:129], 1, s[64:65]
	v_mul_lo_u32 v132, s63, v188
	v_mul_lo_u32 v133, s62, v189
	v_mad_u64_u32 v[130:131], s[64:65], s62, v188, 0
	v_add3_u32 v131, v131, v133, v132
	v_lshl_add_u64 v[134:135], v[130:131], 1, v[128:129]
	s_waitcnt vmcnt(0)
	v_pk_mul_f32 v[132:133], v[126:127], v[190:191] op_sel_hi:[1,0]
	v_pk_mul_f32 v[130:131], v[124:125], v[190:191] op_sel_hi:[1,0]
	v_pk_mul_f32 v[136:137], v[122:123], v[190:191] op_sel_hi:[1,0]
	v_pk_mul_f32 v[138:139], v[120:121], v[190:191] op_sel_hi:[1,0]
	v_cvt_pk_bf16_f32 v130, v130, v131
	v_cvt_pk_bf16_f32 v131, v132, v133
	s_nop 0
	v_cvt_pk_bf16_f32 v132, v138, v139
	v_cvt_pk_bf16_f32 v133, v136, v137
	global_store_dwordx4 v[134:135], v[130:133], off sc1
	v_pk_mul_f32 v[136:137], v[114:115], v[190:191] op_sel_hi:[1,0]
	v_pk_mul_f32 v[138:139], v[112:113], v[190:191] op_sel_hi:[1,0]
	v_pk_mul_f32 v[132:133], v[118:119], v[190:191] op_sel_hi:[1,0]
	v_pk_mul_f32 v[130:131], v[116:117], v[190:191] op_sel_hi:[1,0]
	s_nop 0
	v_cvt_pk_bf16_f32 v130, v130, v131
	v_cvt_pk_bf16_f32 v131, v132, v133
	v_cvt_pk_bf16_f32 v132, v138, v139
	v_cvt_pk_bf16_f32 v133, v136, v137
	global_store_dwordx4 v[134:135], v[130:133], off offset:256 sc1
	v_pk_mul_f32 v[136:137], v[106:107], v[184:185] op_sel_hi:[1,0]
	v_pk_mul_f32 v[138:139], v[104:105], v[184:185] op_sel_hi:[1,0]
	v_mul_lo_u32 v132, s63, v182
	v_mul_lo_u32 v133, s62, v183
	v_mad_u64_u32 v[130:131], s[64:65], s62, v182, 0
	v_add3_u32 v131, v131, v133, v132
	v_lshl_add_u64 v[134:135], v[130:131], 1, v[128:129]
	v_pk_mul_f32 v[132:133], v[110:111], v[184:185] op_sel_hi:[1,0]
	v_pk_mul_f32 v[130:131], v[108:109], v[184:185] op_sel_hi:[1,0]
	s_nop 0
	v_cvt_pk_bf16_f32 v130, v130, v131
	v_cvt_pk_bf16_f32 v131, v132, v133
	v_cvt_pk_bf16_f32 v132, v138, v139
	v_cvt_pk_bf16_f32 v133, v136, v137
	global_store_dwordx4 v[134:135], v[130:133], off sc1
	v_pk_mul_f32 v[136:137], v[98:99], v[184:185] op_sel_hi:[1,0]
	v_pk_mul_f32 v[138:139], v[96:97], v[184:185] op_sel_hi:[1,0]
	v_pk_mul_f32 v[132:133], v[102:103], v[184:185] op_sel_hi:[1,0]
	v_pk_mul_f32 v[130:131], v[100:101], v[184:185] op_sel_hi:[1,0]
	s_nop 0
	v_cvt_pk_bf16_f32 v130, v130, v131
	v_cvt_pk_bf16_f32 v131, v132, v133
	v_cvt_pk_bf16_f32 v132, v138, v139
	v_cvt_pk_bf16_f32 v133, v136, v137
	global_store_dwordx4 v[134:135], v[130:133], off offset:256 sc1
	v_pk_mul_f32 v[136:137], v[90:91], v[178:179] op_sel_hi:[1,0]
	v_pk_mul_f32 v[138:139], v[88:89], v[178:179] op_sel_hi:[1,0]
	v_mul_lo_u32 v132, s63, v176
	v_mul_lo_u32 v133, s62, v177
	v_mad_u64_u32 v[130:131], s[64:65], s62, v176, 0
	v_add3_u32 v131, v131, v133, v132
	v_lshl_add_u64 v[134:135], v[130:131], 1, v[128:129]
	v_pk_mul_f32 v[132:133], v[94:95], v[178:179] op_sel_hi:[1,0]
	v_pk_mul_f32 v[130:131], v[92:93], v[178:179] op_sel_hi:[1,0]
	s_nop 0
	v_cvt_pk_bf16_f32 v130, v130, v131
	v_cvt_pk_bf16_f32 v131, v132, v133
	v_cvt_pk_bf16_f32 v132, v138, v139
	v_cvt_pk_bf16_f32 v133, v136, v137
	global_store_dwordx4 v[134:135], v[130:133], off sc1
	v_pk_mul_f32 v[136:137], v[82:83], v[178:179] op_sel_hi:[1,0]
	v_pk_mul_f32 v[138:139], v[80:81], v[178:179] op_sel_hi:[1,0]
	v_pk_mul_f32 v[132:133], v[86:87], v[178:179] op_sel_hi:[1,0]
	v_pk_mul_f32 v[130:131], v[84:85], v[178:179] op_sel_hi:[1,0]
	s_nop 0
	v_cvt_pk_bf16_f32 v130, v130, v131
	v_cvt_pk_bf16_f32 v131, v132, v133
	v_cvt_pk_bf16_f32 v132, v138, v139
	v_cvt_pk_bf16_f32 v133, v136, v137
	global_store_dwordx4 v[134:135], v[130:133], off offset:256 sc1
	v_pk_mul_f32 v[136:137], v[74:75], v[172:173] op_sel_hi:[1,0]
	v_pk_mul_f32 v[138:139], v[72:73], v[172:173] op_sel_hi:[1,0]
	v_mul_lo_u32 v132, s63, v170
	v_mul_lo_u32 v133, s62, v171
	v_mad_u64_u32 v[130:131], s[64:65], s62, v170, 0
	v_add3_u32 v131, v131, v133, v132
	v_lshl_add_u64 v[134:135], v[130:131], 1, v[128:129]
	v_pk_mul_f32 v[132:133], v[78:79], v[172:173] op_sel_hi:[1,0]
	v_pk_mul_f32 v[130:131], v[76:77], v[172:173] op_sel_hi:[1,0]
	s_nop 0
	v_cvt_pk_bf16_f32 v130, v130, v131
	v_cvt_pk_bf16_f32 v131, v132, v133
	v_cvt_pk_bf16_f32 v132, v138, v139
	v_cvt_pk_bf16_f32 v133, v136, v137
	global_store_dwordx4 v[134:135], v[130:133], off sc1
	v_pk_mul_f32 v[136:137], v[66:67], v[172:173] op_sel_hi:[1,0]
	v_pk_mul_f32 v[138:139], v[64:65], v[172:173] op_sel_hi:[1,0]
	v_pk_mul_f32 v[132:133], v[70:71], v[172:173] op_sel_hi:[1,0]
	v_pk_mul_f32 v[130:131], v[68:69], v[172:173] op_sel_hi:[1,0]
	s_nop 0
; DI v4u pack8(const f4& a, const f4& b) { v4u w; w.x = cvt_pk_bf16(a[0], a[1]); w.y = cvt_pk_bf16(a[2], a[3]); w.z = cvt_pk_bf16(b[0], b[1]); w.w = cvt_pk_bf16(b[2], b[3]); return w; }
;     DI void operator()(f4 (&acc)[2][2][4][2], const Unit& u, int wr, int wc, int fr, int fq) const {
;     ...
;         } else if (kind == 0) {
; #pragma unroll
;             for (int ai = 0; ai < 2; ++ai)
; #pragma unroll
;                 for (int m = 0; m < 4; ++m) { const int row = row0 + ai * HALF + m * 16; const float rs = rsv[ai][m];
; #pragma unroll
;                     for (int bj = 0; bj < 2; ++bj) *(v4u*)(dst + (size_t)row * ld + cb + bj * HALF + wc * 32 + 8 * fq) = pack8(acc[ai][bj][m][0] * rs, acc[ai][bj][m][1] * rs); }
	v_cvt_pk_bf16_f32 v130, v130, v131
	v_cvt_pk_bf16_f32 v131, v132, v133
	v_cvt_pk_bf16_f32 v132, v138, v139
	v_cvt_pk_bf16_f32 v133, v136, v137
	global_store_dwordx4 v[134:135], v[130:133], off offset:256 sc1
	v_pk_mul_f32 v[136:137], v[58:59], v[166:167] op_sel_hi:[1,0]
	v_pk_mul_f32 v[138:139], v[56:57], v[166:167] op_sel_hi:[1,0]
	v_mul_lo_u32 v132, s63, v186
	v_mul_lo_u32 v133, s62, v187
	v_mad_u64_u32 v[130:131], s[64:65], s62, v186, 0
	v_add3_u32 v131, v131, v133, v132
	v_lshl_add_u64 v[134:135], v[130:131], 1, v[128:129]
	v_pk_mul_f32 v[132:133], v[62:63], v[166:167] op_sel_hi:[1,0]
	v_pk_mul_f32 v[130:131], v[60:61], v[166:167] op_sel_hi:[1,0]
	s_nop 0
	v_cvt_pk_bf16_f32 v130, v130, v131
	v_cvt_pk_bf16_f32 v131, v132, v133
	v_cvt_pk_bf16_f32 v132, v138, v139
	v_cvt_pk_bf16_f32 v133, v136, v137
	global_store_dwordx4 v[134:135], v[130:133], off sc1
	v_pk_mul_f32 v[136:137], v[50:51], v[166:167] op_sel_hi:[1,0]
	v_pk_mul_f32 v[138:139], v[48:49], v[166:167] op_sel_hi:[1,0]
	v_pk_mul_f32 v[132:133], v[54:55], v[166:167] op_sel_hi:[1,0]
	v_pk_mul_f32 v[130:131], v[52:53], v[166:167] op_sel_hi:[1,0]
	s_nop 0
	v_cvt_pk_bf16_f32 v130, v130, v131
	v_cvt_pk_bf16_f32 v131, v132, v133
	v_cvt_pk_bf16_f32 v132, v138, v139
	v_cvt_pk_bf16_f32 v133, v136, v137
	global_store_dwordx4 v[134:135], v[130:133], off offset:256 sc1
	v_pk_mul_f32 v[136:137], v[42:43], v[164:165] op_sel_hi:[1,0]
	v_pk_mul_f32 v[138:139], v[40:41], v[164:165] op_sel_hi:[1,0]
	v_mul_lo_u32 v132, s63, v180
	v_mul_lo_u32 v133, s62, v181
	v_mad_u64_u32 v[130:131], s[64:65], s62, v180, 0
	v_add3_u32 v131, v131, v133, v132
	v_lshl_add_u64 v[134:135], v[130:131], 1, v[128:129]
	v_pk_mul_f32 v[132:133], v[46:47], v[164:165] op_sel_hi:[1,0]
	v_pk_mul_f32 v[130:131], v[44:45], v[164:165] op_sel_hi:[1,0]
	s_nop 0
	v_cvt_pk_bf16_f32 v130, v130, v131
	v_cvt_pk_bf16_f32 v131, v132, v133
	v_cvt_pk_bf16_f32 v132, v138, v139
	v_cvt_pk_bf16_f32 v133, v136, v137
	global_store_dwordx4 v[134:135], v[130:133], off sc1
	v_pk_mul_f32 v[136:137], v[34:35], v[164:165] op_sel_hi:[1,0]
	v_pk_mul_f32 v[138:139], v[32:33], v[164:165] op_sel_hi:[1,0]
	v_pk_mul_f32 v[132:133], v[38:39], v[164:165] op_sel_hi:[1,0]
	v_pk_mul_f32 v[130:131], v[36:37], v[164:165] op_sel_hi:[1,0]
	s_nop 0
	v_cvt_pk_bf16_f32 v130, v130, v131
	v_cvt_pk_bf16_f32 v131, v132, v133
	v_cvt_pk_bf16_f32 v132, v138, v139
	v_cvt_pk_bf16_f32 v133, v136, v137
	global_store_dwordx4 v[134:135], v[130:133], off offset:256 sc1
	v_pk_mul_f32 v[136:137], v[26:27], v[162:163] op_sel_hi:[1,0]
	v_pk_mul_f32 v[138:139], v[24:25], v[162:163] op_sel_hi:[1,0]
	v_mul_lo_u32 v132, s63, v174
	v_mul_lo_u32 v133, s62, v175
	v_mad_u64_u32 v[130:131], s[64:65], s62, v174, 0
	v_add3_u32 v131, v131, v133, v132
	v_lshl_add_u64 v[134:135], v[130:131], 1, v[128:129]
	v_pk_mul_f32 v[132:133], v[30:31], v[162:163] op_sel_hi:[1,0]
	v_pk_mul_f32 v[130:131], v[28:29], v[162:163] op_sel_hi:[1,0]
	s_nop 0
	v_cvt_pk_bf16_f32 v130, v130, v131
	v_cvt_pk_bf16_f32 v131, v132, v133
	v_cvt_pk_bf16_f32 v132, v138, v139
	v_cvt_pk_bf16_f32 v133, v136, v137
	global_store_dwordx4 v[134:135], v[130:133], off sc1
	v_pk_mul_f32 v[136:137], v[18:19], v[162:163] op_sel_hi:[1,0]
	v_pk_mul_f32 v[138:139], v[16:17], v[162:163] op_sel_hi:[1,0]
	v_pk_mul_f32 v[132:133], v[22:23], v[162:163] op_sel_hi:[1,0]
	v_pk_mul_f32 v[130:131], v[20:21], v[162:163] op_sel_hi:[1,0]
	s_nop 0
	v_cvt_pk_bf16_f32 v130, v130, v131
	v_cvt_pk_bf16_f32 v131, v132, v133
	v_cvt_pk_bf16_f32 v132, v138, v139
	v_cvt_pk_bf16_f32 v133, v136, v137
	global_store_dwordx4 v[134:135], v[130:133], off offset:256 sc1
	v_pk_mul_f32 v[134:135], v[10:11], v[160:161] op_sel_hi:[1,0]
	v_pk_mul_f32 v[136:137], v[8:9], v[160:161] op_sel_hi:[1,0]
	v_mul_lo_u32 v132, s63, v168
	v_mul_lo_u32 v133, s62, v169
	v_mad_u64_u32 v[130:131], s[62:63], s62, v168, 0
	v_add3_u32 v131, v131, v133, v132
	v_lshl_add_u64 v[132:133], v[130:131], 1, v[128:129]
	v_pk_mul_f32 v[130:131], v[14:15], v[160:161] op_sel_hi:[1,0]
	v_pk_mul_f32 v[128:129], v[12:13], v[160:161] op_sel_hi:[1,0]
	s_nop 0
	v_cvt_pk_bf16_f32 v128, v128, v129
	v_cvt_pk_bf16_f32 v129, v130, v131
	v_cvt_pk_bf16_f32 v130, v136, v137
	v_cvt_pk_bf16_f32 v131, v134, v135
	global_store_dwordx4 v[132:133], v[128:131], off sc1
	v_pk_mul_f32 v[134:135], v[2:3], v[160:161] op_sel_hi:[1,0]
	v_pk_mul_f32 v[136:137], v[0:1], v[160:161] op_sel_hi:[1,0]
	v_pk_mul_f32 v[130:131], v[6:7], v[160:161] op_sel_hi:[1,0]
	v_pk_mul_f32 v[128:129], v[4:5], v[160:161] op_sel_hi:[1,0]
	s_nop 0
	v_cvt_pk_bf16_f32 v128, v128, v129
	v_cvt_pk_bf16_f32 v129, v130, v131
	v_cvt_pk_bf16_f32 v130, v136, v137
	v_cvt_pk_bf16_f32 v131, v134, v135
	global_store_dwordx4 v[132:133], v[128:131], off offset:256 sc1

; DI v4u pack8(const f4& a, const f4& b) { v4u w; w.x = cvt_pk_bf16(a[0], a[1]); w.y = cvt_pk_bf16(a[2], a[3]); w.z = cvt_pk_bf16(b[0], b[1]); w.w = cvt_pk_bf16(b[2], b[3]); return w; }
;     DI void operator()(f4 (&acc)[2][2][4][2], const Unit& u, int wr, int wc, int fr, int fq) const {
;     ...
;         if (kind == 3) {
;             const int col = cb + wc * 32 + 8 * fq;
;             const f4 ba0 = *(const f4*)(bgate + col), ba1 = *(const f4*)(bgate + col + 4), bb0 = *(const f4*)(bgate + D + col), bb1 = *(const f4*)(bgate + D + col + 4);
; #pragma unroll
;             for (int ai = 0; ai < 2; ++ai)
; #pragma unroll
;                 for (int m = 0; m < 4; ++m) { const int row = row0 + ai * HALF + m * 16; const float rs = rsv[ai][m];
;                     const f4 za0 = acc[ai][0][m][0] * rs + ba0, za1 = acc[ai][0][m][1] * rs + ba1, zb0 = acc[ai][1][m][0] * rs + bb0, zb1 = acc[ai][1][m][1] * rs + bb1;
;                     f4 r0, r1, g0, g1;
; #pragma unroll
;                     for (int t = 0; t < 4; ++t) { const float eb0 = 1.0f + __expf(-zb0[t]), eb1 = 1.0f + __expf(-zb1[t]);
;                         r0[t] = eb0 * __builtin_amdgcn_rcpf(1.0f + __expf(-za0[t])); r1[t] = eb1 * __builtin_amdgcn_rcpf(1.0f + __expf(-za1[t]));
;                         g0[t] = __builtin_amdgcn_rcpf(eb0); g1[t] = __builtin_amdgcn_rcpf(eb1); }
;                     *(v4u*)(dst + (size_t)row * D + col) = pack8(r0, r1); *(v4u*)(dst + (size_t)M * D + (size_t)row * D + col) = pack8(g0, g1); }
.LBB0_326:
	s_add_i32 s51, s58, s82
	v_lshl_add_u32 v192, v173, 3, s51
	v_ashrrev_i32_e32 v193, 31, v192
	v_lshlrev_b64 v[128:129], 2, v[192:193]
	v_lshl_add_u64 v[130:131], s[48:49], 0, v[128:129]
	v_lshl_add_u64 v[128:129], s[6:7], 0, v[128:129]
	global_load_dwordx4 v[136:139], v[130:131], off offset:16
	global_load_dwordx4 v[140:143], v[130:131], off
	global_load_dwordx4 v[132:135], v[128:129], off
	s_nop 0
	global_load_dwordx4 v[128:131], v[128:129], off offset:16
	s_mov_b64 s[58:59], 0x8000000
	v_lshl_add_u64 v[194:195], v[192:193], 1, s[60:61]
	v_lshl_add_u64 v[192:193], v[194:195], 0, s[58:59]
	s_waitcnt vmcnt(0)
	v_fma_f32 v112, v112, v190, v136
	v_fma_f32 v124, v124, v190, v132
	v_fma_f32 v120, v120, v190, v128
	v_fma_f32 v125, v125, v190, v133
	v_fma_f32 v121, v121, v190, v129
	v_fma_f32 v126, v126, v190, v134
	v_fma_f32 v122, v122, v190, v130
	v_fma_f32 v127, v127, v190, v135
	v_mul_f32_e32 v124, 0xbfb8aa3b, v124
	v_mul_f32_e32 v120, 0xbfb8aa3b, v120
	v_mul_f32_e32 v125, 0xbfb8aa3b, v125
	v_mul_f32_e32 v121, 0xbfb8aa3b, v121
	v_mul_f32_e32 v126, 0xbfb8aa3b, v126
	v_mul_f32_e32 v122, 0xbfb8aa3b, v122
	v_mul_f32_e32 v127, 0xbfb8aa3b, v127
	v_fma_f32 v123, v123, v190, v131
	v_exp_f32_e32 v124, v124
	v_exp_f32_e32 v120, v120
	v_exp_f32_e32 v125, v125
	v_exp_f32_e32 v121, v121
	v_exp_f32_e32 v126, v126
	v_exp_f32_e32 v122, v122
	v_exp_f32_e32 v127, v127
	v_mul_f32_e32 v123, 0xbfb8aa3b, v123
	v_fma_f32 v116, v116, v190, v140
	v_fma_f32 v117, v117, v190, v141
	v_fma_f32 v113, v113, v190, v137
	v_fma_f32 v118, v118, v190, v142
	v_fma_f32 v114, v114, v190, v138
	v_fma_f32 v119, v119, v190, v143
	v_exp_f32_e32 v123, v123
	v_fma_f32 v108, v108, v184, v132
	v_fma_f32 v104, v104, v184, v128
	v_mul_f32_e32 v116, 0xbfb8aa3b, v116
	v_mul_f32_e32 v112, 0xbfb8aa3b, v112
	v_mul_f32_e32 v117, 0xbfb8aa3b, v117
	v_mul_f32_e32 v113, 0xbfb8aa3b, v113
	v_mul_f32_e32 v118, 0xbfb8aa3b, v118
	v_mul_f32_e32 v114, 0xbfb8aa3b, v114
	v_mul_f32_e32 v119, 0xbfb8aa3b, v119
	v_mul_f32_e32 v108, 0xbfb8aa3b, v108
	v_mul_f32_e32 v104, 0xbfb8aa3b, v104
	v_fma_f32 v115, v115, v190, v139
	v_exp_f32_e32 v116, v116
	v_exp_f32_e32 v112, v112
	v_exp_f32_e32 v117, v117
	v_exp_f32_e32 v113, v113
	v_exp_f32_e32 v118, v118
	v_exp_f32_e32 v114, v114
	v_exp_f32_e32 v119, v119
	v_add_f32_e32 v124, 1.0, v124
	v_add_f32_e32 v120, 1.0, v120
	v_add_f32_e32 v125, 1.0, v125
	v_add_f32_e32 v121, 1.0, v121
	v_add_f32_e32 v126, 1.0, v126
	v_add_f32_e32 v122, 1.0, v122
	v_add_f32_e32 v127, 1.0, v127
	v_exp_f32_e32 v108, v108
	v_exp_f32_e32 v104, v104
	v_mul_f32_e32 v115, 0xbfb8aa3b, v115
	v_rcp_f32_e32 v124, v124
	v_rcp_f32_e32 v120, v120
	v_rcp_f32_e32 v125, v125
	v_rcp_f32_e32 v121, v121
	v_rcp_f32_e32 v126, v126
	v_rcp_f32_e32 v122, v122
	v_rcp_f32_e32 v127, v127
	v_exp_f32_e32 v115, v115
	v_add_f32_e32 v123, 1.0, v123
	v_fma_f32 v100, v100, v184, v140
	v_fma_f32 v96, v96, v184, v136
	v_rcp_f32_e32 v123, v123
	v_mul_f32_e32 v100, 0xbfb8aa3b, v100
	v_mul_f32_e32 v96, 0xbfb8aa3b, v96
	v_add_f32_e32 v116, 1.0, v116
	v_add_f32_e32 v112, 1.0, v112
	v_add_f32_e32 v117, 1.0, v117
	v_add_f32_e32 v113, 1.0, v113
	v_add_f32_e32 v118, 1.0, v118
	v_add_f32_e32 v114, 1.0, v114
	v_add_f32_e32 v119, 1.0, v119
	v_exp_f32_e32 v100, v100
	v_exp_f32_e32 v96, v96
	v_add_f32_e32 v108, 1.0, v108
	v_add_f32_e32 v104, 1.0, v104
	v_rcp_f32_e32 v173, v116
	v_rcp_f32_e32 v179, v112
	v_rcp_f32_e32 v185, v117
	v_rcp_f32_e32 v190, v113
	v_rcp_f32_e32 v191, v118
	v_rcp_f32_e32 v196, v114
	v_mul_f32_e32 v116, v124, v116
	v_mul_f32_e32 v120, v120, v112
	v_mul_f32_e32 v112, v125, v117
	v_mul_f32_e32 v117, v121, v113
	v_mul_f32_e32 v113, v126, v118
	v_mul_f32_e32 v118, v122, v114
	v_mul_f32_e32 v114, v127, v119
	v_rcp_f32_e32 v108, v108
	v_rcp_f32_e32 v104, v104
	v_add_f32_e32 v115, 1.0, v115
	v_cvt_pk_bf16_f32 v112, v116, v112
	v_cvt_pk_bf16_f32 v113, v113, v114
	v_cvt_pk_bf16_f32 v114, v120, v117
	v_lshlrev_b64 v[116:117], 13, v[188:189]
	v_mul_f32_e32 v121, v123, v115
	v_rcp_f32_e32 v122, v119
	v_rcp_f32_e32 v123, v115
	v_cvt_pk_bf16_f32 v115, v118, v121
	v_lshl_add_u64 v[118:119], v[194:195], 0, v[116:117]
	global_store_dwordx4 v[118:119], v[112:115], off sc1
	v_lshl_add_u64 v[116:117], v[192:193], 0, v[116:117]
	v_add_f32_e32 v100, 1.0, v100
	v_cvt_pk_bf16_f32 v112, v173, v185
	v_cvt_pk_bf16_f32 v113, v191, v122
	v_add_f32_e32 v96, 1.0, v96
	v_cvt_pk_bf16_f32 v114, v179, v190
	v_cvt_pk_bf16_f32 v115, v196, v123
	global_store_dwordx4 v[116:117], v[112:115], off sc1
	v_mul_f32_e32 v108, v108, v100
	v_mul_f32_e32 v104, v104, v96
	v_rcp_f32_e32 v112, v100
	v_rcp_f32_e32 v113, v96
	v_fma_f32 v96, v101, v184, v141
	v_fma_f32 v100, v109, v184, v133
	v_fma_f32 v101, v105, v184, v129
	v_mul_f32_e32 v100, 0xbfb8aa3b, v100
	v_mul_f32_e32 v101, 0xbfb8aa3b, v101
	v_exp_f32_e32 v100, v100
	v_exp_f32_e32 v101, v101
	v_fma_f32 v97, v97, v184, v137
	v_mul_f32_e32 v96, 0xbfb8aa3b, v96
	v_mul_f32_e32 v97, 0xbfb8aa3b, v97
	v_exp_f32_e32 v96, v96
	v_exp_f32_e32 v97, v97
	v_add_f32_e32 v100, 1.0, v100
	v_add_f32_e32 v101, 1.0, v101
	v_rcp_f32_e32 v100, v100
	v_rcp_f32_e32 v101, v101
	v_add_f32_e32 v96, 1.0, v96
	v_add_f32_e32 v97, 1.0, v97
	v_mul_f32_e32 v100, v100, v96
	v_mul_f32_e32 v101, v101, v97
	v_rcp_f32_e32 v105, v96
	v_rcp_f32_e32 v109, v97
	v_fma_f32 v96, v102, v184, v142
	v_fma_f32 v97, v98, v184, v138
	v_fma_f32 v98, v110, v184, v134
	v_fma_f32 v102, v106, v184, v130
	v_mul_f32_e32 v98, 0xbfb8aa3b, v98
	v_mul_f32_e32 v102, 0xbfb8aa3b, v102
	v_exp_f32_e32 v98, v98
	v_exp_f32_e32 v102, v102
	v_mul_f32_e32 v96, 0xbfb8aa3b, v96
	v_mul_f32_e32 v97, 0xbfb8aa3b, v97
	v_exp_f32_e32 v96, v96
	v_exp_f32_e32 v97, v97
	v_add_f32_e32 v98, 1.0, v98
; DI v4u pack8(const f4& a, const f4& b) { v4u w; w.x = cvt_pk_bf16(a[0], a[1]); w.y = cvt_pk_bf16(a[2], a[3]); w.z = cvt_pk_bf16(b[0], b[1]); w.w = cvt_pk_bf16(b[2], b[3]); return w; }
;     DI void operator()(f4 (&acc)[2][2][4][2], const Unit& u, int wr, int wc, int fr, int fq) const {
;     ...
;                 for (int m = 0; m < 4; ++m) { const int row = row0 + ai * HALF + m * 16; const float rs = rsv[ai][m];
;                     const f4 za0 = acc[ai][0][m][0] * rs + ba0, za1 = acc[ai][0][m][1] * rs + ba1, zb0 = acc[ai][1][m][0] * rs + bb0, zb1 = acc[ai][1][m][1] * rs + bb1;
;                     f4 r0, r1, g0, g1;
; #pragma unroll
;                     for (int t = 0; t < 4; ++t) { const float eb0 = 1.0f + __expf(-zb0[t]), eb1 = 1.0f + __expf(-zb1[t]);
;                         r0[t] = eb0 * __builtin_amdgcn_rcpf(1.0f + __expf(-za0[t])); r1[t] = eb1 * __builtin_amdgcn_rcpf(1.0f + __expf(-za1[t]));
;                         g0[t] = __builtin_amdgcn_rcpf(eb0); g1[t] = __builtin_amdgcn_rcpf(eb1); }
;                     *(v4u*)(dst + (size_t)row * D + col) = pack8(r0, r1); *(v4u*)(dst + (size_t)M * D + (size_t)row * D + col) = pack8(g0, g1); }
	v_add_f32_e32 v102, 1.0, v102
	v_rcp_f32_e32 v98, v98
	v_rcp_f32_e32 v102, v102
	v_add_f32_e32 v96, 1.0, v96
	v_add_f32_e32 v97, 1.0, v97
	v_mul_f32_e32 v98, v98, v96
	v_mul_f32_e32 v102, v102, v97
	v_rcp_f32_e32 v106, v96
	v_rcp_f32_e32 v110, v97
	v_fma_f32 v96, v103, v184, v143
	v_fma_f32 v97, v99, v184, v139
	v_fma_f32 v99, v111, v184, v135
	v_fma_f32 v103, v107, v184, v131
	v_mul_f32_e32 v99, 0xbfb8aa3b, v99
	v_mul_f32_e32 v103, 0xbfb8aa3b, v103
	v_exp_f32_e32 v99, v99
	v_exp_f32_e32 v103, v103
	v_fma_f32 v92, v92, v178, v132
	v_fma_f32 v88, v88, v178, v128
	v_mul_f32_e32 v92, 0xbfb8aa3b, v92
	v_mul_f32_e32 v88, 0xbfb8aa3b, v88
	v_mul_f32_e32 v96, 0xbfb8aa3b, v96
	v_mul_f32_e32 v97, 0xbfb8aa3b, v97
	v_exp_f32_e32 v92, v92
	v_exp_f32_e32 v88, v88
	v_exp_f32_e32 v96, v96
	v_exp_f32_e32 v97, v97
	v_add_f32_e32 v99, 1.0, v99
	v_add_f32_e32 v103, 1.0, v103
	v_rcp_f32_e32 v99, v99
	v_rcp_f32_e32 v103, v103
	v_fma_f32 v84, v84, v178, v140
	v_fma_f32 v80, v80, v178, v136
	v_mul_f32_e32 v84, 0xbfb8aa3b, v84
	v_mul_f32_e32 v80, 0xbfb8aa3b, v80
	v_exp_f32_e32 v84, v84
	v_exp_f32_e32 v80, v80
	v_add_f32_e32 v92, 1.0, v92
	v_add_f32_e32 v88, 1.0, v88
	v_add_f32_e32 v96, 1.0, v96
	v_add_f32_e32 v97, 1.0, v97
	v_rcp_f32_e32 v92, v92
	v_rcp_f32_e32 v88, v88
	v_mul_f32_e32 v99, v99, v96
	v_mul_f32_e32 v103, v103, v97
	v_rcp_f32_e32 v107, v96
	v_rcp_f32_e32 v111, v97
	v_cvt_pk_bf16_f32 v96, v108, v100
	v_cvt_pk_bf16_f32 v97, v98, v99
	v_cvt_pk_bf16_f32 v98, v104, v101
	v_lshlrev_b64 v[100:101], 13, v[182:183]
	v_cvt_pk_bf16_f32 v99, v102, v103
	v_lshl_add_u64 v[102:103], v[194:195], 0, v[100:101]
	global_store_dwordx4 v[102:103], v[96:99], off sc1
	v_lshl_add_u64 v[100:101], v[192:193], 0, v[100:101]
	v_add_f32_e32 v84, 1.0, v84
	v_cvt_pk_bf16_f32 v96, v112, v105
	v_cvt_pk_bf16_f32 v97, v106, v107
	v_add_f32_e32 v80, 1.0, v80
	v_cvt_pk_bf16_f32 v98, v113, v109
	v_cvt_pk_bf16_f32 v99, v110, v111
	global_store_dwordx4 v[100:101], v[96:99], off sc1
	v_mul_f32_e32 v92, v92, v84
	v_mul_f32_e32 v88, v88, v80
	v_rcp_f32_e32 v96, v84
	v_rcp_f32_e32 v97, v80
	v_fma_f32 v80, v85, v178, v141
	v_fma_f32 v84, v93, v178, v133
	v_fma_f32 v85, v89, v178, v129
	v_mul_f32_e32 v84, 0xbfb8aa3b, v84
	v_mul_f32_e32 v85, 0xbfb8aa3b, v85
	v_exp_f32_e32 v84, v84
	v_exp_f32_e32 v85, v85
	v_fma_f32 v81, v81, v178, v137
	v_mul_f32_e32 v80, 0xbfb8aa3b, v80
	v_mul_f32_e32 v81, 0xbfb8aa3b, v81
	v_exp_f32_e32 v80, v80
	v_exp_f32_e32 v81, v81
	v_add_f32_e32 v84, 1.0, v84
	v_add_f32_e32 v85, 1.0, v85
	v_rcp_f32_e32 v84, v84
	v_rcp_f32_e32 v85, v85
	v_add_f32_e32 v80, 1.0, v80
	v_add_f32_e32 v81, 1.0, v81
	v_mul_f32_e32 v84, v84, v80
	v_mul_f32_e32 v85, v85, v81
	v_rcp_f32_e32 v89, v80
	v_rcp_f32_e32 v93, v81
	v_fma_f32 v80, v86, v178, v142
	v_fma_f32 v81, v82, v178, v138
	v_fma_f32 v82, v94, v178, v134
	v_fma_f32 v86, v90, v178, v130
	v_mul_f32_e32 v82, 0xbfb8aa3b, v82
	v_mul_f32_e32 v86, 0xbfb8aa3b, v86
	v_exp_f32_e32 v82, v82
	v_exp_f32_e32 v86, v86
	v_mul_f32_e32 v80, 0xbfb8aa3b, v80
	v_mul_f32_e32 v81, 0xbfb8aa3b, v81
	v_exp_f32_e32 v80, v80
	v_exp_f32_e32 v81, v81
	v_add_f32_e32 v82, 1.0, v82
	v_add_f32_e32 v86, 1.0, v86
	v_rcp_f32_e32 v82, v82
	v_rcp_f32_e32 v86, v86
	v_add_f32_e32 v80, 1.0, v80
	v_add_f32_e32 v81, 1.0, v81
	v_mul_f32_e32 v82, v82, v80
	v_mul_f32_e32 v86, v86, v81
	v_rcp_f32_e32 v90, v80
	v_rcp_f32_e32 v94, v81
	v_fma_f32 v80, v87, v178, v143
	v_fma_f32 v81, v83, v178, v139
	v_fma_f32 v83, v95, v178, v135
	v_fma_f32 v87, v91, v178, v131
	v_mul_f32_e32 v83, 0xbfb8aa3b, v83
	v_mul_f32_e32 v87, 0xbfb8aa3b, v87
	v_exp_f32_e32 v83, v83
	v_exp_f32_e32 v87, v87
	v_fma_f32 v76, v76, v172, v132
	v_fma_f32 v72, v72, v172, v128
	v_mul_f32_e32 v76, 0xbfb8aa3b, v76
	v_mul_f32_e32 v72, 0xbfb8aa3b, v72
	v_mul_f32_e32 v80, 0xbfb8aa3b, v80
	v_mul_f32_e32 v81, 0xbfb8aa3b, v81
	v_exp_f32_e32 v76, v76
	v_exp_f32_e32 v72, v72
	v_exp_f32_e32 v80, v80
	v_exp_f32_e32 v81, v81
	v_add_f32_e32 v83, 1.0, v83
	v_add_f32_e32 v87, 1.0, v87
	v_rcp_f32_e32 v83, v83
	v_rcp_f32_e32 v87, v87
	v_fma_f32 v68, v68, v172, v140
	v_fma_f32 v64, v64, v172, v136
	v_mul_f32_e32 v68, 0xbfb8aa3b, v68
	v_mul_f32_e32 v64, 0xbfb8aa3b, v64
	v_exp_f32_e32 v68, v68
	v_exp_f32_e32 v64, v64
	v_add_f32_e32 v76, 1.0, v76
	v_add_f32_e32 v72, 1.0, v72
	v_add_f32_e32 v80, 1.0, v80
	v_add_f32_e32 v81, 1.0, v81
	v_rcp_f32_e32 v76, v76
	v_rcp_f32_e32 v72, v72
	v_mul_f32_e32 v83, v83, v80
	v_mul_f32_e32 v87, v87, v81
	v_rcp_f32_e32 v91, v80
	v_rcp_f32_e32 v95, v81
	v_cvt_pk_bf16_f32 v80, v92, v84
	v_cvt_pk_bf16_f32 v81, v82, v83
	v_cvt_pk_bf16_f32 v82, v88, v85
	v_lshlrev_b64 v[84:85], 13, v[176:177]
	v_cvt_pk_bf16_f32 v83, v86, v87
	v_lshl_add_u64 v[86:87], v[194:195], 0, v[84:85]
	global_store_dwordx4 v[86:87], v[80:83], off sc1
	v_lshl_add_u64 v[84:85], v[192:193], 0, v[84:85]
	v_add_f32_e32 v68, 1.0, v68
	v_cvt_pk_bf16_f32 v80, v96, v89
	v_cvt_pk_bf16_f32 v81, v90, v91
	v_add_f32_e32 v64, 1.0, v64
	v_cvt_pk_bf16_f32 v82, v97, v93
	v_cvt_pk_bf16_f32 v83, v94, v95
	global_store_dwordx4 v[84:85], v[80:83], off sc1
	v_mul_f32_e32 v76, v76, v68
	v_mul_f32_e32 v72, v72, v64
	v_rcp_f32_e32 v80, v68
	v_rcp_f32_e32 v81, v64
	v_fma_f32 v64, v69, v172, v141
	v_fma_f32 v68, v77, v172, v133
	v_fma_f32 v69, v73, v172, v129
	v_mul_f32_e32 v68, 0xbfb8aa3b, v68
	v_mul_f32_e32 v69, 0xbfb8aa3b, v69
	v_exp_f32_e32 v68, v68
	v_exp_f32_e32 v69, v69
	v_fma_f32 v65, v65, v172, v137
	v_mul_f32_e32 v64, 0xbfb8aa3b, v64
	v_mul_f32_e32 v65, 0xbfb8aa3b, v65
	v_exp_f32_e32 v64, v64
	v_exp_f32_e32 v65, v65
	v_add_f32_e32 v68, 1.0, v68
	v_add_f32_e32 v69, 1.0, v69
	v_rcp_f32_e32 v68, v68
	v_rcp_f32_e32 v69, v69
	v_add_f32_e32 v64, 1.0, v64
; DI v4u pack8(const f4& a, const f4& b) { v4u w; w.x = cvt_pk_bf16(a[0], a[1]); w.y = cvt_pk_bf16(a[2], a[3]); w.z = cvt_pk_bf16(b[0], b[1]); w.w = cvt_pk_bf16(b[2], b[3]); return w; }
;     DI void operator()(f4 (&acc)[2][2][4][2], const Unit& u, int wr, int wc, int fr, int fq) const {
;     ...
;                 for (int m = 0; m < 4; ++m) { const int row = row0 + ai * HALF + m * 16; const float rs = rsv[ai][m];
;                     const f4 za0 = acc[ai][0][m][0] * rs + ba0, za1 = acc[ai][0][m][1] * rs + ba1, zb0 = acc[ai][1][m][0] * rs + bb0, zb1 = acc[ai][1][m][1] * rs + bb1;
;                     f4 r0, r1, g0, g1;
; #pragma unroll
;                     for (int t = 0; t < 4; ++t) { const float eb0 = 1.0f + __expf(-zb0[t]), eb1 = 1.0f + __expf(-zb1[t]);
;                         r0[t] = eb0 * __builtin_amdgcn_rcpf(1.0f + __expf(-za0[t])); r1[t] = eb1 * __builtin_amdgcn_rcpf(1.0f + __expf(-za1[t]));
;                         g0[t] = __builtin_amdgcn_rcpf(eb0); g1[t] = __builtin_amdgcn_rcpf(eb1); }
;                     *(v4u*)(dst + (size_t)row * D + col) = pack8(r0, r1); *(v4u*)(dst + (size_t)M * D + (size_t)row * D + col) = pack8(g0, g1); }
	v_add_f32_e32 v65, 1.0, v65
	v_mul_f32_e32 v68, v68, v64
	v_mul_f32_e32 v69, v69, v65
	v_rcp_f32_e32 v73, v64
	v_rcp_f32_e32 v77, v65
	v_fma_f32 v64, v70, v172, v142
	v_fma_f32 v65, v66, v172, v138
	v_fma_f32 v66, v78, v172, v134
	v_fma_f32 v70, v74, v172, v130
	v_mul_f32_e32 v66, 0xbfb8aa3b, v66
	v_mul_f32_e32 v70, 0xbfb8aa3b, v70
	v_exp_f32_e32 v66, v66
	v_exp_f32_e32 v70, v70
	v_mul_f32_e32 v64, 0xbfb8aa3b, v64
	v_mul_f32_e32 v65, 0xbfb8aa3b, v65
	v_exp_f32_e32 v64, v64
	v_exp_f32_e32 v65, v65
	v_add_f32_e32 v66, 1.0, v66
	v_add_f32_e32 v70, 1.0, v70
	v_rcp_f32_e32 v66, v66
	v_rcp_f32_e32 v70, v70
	v_add_f32_e32 v64, 1.0, v64
	v_add_f32_e32 v65, 1.0, v65
	v_mul_f32_e32 v66, v66, v64
	v_mul_f32_e32 v70, v70, v65
	v_rcp_f32_e32 v74, v64
	v_rcp_f32_e32 v78, v65
	v_fma_f32 v64, v71, v172, v143
	v_fma_f32 v65, v67, v172, v139
	v_fma_f32 v67, v79, v172, v135
	v_fma_f32 v71, v75, v172, v131
	v_mul_f32_e32 v67, 0xbfb8aa3b, v67
	v_mul_f32_e32 v71, 0xbfb8aa3b, v71
	v_exp_f32_e32 v67, v67
	v_exp_f32_e32 v71, v71
	v_fma_f32 v60, v60, v166, v132
	v_fma_f32 v56, v56, v166, v128
	v_mul_f32_e32 v60, 0xbfb8aa3b, v60
	v_mul_f32_e32 v56, 0xbfb8aa3b, v56
	v_mul_f32_e32 v64, 0xbfb8aa3b, v64
	v_mul_f32_e32 v65, 0xbfb8aa3b, v65
	v_exp_f32_e32 v60, v60
	v_exp_f32_e32 v56, v56
	v_exp_f32_e32 v64, v64
	v_exp_f32_e32 v65, v65
	v_add_f32_e32 v67, 1.0, v67
	v_add_f32_e32 v71, 1.0, v71
	v_rcp_f32_e32 v67, v67
	v_rcp_f32_e32 v71, v71
	v_fma_f32 v52, v52, v166, v140
	v_fma_f32 v48, v48, v166, v136
	v_mul_f32_e32 v52, 0xbfb8aa3b, v52
	v_mul_f32_e32 v48, 0xbfb8aa3b, v48
	v_exp_f32_e32 v52, v52
	v_exp_f32_e32 v48, v48
	v_add_f32_e32 v60, 1.0, v60
	v_add_f32_e32 v56, 1.0, v56
	v_add_f32_e32 v64, 1.0, v64
	v_add_f32_e32 v65, 1.0, v65
	v_rcp_f32_e32 v60, v60
	v_rcp_f32_e32 v56, v56
	v_mul_f32_e32 v67, v67, v64
	v_mul_f32_e32 v71, v71, v65
	v_rcp_f32_e32 v75, v64
	v_rcp_f32_e32 v79, v65
	v_cvt_pk_bf16_f32 v64, v76, v68
	v_cvt_pk_bf16_f32 v65, v66, v67
	v_cvt_pk_bf16_f32 v66, v72, v69
	v_lshlrev_b64 v[68:69], 13, v[170:171]
	v_cvt_pk_bf16_f32 v67, v70, v71
	v_lshl_add_u64 v[70:71], v[194:195], 0, v[68:69]
	global_store_dwordx4 v[70:71], v[64:67], off sc1
	v_lshl_add_u64 v[68:69], v[192:193], 0, v[68:69]
	v_add_f32_e32 v52, 1.0, v52
	v_cvt_pk_bf16_f32 v64, v80, v73
	v_cvt_pk_bf16_f32 v65, v74, v75
	v_add_f32_e32 v48, 1.0, v48
	v_cvt_pk_bf16_f32 v66, v81, v77
	v_cvt_pk_bf16_f32 v67, v78, v79
	global_store_dwordx4 v[68:69], v[64:67], off sc1
	v_mul_f32_e32 v60, v60, v52
	v_mul_f32_e32 v56, v56, v48
	v_rcp_f32_e32 v64, v52
	v_rcp_f32_e32 v65, v48
	v_fma_f32 v48, v53, v166, v141
	v_fma_f32 v52, v61, v166, v133
	v_fma_f32 v53, v57, v166, v129
	v_mul_f32_e32 v52, 0xbfb8aa3b, v52
	v_mul_f32_e32 v53, 0xbfb8aa3b, v53
	v_exp_f32_e32 v52, v52
	v_exp_f32_e32 v53, v53
	v_fma_f32 v49, v49, v166, v137
	v_mul_f32_e32 v48, 0xbfb8aa3b, v48
	v_mul_f32_e32 v49, 0xbfb8aa3b, v49
	v_exp_f32_e32 v48, v48
	v_exp_f32_e32 v49, v49
	v_add_f32_e32 v52, 1.0, v52
	v_add_f32_e32 v53, 1.0, v53
	v_rcp_f32_e32 v52, v52
	v_rcp_f32_e32 v53, v53
	v_add_f32_e32 v48, 1.0, v48
	v_add_f32_e32 v49, 1.0, v49
	v_mul_f32_e32 v52, v52, v48
	v_mul_f32_e32 v53, v53, v49
	v_rcp_f32_e32 v57, v48
	v_rcp_f32_e32 v61, v49
	v_fma_f32 v48, v54, v166, v142
	v_fma_f32 v49, v50, v166, v138
	v_fma_f32 v50, v62, v166, v134
	v_fma_f32 v54, v58, v166, v130
	v_mul_f32_e32 v50, 0xbfb8aa3b, v50
	v_mul_f32_e32 v54, 0xbfb8aa3b, v54
	v_exp_f32_e32 v50, v50
	v_exp_f32_e32 v54, v54
	v_mul_f32_e32 v48, 0xbfb8aa3b, v48
	v_mul_f32_e32 v49, 0xbfb8aa3b, v49
	v_exp_f32_e32 v48, v48
	v_exp_f32_e32 v49, v49
	v_add_f32_e32 v50, 1.0, v50
	v_add_f32_e32 v54, 1.0, v54
	v_rcp_f32_e32 v50, v50
	v_rcp_f32_e32 v54, v54
	v_add_f32_e32 v48, 1.0, v48
	v_add_f32_e32 v49, 1.0, v49
	v_mul_f32_e32 v50, v50, v48
	v_mul_f32_e32 v54, v54, v49
	v_rcp_f32_e32 v58, v48
	v_rcp_f32_e32 v62, v49
	v_fma_f32 v48, v55, v166, v143
	v_fma_f32 v49, v51, v166, v139
	v_fma_f32 v51, v63, v166, v135
	v_fma_f32 v55, v59, v166, v131
	v_mul_f32_e32 v51, 0xbfb8aa3b, v51
	v_mul_f32_e32 v55, 0xbfb8aa3b, v55
	v_exp_f32_e32 v51, v51
	v_exp_f32_e32 v55, v55
	v_fma_f32 v44, v44, v164, v132
	v_fma_f32 v40, v40, v164, v128
	v_mul_f32_e32 v44, 0xbfb8aa3b, v44
	v_mul_f32_e32 v40, 0xbfb8aa3b, v40
	v_mul_f32_e32 v48, 0xbfb8aa3b, v48
	v_mul_f32_e32 v49, 0xbfb8aa3b, v49
	v_exp_f32_e32 v44, v44
	v_exp_f32_e32 v40, v40
	v_exp_f32_e32 v48, v48
	v_exp_f32_e32 v49, v49
	v_add_f32_e32 v51, 1.0, v51
	v_add_f32_e32 v55, 1.0, v55
	v_rcp_f32_e32 v51, v51
	v_rcp_f32_e32 v55, v55
	v_fma_f32 v36, v36, v164, v140
	v_fma_f32 v32, v32, v164, v136
	v_mul_f32_e32 v36, 0xbfb8aa3b, v36
	v_mul_f32_e32 v32, 0xbfb8aa3b, v32
	v_exp_f32_e32 v36, v36
	v_exp_f32_e32 v32, v32
	v_add_f32_e32 v44, 1.0, v44
	v_add_f32_e32 v40, 1.0, v40
	v_add_f32_e32 v48, 1.0, v48
	v_add_f32_e32 v49, 1.0, v49
	v_rcp_f32_e32 v44, v44
	v_rcp_f32_e32 v40, v40
	v_mul_f32_e32 v51, v51, v48
	v_mul_f32_e32 v55, v55, v49
	v_rcp_f32_e32 v59, v48
	v_rcp_f32_e32 v63, v49
	v_cvt_pk_bf16_f32 v48, v60, v52
	v_cvt_pk_bf16_f32 v49, v50, v51
	v_cvt_pk_bf16_f32 v50, v56, v53
	v_lshlrev_b64 v[52:53], 13, v[186:187]
	v_cvt_pk_bf16_f32 v51, v54, v55
	v_lshl_add_u64 v[54:55], v[194:195], 0, v[52:53]
	global_store_dwordx4 v[54:55], v[48:51], off sc1
	v_lshl_add_u64 v[52:53], v[192:193], 0, v[52:53]
	v_add_f32_e32 v36, 1.0, v36
	v_cvt_pk_bf16_f32 v48, v64, v57
	v_cvt_pk_bf16_f32 v49, v58, v59
	v_add_f32_e32 v32, 1.0, v32
	v_cvt_pk_bf16_f32 v50, v65, v61
	v_cvt_pk_bf16_f32 v51, v62, v63
	global_store_dwordx4 v[52:53], v[48:51], off sc1
	v_mul_f32_e32 v44, v44, v36
	v_mul_f32_e32 v40, v40, v32
	v_rcp_f32_e32 v48, v36
	v_rcp_f32_e32 v49, v32
	v_fma_f32 v32, v37, v164, v141
; DI v4u pack8(const f4& a, const f4& b) { v4u w; w.x = cvt_pk_bf16(a[0], a[1]); w.y = cvt_pk_bf16(a[2], a[3]); w.z = cvt_pk_bf16(b[0], b[1]); w.w = cvt_pk_bf16(b[2], b[3]); return w; }
;     DI void operator()(f4 (&acc)[2][2][4][2], const Unit& u, int wr, int wc, int fr, int fq) const {
;     ...
;                 for (int m = 0; m < 4; ++m) { const int row = row0 + ai * HALF + m * 16; const float rs = rsv[ai][m];
;                     const f4 za0 = acc[ai][0][m][0] * rs + ba0, za1 = acc[ai][0][m][1] * rs + ba1, zb0 = acc[ai][1][m][0] * rs + bb0, zb1 = acc[ai][1][m][1] * rs + bb1;
;                     f4 r0, r1, g0, g1;
; #pragma unroll
;                     for (int t = 0; t < 4; ++t) { const float eb0 = 1.0f + __expf(-zb0[t]), eb1 = 1.0f + __expf(-zb1[t]);
;                         r0[t] = eb0 * __builtin_amdgcn_rcpf(1.0f + __expf(-za0[t])); r1[t] = eb1 * __builtin_amdgcn_rcpf(1.0f + __expf(-za1[t]));
;                         g0[t] = __builtin_amdgcn_rcpf(eb0); g1[t] = __builtin_amdgcn_rcpf(eb1); }
;                     *(v4u*)(dst + (size_t)row * D + col) = pack8(r0, r1); *(v4u*)(dst + (size_t)M * D + (size_t)row * D + col) = pack8(g0, g1); }
	v_fma_f32 v36, v45, v164, v133
	v_fma_f32 v37, v41, v164, v129
	v_mul_f32_e32 v36, 0xbfb8aa3b, v36
	v_mul_f32_e32 v37, 0xbfb8aa3b, v37
	v_exp_f32_e32 v36, v36
	v_exp_f32_e32 v37, v37
	v_fma_f32 v33, v33, v164, v137
	v_mul_f32_e32 v32, 0xbfb8aa3b, v32
	v_mul_f32_e32 v33, 0xbfb8aa3b, v33
	v_exp_f32_e32 v32, v32
	v_exp_f32_e32 v33, v33
	v_add_f32_e32 v36, 1.0, v36
	v_add_f32_e32 v37, 1.0, v37
	v_rcp_f32_e32 v36, v36
	v_rcp_f32_e32 v37, v37
	v_add_f32_e32 v32, 1.0, v32
	v_add_f32_e32 v33, 1.0, v33
	v_mul_f32_e32 v36, v36, v32
	v_mul_f32_e32 v37, v37, v33
	v_rcp_f32_e32 v41, v32
	v_rcp_f32_e32 v45, v33
	v_fma_f32 v32, v38, v164, v142
	v_fma_f32 v33, v34, v164, v138
	v_fma_f32 v34, v46, v164, v134
	v_fma_f32 v38, v42, v164, v130
	v_mul_f32_e32 v34, 0xbfb8aa3b, v34
	v_mul_f32_e32 v38, 0xbfb8aa3b, v38
	v_exp_f32_e32 v34, v34
	v_exp_f32_e32 v38, v38
	v_mul_f32_e32 v32, 0xbfb8aa3b, v32
	v_mul_f32_e32 v33, 0xbfb8aa3b, v33
	v_exp_f32_e32 v32, v32
	v_exp_f32_e32 v33, v33
	v_add_f32_e32 v34, 1.0, v34
	v_add_f32_e32 v38, 1.0, v38
	v_rcp_f32_e32 v34, v34
	v_rcp_f32_e32 v38, v38
	v_add_f32_e32 v32, 1.0, v32
	v_add_f32_e32 v33, 1.0, v33
	v_mul_f32_e32 v34, v34, v32
	v_mul_f32_e32 v38, v38, v33
	v_rcp_f32_e32 v42, v32
	v_rcp_f32_e32 v46, v33
	v_fma_f32 v32, v39, v164, v143
	v_fma_f32 v33, v35, v164, v139
	v_fma_f32 v35, v47, v164, v135
	v_fma_f32 v39, v43, v164, v131
	v_mul_f32_e32 v35, 0xbfb8aa3b, v35
	v_mul_f32_e32 v39, 0xbfb8aa3b, v39
	v_exp_f32_e32 v35, v35
	v_exp_f32_e32 v39, v39
	v_fma_f32 v28, v28, v162, v132
	v_fma_f32 v24, v24, v162, v128
	v_mul_f32_e32 v28, 0xbfb8aa3b, v28
	v_mul_f32_e32 v24, 0xbfb8aa3b, v24
	v_mul_f32_e32 v32, 0xbfb8aa3b, v32
	v_mul_f32_e32 v33, 0xbfb8aa3b, v33
	v_exp_f32_e32 v28, v28
	v_exp_f32_e32 v24, v24
	v_exp_f32_e32 v32, v32
	v_exp_f32_e32 v33, v33
	v_add_f32_e32 v35, 1.0, v35
	v_add_f32_e32 v39, 1.0, v39
	v_rcp_f32_e32 v35, v35
	v_rcp_f32_e32 v39, v39
	v_fma_f32 v20, v20, v162, v140
	v_fma_f32 v16, v16, v162, v136
	v_mul_f32_e32 v20, 0xbfb8aa3b, v20
	v_mul_f32_e32 v16, 0xbfb8aa3b, v16
	v_exp_f32_e32 v20, v20
	v_exp_f32_e32 v16, v16
	v_add_f32_e32 v28, 1.0, v28
	v_add_f32_e32 v24, 1.0, v24
	v_add_f32_e32 v32, 1.0, v32
	v_add_f32_e32 v33, 1.0, v33
	v_rcp_f32_e32 v28, v28
	v_rcp_f32_e32 v24, v24
	v_mul_f32_e32 v35, v35, v32
	v_mul_f32_e32 v39, v39, v33
	v_rcp_f32_e32 v43, v32
	v_rcp_f32_e32 v47, v33
	v_cvt_pk_bf16_f32 v32, v44, v36
	v_cvt_pk_bf16_f32 v33, v34, v35
	v_cvt_pk_bf16_f32 v34, v40, v37
	v_lshlrev_b64 v[36:37], 13, v[180:181]
	v_cvt_pk_bf16_f32 v35, v38, v39
	v_lshl_add_u64 v[38:39], v[194:195], 0, v[36:37]
	global_store_dwordx4 v[38:39], v[32:35], off sc1
	v_lshl_add_u64 v[36:37], v[192:193], 0, v[36:37]
	v_add_f32_e32 v20, 1.0, v20
	v_cvt_pk_bf16_f32 v32, v48, v41
	v_cvt_pk_bf16_f32 v33, v42, v43
	v_add_f32_e32 v16, 1.0, v16
	v_cvt_pk_bf16_f32 v34, v49, v45
	v_cvt_pk_bf16_f32 v35, v46, v47
	global_store_dwordx4 v[36:37], v[32:35], off sc1
	v_mul_f32_e32 v28, v28, v20
	v_mul_f32_e32 v24, v24, v16
	v_rcp_f32_e32 v32, v20
	v_rcp_f32_e32 v33, v16
	v_fma_f32 v16, v21, v162, v141
	v_fma_f32 v20, v29, v162, v133
	v_fma_f32 v21, v25, v162, v129
	v_mul_f32_e32 v20, 0xbfb8aa3b, v20
	v_mul_f32_e32 v21, 0xbfb8aa3b, v21
	v_exp_f32_e32 v20, v20
	v_exp_f32_e32 v21, v21
	v_fma_f32 v17, v17, v162, v137
	v_mul_f32_e32 v16, 0xbfb8aa3b, v16
	v_mul_f32_e32 v17, 0xbfb8aa3b, v17
	v_exp_f32_e32 v16, v16
	v_exp_f32_e32 v17, v17
	v_add_f32_e32 v20, 1.0, v20
	v_add_f32_e32 v21, 1.0, v21
	v_rcp_f32_e32 v20, v20
	v_rcp_f32_e32 v21, v21
	v_add_f32_e32 v16, 1.0, v16
	v_add_f32_e32 v17, 1.0, v17
	v_mul_f32_e32 v20, v20, v16
	v_mul_f32_e32 v21, v21, v17
	v_rcp_f32_e32 v25, v16
	v_rcp_f32_e32 v29, v17
	v_fma_f32 v16, v22, v162, v142
	v_fma_f32 v17, v18, v162, v138
	v_fma_f32 v18, v30, v162, v134
	v_fma_f32 v22, v26, v162, v130
	v_mul_f32_e32 v18, 0xbfb8aa3b, v18
	v_mul_f32_e32 v22, 0xbfb8aa3b, v22
	v_exp_f32_e32 v18, v18
	v_exp_f32_e32 v22, v22
	v_mul_f32_e32 v16, 0xbfb8aa3b, v16
	v_mul_f32_e32 v17, 0xbfb8aa3b, v17
	v_exp_f32_e32 v16, v16
	v_exp_f32_e32 v17, v17
	v_add_f32_e32 v18, 1.0, v18
	v_add_f32_e32 v22, 1.0, v22
	v_rcp_f32_e32 v18, v18
	v_rcp_f32_e32 v22, v22
	v_add_f32_e32 v16, 1.0, v16
	v_add_f32_e32 v17, 1.0, v17
; DI v4u pack8(const f4& a, const f4& b) { v4u w; w.x = cvt_pk_bf16(a[0], a[1]); w.y = cvt_pk_bf16(a[2], a[3]); w.z = cvt_pk_bf16(b[0], b[1]); w.w = cvt_pk_bf16(b[2], b[3]); return w; }
;     DI void operator()(f4 (&acc)[2][2][4][2], const Unit& u, int wr, int wc, int fr, int fq) const {
;     ...
;                 for (int m = 0; m < 4; ++m) { const int row = row0 + ai * HALF + m * 16; const float rs = rsv[ai][m];
;                     const f4 za0 = acc[ai][0][m][0] * rs + ba0, za1 = acc[ai][0][m][1] * rs + ba1, zb0 = acc[ai][1][m][0] * rs + bb0, zb1 = acc[ai][1][m][1] * rs + bb1;
;                     f4 r0, r1, g0, g1;
; #pragma unroll
;                     for (int t = 0; t < 4; ++t) { const float eb0 = 1.0f + __expf(-zb0[t]), eb1 = 1.0f + __expf(-zb1[t]);
;                         r0[t] = eb0 * __builtin_amdgcn_rcpf(1.0f + __expf(-za0[t])); r1[t] = eb1 * __builtin_amdgcn_rcpf(1.0f + __expf(-za1[t]));
;                         g0[t] = __builtin_amdgcn_rcpf(eb0); g1[t] = __builtin_amdgcn_rcpf(eb1); }
;                     *(v4u*)(dst + (size_t)row * D + col) = pack8(r0, r1); *(v4u*)(dst + (size_t)M * D + (size_t)row * D + col) = pack8(g0, g1); }
	v_mul_f32_e32 v18, v18, v16
	v_mul_f32_e32 v22, v22, v17
	v_rcp_f32_e32 v26, v16
	v_rcp_f32_e32 v30, v17
	v_fma_f32 v16, v23, v162, v143
	v_fma_f32 v17, v19, v162, v139
	v_fma_f32 v19, v31, v162, v135
	v_fma_f32 v23, v27, v162, v131
	v_mul_f32_e32 v19, 0xbfb8aa3b, v19
	v_mul_f32_e32 v23, 0xbfb8aa3b, v23
	v_exp_f32_e32 v19, v19
	v_exp_f32_e32 v23, v23
	v_fma_f32 v12, v12, v160, v132
	v_fma_f32 v8, v8, v160, v128
	v_mul_f32_e32 v12, 0xbfb8aa3b, v12
	v_mul_f32_e32 v8, 0xbfb8aa3b, v8
	v_mul_f32_e32 v16, 0xbfb8aa3b, v16
	v_mul_f32_e32 v17, 0xbfb8aa3b, v17
	v_exp_f32_e32 v12, v12
	v_exp_f32_e32 v8, v8
	v_exp_f32_e32 v16, v16
	v_exp_f32_e32 v17, v17
	v_add_f32_e32 v19, 1.0, v19
	v_add_f32_e32 v23, 1.0, v23
	v_rcp_f32_e32 v19, v19
	v_rcp_f32_e32 v23, v23
	v_fma_f32 v4, v4, v160, v140
	v_fma_f32 v0, v0, v160, v136
	v_mul_f32_e32 v4, 0xbfb8aa3b, v4
	v_mul_f32_e32 v0, 0xbfb8aa3b, v0
	v_exp_f32_e32 v4, v4
	v_exp_f32_e32 v0, v0
	v_add_f32_e32 v12, 1.0, v12
	v_add_f32_e32 v8, 1.0, v8
	v_add_f32_e32 v16, 1.0, v16
	v_add_f32_e32 v17, 1.0, v17
	v_rcp_f32_e32 v12, v12
	v_rcp_f32_e32 v8, v8
	v_mul_f32_e32 v19, v19, v16
	v_mul_f32_e32 v23, v23, v17
	v_rcp_f32_e32 v27, v16
	v_rcp_f32_e32 v31, v17
	v_cvt_pk_bf16_f32 v16, v28, v20
	v_cvt_pk_bf16_f32 v17, v18, v19
	v_cvt_pk_bf16_f32 v18, v24, v21
	v_lshlrev_b64 v[20:21], 13, v[174:175]
	v_cvt_pk_bf16_f32 v19, v22, v23
	v_lshl_add_u64 v[22:23], v[194:195], 0, v[20:21]
	global_store_dwordx4 v[22:23], v[16:19], off sc1
	v_lshl_add_u64 v[20:21], v[192:193], 0, v[20:21]
	v_add_f32_e32 v4, 1.0, v4
	v_cvt_pk_bf16_f32 v16, v32, v25
	v_cvt_pk_bf16_f32 v17, v26, v27
	v_add_f32_e32 v0, 1.0, v0
	v_cvt_pk_bf16_f32 v18, v33, v29
	v_cvt_pk_bf16_f32 v19, v30, v31
	global_store_dwordx4 v[20:21], v[16:19], off sc1
	v_mul_f32_e32 v12, v12, v4
	v_mul_f32_e32 v8, v8, v0
	v_rcp_f32_e32 v16, v4
	v_rcp_f32_e32 v17, v0
	v_fma_f32 v0, v5, v160, v141
	v_fma_f32 v4, v13, v160, v133
	v_fma_f32 v5, v9, v160, v129
	v_mul_f32_e32 v4, 0xbfb8aa3b, v4
	v_mul_f32_e32 v5, 0xbfb8aa3b, v5
	v_exp_f32_e32 v4, v4
	v_exp_f32_e32 v5, v5
	v_fma_f32 v1, v1, v160, v137
	v_mul_f32_e32 v0, 0xbfb8aa3b, v0
	v_mul_f32_e32 v1, 0xbfb8aa3b, v1
	v_exp_f32_e32 v0, v0
	v_exp_f32_e32 v1, v1
	v_add_f32_e32 v4, 1.0, v4
	v_add_f32_e32 v5, 1.0, v5
	v_rcp_f32_e32 v4, v4
	v_rcp_f32_e32 v5, v5
	v_add_f32_e32 v0, 1.0, v0
	v_add_f32_e32 v1, 1.0, v1
	v_mul_f32_e32 v4, v4, v0
	v_mul_f32_e32 v5, v5, v1
	v_rcp_f32_e32 v9, v0
	v_rcp_f32_e32 v13, v1
	v_fma_f32 v0, v6, v160, v142
	v_fma_f32 v1, v2, v160, v138
	v_fma_f32 v2, v14, v160, v134
	v_fma_f32 v6, v10, v160, v130
	v_mul_f32_e32 v2, 0xbfb8aa3b, v2
	v_mul_f32_e32 v6, 0xbfb8aa3b, v6
	v_exp_f32_e32 v2, v2
	v_exp_f32_e32 v6, v6
	v_mul_f32_e32 v0, 0xbfb8aa3b, v0
	v_mul_f32_e32 v1, 0xbfb8aa3b, v1
	v_exp_f32_e32 v0, v0
	v_exp_f32_e32 v1, v1
	v_add_f32_e32 v2, 1.0, v2
	v_add_f32_e32 v6, 1.0, v6
	v_fmac_f32_e32 v135, v15, v160
	v_fmac_f32_e32 v131, v11, v160
	v_rcp_f32_e32 v2, v2
	v_rcp_f32_e32 v6, v6
	v_fmac_f32_e32 v143, v7, v160
	v_fmac_f32_e32 v139, v3, v160
	v_mul_f32_e32 v3, 0xbfb8aa3b, v135
	v_mul_f32_e32 v7, 0xbfb8aa3b, v131
	v_exp_f32_e32 v3, v3
	v_exp_f32_e32 v7, v7
	v_add_f32_e32 v0, 1.0, v0
	v_add_f32_e32 v1, 1.0, v1
	v_mul_f32_e32 v2, v2, v0
	v_mul_f32_e32 v6, v6, v1
	v_rcp_f32_e32 v10, v0
	v_rcp_f32_e32 v14, v1
	v_mul_f32_e32 v0, 0xbfb8aa3b, v143
	v_mul_f32_e32 v1, 0xbfb8aa3b, v139
	v_exp_f32_e32 v0, v0
	v_exp_f32_e32 v1, v1
	v_add_f32_e32 v3, 1.0, v3
	v_add_f32_e32 v7, 1.0, v7
	v_rcp_f32_e32 v3, v3
	v_rcp_f32_e32 v7, v7
	v_add_f32_e32 v0, 1.0, v0
	v_add_f32_e32 v1, 1.0, v1
	v_mul_f32_e32 v3, v3, v0
	v_mul_f32_e32 v7, v7, v1
	v_rcp_f32_e32 v11, v0
	v_rcp_f32_e32 v15, v1
	v_cvt_pk_bf16_f32 v0, v12, v4
	v_cvt_pk_bf16_f32 v1, v2, v3
	v_cvt_pk_bf16_f32 v2, v8, v5
	v_lshlrev_b64 v[4:5], 13, v[168:169]
	v_cvt_pk_bf16_f32 v3, v6, v7
	v_lshl_add_u64 v[6:7], v[194:195], 0, v[4:5]
	v_lshl_add_u64 v[4:5], v[192:193], 0, v[4:5]
	global_store_dwordx4 v[6:7], v[0:3], off sc1
	s_nop 1
	v_cvt_pk_bf16_f32 v0, v16, v9
	v_cvt_pk_bf16_f32 v1, v10, v11
	v_cvt_pk_bf16_f32 v2, v17, v13
	v_cvt_pk_bf16_f32 v3, v14, v15
	global_store_dwordx4 v[4:5], v[0:3], off sc1
	s_andn2_b64 vcc, exec, s[4:5]
	s_mov_b64 s[4:5], -1
	s_cbranch_vccnz .LBB0_273

; DI float sigmoidf_(float z) { return 1.0f / (1.0f + __expf(-z)); }
; DI v4u pack8(const f4& a, const f4& b) { v4u w; w.x = cvt_pk_bf16(a[0], a[1]); w.y = cvt_pk_bf16(a[2], a[3]); w.z = cvt_pk_bf16(b[0], b[1]); w.w = cvt_pk_bf16(b[2], b[3]); return w; }
; DI void unpack8(const v4u& w, f4& a, f4& b) { a[0] = bf_lo(w.x); a[1] = bf_hi(w.x); a[2] = bf_lo(w.y); a[3] = bf_hi(w.y); b[0] = bf_lo(w.z); b[1] = bf_hi(w.z); b[2] = bf_lo(w.w); b[3] = bf_hi(w.w); }
; DI void build_alora(unsigned char* ws, int gtid, int NT) {
;     ...
;     for (int e = gtid; e < 3 * M * 32; e += NT) {
;         const int which = e / (M * 32), r = e - which * (M * 32), m = r >> 5, j0 = (r & 31) * 8;
;         f32x4 o0 = {0.f, 0.f, 0.f, 0.f}, o1 = o0;
;         const int width = which == 2 ? 256 : 96, ca = which == 0 ? 0 : (which == 1 ? 128 : 256), cbb = which == 0 ? 512 : (which == 1 ? 640 : 768);
;         if (j0 < width) {
;             f32x4 c0, c1, p0 = {0.f, 0.f, 0.f, 0.f}, p1 = p0;
;             epi::unpack8(*(const v4u*)(L + (size_t)m * LORA_LD + ca + j0), c0, c1);
;             if ((m & (SEQ - 1)) != 0) epi::unpack8(*(const v4u*)(L + (size_t)(m - 1) * LORA_LD + cbb + j0), p0, p1);
;             o0 = c0 + p0; o1 = c1 + p1;
;             if (which == 0) {
; #pragma unroll
;                 for (int t = 0; t < 4; ++t) { o0[t] = 1.0f - 2.0f / (__expf(2.0f * o0[t]) + 1.0f); o1[t] = 1.0f - 2.0f / (__expf(2.0f * o1[t]) + 1.0f); } }
;             if (which == 2) {
; #pragma unroll
;                 for (int t = 0; t < 4; ++t) { o0[t] = sigmoidf_(o0[t]); o1[t] = sigmoidf_(o1[t]); } }
;         }
;         *(v4u*)(A + ((size_t)which * M + m) * 256 + j0) = epi::pack8(o0, o1);
;     }
.LBB0_494:
	s_or_b64 exec, exec, s[16:17]
	v_ashrrev_i32_e32 v12, 19, v27
	v_ashrrev_i32_e32 v13, 31, v12
	v_cvt_pk_bf16_f32 v0, v0, v1
	v_cvt_pk_bf16_f32 v1, v2, v3
	v_cvt_pk_bf16_f32 v2, v4, v5
	v_lshlrev_b64 v[4:5], 23, v[12:13]
	v_cvt_pk_bf16_f32 v3, v6, v7
	v_lshl_add_u64 v[4:5], s[12:13], 0, v[4:5]
	v_lshlrev_b64 v[6:7], 9, v[10:11]
	v_add_u32_e32 v20, s20, v20
	v_lshl_add_u64 v[4:5], v[4:5], 0, v[6:7]
	v_cmp_lt_i32_e32 vcc, s26, v20
	v_lshl_add_u64 v[4:5], v[8:9], 1, v[4:5]
	s_or_b64 s[14:15], vcc, s[14:15]
	v_add_u32_e32 v21, s21, v21
	global_store_dwordx4 v[4:5], v[0:3], off sc1
	s_andn2_b64 exec, exec, s[14:15]
	s_cbranch_execz .LBB0_504

; DI v4u pack8(const f4& a, const f4& b) { v4u w; w.x = cvt_pk_bf16(a[0], a[1]); w.y = cvt_pk_bf16(a[2], a[3]); w.z = cvt_pk_bf16(b[0], b[1]); w.w = cvt_pk_bf16(b[2], b[3]); return w; }
;     DI void operator()(f4 (&acc)[2][2][4][2], const Unit& u, int wr, int wc, int fr, int fq) const {
;     ...
;         } else {
; #pragma unroll
;             for (int bj = 0; bj < 2; ++bj)
; #pragma unroll
;                 for (int ai = 0; ai < 2; ++ai)
; #pragma unroll
;                     for (int m = 0; m < 4; ++m) *(v4u*)(gout + (size_t)(row0 + ai * HALF + m * 16) * DB + col0 + bj * HALF) = pack8(acc[ai][bj][m][0], acc[ai][bj][m][1]);
;         }
.LBB0_2064:
	s_lshl_b32 s0, s10, 8
	s_and_b32 s0, s0, 0x3f00
	s_add_i32 s0, s0, s54
	v_mbcnt_lo_u32_b32 v128, -1, 0
	v_mbcnt_hi_u32_b32 v128, -1, v128
	s_nop 0
	v_and_or_b32 v144, v128, 15, s0
	s_lshl_b32 s0, s11, 8
	s_and_b32 s0, s0, 0x700
	v_ashrrev_i32_e32 v128, 1, v128
	v_and_b32_e32 v128, -8, v128
	s_or_b32 s0, s0, s55
	v_add_u32_e32 v150, s0, v128
	s_mov_b64 s[0:1], -1
	s_cmp_gt_u32 s10, 63
	v_ashrrev_i32_e32 v151, 31, v150
	s_cbranch_scc0 .LBB0_2071
	s_cmpk_lt_u32 s10, 0x80
	v_lshlrev_b64 v[152:153], 1, v[150:151]
	s_cbranch_scc1 .LBB0_2067
	v_lshlrev_b64 v[132:133], 12, v[144:145]
	v_or_b32_e32 v134, 16, v144
	v_mov_b32_e32 v135, v145
	v_lshl_add_u64 v[132:133], s[30:31], 0, v[132:133]
	v_lshlrev_b64 v[134:135], 12, v[134:135]
	v_or_b32_e32 v154, 32, v144
	v_mov_b32_e32 v155, v145
	v_cvt_pk_bf16_f32 v128, v124, v125
	v_cvt_pk_bf16_f32 v129, v126, v127
	v_cvt_pk_bf16_f32 v130, v120, v121
	v_cvt_pk_bf16_f32 v131, v122, v123
	v_lshl_add_u64 v[132:133], v[132:133], 0, v[152:153]
	v_lshl_add_u64 v[134:135], s[30:31], 0, v[134:135]
	v_lshlrev_b64 v[154:155], 12, v[154:155]
	v_or_b32_e32 v156, 48, v144
	v_mov_b32_e32 v157, v145
	global_store_dwordx4 v[132:133], v[128:131], off sc1
	v_lshl_add_u64 v[134:135], v[134:135], 0, v[152:153]
	v_lshl_add_u64 v[154:155], s[30:31], 0, v[154:155]
	v_cvt_pk_bf16_f32 v128, v116, v117
	v_cvt_pk_bf16_f32 v129, v118, v119
	v_cvt_pk_bf16_f32 v130, v112, v113
	v_cvt_pk_bf16_f32 v131, v114, v115
	v_lshlrev_b64 v[156:157], 12, v[156:157]
	v_add_u32_e32 v158, 0x80, v144
	v_mov_b32_e32 v159, v145
	global_store_dwordx4 v[134:135], v[128:131], off sc1
	v_lshl_add_u64 v[154:155], v[154:155], 0, v[152:153]
	v_lshl_add_u64 v[156:157], s[30:31], 0, v[156:157]
	v_cvt_pk_bf16_f32 v128, v108, v109
	v_cvt_pk_bf16_f32 v129, v110, v111
	v_cvt_pk_bf16_f32 v130, v104, v105
	v_cvt_pk_bf16_f32 v131, v106, v107
	v_lshlrev_b64 v[158:159], 12, v[158:159]
	v_add_u32_e32 v160, 0x90, v144
	v_mov_b32_e32 v161, v145
	global_store_dwordx4 v[154:155], v[128:131], off sc1
	v_lshl_add_u64 v[156:157], v[156:157], 0, v[152:153]
	v_lshl_add_u64 v[158:159], s[30:31], 0, v[158:159]
	v_cvt_pk_bf16_f32 v128, v100, v101
	v_cvt_pk_bf16_f32 v129, v102, v103
	v_cvt_pk_bf16_f32 v130, v96, v97
	v_cvt_pk_bf16_f32 v131, v98, v99
	v_lshlrev_b64 v[160:161], 12, v[160:161]
	v_add_u32_e32 v162, 0xa0, v144
	v_mov_b32_e32 v163, v145
	global_store_dwordx4 v[156:157], v[128:131], off sc1
	v_lshl_add_u64 v[158:159], v[158:159], 0, v[152:153]
	v_lshl_add_u64 v[160:161], s[30:31], 0, v[160:161]
	v_cvt_pk_bf16_f32 v128, v92, v93
	v_cvt_pk_bf16_f32 v129, v94, v95
	v_cvt_pk_bf16_f32 v130, v88, v89
	v_cvt_pk_bf16_f32 v131, v90, v91
	v_lshlrev_b64 v[162:163], 12, v[162:163]
	v_add_u32_e32 v164, 0xb0, v144
	v_mov_b32_e32 v165, v145
	global_store_dwordx4 v[158:159], v[128:131], off sc1
	v_lshl_add_u64 v[160:161], v[160:161], 0, v[152:153]
	v_lshl_add_u64 v[162:163], s[30:31], 0, v[162:163]
	v_cvt_pk_bf16_f32 v128, v84, v85
	v_cvt_pk_bf16_f32 v129, v86, v87
	v_cvt_pk_bf16_f32 v130, v80, v81
	v_cvt_pk_bf16_f32 v131, v82, v83
	v_lshlrev_b64 v[164:165], 12, v[164:165]
	global_store_dwordx4 v[160:161], v[128:131], off sc1
	v_lshl_add_u64 v[162:163], v[162:163], 0, v[152:153]
	v_lshl_add_u64 v[164:165], s[30:31], 0, v[164:165]
	v_cvt_pk_bf16_f32 v128, v76, v77
	v_cvt_pk_bf16_f32 v129, v78, v79
	v_cvt_pk_bf16_f32 v130, v72, v73
	v_cvt_pk_bf16_f32 v131, v74, v75
	global_store_dwordx4 v[162:163], v[128:131], off sc1
	v_lshl_add_u64 v[164:165], v[164:165], 0, v[152:153]
	s_mov_b64 s[0:1], 0
	v_cvt_pk_bf16_f32 v128, v68, v69
	v_cvt_pk_bf16_f32 v129, v70, v71
	v_cvt_pk_bf16_f32 v130, v64, v65
	v_cvt_pk_bf16_f32 v131, v66, v67
	global_store_dwordx4 v[164:165], v[128:131], off sc1
	s_nop 1
	v_cvt_pk_bf16_f32 v128, v60, v61
	v_cvt_pk_bf16_f32 v129, v62, v63
	v_cvt_pk_bf16_f32 v130, v56, v57
	v_cvt_pk_bf16_f32 v131, v58, v59
	global_store_dwordx4 v[132:133], v[128:131], off offset:256 sc1
	s_nop 1
	v_cvt_pk_bf16_f32 v128, v52, v53
	v_cvt_pk_bf16_f32 v129, v54, v55
	v_cvt_pk_bf16_f32 v130, v48, v49
	v_cvt_pk_bf16_f32 v131, v50, v51
	global_store_dwordx4 v[134:135], v[128:131], off offset:256 sc1
	s_nop 1
	v_cvt_pk_bf16_f32 v128, v44, v45
	v_cvt_pk_bf16_f32 v129, v46, v47
	v_cvt_pk_bf16_f32 v130, v40, v41
	v_cvt_pk_bf16_f32 v131, v42, v43
	global_store_dwordx4 v[154:155], v[128:131], off offset:256 sc1
	s_nop 1
	v_cvt_pk_bf16_f32 v128, v36, v37
	v_cvt_pk_bf16_f32 v129, v38, v39
	v_cvt_pk_bf16_f32 v130, v32, v33
	v_cvt_pk_bf16_f32 v131, v34, v35
	global_store_dwordx4 v[156:157], v[128:131], off offset:256 sc1
	s_nop 1
	v_cvt_pk_bf16_f32 v128, v28, v29
	v_cvt_pk_bf16_f32 v129, v30, v31
	v_cvt_pk_bf16_f32 v130, v24, v25
	v_cvt_pk_bf16_f32 v131, v26, v27
	global_store_dwordx4 v[158:159], v[128:131], off offset:256 sc1
	s_nop 1
	v_cvt_pk_bf16_f32 v128, v20, v21
	v_cvt_pk_bf16_f32 v129, v22, v23
	v_cvt_pk_bf16_f32 v130, v16, v17
	v_cvt_pk_bf16_f32 v131, v18, v19
	global_store_dwordx4 v[160:161], v[128:131], off offset:256 sc1
	s_nop 1
	v_cvt_pk_bf16_f32 v128, v12, v13
	v_cvt_pk_bf16_f32 v129, v14, v15
	v_cvt_pk_bf16_f32 v130, v8, v9
	v_cvt_pk_bf16_f32 v131, v10, v11
	global_store_dwordx4 v[162:163], v[128:131], off offset:256 sc1
	s_nop 1
	v_cvt_pk_bf16_f32 v128, v4, v5
	v_cvt_pk_bf16_f32 v129, v6, v7
	v_cvt_pk_bf16_f32 v130, v0, v1
	v_cvt_pk_bf16_f32 v131, v2, v3
	global_store_dwordx4 v[164:165], v[128:131], off offset:256 sc1
; DI float sigmoidf_(float z) { return 1.0f / (1.0f + __expf(-z)); }
; DI v4u pack8(const f4& a, const f4& b) { v4u w; w.x = cvt_pk_bf16(a[0], a[1]); w.y = cvt_pk_bf16(a[2], a[3]); w.z = cvt_pk_bf16(b[0], b[1]); w.w = cvt_pk_bf16(b[2], b[3]); return w; }
;     DI void operator()(f4 (&acc)[2][2][4][2], const Unit& u, int wr, int wc, int fr, int fq) const {
;     ...
;         } else if (which == 1) {
; #pragma unroll
;             for (int bj = 0; bj < 2; ++bj) { const int col = col0 + bj * HALF; const f4 z0 = *(const f4*)(a0 + col), z1 = *(const f4*)(a0 + col + 4);
; #pragma unroll
;                 for (int ai = 0; ai < 2; ++ai)
; #pragma unroll
;                     for (int m = 0; m < 4; ++m) { const size_t off = (size_t)(row0 + ai * HALF + m * 16) * DB + col;
;                         f4 x0 = acc[ai][bj][m][0] + z0, x1 = acc[ai][bj][m][1] + z1;
; #pragma unroll
;                         for (int e = 0; e < 4; ++e) { x0[e] = sigmoidf_(x0[e]); x1[e] = sigmoidf_(x1[e]); }
;                         *(v4u*)(aout + off) = pack8(x0, x1);
;                         asm volatile("" ::: "memory"); } }
.LBB0_2067:
	s_andn2_b64 vcc, exec, s[0:1]
	s_cbranch_vccnz .LBB0_2069
	v_lshl_add_u64 v[154:155], v[150:151], 2, s[22:23]
	global_load_dwordx4 v[132:135], v[154:155], off
	global_load_dwordx4 v[128:131], v[154:155], off offset:16
	s_waitcnt vmcnt(0)
	v_pk_add_f32 v[158:159], v[124:125], v[132:133]
	v_pk_add_f32 v[162:163], v[120:121], v[128:129]
	v_mul_f32_e32 v158, 0xbfb8aa3b, v158
	v_mul_f32_e32 v162, 0xbfb8aa3b, v162
	v_exp_f32_e32 v158, v158
	v_mul_f32_e32 v159, 0xbfb8aa3b, v159
	v_exp_f32_e32 v162, v162
	v_pk_add_f32 v[156:157], v[126:127], v[134:135]
	v_mul_f32_e32 v163, 0xbfb8aa3b, v163
	v_exp_f32_e32 v159, v159
	v_mul_f32_e32 v156, 0xbfb8aa3b, v156
	v_exp_f32_e32 v163, v163
	v_exp_f32_e32 v156, v156
	v_add_f32_e32 v158, 1.0, v158
	v_add_f32_e32 v162, 1.0, v162
	v_pk_add_f32 v[160:161], v[122:123], v[130:131]
	v_add_f32_e32 v159, 1.0, v159
	v_mul_f32_e32 v160, 0xbfb8aa3b, v160
	v_add_f32_e32 v163, 1.0, v163
	v_exp_f32_e32 v160, v160
	v_add_f32_e32 v156, 1.0, v156
	v_add_f32_e32 v160, 1.0, v160
	v_mul_f32_e32 v157, 0xbfb8aa3b, v157
	v_exp_f32_e32 v157, v157
	v_rcp_f32_e32 v158, v158
	v_rcp_f32_e32 v162, v162
	v_rcp_f32_e32 v159, v159
	v_add_f32_e32 v157, 1.0, v157
	v_rcp_f32_e32 v163, v163
	v_rcp_f32_e32 v156, v156
	v_mul_f32_e32 v161, 0xbfb8aa3b, v161
	v_rcp_f32_e32 v164, v160
	v_exp_f32_e32 v161, v161
	s_nop 0
	v_add_f32_e32 v161, 1.0, v161
	v_rcp_f32_e32 v157, v157
	v_cvt_pk_bf16_f32 v158, v158, v159
	v_rcp_f32_e32 v161, v161
	v_cvt_pk_bf16_f32 v159, v156, v157
	v_cvt_pk_bf16_f32 v160, v162, v163
	v_pk_add_f32 v[162:163], v[116:117], v[132:133]
	v_lshlrev_b64 v[156:157], 12, v[144:145]
	v_mul_f32_e32 v162, 0xbfb8aa3b, v162
	v_exp_f32_e32 v162, v162
	v_lshl_add_u64 v[156:157], s[28:29], 0, v[156:157]
	v_lshl_add_u64 v[156:157], v[156:157], 0, v[152:153]
	v_cvt_pk_bf16_f32 v161, v164, v161
	global_store_dwordx4 v[156:157], v[158:161], off sc1
	v_pk_add_f32 v[166:167], v[112:113], v[128:129]
	v_mul_f32_e32 v163, 0xbfb8aa3b, v163
	v_add_f32_e32 v159, 1.0, v162
	v_mul_f32_e32 v166, 0xbfb8aa3b, v166
	v_exp_f32_e32 v166, v166
	v_exp_f32_e32 v163, v163
	v_add_f32_e32 v166, 1.0, v166
	v_rcp_f32_e32 v162, v159
	v_add_f32_e32 v163, 1.0, v163
	v_mul_f32_e32 v167, 0xbfb8aa3b, v167
	v_rcp_f32_e32 v166, v166
	v_exp_f32_e32 v167, v167
	s_nop 0
	v_add_f32_e32 v167, 1.0, v167
	v_pk_add_f32 v[160:161], v[118:119], v[134:135]
	v_mul_f32_e32 v160, 0xbfb8aa3b, v160
	v_rcp_f32_e32 v163, v163
	v_exp_f32_e32 v160, v160
	s_nop 0
	v_add_f32_e32 v160, 1.0, v160
	v_pk_add_f32 v[164:165], v[114:115], v[130:131]
	v_mul_f32_e32 v164, 0xbfb8aa3b, v164
	v_rcp_f32_e32 v167, v167
	v_exp_f32_e32 v164, v164
	s_nop 0
	v_add_f32_e32 v164, 1.0, v164
	v_mul_f32_e32 v161, 0xbfb8aa3b, v161
	v_rcp_f32_e32 v168, v160
	v_exp_f32_e32 v161, v161
	s_nop 0
	v_add_f32_e32 v161, 1.0, v161
	v_mul_f32_e32 v165, 0xbfb8aa3b, v165
	v_rcp_f32_e32 v164, v164
	v_exp_f32_e32 v165, v165
	s_nop 0
	v_add_f32_e32 v165, 1.0, v165
	v_rcp_f32_e32 v161, v161
	v_rcp_f32_e32 v165, v165
	v_cvt_pk_bf16_f32 v160, v162, v163
	v_cvt_pk_bf16_f32 v161, v168, v161
	v_cvt_pk_bf16_f32 v162, v166, v167
	v_cvt_pk_bf16_f32 v163, v164, v165
	v_pk_add_f32 v[164:165], v[108:109], v[132:133]
	v_or_b32_e32 v158, 16, v144
	v_mul_f32_e32 v164, 0xbfb8aa3b, v164
	v_mov_b32_e32 v159, v145
	v_exp_f32_e32 v164, v164
	v_lshlrev_b64 v[158:159], 12, v[158:159]
	v_lshl_add_u64 v[158:159], s[28:29], 0, v[158:159]
	v_lshl_add_u64 v[158:159], v[158:159], 0, v[152:153]
	global_store_dwordx4 v[158:159], v[160:163], off sc1
	v_pk_add_f32 v[168:169], v[104:105], v[128:129]
	v_mul_f32_e32 v165, 0xbfb8aa3b, v165
	v_add_f32_e32 v161, 1.0, v164
	v_mul_f32_e32 v168, 0xbfb8aa3b, v168
	v_exp_f32_e32 v168, v168
	v_exp_f32_e32 v165, v165
	v_add_f32_e32 v168, 1.0, v168
	v_rcp_f32_e32 v164, v161
	v_add_f32_e32 v165, 1.0, v165
	v_mul_f32_e32 v169, 0xbfb8aa3b, v169
	v_rcp_f32_e32 v168, v168
	v_exp_f32_e32 v169, v169
	s_nop 0
	v_add_f32_e32 v169, 1.0, v169
	v_pk_add_f32 v[162:163], v[110:111], v[134:135]
	v_mul_f32_e32 v162, 0xbfb8aa3b, v162
	v_rcp_f32_e32 v165, v165
	v_exp_f32_e32 v162, v162
	s_nop 0
	v_add_f32_e32 v162, 1.0, v162
	v_pk_add_f32 v[166:167], v[106:107], v[130:131]
	v_mul_f32_e32 v166, 0xbfb8aa3b, v166
	v_rcp_f32_e32 v169, v169
	v_exp_f32_e32 v166, v166
	s_nop 0
	v_add_f32_e32 v166, 1.0, v166
	v_mul_f32_e32 v163, 0xbfb8aa3b, v163
	v_rcp_f32_e32 v175, v162
	v_exp_f32_e32 v163, v163
	s_nop 0
	v_add_f32_e32 v163, 1.0, v163
	v_mul_f32_e32 v167, 0xbfb8aa3b, v167
	v_rcp_f32_e32 v166, v166
	v_exp_f32_e32 v167, v167
	s_nop 0
	v_add_f32_e32 v167, 1.0, v167
	v_rcp_f32_e32 v163, v163
	v_rcp_f32_e32 v167, v167
	v_cvt_pk_bf16_f32 v162, v164, v165
	v_cvt_pk_bf16_f32 v163, v175, v163
	v_cvt_pk_bf16_f32 v164, v168, v169
	v_cvt_pk_bf16_f32 v165, v166, v167
	v_pk_add_f32 v[166:167], v[100:101], v[132:133]
	v_or_b32_e32 v160, 32, v144
	v_mul_f32_e32 v166, 0xbfb8aa3b, v166
	v_mov_b32_e32 v161, v145
	v_exp_f32_e32 v166, v166
	v_lshlrev_b64 v[160:161], 12, v[160:161]
	v_lshl_add_u64 v[160:161], s[28:29], 0, v[160:161]
	v_lshl_add_u64 v[160:161], v[160:161], 0, v[152:153]
	global_store_dwordx4 v[160:161], v[162:165], off sc1
	v_pk_add_f32 v[176:177], v[96:97], v[128:129]
	v_mul_f32_e32 v167, 0xbfb8aa3b, v167
	v_add_f32_e32 v163, 1.0, v166
	v_mul_f32_e32 v176, 0xbfb8aa3b, v176
	v_exp_f32_e32 v176, v176
	v_exp_f32_e32 v167, v167
	v_add_f32_e32 v176, 1.0, v176
	v_rcp_f32_e32 v166, v163
	v_add_f32_e32 v167, 1.0, v167
	v_mul_f32_e32 v177, 0xbfb8aa3b, v177
	v_rcp_f32_e32 v175, v176
	v_exp_f32_e32 v177, v177
	s_nop 0
	v_add_f32_e32 v177, 1.0, v177
	v_pk_add_f32 v[164:165], v[102:103], v[134:135]
	v_mul_f32_e32 v164, 0xbfb8aa3b, v164
	v_rcp_f32_e32 v167, v167
; DI float sigmoidf_(float z) { return 1.0f / (1.0f + __expf(-z)); }
; DI v4u pack8(const f4& a, const f4& b) { v4u w; w.x = cvt_pk_bf16(a[0], a[1]); w.y = cvt_pk_bf16(a[2], a[3]); w.z = cvt_pk_bf16(b[0], b[1]); w.w = cvt_pk_bf16(b[2], b[3]); return w; }
;     DI void operator()(f4 (&acc)[2][2][4][2], const Unit& u, int wr, int wc, int fr, int fq) const {
;     ...
;             for (int bj = 0; bj < 2; ++bj) { const int col = col0 + bj * HALF; const f4 z0 = *(const f4*)(a0 + col), z1 = *(const f4*)(a0 + col + 4);
; #pragma unroll
;                 for (int ai = 0; ai < 2; ++ai)
; #pragma unroll
;                     for (int m = 0; m < 4; ++m) { const size_t off = (size_t)(row0 + ai * HALF + m * 16) * DB + col;
;                         f4 x0 = acc[ai][bj][m][0] + z0, x1 = acc[ai][bj][m][1] + z1;
; #pragma unroll
;                         for (int e = 0; e < 4; ++e) { x0[e] = sigmoidf_(x0[e]); x1[e] = sigmoidf_(x1[e]); }
;                         *(v4u*)(aout + off) = pack8(x0, x1);
;                         asm volatile("" ::: "memory"); } }
	v_exp_f32_e32 v164, v164
	s_nop 0
	v_add_f32_e32 v164, 1.0, v164
	v_pk_add_f32 v[168:169], v[98:99], v[130:131]
	v_mul_f32_e32 v168, 0xbfb8aa3b, v168
	v_rcp_f32_e32 v176, v177
	v_exp_f32_e32 v168, v168
	s_nop 0
	v_add_f32_e32 v168, 1.0, v168
	v_mul_f32_e32 v165, 0xbfb8aa3b, v165
	v_rcp_f32_e32 v177, v164
	v_exp_f32_e32 v165, v165
	s_nop 0
	v_add_f32_e32 v165, 1.0, v165
	v_mul_f32_e32 v169, 0xbfb8aa3b, v169
	v_rcp_f32_e32 v168, v168
	v_exp_f32_e32 v169, v169
	s_nop 0
	v_add_f32_e32 v169, 1.0, v169
	v_rcp_f32_e32 v165, v165
	v_rcp_f32_e32 v169, v169
	v_cvt_pk_bf16_f32 v164, v166, v167
	v_cvt_pk_bf16_f32 v165, v177, v165
	v_cvt_pk_bf16_f32 v166, v175, v176
	v_cvt_pk_bf16_f32 v167, v168, v169
	v_pk_add_f32 v[168:169], v[92:93], v[132:133]
	v_or_b32_e32 v162, 48, v144
	v_mul_f32_e32 v168, 0xbfb8aa3b, v168
	v_mov_b32_e32 v163, v145
	v_exp_f32_e32 v168, v168
	v_lshlrev_b64 v[162:163], 12, v[162:163]
	v_lshl_add_u64 v[162:163], s[28:29], 0, v[162:163]
	v_lshl_add_u64 v[162:163], v[162:163], 0, v[152:153]
	global_store_dwordx4 v[162:163], v[164:167], off sc1
	v_pk_add_f32 v[178:179], v[88:89], v[128:129]
	v_mul_f32_e32 v169, 0xbfb8aa3b, v169
	v_add_f32_e32 v165, 1.0, v168
	v_mul_f32_e32 v178, 0xbfb8aa3b, v178
	v_exp_f32_e32 v178, v178
	v_exp_f32_e32 v169, v169
	v_add_f32_e32 v178, 1.0, v178
	v_rcp_f32_e32 v168, v165
	v_add_f32_e32 v169, 1.0, v169
	v_mul_f32_e32 v179, 0xbfb8aa3b, v179
	v_rcp_f32_e32 v175, v178
	v_exp_f32_e32 v179, v179
	s_nop 0
	v_add_f32_e32 v179, 1.0, v179
	v_pk_add_f32 v[166:167], v[94:95], v[134:135]
	v_mul_f32_e32 v166, 0xbfb8aa3b, v166
	v_rcp_f32_e32 v169, v169
	v_exp_f32_e32 v166, v166
	s_nop 0
	v_add_f32_e32 v166, 1.0, v166
	v_pk_add_f32 v[176:177], v[90:91], v[130:131]
	v_mul_f32_e32 v176, 0xbfb8aa3b, v176
	v_rcp_f32_e32 v178, v179
	v_exp_f32_e32 v176, v176
	s_nop 0
	v_add_f32_e32 v176, 1.0, v176
	v_mul_f32_e32 v167, 0xbfb8aa3b, v167
	v_rcp_f32_e32 v179, v166
	v_exp_f32_e32 v167, v167
	s_nop 0
	v_add_f32_e32 v167, 1.0, v167
	v_mul_f32_e32 v177, 0xbfb8aa3b, v177
	v_rcp_f32_e32 v176, v176
	v_exp_f32_e32 v177, v177
	s_nop 0
	v_add_f32_e32 v177, 1.0, v177
	v_rcp_f32_e32 v167, v167
	v_rcp_f32_e32 v177, v177
	v_cvt_pk_bf16_f32 v166, v168, v169
	v_cvt_pk_bf16_f32 v167, v179, v167
	v_cvt_pk_bf16_f32 v168, v175, v178
	v_cvt_pk_bf16_f32 v169, v176, v177
	v_pk_add_f32 v[176:177], v[84:85], v[132:133]
	v_add_u32_e32 v164, 0x80, v144
	v_mul_f32_e32 v175, 0xbfb8aa3b, v176
	v_mov_b32_e32 v165, v145
	v_exp_f32_e32 v175, v175
	v_lshlrev_b64 v[164:165], 12, v[164:165]
	v_lshl_add_u64 v[164:165], s[28:29], 0, v[164:165]
	v_lshl_add_u64 v[164:165], v[164:165], 0, v[152:153]
	global_store_dwordx4 v[164:165], v[166:169], off sc1
	v_pk_add_f32 v[180:181], v[80:81], v[128:129]
	v_mul_f32_e32 v177, 0xbfb8aa3b, v177
	v_add_f32_e32 v167, 1.0, v175
	v_mul_f32_e32 v180, 0xbfb8aa3b, v180
	v_exp_f32_e32 v180, v180
	v_exp_f32_e32 v177, v177
	v_add_f32_e32 v180, 1.0, v180
	v_rcp_f32_e32 v175, v167
	v_add_f32_e32 v177, 1.0, v177
	v_mul_f32_e32 v181, 0xbfb8aa3b, v181
	v_rcp_f32_e32 v180, v180
	v_exp_f32_e32 v181, v181
	s_nop 0
	v_add_f32_e32 v181, 1.0, v181
	v_pk_add_f32 v[168:169], v[86:87], v[134:135]
	v_mul_f32_e32 v168, 0xbfb8aa3b, v168
	v_rcp_f32_e32 v176, v177
	v_exp_f32_e32 v168, v168
	s_nop 0
	v_add_f32_e32 v168, 1.0, v168
	v_pk_add_f32 v[178:179], v[82:83], v[130:131]
	v_mul_f32_e32 v178, 0xbfb8aa3b, v178
	v_rcp_f32_e32 v181, v181
	v_exp_f32_e32 v178, v178
	s_nop 0
	v_add_f32_e32 v178, 1.0, v178
	v_mul_f32_e32 v169, 0xbfb8aa3b, v169
	v_rcp_f32_e32 v168, v168
	v_exp_f32_e32 v169, v169
	s_nop 0
	v_add_f32_e32 v169, 1.0, v169
	v_rcp_f32_e32 v184, v178
	v_mul_f32_e32 v178, 0xbfb8aa3b, v179
	v_exp_f32_e32 v178, v178
	s_nop 0
	v_add_f32_e32 v178, 1.0, v178
	v_rcp_f32_e32 v169, v169
	v_cvt_pk_bf16_f32 v176, v175, v176
	v_cvt_pk_bf16_f32 v177, v168, v169
	v_pk_add_f32 v[168:169], v[76:77], v[132:133]
	v_rcp_f32_e32 v179, v178
	v_mul_f32_e32 v168, 0xbfb8aa3b, v168
	v_exp_f32_e32 v175, v168
	v_cvt_pk_bf16_f32 v178, v180, v181
	v_pk_add_f32 v[180:181], v[72:73], v[128:129]
	v_cvt_pk_bf16_f32 v179, v184, v179
	v_add_f32_e32 v175, 1.0, v175
	v_mul_f32_e32 v180, 0xbfb8aa3b, v180
	v_exp_f32_e32 v180, v180
	v_mul_f32_e32 v169, 0xbfb8aa3b, v169
	v_add_f32_e32 v180, 1.0, v180
	v_rcp_f32_e32 v175, v175
	v_exp_f32_e32 v169, v169
	s_nop 0
	v_add_f32_e32 v169, 1.0, v169
	v_mul_f32_e32 v181, 0xbfb8aa3b, v181
	v_rcp_f32_e32 v180, v180
	v_exp_f32_e32 v181, v181
	v_add_u32_e32 v166, 0x90, v144
	v_mov_b32_e32 v167, v145
	v_add_f32_e32 v181, 1.0, v181
	v_lshlrev_b64 v[166:167], 12, v[166:167]
	v_lshl_add_u64 v[166:167], s[28:29], 0, v[166:167]
	v_lshl_add_u64 v[166:167], v[166:167], 0, v[152:153]
	global_store_dwordx4 v[166:167], v[176:179], off sc1
	v_rcp_f32_e32 v182, v169
	s_nop 0
	v_pk_add_f32 v[176:177], v[78:79], v[134:135]
	v_mul_f32_e32 v176, 0xbfb8aa3b, v176
	v_exp_f32_e32 v176, v176
	s_nop 0
	v_add_f32_e32 v176, 1.0, v176
	v_pk_add_f32 v[178:179], v[74:75], v[130:131]
	v_mul_f32_e32 v178, 0xbfb8aa3b, v178
	v_rcp_f32_e32 v181, v181
	v_exp_f32_e32 v178, v178
	s_nop 0
	v_add_f32_e32 v178, 1.0, v178
	v_mul_f32_e32 v177, 0xbfb8aa3b, v177
	v_rcp_f32_e32 v183, v176
	v_exp_f32_e32 v177, v177
	s_nop 0
	v_add_f32_e32 v177, 1.0, v177
	v_rcp_f32_e32 v186, v178
	v_mul_f32_e32 v178, 0xbfb8aa3b, v179
	v_exp_f32_e32 v178, v178
	s_nop 0
	v_add_f32_e32 v178, 1.0, v178
	v_rcp_f32_e32 v177, v177
	v_pk_add_f32 v[132:133], v[68:69], v[132:133]
	v_mul_f32_e32 v132, 0xbfb8aa3b, v132
	v_cvt_pk_bf16_f32 v176, v175, v182
	v_exp_f32_e32 v175, v132
	v_add_u32_e32 v168, 0xa0, v144
	v_rcp_f32_e32 v179, v178
	v_mov_b32_e32 v169, v145
	v_lshlrev_b64 v[168:169], 12, v[168:169]
; DI float sigmoidf_(float z) { return 1.0f / (1.0f + __expf(-z)); }
; DI v4u pack8(const f4& a, const f4& b) { v4u w; w.x = cvt_pk_bf16(a[0], a[1]); w.y = cvt_pk_bf16(a[2], a[3]); w.z = cvt_pk_bf16(b[0], b[1]); w.w = cvt_pk_bf16(b[2], b[3]); return w; }
;     DI void operator()(f4 (&acc)[2][2][4][2], const Unit& u, int wr, int wc, int fr, int fq) const {
;     ...
;             for (int bj = 0; bj < 2; ++bj) { const int col = col0 + bj * HALF; const f4 z0 = *(const f4*)(a0 + col), z1 = *(const f4*)(a0 + col + 4);
; #pragma unroll
;                 for (int ai = 0; ai < 2; ++ai)
; #pragma unroll
;                     for (int m = 0; m < 4; ++m) { const size_t off = (size_t)(row0 + ai * HALF + m * 16) * DB + col;
;                         f4 x0 = acc[ai][bj][m][0] + z0, x1 = acc[ai][bj][m][1] + z1;
; #pragma unroll
;                         for (int e = 0; e < 4; ++e) { x0[e] = sigmoidf_(x0[e]); x1[e] = sigmoidf_(x1[e]); }
;                         *(v4u*)(aout + off) = pack8(x0, x1);
;                         asm volatile("" ::: "memory"); } }
	v_lshl_add_u64 v[168:169], s[28:29], 0, v[168:169]
	v_lshl_add_u64 v[168:169], v[168:169], 0, v[152:153]
	v_add_f32_e32 v175, 1.0, v175
	v_cvt_pk_bf16_f32 v177, v183, v177
	v_cvt_pk_bf16_f32 v178, v180, v181
	v_cvt_pk_bf16_f32 v179, v186, v179
	global_store_dwordx4 v[168:169], v[176:179], off sc1
	v_pk_add_f32 v[128:129], v[64:65], v[128:129]
	v_mul_f32_e32 v133, 0xbfb8aa3b, v133
	v_mul_f32_e32 v128, 0xbfb8aa3b, v128
	v_exp_f32_e32 v128, v128
	v_exp_f32_e32 v133, v133
	v_add_f32_e32 v128, 1.0, v128
	v_rcp_f32_e32 v175, v175
	v_add_f32_e32 v133, 1.0, v133
	v_mul_f32_e32 v129, 0xbfb8aa3b, v129
	v_rcp_f32_e32 v176, v128
	v_exp_f32_e32 v129, v129
	s_nop 0
	v_add_f32_e32 v129, 1.0, v129
	v_pk_add_f32 v[134:135], v[70:71], v[134:135]
	v_mul_f32_e32 v134, 0xbfb8aa3b, v134
	v_rcp_f32_e32 v128, v133
	v_exp_f32_e32 v134, v134
	s_nop 0
	v_add_f32_e32 v134, 1.0, v134
	v_pk_add_f32 v[130:131], v[66:67], v[130:131]
	v_mul_f32_e32 v130, 0xbfb8aa3b, v130
	v_rcp_f32_e32 v177, v129
	v_exp_f32_e32 v130, v130
	s_nop 0
	v_add_f32_e32 v130, 1.0, v130
	v_mul_f32_e32 v135, 0xbfb8aa3b, v135
	v_exp_f32_e32 v135, v135
	v_rcp_f32_e32 v129, v134
	v_add_f32_e32 v135, 1.0, v135
	v_mul_f32_e32 v131, 0xbfb8aa3b, v131
	v_rcp_f32_e32 v134, v130
	v_exp_f32_e32 v131, v131
	s_nop 0
	v_add_f32_e32 v131, 1.0, v131
	v_rcp_f32_e32 v130, v135
	v_add_u32_e32 v132, 0xb0, v144
	v_rcp_f32_e32 v131, v131
	v_mov_b32_e32 v133, v145
	v_lshlrev_b64 v[132:133], 12, v[132:133]
	v_lshl_add_u64 v[132:133], s[28:29], 0, v[132:133]
	v_lshl_add_u64 v[152:153], v[132:133], 0, v[152:153]
	v_cvt_pk_bf16_f32 v128, v175, v128
	v_cvt_pk_bf16_f32 v129, v129, v130
	v_cvt_pk_bf16_f32 v130, v176, v177
	v_cvt_pk_bf16_f32 v131, v134, v131
	global_store_dwordx4 v[152:153], v[128:131], off sc1
	global_load_dwordx4 v[132:135], v[154:155], off offset:512
	global_load_dwordx4 v[128:131], v[154:155], off offset:528
	s_waitcnt vmcnt(0)
	v_pk_add_f32 v[154:155], v[60:61], v[132:133]
	s_nop 0
	v_mul_f32_e32 v154, 0xbfb8aa3b, v154
	v_exp_f32_e32 v154, v154
	v_pk_add_f32 v[180:181], v[56:57], v[128:129]
	v_mul_f32_e32 v155, 0xbfb8aa3b, v155
	v_mul_f32_e32 v180, 0xbfb8aa3b, v180
	v_add_f32_e32 v154, 1.0, v154
	v_exp_f32_e32 v180, v180
	v_exp_f32_e32 v155, v155
	v_mul_f32_e32 v181, 0xbfb8aa3b, v181
	v_add_f32_e32 v180, 1.0, v180
	v_rcp_f32_e32 v154, v154
	v_add_f32_e32 v155, 1.0, v155
	v_rcp_f32_e32 v175, v180
	v_exp_f32_e32 v181, v181
	s_nop 0
	v_add_f32_e32 v181, 1.0, v181
	v_pk_add_f32 v[176:177], v[62:63], v[134:135]
	v_mul_f32_e32 v176, 0xbfb8aa3b, v176
	v_rcp_f32_e32 v155, v155
	v_exp_f32_e32 v176, v176
	s_nop 0
	v_add_f32_e32 v176, 1.0, v176
	v_pk_add_f32 v[178:179], v[58:59], v[130:131]
	v_mul_f32_e32 v178, 0xbfb8aa3b, v178
	v_rcp_f32_e32 v180, v181
	v_exp_f32_e32 v178, v178
	s_nop 0
	v_add_f32_e32 v178, 1.0, v178
	v_mul_f32_e32 v177, 0xbfb8aa3b, v177
	v_rcp_f32_e32 v181, v176
	v_exp_f32_e32 v177, v177
	s_nop 0
	v_add_f32_e32 v177, 1.0, v177
	v_mul_f32_e32 v179, 0xbfb8aa3b, v179
	v_rcp_f32_e32 v182, v178
	v_exp_f32_e32 v179, v179
	s_nop 0
	v_add_f32_e32 v179, 1.0, v179
	v_rcp_f32_e32 v177, v177
	v_rcp_f32_e32 v179, v179
	v_cvt_pk_bf16_f32 v176, v154, v155
	v_pk_add_f32 v[154:155], v[52:53], v[132:133]
	v_cvt_pk_bf16_f32 v177, v181, v177
	v_cvt_pk_bf16_f32 v178, v175, v180
	v_cvt_pk_bf16_f32 v179, v182, v179
	global_store_dwordx4 v[156:157], v[176:179], off offset:256 sc1
	v_mul_f32_e32 v154, 0xbfb8aa3b, v154
	v_exp_f32_e32 v154, v154
	v_pk_add_f32 v[178:179], v[48:49], v[128:129]
	v_mul_f32_e32 v155, 0xbfb8aa3b, v155
	v_mul_f32_e32 v178, 0xbfb8aa3b, v178
	v_add_f32_e32 v154, 1.0, v154
	v_exp_f32_e32 v178, v178
	v_exp_f32_e32 v155, v155
	v_mul_f32_e32 v179, 0xbfb8aa3b, v179
	v_add_f32_e32 v178, 1.0, v178
	v_rcp_f32_e32 v154, v154
	v_add_f32_e32 v155, 1.0, v155
	v_rcp_f32_e32 v175, v178
	v_exp_f32_e32 v179, v179
	s_nop 0
	v_add_f32_e32 v179, 1.0, v179
	v_pk_add_f32 v[156:157], v[54:55], v[134:135]
	v_mul_f32_e32 v156, 0xbfb8aa3b, v156
	v_rcp_f32_e32 v155, v155
	v_exp_f32_e32 v156, v156
	s_nop 0
	v_add_f32_e32 v156, 1.0, v156
	v_pk_add_f32 v[176:177], v[50:51], v[130:131]
	v_mul_f32_e32 v176, 0xbfb8aa3b, v176
	v_rcp_f32_e32 v178, v179
	v_exp_f32_e32 v176, v176
	s_nop 0
	v_add_f32_e32 v176, 1.0, v176
	v_mul_f32_e32 v157, 0xbfb8aa3b, v157
	v_rcp_f32_e32 v156, v156
	v_exp_f32_e32 v157, v157
	s_nop 0
	v_add_f32_e32 v157, 1.0, v157
	v_mul_f32_e32 v177, 0xbfb8aa3b, v177
	v_rcp_f32_e32 v179, v176
	v_exp_f32_e32 v177, v177
	s_nop 0
	v_add_f32_e32 v177, 1.0, v177
	v_rcp_f32_e32 v157, v157
	v_rcp_f32_e32 v180, v177
	v_pk_add_f32 v[176:177], v[44:45], v[132:133]
	v_cvt_pk_bf16_f32 v154, v154, v155
	v_cvt_pk_bf16_f32 v155, v156, v157
	v_cvt_pk_bf16_f32 v156, v175, v178
	s_nop 0
	v_mul_f32_e32 v157, 0xbfb8aa3b, v176
	v_exp_f32_e32 v175, v157
	v_cvt_pk_bf16_f32 v157, v179, v180
	global_store_dwordx4 v[158:159], v[154:157], off offset:256 sc1
	v_pk_add_f32 v[158:159], v[40:41], v[128:129]
	v_add_f32_e32 v175, 1.0, v175
	v_mul_f32_e32 v158, 0xbfb8aa3b, v158
	v_exp_f32_e32 v158, v158
	v_mul_f32_e32 v177, 0xbfb8aa3b, v177
	v_add_f32_e32 v158, 1.0, v158
	v_rcp_f32_e32 v175, v175
	v_exp_f32_e32 v177, v177
	s_nop 0
	v_add_f32_e32 v177, 1.0, v177
	v_mul_f32_e32 v159, 0xbfb8aa3b, v159
	v_rcp_f32_e32 v158, v158
	v_exp_f32_e32 v159, v159
	s_nop 0
	v_add_f32_e32 v159, 1.0, v159
	v_pk_add_f32 v[154:155], v[46:47], v[134:135]
	v_mul_f32_e32 v154, 0xbfb8aa3b, v154
	v_rcp_f32_e32 v176, v177
	v_exp_f32_e32 v154, v154
	s_nop 0
	v_add_f32_e32 v154, 1.0, v154
	v_pk_add_f32 v[156:157], v[42:43], v[130:131]
	v_mul_f32_e32 v156, 0xbfb8aa3b, v156
	v_rcp_f32_e32 v159, v159
	v_exp_f32_e32 v156, v156
	s_nop 0
	v_add_f32_e32 v156, 1.0, v156
; DI float sigmoidf_(float z) { return 1.0f / (1.0f + __expf(-z)); }
; DI v4u pack8(const f4& a, const f4& b) { v4u w; w.x = cvt_pk_bf16(a[0], a[1]); w.y = cvt_pk_bf16(a[2], a[3]); w.z = cvt_pk_bf16(b[0], b[1]); w.w = cvt_pk_bf16(b[2], b[3]); return w; }
;     DI void operator()(f4 (&acc)[2][2][4][2], const Unit& u, int wr, int wc, int fr, int fq) const {
;     ...
;             for (int bj = 0; bj < 2; ++bj) { const int col = col0 + bj * HALF; const f4 z0 = *(const f4*)(a0 + col), z1 = *(const f4*)(a0 + col + 4);
; #pragma unroll
;                 for (int ai = 0; ai < 2; ++ai)
; #pragma unroll
;                     for (int m = 0; m < 4; ++m) { const size_t off = (size_t)(row0 + ai * HALF + m * 16) * DB + col;
;                         f4 x0 = acc[ai][bj][m][0] + z0, x1 = acc[ai][bj][m][1] + z1;
; #pragma unroll
;                         for (int e = 0; e < 4; ++e) { x0[e] = sigmoidf_(x0[e]); x1[e] = sigmoidf_(x1[e]); }
;                         *(v4u*)(aout + off) = pack8(x0, x1);
;                         asm volatile("" ::: "memory"); } }
	v_mul_f32_e32 v155, 0xbfb8aa3b, v155
	v_rcp_f32_e32 v177, v154
	v_exp_f32_e32 v155, v155
	s_nop 0
	v_add_f32_e32 v155, 1.0, v155
	v_mul_f32_e32 v157, 0xbfb8aa3b, v157
	v_rcp_f32_e32 v178, v156
	v_exp_f32_e32 v157, v157
	s_nop 0
	v_add_f32_e32 v157, 1.0, v157
	v_rcp_f32_e32 v155, v155
	v_rcp_f32_e32 v157, v157
	v_cvt_pk_bf16_f32 v154, v175, v176
	v_cvt_pk_bf16_f32 v155, v177, v155
	v_cvt_pk_bf16_f32 v156, v158, v159
	v_pk_add_f32 v[158:159], v[36:37], v[132:133]
	v_cvt_pk_bf16_f32 v157, v178, v157
	global_store_dwordx4 v[160:161], v[154:157], off offset:256 sc1
	v_mul_f32_e32 v158, 0xbfb8aa3b, v158
	v_exp_f32_e32 v158, v158
	v_pk_add_f32 v[160:161], v[32:33], v[128:129]
	v_mul_f32_e32 v159, 0xbfb8aa3b, v159
	v_mul_f32_e32 v160, 0xbfb8aa3b, v160
	v_add_f32_e32 v158, 1.0, v158
	v_exp_f32_e32 v160, v160
	v_exp_f32_e32 v159, v159
	v_mul_f32_e32 v161, 0xbfb8aa3b, v161
	v_add_f32_e32 v160, 1.0, v160
	v_rcp_f32_e32 v158, v158
	v_add_f32_e32 v159, 1.0, v159
	v_rcp_f32_e32 v160, v160
	v_exp_f32_e32 v161, v161
	s_nop 0
	v_add_f32_e32 v161, 1.0, v161
	v_pk_add_f32 v[154:155], v[38:39], v[134:135]
	v_mul_f32_e32 v154, 0xbfb8aa3b, v154
	v_rcp_f32_e32 v159, v159
	v_exp_f32_e32 v154, v154
	s_nop 0
	v_add_f32_e32 v154, 1.0, v154
	v_pk_add_f32 v[156:157], v[34:35], v[130:131]
	v_mul_f32_e32 v156, 0xbfb8aa3b, v156
	v_rcp_f32_e32 v161, v161
	v_exp_f32_e32 v156, v156
	s_nop 0
	v_add_f32_e32 v156, 1.0, v156
	v_mul_f32_e32 v155, 0xbfb8aa3b, v155
	v_rcp_f32_e32 v175, v154
	v_exp_f32_e32 v155, v155
	s_nop 0
	v_add_f32_e32 v155, 1.0, v155
	v_mul_f32_e32 v157, 0xbfb8aa3b, v157
	v_rcp_f32_e32 v176, v156
	v_exp_f32_e32 v157, v157
	s_nop 0
	v_add_f32_e32 v157, 1.0, v157
	v_rcp_f32_e32 v155, v155
	v_rcp_f32_e32 v157, v157
	v_cvt_pk_bf16_f32 v154, v158, v159
	v_pk_add_f32 v[158:159], v[28:29], v[132:133]
	v_cvt_pk_bf16_f32 v155, v175, v155
	v_cvt_pk_bf16_f32 v156, v160, v161
	v_cvt_pk_bf16_f32 v157, v176, v157
	global_store_dwordx4 v[162:163], v[154:157], off offset:256 sc1
	v_mul_f32_e32 v158, 0xbfb8aa3b, v158
	v_exp_f32_e32 v158, v158
	v_pk_add_f32 v[160:161], v[24:25], v[128:129]
	v_mul_f32_e32 v159, 0xbfb8aa3b, v159
	v_mul_f32_e32 v160, 0xbfb8aa3b, v160
	v_add_f32_e32 v158, 1.0, v158
	v_exp_f32_e32 v160, v160
	v_exp_f32_e32 v159, v159
	v_mul_f32_e32 v161, 0xbfb8aa3b, v161
	v_add_f32_e32 v160, 1.0, v160
	v_rcp_f32_e32 v158, v158
	v_add_f32_e32 v159, 1.0, v159
	v_rcp_f32_e32 v160, v160
	v_exp_f32_e32 v161, v161
	s_nop 0
	v_add_f32_e32 v161, 1.0, v161
	v_pk_add_f32 v[154:155], v[30:31], v[134:135]
	v_mul_f32_e32 v154, 0xbfb8aa3b, v154
	v_rcp_f32_e32 v159, v159
	v_exp_f32_e32 v154, v154
	s_nop 0
	v_add_f32_e32 v154, 1.0, v154
	v_pk_add_f32 v[156:157], v[26:27], v[130:131]
	v_mul_f32_e32 v156, 0xbfb8aa3b, v156
	v_rcp_f32_e32 v161, v161
	v_exp_f32_e32 v156, v156
	s_nop 0
	v_add_f32_e32 v156, 1.0, v156
	v_mul_f32_e32 v155, 0xbfb8aa3b, v155
	v_rcp_f32_e32 v162, v154
	v_exp_f32_e32 v155, v155
	s_nop 0
	v_add_f32_e32 v155, 1.0, v155
	v_mul_f32_e32 v157, 0xbfb8aa3b, v157
	v_rcp_f32_e32 v163, v156
	v_exp_f32_e32 v157, v157
	s_nop 0
	v_add_f32_e32 v157, 1.0, v157
	v_rcp_f32_e32 v155, v155
	v_rcp_f32_e32 v157, v157
	v_cvt_pk_bf16_f32 v154, v158, v159
	v_pk_add_f32 v[158:159], v[20:21], v[132:133]
	v_cvt_pk_bf16_f32 v155, v162, v155
	v_cvt_pk_bf16_f32 v156, v160, v161
	v_cvt_pk_bf16_f32 v157, v163, v157
	v_pk_add_f32 v[160:161], v[16:17], v[128:129]
	v_mul_f32_e32 v158, 0xbfb8aa3b, v158
	v_exp_f32_e32 v158, v158
	v_mul_f32_e32 v160, 0xbfb8aa3b, v160
	global_store_dwordx4 v[164:165], v[154:157], off offset:256 sc1
	v_exp_f32_e32 v160, v160
	v_add_f32_e32 v158, 1.0, v158
	v_add_f32_e32 v160, 1.0, v160
	v_mul_f32_e32 v159, 0xbfb8aa3b, v159
	v_exp_f32_e32 v159, v159
	v_rcp_f32_e32 v158, v158
	v_add_f32_e32 v159, 1.0, v159
	v_mul_f32_e32 v161, 0xbfb8aa3b, v161
; DI float sigmoidf_(float z) { return 1.0f / (1.0f + __expf(-z)); }
; DI v4u pack8(const f4& a, const f4& b) { v4u w; w.x = cvt_pk_bf16(a[0], a[1]); w.y = cvt_pk_bf16(a[2], a[3]); w.z = cvt_pk_bf16(b[0], b[1]); w.w = cvt_pk_bf16(b[2], b[3]); return w; }
;     DI void operator()(f4 (&acc)[2][2][4][2], const Unit& u, int wr, int wc, int fr, int fq) const {
;     ...
;             for (int bj = 0; bj < 2; ++bj) { const int col = col0 + bj * HALF; const f4 z0 = *(const f4*)(a0 + col), z1 = *(const f4*)(a0 + col + 4);
; #pragma unroll
;                 for (int ai = 0; ai < 2; ++ai)
; #pragma unroll
;                     for (int m = 0; m < 4; ++m) { const size_t off = (size_t)(row0 + ai * HALF + m * 16) * DB + col;
;                         f4 x0 = acc[ai][bj][m][0] + z0, x1 = acc[ai][bj][m][1] + z1;
; #pragma unroll
;                         for (int e = 0; e < 4; ++e) { x0[e] = sigmoidf_(x0[e]); x1[e] = sigmoidf_(x1[e]); }
;                         *(v4u*)(aout + off) = pack8(x0, x1);
;                         asm volatile("" ::: "memory"); } }
	v_rcp_f32_e32 v160, v160
	v_exp_f32_e32 v161, v161
	s_nop 0
	v_add_f32_e32 v161, 1.0, v161
	v_pk_add_f32 v[154:155], v[22:23], v[134:135]
	v_mul_f32_e32 v154, 0xbfb8aa3b, v154
	v_rcp_f32_e32 v159, v159
	v_exp_f32_e32 v154, v154
	s_nop 0
	v_add_f32_e32 v154, 1.0, v154
	v_pk_add_f32 v[156:157], v[18:19], v[130:131]
	v_mul_f32_e32 v156, 0xbfb8aa3b, v156
	v_rcp_f32_e32 v161, v161
	v_exp_f32_e32 v156, v156
	s_nop 0
	v_add_f32_e32 v156, 1.0, v156
	v_mul_f32_e32 v155, 0xbfb8aa3b, v155
	v_rcp_f32_e32 v162, v154
	v_exp_f32_e32 v155, v155
	s_nop 0
	v_add_f32_e32 v155, 1.0, v155
	v_mul_f32_e32 v157, 0xbfb8aa3b, v157
	v_rcp_f32_e32 v163, v156
	v_exp_f32_e32 v157, v157
	s_nop 0
	v_add_f32_e32 v157, 1.0, v157
	v_rcp_f32_e32 v155, v155
	v_rcp_f32_e32 v157, v157
	v_cvt_pk_bf16_f32 v154, v158, v159
	v_pk_add_f32 v[158:159], v[12:13], v[132:133]
	v_cvt_pk_bf16_f32 v155, v162, v155
	v_cvt_pk_bf16_f32 v156, v160, v161
	v_cvt_pk_bf16_f32 v157, v163, v157
	v_pk_add_f32 v[160:161], v[8:9], v[128:129]
	v_mul_f32_e32 v158, 0xbfb8aa3b, v158
	v_exp_f32_e32 v158, v158
	v_mul_f32_e32 v160, 0xbfb8aa3b, v160
	v_exp_f32_e32 v160, v160
	global_store_dwordx4 v[166:167], v[154:157], off offset:256 sc1
	v_add_f32_e32 v158, 1.0, v158
	v_add_f32_e32 v160, 1.0, v160
	v_mul_f32_e32 v159, 0xbfb8aa3b, v159
	v_exp_f32_e32 v159, v159
	v_rcp_f32_e32 v158, v158
	v_add_f32_e32 v159, 1.0, v159
	v_mul_f32_e32 v161, 0xbfb8aa3b, v161
	v_rcp_f32_e32 v160, v160
	v_exp_f32_e32 v161, v161
	s_nop 0
	v_add_f32_e32 v161, 1.0, v161
	v_pk_add_f32 v[154:155], v[14:15], v[134:135]
	v_mul_f32_e32 v154, 0xbfb8aa3b, v154
	v_rcp_f32_e32 v159, v159
	v_exp_f32_e32 v154, v154
	s_nop 0
	v_add_f32_e32 v154, 1.0, v154
	v_pk_add_f32 v[156:157], v[10:11], v[130:131]
	v_mul_f32_e32 v156, 0xbfb8aa3b, v156
	v_rcp_f32_e32 v161, v161
	v_exp_f32_e32 v156, v156
	s_nop 0
	v_add_f32_e32 v156, 1.0, v156
	v_mul_f32_e32 v155, 0xbfb8aa3b, v155
	v_rcp_f32_e32 v162, v154
	v_exp_f32_e32 v155, v155
	s_nop 0
	v_add_f32_e32 v155, 1.0, v155
	v_mul_f32_e32 v157, 0xbfb8aa3b, v157
	v_rcp_f32_e32 v163, v156
	v_exp_f32_e32 v157, v157
	s_nop 0
	v_add_f32_e32 v157, 1.0, v157
	v_rcp_f32_e32 v155, v155
	v_pk_add_f32 v[132:133], v[4:5], v[132:133]
	v_mul_f32_e32 v132, 0xbfb8aa3b, v132
	v_exp_f32_e32 v132, v132
	v_rcp_f32_e32 v157, v157
	v_cvt_pk_bf16_f32 v154, v158, v159
	v_add_f32_e32 v132, 1.0, v132
	v_cvt_pk_bf16_f32 v155, v162, v155
	v_cvt_pk_bf16_f32 v156, v160, v161
	v_cvt_pk_bf16_f32 v157, v163, v157
	global_store_dwordx4 v[168:169], v[154:157], off offset:256 sc1
	v_pk_add_f32 v[128:129], v[0:1], v[128:129]
	v_mul_f32_e32 v133, 0xbfb8aa3b, v133
	v_mul_f32_e32 v128, 0xbfb8aa3b, v128
	v_exp_f32_e32 v128, v128
	v_exp_f32_e32 v133, v133
	v_add_f32_e32 v128, 1.0, v128
	v_rcp_f32_e32 v132, v132
	v_add_f32_e32 v133, 1.0, v133
	v_mul_f32_e32 v129, 0xbfb8aa3b, v129
	v_rcp_f32_e32 v154, v128
	v_exp_f32_e32 v129, v129
	s_nop 0
	v_add_f32_e32 v129, 1.0, v129
	v_pk_add_f32 v[134:135], v[6:7], v[134:135]
	v_mul_f32_e32 v134, 0xbfb8aa3b, v134
	v_rcp_f32_e32 v128, v133
	v_exp_f32_e32 v134, v134
	s_nop 0
	v_add_f32_e32 v134, 1.0, v134
	v_pk_add_f32 v[130:131], v[2:3], v[130:131]
	v_mul_f32_e32 v130, 0xbfb8aa3b, v130
	v_rcp_f32_e32 v133, v129
	v_exp_f32_e32 v130, v130
	s_nop 0
	v_add_f32_e32 v130, 1.0, v130
	v_mul_f32_e32 v135, 0xbfb8aa3b, v135
	v_rcp_f32_e32 v129, v134
	v_exp_f32_e32 v135, v135
	s_nop 0
	v_add_f32_e32 v135, 1.0, v135
	v_mul_f32_e32 v131, 0xbfb8aa3b, v131
	v_rcp_f32_e32 v134, v130
	v_exp_f32_e32 v131, v131
	s_nop 0
	v_add_f32_e32 v131, 1.0, v131
	v_rcp_f32_e32 v130, v135
	v_rcp_f32_e32 v131, v131
	v_cvt_pk_bf16_f32 v128, v132, v128
	v_cvt_pk_bf16_f32 v129, v129, v130
	v_cvt_pk_bf16_f32 v130, v154, v133
	v_cvt_pk_bf16_f32 v131, v134, v131
	global_store_dwordx4 v[152:153], v[128:131], off offset:256 sc1

; DI float sigmoidf_(float z) { return 1.0f / (1.0f + __expf(-z)); }
;     DI void operator()(f4 (&acc)[2][2][4][2], const Unit& u, int wr, int wc, int fr, int fq) const {
;     ...
;         if (which == 0) {
; #pragma unroll
;             for (int bj = 0; bj < 2; ++bj) { const int col = col0 + bj * HALF; const f4 z0 = *(const f4*)(w0 + col), z1 = *(const f4*)(w0 + col + 4);
; #pragma unroll
;                 for (int ai = 0; ai < 2; ++ai)
; #pragma unroll
;                     for (int m = 0; m < 4; ++m) { const size_t off = (size_t)(row0 + ai * HALF + m * 16) * DB + col;
;                         f4 x0 = acc[ai][bj][m][0] + z0, x1 = acc[ai][bj][m][1] + z1;
; #pragma unroll
;                         for (int e = 0; e < 4; ++e) { x0[e] = __expf(-0.6065306597126334f * sigmoidf_(x0[e])); x1[e] = __expf(-0.6065306597126334f * sigmoidf_(x1[e])); }
;                         { typedef _Float16 h2_ __attribute__((ext_vector_type(2)));
;                           const h2_ q0 = {(_Float16)x0[0], (_Float16)x0[1]}, q1 = {(_Float16)x0[2], (_Float16)x0[3]}, q2 = {(_Float16)x1[0], (_Float16)x1[1]}, q3 = {(_Float16)x1[2], (_Float16)x1[3]};
;                           v4u w_; w_.x = __builtin_bit_cast(unsigned, q0); w_.y = __builtin_bit_cast(unsigned, q1); w_.z = __builtin_bit_cast(unsigned, q2); w_.w = __builtin_bit_cast(unsigned, q3);
;                           *(v4u*)((_Float16*)decay + off) = w_; }
;                         asm volatile("" ::: "memory"); } }
.LBB0_2072:
	v_lshl_add_u64 v[152:153], v[150:151], 2, s[20:21]
	global_load_dwordx4 v[132:135], v[152:153], off
	global_load_dwordx4 v[128:131], v[152:153], off offset:16
	s_waitcnt vmcnt(0)
	v_pk_add_f32 v[124:125], v[124:125], v[132:133]
	v_pk_add_f32 v[120:121], v[120:121], v[128:129]
	v_mul_f32_e32 v124, 0xbfb8aa3b, v124
	v_mul_f32_e32 v120, 0xbfb8aa3b, v120
	v_exp_f32_e32 v124, v124
	v_mul_f32_e32 v125, 0xbfb8aa3b, v125
	v_exp_f32_e32 v120, v120
	v_pk_add_f32 v[126:127], v[126:127], v[134:135]
	v_mul_f32_e32 v121, 0xbfb8aa3b, v121
	v_exp_f32_e32 v125, v125
	v_mul_f32_e32 v126, 0xbfb8aa3b, v126
	v_exp_f32_e32 v121, v121
	v_exp_f32_e32 v126, v126
	v_add_f32_e32 v124, 1.0, v124
	v_add_f32_e32 v120, 1.0, v120
	v_add_f32_e32 v125, 1.0, v125
	v_add_f32_e32 v121, 1.0, v121
	v_add_f32_e32 v126, 1.0, v126
	v_pk_add_f32 v[122:123], v[122:123], v[130:131]
	v_mul_f32_e32 v122, 0xbfb8aa3b, v122
	v_exp_f32_e32 v122, v122
	v_rcp_f32_e32 v124, v124
	v_rcp_f32_e32 v120, v120
	v_rcp_f32_e32 v125, v125
	v_add_f32_e32 v122, 1.0, v122
	v_rcp_f32_e32 v121, v121
	v_rcp_f32_e32 v126, v126
	v_mul_f32_e32 v127, 0xbfb8aa3b, v127
	v_exp_f32_e32 v127, v127
	v_mul_f32_e32 v123, 0xbfb8aa3b, v123
	v_add_f32_e32 v127, 1.0, v127
	v_rcp_f32_e32 v122, v122
	v_exp_f32_e32 v123, v123
	v_mul_f32_e32 v124, 0xbf1b4598, v124
	v_mul_f32_e32 v120, 0xbf1b4598, v120
	v_add_f32_e32 v123, 1.0, v123
	v_rcp_f32_e32 v127, v127
	v_mul_f32_e32 v125, 0xbf1b4598, v125
	v_mul_f32_e32 v121, 0xbf1b4598, v121
	v_mul_f32_e32 v126, 0xbf1b4598, v126
	v_mul_f32_e32 v127, 0xbf1b4598, v127
	v_rcp_f32_e32 v123, v123
	v_mul_f32_e32 v124, 0x3fb8aa3b, v124
	v_mul_f32_e32 v120, 0x3fb8aa3b, v120
	v_mul_f32_e32 v125, 0x3fb8aa3b, v125
	v_mul_f32_e32 v121, 0x3fb8aa3b, v121
	v_mul_f32_e32 v126, 0x3fb8aa3b, v126
	v_mul_f32_e32 v122, 0xbf1b4598, v122
	v_mul_f32_e32 v127, 0x3fb8aa3b, v127
	v_mul_f32_e32 v123, 0xbf1b4598, v123
	v_exp_f32_e32 v124, v124
	v_exp_f32_e32 v120, v120
	v_exp_f32_e32 v125, v125
	v_exp_f32_e32 v121, v121
	v_exp_f32_e32 v126, v126
	v_mul_f32_e32 v122, 0x3fb8aa3b, v122
	v_exp_f32_e32 v127, v127
	v_mul_f32_e32 v123, 0x3fb8aa3b, v123
	v_pk_add_f32 v[116:117], v[116:117], v[132:133]
	v_exp_f32_e32 v122, v122
	v_exp_f32_e32 v123, v123
	v_mul_f32_e32 v116, 0xbfb8aa3b, v116
	v_exp_f32_e32 v116, v116
	v_cvt_pk_f16_f32 v124, v124, v125
	v_cvt_pk_f16_f32 v125, v126, v127
	v_cvt_pk_f16_f32 v126, v120, v121
	v_lshlrev_b64 v[120:121], 12, v[144:145]
	v_cvt_pk_f16_f32 v127, v122, v123
	v_lshl_add_u64 v[120:121], s[26:27], 0, v[120:121]
	v_lshlrev_b64 v[122:123], 1, v[150:151]
	v_lshl_add_u64 v[120:121], v[120:121], 0, v[122:123]
	v_add_f32_e32 v116, 1.0, v116
	global_store_dwordx4 v[120:121], v[124:127], off sc1
	v_pk_add_f32 v[112:113], v[112:113], v[128:129]
	v_mul_f32_e32 v117, 0xbfb8aa3b, v117
	v_mul_f32_e32 v112, 0xbfb8aa3b, v112
	v_exp_f32_e32 v112, v112
	v_exp_f32_e32 v117, v117
	v_add_f32_e32 v112, 1.0, v112
	v_rcp_f32_e32 v116, v116
	v_add_f32_e32 v117, 1.0, v117
	v_mul_f32_e32 v113, 0xbfb8aa3b, v113
	v_exp_f32_e32 v113, v113
	v_rcp_f32_e32 v112, v112
	v_add_f32_e32 v113, 1.0, v113
	v_pk_add_f32 v[118:119], v[118:119], v[134:135]
	v_pk_add_f32 v[114:115], v[114:115], v[130:131]
	v_rcp_f32_e32 v117, v117
	v_mul_f32_e32 v118, 0xbfb8aa3b, v118
	v_exp_f32_e32 v118, v118
	v_mul_f32_e32 v114, 0xbfb8aa3b, v114
	v_add_f32_e32 v118, 1.0, v118
	v_rcp_f32_e32 v113, v113
	v_exp_f32_e32 v114, v114
	v_mul_f32_e32 v119, 0xbfb8aa3b, v119
	v_exp_f32_e32 v119, v119
	v_add_f32_e32 v114, 1.0, v114
	v_rcp_f32_e32 v118, v118
	v_add_f32_e32 v119, 1.0, v119
	v_mul_f32_e32 v115, 0xbfb8aa3b, v115
	v_exp_f32_e32 v115, v115
	v_rcp_f32_e32 v114, v114
	s_nop 0
	v_mul_f32_e32 v114, 0xbf1b4598, v114
	v_mul_f32_e32 v114, 0x3fb8aa3b, v114
	v_exp_f32_e32 v127, v114
	v_add_f32_e32 v115, 1.0, v115
	v_rcp_f32_e32 v114, v119
	s_nop 0
	v_mul_f32_e32 v114, 0xbf1b4598, v114
	v_mul_f32_e32 v114, 0x3fb8aa3b, v114
	v_exp_f32_e32 v126, v114
	v_mul_f32_e32 v116, 0xbf1b4598, v116
	v_mul_f32_e32 v112, 0xbf1b4598, v112
	v_mul_f32_e32 v117, 0xbf1b4598, v117
	v_mul_f32_e32 v113, 0xbf1b4598, v113
	v_mul_f32_e32 v116, 0x3fb8aa3b, v116
	v_mul_f32_e32 v112, 0x3fb8aa3b, v112
	v_mul_f32_e32 v117, 0x3fb8aa3b, v117
	v_mul_f32_e32 v113, 0x3fb8aa3b, v113
	v_rcp_f32_e32 v114, v115
	v_exp_f32_e32 v116, v116
	v_exp_f32_e32 v112, v112
	v_exp_f32_e32 v117, v117
	v_exp_f32_e32 v113, v113
	v_mul_f32_e32 v118, 0xbf1b4598, v118
	v_mul_f32_e32 v114, 0xbf1b4598, v114
	v_pk_add_f32 v[108:109], v[108:109], v[132:133]
	v_mul_f32_e32 v118, 0x3fb8aa3b, v118
	v_mul_f32_e32 v114, 0x3fb8aa3b, v114
	v_mul_f32_e32 v108, 0xbfb8aa3b, v108
	v_exp_f32_e32 v118, v118
	v_exp_f32_e32 v119, v114
	v_exp_f32_e32 v108, v108
	v_or_b32_e32 v124, 16, v144
	v_mov_b32_e32 v125, v145
	v_cvt_pk_f16_f32 v114, v116, v117
	v_cvt_pk_f16_f32 v116, v112, v113
	v_lshlrev_b64 v[112:113], 12, v[124:125]
	v_lshl_add_u64 v[112:113], s[26:27], 0, v[112:113]
	v_cvt_pk_f16_f32 v115, v118, v126
	v_cvt_pk_f16_f32 v117, v127, v119
	v_lshl_add_u64 v[112:113], v[112:113], 0, v[122:123]
	v_add_f32_e32 v108, 1.0, v108
	global_store_dwordx4 v[112:113], v[114:117], off sc1
	v_pk_add_f32 v[104:105], v[104:105], v[128:129]
	v_mul_f32_e32 v109, 0xbfb8aa3b, v109
	v_mul_f32_e32 v104, 0xbfb8aa3b, v104
	v_exp_f32_e32 v104, v104
	v_exp_f32_e32 v109, v109
	v_add_f32_e32 v104, 1.0, v104
	v_rcp_f32_e32 v108, v108
	v_add_f32_e32 v109, 1.0, v109
	v_mul_f32_e32 v105, 0xbfb8aa3b, v105
	v_exp_f32_e32 v105, v105
	v_rcp_f32_e32 v104, v104
	v_add_f32_e32 v105, 1.0, v105
	v_pk_add_f32 v[110:111], v[110:111], v[134:135]
	v_pk_add_f32 v[106:107], v[106:107], v[130:131]
	v_rcp_f32_e32 v109, v109
	v_mul_f32_e32 v110, 0xbfb8aa3b, v110
; DI float sigmoidf_(float z) { return 1.0f / (1.0f + __expf(-z)); }
;     DI void operator()(f4 (&acc)[2][2][4][2], const Unit& u, int wr, int wc, int fr, int fq) const {
;     ...
;                 for (int ai = 0; ai < 2; ++ai)
; #pragma unroll
;                     for (int m = 0; m < 4; ++m) { const size_t off = (size_t)(row0 + ai * HALF + m * 16) * DB + col;
;                         f4 x0 = acc[ai][bj][m][0] + z0, x1 = acc[ai][bj][m][1] + z1;
; #pragma unroll
;                         for (int e = 0; e < 4; ++e) { x0[e] = __expf(-0.6065306597126334f * sigmoidf_(x0[e])); x1[e] = __expf(-0.6065306597126334f * sigmoidf_(x1[e])); }
;                         { typedef _Float16 h2_ __attribute__((ext_vector_type(2)));
;                           const h2_ q0 = {(_Float16)x0[0], (_Float16)x0[1]}, q1 = {(_Float16)x0[2], (_Float16)x0[3]}, q2 = {(_Float16)x1[0], (_Float16)x1[1]}, q3 = {(_Float16)x1[2], (_Float16)x1[3]};
;                           v4u w_; w_.x = __builtin_bit_cast(unsigned, q0); w_.y = __builtin_bit_cast(unsigned, q1); w_.z = __builtin_bit_cast(unsigned, q2); w_.w = __builtin_bit_cast(unsigned, q3);
;                           *(v4u*)((_Float16*)decay + off) = w_; }
;                         asm volatile("" ::: "memory"); } }
	v_exp_f32_e32 v110, v110
	v_mul_f32_e32 v106, 0xbfb8aa3b, v106
	v_add_f32_e32 v110, 1.0, v110
	v_rcp_f32_e32 v105, v105
	v_exp_f32_e32 v106, v106
	v_mul_f32_e32 v111, 0xbfb8aa3b, v111
	v_exp_f32_e32 v111, v111
	v_add_f32_e32 v106, 1.0, v106
	v_rcp_f32_e32 v110, v110
	v_add_f32_e32 v111, 1.0, v111
	v_mul_f32_e32 v107, 0xbfb8aa3b, v107
	v_exp_f32_e32 v107, v107
	v_rcp_f32_e32 v106, v106
	s_nop 0
	v_mul_f32_e32 v106, 0xbf1b4598, v106
	v_mul_f32_e32 v106, 0x3fb8aa3b, v106
	v_exp_f32_e32 v117, v106
	v_add_f32_e32 v107, 1.0, v107
	v_rcp_f32_e32 v106, v111
	s_nop 0
	v_mul_f32_e32 v106, 0xbf1b4598, v106
	v_mul_f32_e32 v106, 0x3fb8aa3b, v106
	v_exp_f32_e32 v116, v106
	v_mul_f32_e32 v108, 0xbf1b4598, v108
	v_mul_f32_e32 v104, 0xbf1b4598, v104
	v_mul_f32_e32 v109, 0xbf1b4598, v109
	v_mul_f32_e32 v105, 0xbf1b4598, v105
	v_mul_f32_e32 v108, 0x3fb8aa3b, v108
	v_mul_f32_e32 v104, 0x3fb8aa3b, v104
	v_mul_f32_e32 v109, 0x3fb8aa3b, v109
	v_mul_f32_e32 v105, 0x3fb8aa3b, v105
	v_rcp_f32_e32 v106, v107
	v_exp_f32_e32 v108, v108
	v_exp_f32_e32 v104, v104
	v_exp_f32_e32 v109, v109
	v_exp_f32_e32 v105, v105
	v_mul_f32_e32 v110, 0xbf1b4598, v110
	v_mul_f32_e32 v106, 0xbf1b4598, v106
	v_pk_add_f32 v[100:101], v[100:101], v[132:133]
	v_mul_f32_e32 v110, 0x3fb8aa3b, v110
	v_mul_f32_e32 v106, 0x3fb8aa3b, v106
	v_mul_f32_e32 v100, 0xbfb8aa3b, v100
	v_exp_f32_e32 v110, v110
	v_exp_f32_e32 v111, v106
	v_exp_f32_e32 v100, v100
	v_or_b32_e32 v114, 32, v144
	v_mov_b32_e32 v115, v145
	v_cvt_pk_f16_f32 v106, v108, v109
	v_cvt_pk_f16_f32 v108, v104, v105
	v_lshlrev_b64 v[104:105], 12, v[114:115]
	v_lshl_add_u64 v[104:105], s[26:27], 0, v[104:105]
	v_cvt_pk_f16_f32 v107, v110, v116
	v_cvt_pk_f16_f32 v109, v117, v111
	v_lshl_add_u64 v[104:105], v[104:105], 0, v[122:123]
	v_add_f32_e32 v100, 1.0, v100
	global_store_dwordx4 v[104:105], v[106:109], off sc1
	v_pk_add_f32 v[96:97], v[96:97], v[128:129]
	v_mul_f32_e32 v101, 0xbfb8aa3b, v101
	v_mul_f32_e32 v96, 0xbfb8aa3b, v96
	v_exp_f32_e32 v96, v96
	v_exp_f32_e32 v101, v101
	v_add_f32_e32 v96, 1.0, v96
	v_rcp_f32_e32 v100, v100
	v_add_f32_e32 v101, 1.0, v101
	v_mul_f32_e32 v97, 0xbfb8aa3b, v97
	v_exp_f32_e32 v97, v97
	v_rcp_f32_e32 v96, v96
	v_add_f32_e32 v97, 1.0, v97
	v_pk_add_f32 v[102:103], v[102:103], v[134:135]
	v_pk_add_f32 v[98:99], v[98:99], v[130:131]
	v_rcp_f32_e32 v101, v101
	v_mul_f32_e32 v102, 0xbfb8aa3b, v102
	v_exp_f32_e32 v102, v102
	v_mul_f32_e32 v98, 0xbfb8aa3b, v98
	v_add_f32_e32 v102, 1.0, v102
	v_rcp_f32_e32 v97, v97
	v_exp_f32_e32 v98, v98
	v_mul_f32_e32 v103, 0xbfb8aa3b, v103
	v_exp_f32_e32 v103, v103
	v_add_f32_e32 v98, 1.0, v98
	v_rcp_f32_e32 v102, v102
	v_add_f32_e32 v103, 1.0, v103
	v_mul_f32_e32 v99, 0xbfb8aa3b, v99
	v_exp_f32_e32 v99, v99
	v_rcp_f32_e32 v98, v98
	s_nop 0
	v_mul_f32_e32 v98, 0xbf1b4598, v98
	v_mul_f32_e32 v98, 0x3fb8aa3b, v98
	v_exp_f32_e32 v109, v98
	v_add_f32_e32 v99, 1.0, v99
	v_rcp_f32_e32 v98, v103
	s_nop 0
	v_mul_f32_e32 v98, 0xbf1b4598, v98
	v_mul_f32_e32 v98, 0x3fb8aa3b, v98
	v_exp_f32_e32 v108, v98
	v_mul_f32_e32 v100, 0xbf1b4598, v100
	v_mul_f32_e32 v96, 0xbf1b4598, v96
	v_mul_f32_e32 v101, 0xbf1b4598, v101
	v_mul_f32_e32 v97, 0xbf1b4598, v97
	v_mul_f32_e32 v100, 0x3fb8aa3b, v100
	v_mul_f32_e32 v96, 0x3fb8aa3b, v96
	v_mul_f32_e32 v101, 0x3fb8aa3b, v101
	v_mul_f32_e32 v97, 0x3fb8aa3b, v97
	v_rcp_f32_e32 v98, v99
	v_exp_f32_e32 v100, v100
	v_exp_f32_e32 v96, v96
	v_exp_f32_e32 v101, v101
	v_exp_f32_e32 v97, v97
	v_mul_f32_e32 v102, 0xbf1b4598, v102
	v_mul_f32_e32 v98, 0xbf1b4598, v98
	v_pk_add_f32 v[92:93], v[92:93], v[132:133]
	v_mul_f32_e32 v102, 0x3fb8aa3b, v102
	v_mul_f32_e32 v98, 0x3fb8aa3b, v98
	v_mul_f32_e32 v92, 0xbfb8aa3b, v92
	v_exp_f32_e32 v102, v102
	v_exp_f32_e32 v103, v98
	v_exp_f32_e32 v92, v92
	v_or_b32_e32 v106, 48, v144
	v_mov_b32_e32 v107, v145
	v_cvt_pk_f16_f32 v98, v100, v101
	v_cvt_pk_f16_f32 v100, v96, v97
	v_lshlrev_b64 v[96:97], 12, v[106:107]
	v_lshl_add_u64 v[96:97], s[26:27], 0, v[96:97]
	v_cvt_pk_f16_f32 v99, v102, v108
	v_cvt_pk_f16_f32 v101, v109, v103
	v_lshl_add_u64 v[96:97], v[96:97], 0, v[122:123]
	v_add_f32_e32 v92, 1.0, v92
	global_store_dwordx4 v[96:97], v[98:101], off sc1
	v_pk_add_f32 v[88:89], v[88:89], v[128:129]
	v_mul_f32_e32 v93, 0xbfb8aa3b, v93
	v_mul_f32_e32 v88, 0xbfb8aa3b, v88
	v_exp_f32_e32 v88, v88
	v_exp_f32_e32 v93, v93
	v_add_f32_e32 v88, 1.0, v88
	v_rcp_f32_e32 v92, v92
	v_add_f32_e32 v93, 1.0, v93
	v_mul_f32_e32 v89, 0xbfb8aa3b, v89
	v_exp_f32_e32 v89, v89
	v_rcp_f32_e32 v88, v88
	v_add_f32_e32 v89, 1.0, v89
	v_pk_add_f32 v[94:95], v[94:95], v[134:135]
	v_pk_add_f32 v[90:91], v[90:91], v[130:131]
	v_rcp_f32_e32 v93, v93
	v_mul_f32_e32 v94, 0xbfb8aa3b, v94
	v_exp_f32_e32 v94, v94
	v_mul_f32_e32 v90, 0xbfb8aa3b, v90
	v_add_f32_e32 v94, 1.0, v94
	v_rcp_f32_e32 v89, v89
	v_exp_f32_e32 v90, v90
	v_mul_f32_e32 v95, 0xbfb8aa3b, v95
	v_exp_f32_e32 v95, v95
	v_add_f32_e32 v90, 1.0, v90
	v_rcp_f32_e32 v94, v94
	v_add_f32_e32 v95, 1.0, v95
	v_mul_f32_e32 v91, 0xbfb8aa3b, v91
	v_exp_f32_e32 v91, v91
	v_rcp_f32_e32 v90, v90
	s_nop 0
	v_mul_f32_e32 v90, 0xbf1b4598, v90
	v_mul_f32_e32 v90, 0x3fb8aa3b, v90
	v_exp_f32_e32 v101, v90
	v_add_f32_e32 v91, 1.0, v91
	v_rcp_f32_e32 v90, v95
	s_nop 0
	v_mul_f32_e32 v90, 0xbf1b4598, v90
	v_mul_f32_e32 v90, 0x3fb8aa3b, v90
	v_exp_f32_e32 v100, v90
	v_mul_f32_e32 v92, 0xbf1b4598, v92
	v_mul_f32_e32 v88, 0xbf1b4598, v88
	v_mul_f32_e32 v93, 0xbf1b4598, v93
	v_mul_f32_e32 v89, 0xbf1b4598, v89
	v_mul_f32_e32 v92, 0x3fb8aa3b, v92
	v_mul_f32_e32 v88, 0x3fb8aa3b, v88
	v_mul_f32_e32 v93, 0x3fb8aa3b, v93
	v_mul_f32_e32 v89, 0x3fb8aa3b, v89
	v_rcp_f32_e32 v90, v91
	v_exp_f32_e32 v92, v92
	v_exp_f32_e32 v88, v88
; DI float sigmoidf_(float z) { return 1.0f / (1.0f + __expf(-z)); }
;     DI void operator()(f4 (&acc)[2][2][4][2], const Unit& u, int wr, int wc, int fr, int fq) const {
;     ...
;                 for (int ai = 0; ai < 2; ++ai)
; #pragma unroll
;                     for (int m = 0; m < 4; ++m) { const size_t off = (size_t)(row0 + ai * HALF + m * 16) * DB + col;
;                         f4 x0 = acc[ai][bj][m][0] + z0, x1 = acc[ai][bj][m][1] + z1;
; #pragma unroll
;                         for (int e = 0; e < 4; ++e) { x0[e] = __expf(-0.6065306597126334f * sigmoidf_(x0[e])); x1[e] = __expf(-0.6065306597126334f * sigmoidf_(x1[e])); }
;                         { typedef _Float16 h2_ __attribute__((ext_vector_type(2)));
;                           const h2_ q0 = {(_Float16)x0[0], (_Float16)x0[1]}, q1 = {(_Float16)x0[2], (_Float16)x0[3]}, q2 = {(_Float16)x1[0], (_Float16)x1[1]}, q3 = {(_Float16)x1[2], (_Float16)x1[3]};
;                           v4u w_; w_.x = __builtin_bit_cast(unsigned, q0); w_.y = __builtin_bit_cast(unsigned, q1); w_.z = __builtin_bit_cast(unsigned, q2); w_.w = __builtin_bit_cast(unsigned, q3);
;                           *(v4u*)((_Float16*)decay + off) = w_; }
;                         asm volatile("" ::: "memory"); } }
	v_exp_f32_e32 v93, v93
	v_exp_f32_e32 v89, v89
	v_mul_f32_e32 v94, 0xbf1b4598, v94
	v_mul_f32_e32 v90, 0xbf1b4598, v90
	v_pk_add_f32 v[84:85], v[84:85], v[132:133]
	v_mul_f32_e32 v94, 0x3fb8aa3b, v94
	v_mul_f32_e32 v90, 0x3fb8aa3b, v90
	v_mul_f32_e32 v84, 0xbfb8aa3b, v84
	v_exp_f32_e32 v94, v94
	v_exp_f32_e32 v95, v90
	v_exp_f32_e32 v84, v84
	v_add_u32_e32 v98, 0x80, v144
	v_mov_b32_e32 v99, v145
	v_cvt_pk_f16_f32 v90, v92, v93
	v_cvt_pk_f16_f32 v92, v88, v89
	v_lshlrev_b64 v[88:89], 12, v[98:99]
	v_lshl_add_u64 v[88:89], s[26:27], 0, v[88:89]
	v_cvt_pk_f16_f32 v91, v94, v100
	v_cvt_pk_f16_f32 v93, v101, v95
	v_lshl_add_u64 v[88:89], v[88:89], 0, v[122:123]
	v_add_f32_e32 v84, 1.0, v84
	global_store_dwordx4 v[88:89], v[90:93], off sc1
	v_pk_add_f32 v[80:81], v[80:81], v[128:129]
	v_mul_f32_e32 v85, 0xbfb8aa3b, v85
	v_mul_f32_e32 v80, 0xbfb8aa3b, v80
	v_exp_f32_e32 v80, v80
	v_exp_f32_e32 v85, v85
	v_add_f32_e32 v80, 1.0, v80
	v_rcp_f32_e32 v84, v84
	v_add_f32_e32 v85, 1.0, v85
	v_mul_f32_e32 v81, 0xbfb8aa3b, v81
	v_exp_f32_e32 v81, v81
	v_rcp_f32_e32 v80, v80
	v_add_f32_e32 v81, 1.0, v81
	v_pk_add_f32 v[86:87], v[86:87], v[134:135]
	v_pk_add_f32 v[82:83], v[82:83], v[130:131]
	v_rcp_f32_e32 v85, v85
	v_mul_f32_e32 v86, 0xbfb8aa3b, v86
	v_exp_f32_e32 v86, v86
	v_mul_f32_e32 v82, 0xbfb8aa3b, v82
	v_add_f32_e32 v86, 1.0, v86
	v_rcp_f32_e32 v81, v81
	v_exp_f32_e32 v82, v82
	v_mul_f32_e32 v87, 0xbfb8aa3b, v87
	v_exp_f32_e32 v87, v87
	v_add_f32_e32 v82, 1.0, v82
	v_rcp_f32_e32 v86, v86
	v_add_f32_e32 v87, 1.0, v87
	v_mul_f32_e32 v83, 0xbfb8aa3b, v83
	v_exp_f32_e32 v83, v83
	v_rcp_f32_e32 v82, v82
	s_nop 0
	v_mul_f32_e32 v82, 0xbf1b4598, v82
	v_mul_f32_e32 v82, 0x3fb8aa3b, v82
	v_exp_f32_e32 v93, v82
	v_add_f32_e32 v83, 1.0, v83
	v_rcp_f32_e32 v82, v87
	s_nop 0
	v_mul_f32_e32 v82, 0xbf1b4598, v82
	v_mul_f32_e32 v82, 0x3fb8aa3b, v82
	v_exp_f32_e32 v92, v82
	v_mul_f32_e32 v84, 0xbf1b4598, v84
	v_mul_f32_e32 v80, 0xbf1b4598, v80
	v_mul_f32_e32 v85, 0xbf1b4598, v85
	v_mul_f32_e32 v81, 0xbf1b4598, v81
	v_mul_f32_e32 v84, 0x3fb8aa3b, v84
	v_mul_f32_e32 v80, 0x3fb8aa3b, v80
	v_mul_f32_e32 v85, 0x3fb8aa3b, v85
	v_mul_f32_e32 v81, 0x3fb8aa3b, v81
	v_rcp_f32_e32 v82, v83
	v_exp_f32_e32 v84, v84
	v_exp_f32_e32 v80, v80
	v_exp_f32_e32 v85, v85
	v_exp_f32_e32 v81, v81
	v_mul_f32_e32 v86, 0xbf1b4598, v86
	v_mul_f32_e32 v82, 0xbf1b4598, v82
	v_pk_add_f32 v[76:77], v[76:77], v[132:133]
	v_mul_f32_e32 v86, 0x3fb8aa3b, v86
	v_mul_f32_e32 v82, 0x3fb8aa3b, v82
	v_mul_f32_e32 v76, 0xbfb8aa3b, v76
	v_exp_f32_e32 v86, v86
	v_exp_f32_e32 v87, v82
	v_exp_f32_e32 v76, v76
	v_add_u32_e32 v90, 0x90, v144
	v_mov_b32_e32 v91, v145
	v_cvt_pk_f16_f32 v82, v84, v85
	v_cvt_pk_f16_f32 v84, v80, v81
	v_lshlrev_b64 v[80:81], 12, v[90:91]
	v_lshl_add_u64 v[80:81], s[26:27], 0, v[80:81]
	v_cvt_pk_f16_f32 v83, v86, v92
	v_cvt_pk_f16_f32 v85, v93, v87
	v_lshl_add_u64 v[80:81], v[80:81], 0, v[122:123]
	v_add_f32_e32 v76, 1.0, v76
	global_store_dwordx4 v[80:81], v[82:85], off sc1
	v_pk_add_f32 v[72:73], v[72:73], v[128:129]
	v_mul_f32_e32 v77, 0xbfb8aa3b, v77
	v_mul_f32_e32 v72, 0xbfb8aa3b, v72
	v_exp_f32_e32 v72, v72
	v_exp_f32_e32 v77, v77
	v_add_f32_e32 v72, 1.0, v72
	v_rcp_f32_e32 v76, v76
	v_add_f32_e32 v77, 1.0, v77
	v_mul_f32_e32 v73, 0xbfb8aa3b, v73
	v_exp_f32_e32 v73, v73
	v_rcp_f32_e32 v72, v72
	v_add_f32_e32 v73, 1.0, v73
	v_pk_add_f32 v[78:79], v[78:79], v[134:135]
	v_pk_add_f32 v[74:75], v[74:75], v[130:131]
	v_rcp_f32_e32 v77, v77
	v_mul_f32_e32 v78, 0xbfb8aa3b, v78
	v_exp_f32_e32 v78, v78
	v_mul_f32_e32 v74, 0xbfb8aa3b, v74
	v_add_f32_e32 v78, 1.0, v78
	v_rcp_f32_e32 v73, v73
	v_exp_f32_e32 v74, v74
	v_mul_f32_e32 v79, 0xbfb8aa3b, v79
	v_exp_f32_e32 v79, v79
	v_add_f32_e32 v74, 1.0, v74
	v_rcp_f32_e32 v78, v78
	v_add_f32_e32 v79, 1.0, v79
	v_mul_f32_e32 v75, 0xbfb8aa3b, v75
	v_exp_f32_e32 v75, v75
	v_rcp_f32_e32 v74, v74
	s_nop 0
	v_mul_f32_e32 v74, 0xbf1b4598, v74
	v_mul_f32_e32 v74, 0x3fb8aa3b, v74
	v_exp_f32_e32 v85, v74
	v_add_f32_e32 v75, 1.0, v75
	v_rcp_f32_e32 v74, v79
	s_nop 0
	v_mul_f32_e32 v74, 0xbf1b4598, v74
	v_mul_f32_e32 v74, 0x3fb8aa3b, v74
	v_exp_f32_e32 v84, v74
	v_mul_f32_e32 v76, 0xbf1b4598, v76
	v_mul_f32_e32 v72, 0xbf1b4598, v72
	v_mul_f32_e32 v77, 0xbf1b4598, v77
	v_mul_f32_e32 v73, 0xbf1b4598, v73
	v_mul_f32_e32 v76, 0x3fb8aa3b, v76
	v_mul_f32_e32 v72, 0x3fb8aa3b, v72
	v_mul_f32_e32 v77, 0x3fb8aa3b, v77
	v_mul_f32_e32 v73, 0x3fb8aa3b, v73
	v_rcp_f32_e32 v74, v75
	v_exp_f32_e32 v76, v76
	v_exp_f32_e32 v72, v72
	v_exp_f32_e32 v77, v77
	v_exp_f32_e32 v73, v73
	v_mul_f32_e32 v78, 0xbf1b4598, v78
	v_mul_f32_e32 v74, 0xbf1b4598, v74
	v_pk_add_f32 v[68:69], v[68:69], v[132:133]
	v_mul_f32_e32 v78, 0x3fb8aa3b, v78
	v_mul_f32_e32 v74, 0x3fb8aa3b, v74
	v_mul_f32_e32 v68, 0xbfb8aa3b, v68
	v_exp_f32_e32 v78, v78
	v_exp_f32_e32 v79, v74
	v_exp_f32_e32 v68, v68
	v_add_u32_e32 v82, 0xa0, v144
	v_mov_b32_e32 v83, v145
	v_cvt_pk_f16_f32 v74, v76, v77
	v_cvt_pk_f16_f32 v76, v72, v73
	v_lshlrev_b64 v[72:73], 12, v[82:83]
	v_lshl_add_u64 v[72:73], s[26:27], 0, v[72:73]
	v_cvt_pk_f16_f32 v75, v78, v84
	v_cvt_pk_f16_f32 v77, v85, v79
	v_lshl_add_u64 v[72:73], v[72:73], 0, v[122:123]
	v_add_f32_e32 v68, 1.0, v68
	global_store_dwordx4 v[72:73], v[74:77], off sc1
	v_pk_add_f32 v[64:65], v[64:65], v[128:129]
	v_mul_f32_e32 v69, 0xbfb8aa3b, v69
	v_mul_f32_e32 v64, 0xbfb8aa3b, v64
	v_exp_f32_e32 v64, v64
	v_exp_f32_e32 v69, v69
	v_add_f32_e32 v64, 1.0, v64
	v_rcp_f32_e32 v68, v68
	v_add_f32_e32 v69, 1.0, v69
	v_mul_f32_e32 v65, 0xbfb8aa3b, v65
	v_exp_f32_e32 v65, v65
	v_rcp_f32_e32 v64, v64
	s_nop 0
	v_mul_f32_e32 v64, 0xbf1b4598, v64
	v_mul_f32_e32 v64, 0x3fb8aa3b, v64
; DI float sigmoidf_(float z) { return 1.0f / (1.0f + __expf(-z)); }
;     DI void operator()(f4 (&acc)[2][2][4][2], const Unit& u, int wr, int wc, int fr, int fq) const {
;     ...
;                 for (int ai = 0; ai < 2; ++ai)
; #pragma unroll
;                     for (int m = 0; m < 4; ++m) { const size_t off = (size_t)(row0 + ai * HALF + m * 16) * DB + col;
;                         f4 x0 = acc[ai][bj][m][0] + z0, x1 = acc[ai][bj][m][1] + z1;
; #pragma unroll
;                         for (int e = 0; e < 4; ++e) { x0[e] = __expf(-0.6065306597126334f * sigmoidf_(x0[e])); x1[e] = __expf(-0.6065306597126334f * sigmoidf_(x1[e])); }
;                         { typedef _Float16 h2_ __attribute__((ext_vector_type(2)));
;                           const h2_ q0 = {(_Float16)x0[0], (_Float16)x0[1]}, q1 = {(_Float16)x0[2], (_Float16)x0[3]}, q2 = {(_Float16)x1[0], (_Float16)x1[1]}, q3 = {(_Float16)x1[2], (_Float16)x1[3]};
;                           v4u w_; w_.x = __builtin_bit_cast(unsigned, q0); w_.y = __builtin_bit_cast(unsigned, q1); w_.z = __builtin_bit_cast(unsigned, q2); w_.w = __builtin_bit_cast(unsigned, q3);
;                           *(v4u*)((_Float16*)decay + off) = w_; }
;                         asm volatile("" ::: "memory"); } }
	v_exp_f32_e32 v76, v64
	v_add_f32_e32 v65, 1.0, v65
	v_rcp_f32_e32 v64, v69
	v_pk_add_f32 v[70:71], v[70:71], v[134:135]
	v_pk_add_f32 v[66:67], v[66:67], v[130:131]
	v_mul_f32_e32 v70, 0xbfb8aa3b, v70
	v_exp_f32_e32 v70, v70
	v_rcp_f32_e32 v65, v65
	v_add_f32_e32 v69, 1.0, v70
	v_mul_f32_e32 v65, 0xbf1b4598, v65
	v_mul_f32_e32 v65, 0x3fb8aa3b, v65
	v_exp_f32_e32 v75, v65
	v_mul_f32_e32 v66, 0xbfb8aa3b, v66
	v_exp_f32_e32 v66, v66
	s_nop 0
	v_add_f32_e32 v66, 1.0, v66
	v_rcp_f32_e32 v65, v69
	v_mul_f32_e32 v71, 0xbfb8aa3b, v71
	v_exp_f32_e32 v71, v71
	v_mul_f32_e32 v67, 0xbfb8aa3b, v67
	v_rcp_f32_e32 v66, v66
	v_add_f32_e32 v69, 1.0, v71
	v_mul_f32_e32 v66, 0xbf1b4598, v66
	v_mul_f32_e32 v66, 0x3fb8aa3b, v66
	v_exp_f32_e32 v74, v66
	v_exp_f32_e32 v67, v67
	s_nop 0
	v_add_f32_e32 v67, 1.0, v67
	v_rcp_f32_e32 v66, v69
	v_mul_f32_e32 v68, 0xbf1b4598, v68
	v_mul_f32_e32 v64, 0xbf1b4598, v64
	v_mul_f32_e32 v68, 0x3fb8aa3b, v68
	v_mul_f32_e32 v64, 0x3fb8aa3b, v64
	v_rcp_f32_e32 v67, v67
	v_exp_f32_e32 v68, v68
	v_exp_f32_e32 v64, v64
	v_mul_f32_e32 v65, 0xbf1b4598, v65
	v_mul_f32_e32 v66, 0xbf1b4598, v66
	v_mul_f32_e32 v67, 0xbf1b4598, v67
	v_mul_f32_e32 v65, 0x3fb8aa3b, v65
	v_mul_f32_e32 v66, 0x3fb8aa3b, v66
	v_mul_f32_e32 v67, 0x3fb8aa3b, v67
	v_exp_f32_e32 v65, v65
	v_exp_f32_e32 v66, v66
	v_exp_f32_e32 v67, v67
	v_add_u32_e32 v144, 0xb0, v144
	v_cvt_pk_f16_f32 v64, v68, v64
	v_lshlrev_b64 v[68:69], 12, v[144:145]
	v_lshl_add_u64 v[68:69], s[26:27], 0, v[68:69]
	v_cvt_pk_f16_f32 v65, v65, v66
	v_cvt_pk_f16_f32 v66, v76, v75
	v_cvt_pk_f16_f32 v67, v74, v67
	v_lshl_add_u64 v[74:75], v[68:69], 0, v[122:123]
	global_store_dwordx4 v[74:75], v[64:67], off sc1
	global_load_dwordx4 v[68:71], v[152:153], off offset:512
	global_load_dwordx4 v[64:67], v[152:153], off offset:528
	s_waitcnt vmcnt(0)
	v_pk_add_f32 v[60:61], v[60:61], v[68:69]
	s_nop 0
	v_mul_f32_e32 v60, 0xbfb8aa3b, v60
	v_exp_f32_e32 v60, v60
	v_pk_add_f32 v[56:57], v[56:57], v[64:65]
	v_mul_f32_e32 v61, 0xbfb8aa3b, v61
	v_mul_f32_e32 v56, 0xbfb8aa3b, v56
	v_add_f32_e32 v60, 1.0, v60
	v_exp_f32_e32 v56, v56
	v_exp_f32_e32 v61, v61
	v_mul_f32_e32 v57, 0xbfb8aa3b, v57
	v_add_f32_e32 v56, 1.0, v56
	v_rcp_f32_e32 v60, v60
	v_add_f32_e32 v61, 1.0, v61
	v_exp_f32_e32 v57, v57
	v_pk_add_f32 v[62:63], v[62:63], v[70:71]
	v_rcp_f32_e32 v56, v56
	s_nop 0
	v_mul_f32_e32 v56, 0xbf1b4598, v56
	v_mul_f32_e32 v56, 0x3fb8aa3b, v56
	v_exp_f32_e32 v78, v56
	v_add_f32_e32 v57, 1.0, v57
	v_rcp_f32_e32 v56, v61
	v_mul_f32_e32 v62, 0xbfb8aa3b, v62
	v_exp_f32_e32 v62, v62
	v_pk_add_f32 v[58:59], v[58:59], v[66:67]
	v_rcp_f32_e32 v57, v57
	v_add_f32_e32 v61, 1.0, v62
	v_mul_f32_e32 v57, 0xbf1b4598, v57
	v_mul_f32_e32 v57, 0x3fb8aa3b, v57
	v_exp_f32_e32 v77, v57
	v_mul_f32_e32 v58, 0xbfb8aa3b, v58
	v_exp_f32_e32 v58, v58
	s_nop 0
	v_add_f32_e32 v58, 1.0, v58
	v_rcp_f32_e32 v57, v61
	v_mul_f32_e32 v63, 0xbfb8aa3b, v63
	v_exp_f32_e32 v63, v63
	v_mul_f32_e32 v59, 0xbfb8aa3b, v59
	v_rcp_f32_e32 v58, v58
	v_add_f32_e32 v61, 1.0, v63
	v_mul_f32_e32 v58, 0xbf1b4598, v58
	v_mul_f32_e32 v58, 0x3fb8aa3b, v58
	v_exp_f32_e32 v76, v58
	v_exp_f32_e32 v59, v59
	s_nop 0
	v_add_f32_e32 v59, 1.0, v59
	v_rcp_f32_e32 v58, v61
	v_mul_f32_e32 v60, 0xbf1b4598, v60
	v_mul_f32_e32 v56, 0xbf1b4598, v56
	v_mul_f32_e32 v57, 0xbf1b4598, v57
	v_rcp_f32_e32 v59, v59
	v_mul_f32_e32 v58, 0xbf1b4598, v58
	v_mul_f32_e32 v59, 0xbf1b4598, v59
	v_pk_add_f32 v[52:53], v[52:53], v[68:69]
	v_mul_f32_e32 v60, 0x3fb8aa3b, v60
	v_mul_f32_e32 v56, 0x3fb8aa3b, v56
	v_mul_f32_e32 v57, 0x3fb8aa3b, v57
	v_mul_f32_e32 v58, 0x3fb8aa3b, v58
	v_mul_f32_e32 v59, 0x3fb8aa3b, v59
	v_mul_f32_e32 v52, 0xbfb8aa3b, v52
	v_exp_f32_e32 v60, v60
	v_exp_f32_e32 v56, v56
	v_exp_f32_e32 v57, v57
	v_exp_f32_e32 v58, v58
	v_exp_f32_e32 v59, v59
	v_exp_f32_e32 v52, v52
	v_cvt_pk_f16_f32 v56, v60, v56
	v_cvt_pk_f16_f32 v57, v57, v58
	v_cvt_pk_f16_f32 v58, v78, v77
	v_cvt_pk_f16_f32 v59, v76, v59
	v_add_f32_e32 v52, 1.0, v52
	global_store_dwordx4 v[120:121], v[56:59], off offset:256 sc1
	v_pk_add_f32 v[48:49], v[48:49], v[64:65]
	v_mul_f32_e32 v53, 0xbfb8aa3b, v53
	v_mul_f32_e32 v48, 0xbfb8aa3b, v48
	v_exp_f32_e32 v48, v48
	v_exp_f32_e32 v53, v53
	v_add_f32_e32 v48, 1.0, v48
	v_rcp_f32_e32 v52, v52
	v_add_f32_e32 v53, 1.0, v53
	v_mul_f32_e32 v49, 0xbfb8aa3b, v49
	v_exp_f32_e32 v49, v49
	v_rcp_f32_e32 v48, v48
	s_nop 0
	v_mul_f32_e32 v48, 0xbf1b4598, v48
	v_mul_f32_e32 v48, 0x3fb8aa3b, v48
	v_exp_f32_e32 v58, v48
	v_add_f32_e32 v49, 1.0, v49
	v_rcp_f32_e32 v48, v53
	v_pk_add_f32 v[54:55], v[54:55], v[70:71]
	v_pk_add_f32 v[50:51], v[50:51], v[66:67]
	v_mul_f32_e32 v54, 0xbfb8aa3b, v54
	v_exp_f32_e32 v54, v54
	v_rcp_f32_e32 v49, v49
	v_add_f32_e32 v53, 1.0, v54
	v_mul_f32_e32 v49, 0xbf1b4598, v49
	v_mul_f32_e32 v49, 0x3fb8aa3b, v49
	v_exp_f32_e32 v57, v49
	v_mul_f32_e32 v50, 0xbfb8aa3b, v50
	v_exp_f32_e32 v50, v50
	s_nop 0
	v_add_f32_e32 v50, 1.0, v50
	v_rcp_f32_e32 v49, v53
	v_mul_f32_e32 v55, 0xbfb8aa3b, v55
	v_exp_f32_e32 v55, v55
	v_mul_f32_e32 v51, 0xbfb8aa3b, v51
	v_rcp_f32_e32 v50, v50
	v_add_f32_e32 v53, 1.0, v55
	v_mul_f32_e32 v50, 0xbf1b4598, v50
	v_mul_f32_e32 v50, 0x3fb8aa3b, v50
	v_exp_f32_e32 v56, v50
	v_exp_f32_e32 v51, v51
	s_nop 0
	v_add_f32_e32 v51, 1.0, v51
	v_rcp_f32_e32 v50, v53
	v_mul_f32_e32 v52, 0xbf1b4598, v52
	v_mul_f32_e32 v48, 0xbf1b4598, v48
	v_mul_f32_e32 v49, 0xbf1b4598, v49
	v_rcp_f32_e32 v51, v51
	v_mul_f32_e32 v50, 0xbf1b4598, v50
	v_mul_f32_e32 v51, 0xbf1b4598, v51
	v_pk_add_f32 v[44:45], v[44:45], v[68:69]
	v_mul_f32_e32 v52, 0x3fb8aa3b, v52
	v_mul_f32_e32 v48, 0x3fb8aa3b, v48
	v_mul_f32_e32 v49, 0x3fb8aa3b, v49
	v_mul_f32_e32 v50, 0x3fb8aa3b, v50
; DI float sigmoidf_(float z) { return 1.0f / (1.0f + __expf(-z)); }
;     DI void operator()(f4 (&acc)[2][2][4][2], const Unit& u, int wr, int wc, int fr, int fq) const {
;     ...
;                 for (int ai = 0; ai < 2; ++ai)
; #pragma unroll
;                     for (int m = 0; m < 4; ++m) { const size_t off = (size_t)(row0 + ai * HALF + m * 16) * DB + col;
;                         f4 x0 = acc[ai][bj][m][0] + z0, x1 = acc[ai][bj][m][1] + z1;
; #pragma unroll
;                         for (int e = 0; e < 4; ++e) { x0[e] = __expf(-0.6065306597126334f * sigmoidf_(x0[e])); x1[e] = __expf(-0.6065306597126334f * sigmoidf_(x1[e])); }
;                         { typedef _Float16 h2_ __attribute__((ext_vector_type(2)));
;                           const h2_ q0 = {(_Float16)x0[0], (_Float16)x0[1]}, q1 = {(_Float16)x0[2], (_Float16)x0[3]}, q2 = {(_Float16)x1[0], (_Float16)x1[1]}, q3 = {(_Float16)x1[2], (_Float16)x1[3]};
;                           v4u w_; w_.x = __builtin_bit_cast(unsigned, q0); w_.y = __builtin_bit_cast(unsigned, q1); w_.z = __builtin_bit_cast(unsigned, q2); w_.w = __builtin_bit_cast(unsigned, q3);
;                           *(v4u*)((_Float16*)decay + off) = w_; }
;                         asm volatile("" ::: "memory"); } }
	v_mul_f32_e32 v51, 0x3fb8aa3b, v51
	v_mul_f32_e32 v44, 0xbfb8aa3b, v44
	v_exp_f32_e32 v52, v52
	v_exp_f32_e32 v48, v48
	v_exp_f32_e32 v49, v49
	v_exp_f32_e32 v50, v50
	v_exp_f32_e32 v51, v51
	v_exp_f32_e32 v44, v44
	v_cvt_pk_f16_f32 v48, v52, v48
	v_cvt_pk_f16_f32 v49, v49, v50
	v_cvt_pk_f16_f32 v50, v58, v57
	v_cvt_pk_f16_f32 v51, v56, v51
	v_add_f32_e32 v44, 1.0, v44
	global_store_dwordx4 v[112:113], v[48:51], off offset:256 sc1
	v_pk_add_f32 v[40:41], v[40:41], v[64:65]
	v_mul_f32_e32 v45, 0xbfb8aa3b, v45
	v_mul_f32_e32 v40, 0xbfb8aa3b, v40
	v_exp_f32_e32 v40, v40
	v_exp_f32_e32 v45, v45
	v_add_f32_e32 v40, 1.0, v40
	v_rcp_f32_e32 v44, v44
	v_add_f32_e32 v45, 1.0, v45
	v_mul_f32_e32 v41, 0xbfb8aa3b, v41
	v_exp_f32_e32 v41, v41
	v_rcp_f32_e32 v40, v40
	s_nop 0
	v_mul_f32_e32 v40, 0xbf1b4598, v40
	v_mul_f32_e32 v40, 0x3fb8aa3b, v40
	v_exp_f32_e32 v50, v40
	v_add_f32_e32 v41, 1.0, v41
	v_rcp_f32_e32 v40, v45
	v_pk_add_f32 v[46:47], v[46:47], v[70:71]
	v_pk_add_f32 v[42:43], v[42:43], v[66:67]
	v_mul_f32_e32 v46, 0xbfb8aa3b, v46
	v_exp_f32_e32 v46, v46
	v_rcp_f32_e32 v41, v41
	v_add_f32_e32 v45, 1.0, v46
	v_mul_f32_e32 v41, 0xbf1b4598, v41
	v_mul_f32_e32 v41, 0x3fb8aa3b, v41
	v_exp_f32_e32 v49, v41
	v_mul_f32_e32 v42, 0xbfb8aa3b, v42
	v_exp_f32_e32 v42, v42
	s_nop 0
	v_add_f32_e32 v42, 1.0, v42
	v_rcp_f32_e32 v41, v45
	v_mul_f32_e32 v47, 0xbfb8aa3b, v47
	v_exp_f32_e32 v47, v47
	v_mul_f32_e32 v43, 0xbfb8aa3b, v43
	v_rcp_f32_e32 v42, v42
	v_add_f32_e32 v45, 1.0, v47
	v_mul_f32_e32 v42, 0xbf1b4598, v42
	v_mul_f32_e32 v42, 0x3fb8aa3b, v42
	v_exp_f32_e32 v48, v42
	v_exp_f32_e32 v43, v43
	s_nop 0
	v_add_f32_e32 v43, 1.0, v43
	v_rcp_f32_e32 v42, v45
	v_mul_f32_e32 v44, 0xbf1b4598, v44
	v_mul_f32_e32 v40, 0xbf1b4598, v40
	v_mul_f32_e32 v41, 0xbf1b4598, v41
	v_rcp_f32_e32 v43, v43
	v_mul_f32_e32 v42, 0xbf1b4598, v42
	v_mul_f32_e32 v43, 0xbf1b4598, v43
	v_pk_add_f32 v[36:37], v[36:37], v[68:69]
	v_mul_f32_e32 v44, 0x3fb8aa3b, v44
	v_mul_f32_e32 v40, 0x3fb8aa3b, v40
	v_mul_f32_e32 v41, 0x3fb8aa3b, v41
	v_mul_f32_e32 v42, 0x3fb8aa3b, v42
	v_mul_f32_e32 v43, 0x3fb8aa3b, v43
	v_mul_f32_e32 v36, 0xbfb8aa3b, v36
	v_exp_f32_e32 v44, v44
	v_exp_f32_e32 v40, v40
	v_exp_f32_e32 v41, v41
	v_exp_f32_e32 v42, v42
	v_exp_f32_e32 v43, v43
	v_exp_f32_e32 v36, v36
	v_cvt_pk_f16_f32 v40, v44, v40
	v_cvt_pk_f16_f32 v41, v41, v42
	v_cvt_pk_f16_f32 v42, v50, v49
	v_cvt_pk_f16_f32 v43, v48, v43
	v_add_f32_e32 v36, 1.0, v36
	global_store_dwordx4 v[104:105], v[40:43], off offset:256 sc1
	v_pk_add_f32 v[32:33], v[32:33], v[64:65]
	v_mul_f32_e32 v37, 0xbfb8aa3b, v37
	v_mul_f32_e32 v32, 0xbfb8aa3b, v32
	v_exp_f32_e32 v32, v32
	v_exp_f32_e32 v37, v37
	v_add_f32_e32 v32, 1.0, v32
	v_rcp_f32_e32 v36, v36
	v_add_f32_e32 v37, 1.0, v37
	v_mul_f32_e32 v33, 0xbfb8aa3b, v33
	v_exp_f32_e32 v33, v33
	v_rcp_f32_e32 v32, v32
	s_nop 0
	v_mul_f32_e32 v32, 0xbf1b4598, v32
	v_mul_f32_e32 v32, 0x3fb8aa3b, v32
	v_exp_f32_e32 v42, v32
	v_add_f32_e32 v33, 1.0, v33
	v_rcp_f32_e32 v32, v37
	v_pk_add_f32 v[38:39], v[38:39], v[70:71]
	v_pk_add_f32 v[34:35], v[34:35], v[66:67]
	v_mul_f32_e32 v38, 0xbfb8aa3b, v38
	v_exp_f32_e32 v38, v38
	v_rcp_f32_e32 v33, v33
	v_add_f32_e32 v37, 1.0, v38
	v_mul_f32_e32 v33, 0xbf1b4598, v33
	v_mul_f32_e32 v33, 0x3fb8aa3b, v33
	v_exp_f32_e32 v41, v33
	v_mul_f32_e32 v34, 0xbfb8aa3b, v34
	v_exp_f32_e32 v34, v34
	s_nop 0
	v_add_f32_e32 v34, 1.0, v34
	v_rcp_f32_e32 v33, v37
	v_mul_f32_e32 v39, 0xbfb8aa3b, v39
	v_exp_f32_e32 v39, v39
	v_mul_f32_e32 v35, 0xbfb8aa3b, v35
	v_rcp_f32_e32 v34, v34
	v_add_f32_e32 v37, 1.0, v39
	v_mul_f32_e32 v34, 0xbf1b4598, v34
	v_mul_f32_e32 v34, 0x3fb8aa3b, v34
	v_exp_f32_e32 v40, v34
	v_exp_f32_e32 v35, v35
	s_nop 0
	v_add_f32_e32 v35, 1.0, v35
	v_rcp_f32_e32 v34, v37
	v_mul_f32_e32 v36, 0xbf1b4598, v36
	v_mul_f32_e32 v32, 0xbf1b4598, v32
	v_mul_f32_e32 v33, 0xbf1b4598, v33
	v_rcp_f32_e32 v35, v35
	v_mul_f32_e32 v34, 0xbf1b4598, v34
	v_mul_f32_e32 v35, 0xbf1b4598, v35
	v_pk_add_f32 v[28:29], v[28:29], v[68:69]
	v_mul_f32_e32 v36, 0x3fb8aa3b, v36
	v_mul_f32_e32 v32, 0x3fb8aa3b, v32
	v_mul_f32_e32 v33, 0x3fb8aa3b, v33
	v_mul_f32_e32 v34, 0x3fb8aa3b, v34
	v_mul_f32_e32 v35, 0x3fb8aa3b, v35
	v_mul_f32_e32 v28, 0xbfb8aa3b, v28
	v_exp_f32_e32 v36, v36
	v_exp_f32_e32 v32, v32
	v_exp_f32_e32 v33, v33
	v_exp_f32_e32 v34, v34
	v_exp_f32_e32 v35, v35
	v_exp_f32_e32 v28, v28
	v_cvt_pk_f16_f32 v32, v36, v32
	v_cvt_pk_f16_f32 v33, v33, v34
	v_cvt_pk_f16_f32 v34, v42, v41
	v_cvt_pk_f16_f32 v35, v40, v35
	v_add_f32_e32 v28, 1.0, v28
	global_store_dwordx4 v[96:97], v[32:35], off offset:256 sc1
	v_pk_add_f32 v[24:25], v[24:25], v[64:65]
	v_mul_f32_e32 v29, 0xbfb8aa3b, v29
	v_mul_f32_e32 v24, 0xbfb8aa3b, v24
	v_exp_f32_e32 v24, v24
	v_exp_f32_e32 v29, v29
	v_add_f32_e32 v24, 1.0, v24
	v_rcp_f32_e32 v28, v28
	v_add_f32_e32 v29, 1.0, v29
	v_mul_f32_e32 v25, 0xbfb8aa3b, v25
	v_exp_f32_e32 v25, v25
	v_rcp_f32_e32 v24, v24
	s_nop 0
	v_mul_f32_e32 v24, 0xbf1b4598, v24
	v_mul_f32_e32 v24, 0x3fb8aa3b, v24
	v_exp_f32_e32 v34, v24
	v_add_f32_e32 v25, 1.0, v25
	v_rcp_f32_e32 v24, v29
	v_pk_add_f32 v[30:31], v[30:31], v[70:71]
	v_pk_add_f32 v[26:27], v[26:27], v[66:67]
	v_mul_f32_e32 v30, 0xbfb8aa3b, v30
	v_exp_f32_e32 v30, v30
	v_rcp_f32_e32 v25, v25
	v_add_f32_e32 v29, 1.0, v30
	v_mul_f32_e32 v25, 0xbf1b4598, v25
	v_mul_f32_e32 v25, 0x3fb8aa3b, v25
	v_exp_f32_e32 v33, v25
	v_mul_f32_e32 v26, 0xbfb8aa3b, v26
	v_exp_f32_e32 v26, v26
	s_nop 0
	v_add_f32_e32 v26, 1.0, v26
	v_rcp_f32_e32 v25, v29
	v_mul_f32_e32 v31, 0xbfb8aa3b, v31
	v_exp_f32_e32 v31, v31
	v_mul_f32_e32 v27, 0xbfb8aa3b, v27
	v_rcp_f32_e32 v26, v26
	v_add_f32_e32 v29, 1.0, v31
	v_mul_f32_e32 v26, 0xbf1b4598, v26
; DI float sigmoidf_(float z) { return 1.0f / (1.0f + __expf(-z)); }
;     DI void operator()(f4 (&acc)[2][2][4][2], const Unit& u, int wr, int wc, int fr, int fq) const {
;     ...
;                 for (int ai = 0; ai < 2; ++ai)
; #pragma unroll
;                     for (int m = 0; m < 4; ++m) { const size_t off = (size_t)(row0 + ai * HALF + m * 16) * DB + col;
;                         f4 x0 = acc[ai][bj][m][0] + z0, x1 = acc[ai][bj][m][1] + z1;
; #pragma unroll
;                         for (int e = 0; e < 4; ++e) { x0[e] = __expf(-0.6065306597126334f * sigmoidf_(x0[e])); x1[e] = __expf(-0.6065306597126334f * sigmoidf_(x1[e])); }
;                         { typedef _Float16 h2_ __attribute__((ext_vector_type(2)));
;                           const h2_ q0 = {(_Float16)x0[0], (_Float16)x0[1]}, q1 = {(_Float16)x0[2], (_Float16)x0[3]}, q2 = {(_Float16)x1[0], (_Float16)x1[1]}, q3 = {(_Float16)x1[2], (_Float16)x1[3]};
;                           v4u w_; w_.x = __builtin_bit_cast(unsigned, q0); w_.y = __builtin_bit_cast(unsigned, q1); w_.z = __builtin_bit_cast(unsigned, q2); w_.w = __builtin_bit_cast(unsigned, q3);
;                           *(v4u*)((_Float16*)decay + off) = w_; }
;                         asm volatile("" ::: "memory"); } }
	v_mul_f32_e32 v26, 0x3fb8aa3b, v26
	v_exp_f32_e32 v32, v26
	v_exp_f32_e32 v27, v27
	s_nop 0
	v_add_f32_e32 v27, 1.0, v27
	v_rcp_f32_e32 v26, v29
	v_mul_f32_e32 v28, 0xbf1b4598, v28
	v_mul_f32_e32 v24, 0xbf1b4598, v24
	v_mul_f32_e32 v25, 0xbf1b4598, v25
	v_rcp_f32_e32 v27, v27
	v_mul_f32_e32 v26, 0xbf1b4598, v26
	v_mul_f32_e32 v27, 0xbf1b4598, v27
	v_pk_add_f32 v[20:21], v[20:21], v[68:69]
	v_mul_f32_e32 v28, 0x3fb8aa3b, v28
	v_mul_f32_e32 v24, 0x3fb8aa3b, v24
	v_mul_f32_e32 v25, 0x3fb8aa3b, v25
	v_mul_f32_e32 v26, 0x3fb8aa3b, v26
	v_mul_f32_e32 v27, 0x3fb8aa3b, v27
	v_mul_f32_e32 v20, 0xbfb8aa3b, v20
	v_exp_f32_e32 v28, v28
	v_exp_f32_e32 v24, v24
	v_exp_f32_e32 v25, v25
	v_exp_f32_e32 v26, v26
	v_exp_f32_e32 v27, v27
	v_exp_f32_e32 v20, v20
	v_cvt_pk_f16_f32 v24, v28, v24
	v_cvt_pk_f16_f32 v25, v25, v26
	v_cvt_pk_f16_f32 v26, v34, v33
	v_cvt_pk_f16_f32 v27, v32, v27
	v_add_f32_e32 v20, 1.0, v20
	global_store_dwordx4 v[88:89], v[24:27], off offset:256 sc1
	v_pk_add_f32 v[16:17], v[16:17], v[64:65]
	v_mul_f32_e32 v21, 0xbfb8aa3b, v21
	v_mul_f32_e32 v16, 0xbfb8aa3b, v16
	v_exp_f32_e32 v16, v16
	v_exp_f32_e32 v21, v21
	v_add_f32_e32 v16, 1.0, v16
	v_rcp_f32_e32 v20, v20
	v_add_f32_e32 v21, 1.0, v21
	v_mul_f32_e32 v17, 0xbfb8aa3b, v17
	v_exp_f32_e32 v17, v17
	v_rcp_f32_e32 v16, v16
	s_nop 0
	v_mul_f32_e32 v16, 0xbf1b4598, v16
	v_mul_f32_e32 v16, 0x3fb8aa3b, v16
	v_exp_f32_e32 v26, v16
	v_add_f32_e32 v17, 1.0, v17
	v_rcp_f32_e32 v16, v21
	v_pk_add_f32 v[22:23], v[22:23], v[70:71]
	v_pk_add_f32 v[18:19], v[18:19], v[66:67]
	v_mul_f32_e32 v22, 0xbfb8aa3b, v22
	v_exp_f32_e32 v22, v22
	v_rcp_f32_e32 v17, v17
	v_add_f32_e32 v21, 1.0, v22
	v_mul_f32_e32 v17, 0xbf1b4598, v17
	v_mul_f32_e32 v17, 0x3fb8aa3b, v17
	v_exp_f32_e32 v25, v17
	v_mul_f32_e32 v18, 0xbfb8aa3b, v18
	v_exp_f32_e32 v18, v18
	s_nop 0
	v_add_f32_e32 v18, 1.0, v18
	v_rcp_f32_e32 v17, v21
	v_mul_f32_e32 v23, 0xbfb8aa3b, v23
	v_exp_f32_e32 v23, v23
	v_mul_f32_e32 v19, 0xbfb8aa3b, v19
	v_rcp_f32_e32 v18, v18
	v_add_f32_e32 v21, 1.0, v23
	v_mul_f32_e32 v18, 0xbf1b4598, v18
	v_mul_f32_e32 v18, 0x3fb8aa3b, v18
	v_exp_f32_e32 v24, v18
	v_exp_f32_e32 v19, v19
	s_nop 0
	v_add_f32_e32 v19, 1.0, v19
	v_rcp_f32_e32 v18, v21
	v_mul_f32_e32 v20, 0xbf1b4598, v20
	v_mul_f32_e32 v16, 0xbf1b4598, v16
	v_mul_f32_e32 v17, 0xbf1b4598, v17
	v_rcp_f32_e32 v19, v19
	v_mul_f32_e32 v18, 0xbf1b4598, v18
	v_mul_f32_e32 v19, 0xbf1b4598, v19
	v_pk_add_f32 v[12:13], v[12:13], v[68:69]
	v_mul_f32_e32 v20, 0x3fb8aa3b, v20
	v_mul_f32_e32 v16, 0x3fb8aa3b, v16
	v_mul_f32_e32 v17, 0x3fb8aa3b, v17
	v_mul_f32_e32 v18, 0x3fb8aa3b, v18
	v_mul_f32_e32 v19, 0x3fb8aa3b, v19
	v_mul_f32_e32 v12, 0xbfb8aa3b, v12
	v_exp_f32_e32 v20, v20
	v_exp_f32_e32 v16, v16
	v_exp_f32_e32 v17, v17
	v_exp_f32_e32 v18, v18
	v_exp_f32_e32 v19, v19
	v_exp_f32_e32 v12, v12
	v_cvt_pk_f16_f32 v16, v20, v16
	v_cvt_pk_f16_f32 v17, v17, v18
	v_cvt_pk_f16_f32 v18, v26, v25
	v_cvt_pk_f16_f32 v19, v24, v19
	v_add_f32_e32 v12, 1.0, v12
	global_store_dwordx4 v[80:81], v[16:19], off offset:256 sc1
	v_pk_add_f32 v[8:9], v[8:9], v[64:65]
	v_mul_f32_e32 v13, 0xbfb8aa3b, v13
	v_mul_f32_e32 v8, 0xbfb8aa3b, v8
	v_exp_f32_e32 v8, v8
	v_exp_f32_e32 v13, v13
	v_add_f32_e32 v8, 1.0, v8
	v_rcp_f32_e32 v12, v12
	v_add_f32_e32 v13, 1.0, v13
	v_mul_f32_e32 v9, 0xbfb8aa3b, v9
	v_exp_f32_e32 v9, v9
	v_rcp_f32_e32 v8, v8
	s_nop 0
	v_mul_f32_e32 v8, 0xbf1b4598, v8
	v_mul_f32_e32 v8, 0x3fb8aa3b, v8
	v_exp_f32_e32 v18, v8
	v_add_f32_e32 v9, 1.0, v9
	v_rcp_f32_e32 v8, v13
	v_pk_add_f32 v[14:15], v[14:15], v[70:71]
	v_pk_add_f32 v[10:11], v[10:11], v[66:67]
	v_mul_f32_e32 v14, 0xbfb8aa3b, v14
	v_exp_f32_e32 v14, v14
	v_rcp_f32_e32 v9, v9
	v_add_f32_e32 v13, 1.0, v14
	v_mul_f32_e32 v9, 0xbf1b4598, v9
	v_mul_f32_e32 v9, 0x3fb8aa3b, v9
	v_exp_f32_e32 v17, v9
	v_mul_f32_e32 v10, 0xbfb8aa3b, v10
	v_exp_f32_e32 v10, v10
	s_nop 0
	v_add_f32_e32 v10, 1.0, v10
	v_rcp_f32_e32 v9, v13
	v_mul_f32_e32 v15, 0xbfb8aa3b, v15
	v_exp_f32_e32 v15, v15
	v_mul_f32_e32 v11, 0xbfb8aa3b, v11
	v_rcp_f32_e32 v10, v10
	v_add_f32_e32 v13, 1.0, v15
	v_mul_f32_e32 v10, 0xbf1b4598, v10
	v_mul_f32_e32 v10, 0x3fb8aa3b, v10
	v_exp_f32_e32 v16, v10
	v_exp_f32_e32 v11, v11
	s_nop 0
	v_add_f32_e32 v11, 1.0, v11
	v_rcp_f32_e32 v10, v13
	v_mul_f32_e32 v12, 0xbf1b4598, v12
	v_mul_f32_e32 v8, 0xbf1b4598, v8
	v_mul_f32_e32 v9, 0xbf1b4598, v9
	v_rcp_f32_e32 v11, v11
	v_mul_f32_e32 v10, 0xbf1b4598, v10
	v_mul_f32_e32 v11, 0xbf1b4598, v11
	v_pk_add_f32 v[4:5], v[4:5], v[68:69]
	v_mul_f32_e32 v12, 0x3fb8aa3b, v12
	v_mul_f32_e32 v8, 0x3fb8aa3b, v8
	v_mul_f32_e32 v9, 0x3fb8aa3b, v9
	v_mul_f32_e32 v10, 0x3fb8aa3b, v10
	v_mul_f32_e32 v11, 0x3fb8aa3b, v11
	v_mul_f32_e32 v4, 0xbfb8aa3b, v4
	v_exp_f32_e32 v12, v12
	v_exp_f32_e32 v8, v8
	v_exp_f32_e32 v9, v9
	v_exp_f32_e32 v10, v10
	v_exp_f32_e32 v11, v11
	v_exp_f32_e32 v4, v4
	v_cvt_pk_f16_f32 v8, v12, v8
	v_cvt_pk_f16_f32 v9, v9, v10
	v_cvt_pk_f16_f32 v10, v18, v17
	v_cvt_pk_f16_f32 v11, v16, v11
	v_add_f32_e32 v4, 1.0, v4
	global_store_dwordx4 v[72:73], v[8:11], off offset:256 sc1
	v_pk_add_f32 v[0:1], v[0:1], v[64:65]
	v_mul_f32_e32 v5, 0xbfb8aa3b, v5
	v_mul_f32_e32 v0, 0xbfb8aa3b, v0
	v_exp_f32_e32 v0, v0
	v_exp_f32_e32 v5, v5
	v_add_f32_e32 v0, 1.0, v0
	v_rcp_f32_e32 v4, v4
	v_add_f32_e32 v5, 1.0, v5
	v_mul_f32_e32 v1, 0xbfb8aa3b, v1
	v_exp_f32_e32 v1, v1
	v_rcp_f32_e32 v0, v0
	s_nop 0
	v_mul_f32_e32 v0, 0xbf1b4598, v0
	v_mul_f32_e32 v0, 0x3fb8aa3b, v0
	v_exp_f32_e32 v10, v0
	v_add_f32_e32 v1, 1.0, v1
	v_rcp_f32_e32 v0, v5
	v_pk_add_f32 v[6:7], v[6:7], v[70:71]
	v_pk_add_f32 v[2:3], v[2:3], v[66:67]
	v_mul_f32_e32 v6, 0xbfb8aa3b, v6
	v_exp_f32_e32 v6, v6
	v_rcp_f32_e32 v1, v1
	v_add_f32_e32 v5, 1.0, v6
	v_mul_f32_e32 v1, 0xbf1b4598, v1
	v_mul_f32_e32 v1, 0x3fb8aa3b, v1
	v_exp_f32_e32 v9, v1
	v_mul_f32_e32 v2, 0xbfb8aa3b, v2
	v_exp_f32_e32 v2, v2
	s_nop 0
	v_add_f32_e32 v2, 1.0, v2
	v_rcp_f32_e32 v1, v5
	v_mul_f32_e32 v7, 0xbfb8aa3b, v7
	v_exp_f32_e32 v7, v7
	v_mul_f32_e32 v3, 0xbfb8aa3b, v3
	v_rcp_f32_e32 v2, v2
	v_add_f32_e32 v5, 1.0, v7
	v_mul_f32_e32 v2, 0xbf1b4598, v2
	v_mul_f32_e32 v2, 0x3fb8aa3b, v2
	v_exp_f32_e32 v8, v2
	v_exp_f32_e32 v3, v3
	s_nop 0
	v_add_f32_e32 v3, 1.0, v3
	v_rcp_f32_e32 v2, v5
	v_mul_f32_e32 v4, 0xbf1b4598, v4
	v_mul_f32_e32 v0, 0xbf1b4598, v0
	v_mul_f32_e32 v1, 0xbf1b4598, v1
	v_rcp_f32_e32 v3, v3
	v_mul_f32_e32 v2, 0xbf1b4598, v2
	v_mul_f32_e32 v3, 0xbf1b4598, v3
	v_mul_f32_e32 v4, 0x3fb8aa3b, v4
	v_mul_f32_e32 v0, 0x3fb8aa3b, v0
	v_mul_f32_e32 v1, 0x3fb8aa3b, v1
	v_mul_f32_e32 v2, 0x3fb8aa3b, v2
	v_mul_f32_e32 v3, 0x3fb8aa3b, v3
	v_exp_f32_e32 v4, v4
	v_exp_f32_e32 v0, v0
	v_exp_f32_e32 v1, v1
	v_exp_f32_e32 v2, v2
	v_exp_f32_e32 v3, v3
	v_cvt_pk_f16_f32 v0, v4, v0
	v_cvt_pk_f16_f32 v1, v1, v2
	v_cvt_pk_f16_f32 v2, v10, v9
	v_cvt_pk_f16_f32 v3, v8, v3
	global_store_dwordx4 v[74:75], v[0:3], off offset:256 sc1
	s_and_b64 vcc, exec, s[6:7]
	s_mov_b64 s[0:1], -1
	s_cbranch_vccnz .LBB0_2052

.LBB0_2155:
	s_or_b64 exec, exec, s[0:1]
	s_waitcnt lgkmcnt(1)
	v_mov_b32_e32 v126, v108
	v_mov_b32_e32 v127, v100
	v_mov_b32_e32 v128, v109
	v_mov_b32_e32 v129, v101
	v_pk_add_f32 v[126:127], v[126:127], v[128:129]
	v_mov_b32_e32 v128, v110
	v_mov_b32_e32 v129, v102
	v_mov_b32_e32 v130, v111
	v_mov_b32_e32 v131, v103
	v_pk_add_f32 v[128:129], v[128:129], v[130:131]
	v_mov_b32_e32 v130, v105
	v_pk_add_f32 v[126:127], v[126:127], v[128:129]
	v_mov_b32_e32 v128, v104
	v_mov_b32_e32 v129, v96
	v_mov_b32_e32 v131, v97
	v_pk_add_f32 v[128:129], v[128:129], v[130:131]
	v_mov_b32_e32 v130, v106
	v_mov_b32_e32 v131, v98
	v_mov_b32_e32 v134, v107
	v_mov_b32_e32 v135, v99
	v_pk_add_f32 v[130:131], v[130:131], v[134:135]
	s_lshl_b32 s31, s29, 4
	v_pk_add_f32 v[128:129], v[128:129], v[130:131]
	s_add_i32 s30, s29, 2
	v_pk_add_f32 v[126:127], v[126:127], v[128:129]
	s_cmpk_gt_u32 s29, 0x1fd
	v_add_f32_e32 v126, v126, v127
	s_cselect_b64 s[14:15], -1, 0
	s_nop 0
	v_add_f32_dpp v126, v126, v126 quad_perm:[1,0,3,2] row_mask:0xf bank_mask:0xf bound_ctrl:1
	s_nop 1
	v_add_f32_dpp v133, v126, v126 quad_perm:[2,3,0,1] row_mask:0xf bank_mask:0xf bound_ctrl:1
	v_fmamk_f32 v109, v133, 0xbc800000, v109
	v_fmamk_f32 v108, v133, 0xbc800000, v108
	v_fmamk_f32 v111, v133, 0xbc800000, v111
	v_fmac_f32_e32 v110, 0xbc800000, v133
	v_pk_mul_f32 v[126:127], v[110:111], v[110:111]
	v_pk_mul_f32 v[128:129], v[108:109], v[108:109]
	v_fmamk_f32 v107, v133, 0xbc800000, v107
	v_pk_mov_b32 v[130:131], v[128:129], v[126:127] op_sel:[1,0]
	v_mov_b32_e32 v129, v127
	v_pk_add_f32 v[126:127], v[130:131], v[128:129]
	v_fmamk_f32 v129, v133, 0xbc800000, v105
	v_fmamk_f32 v128, v133, 0xbc800000, v104
	v_fmac_f32_e32 v106, 0xbc800000, v133
	v_pk_mul_f32 v[104:105], v[106:107], v[106:107]
	v_pk_mul_f32 v[130:131], v[128:129], v[128:129]
	v_fmamk_f32 v101, v133, 0xbc800000, v101
	v_pk_mov_b32 v[134:135], v[130:131], v[104:105] op_sel:[1,0]
	v_mov_b32_e32 v131, v105
	v_pk_add_f32 v[104:105], v[134:135], v[130:131]
	v_fmamk_f32 v100, v133, 0xbc800000, v100
	v_fmamk_f32 v103, v133, 0xbc800000, v103
	v_fmac_f32_e32 v102, 0xbc800000, v133
	v_fmamk_f32 v137, v133, 0xbc800000, v97
	v_fmamk_f32 v136, v133, 0xbc800000, v96
	v_fmamk_f32 v99, v133, 0xbc800000, v99
	v_fmac_f32_e32 v98, 0xbc800000, v133
	v_pk_add_f32 v[126:127], v[126:127], v[126:127] op_sel_hi:[0,1]
	v_pk_add_f32 v[104:105], v[104:105], v[104:105] op_sel_hi:[0,1]
	v_pk_mul_f32 v[130:131], v[102:103], v[102:103]
	v_pk_mul_f32 v[134:135], v[100:101], v[100:101]
	v_pk_mul_f32 v[96:97], v[98:99], v[98:99]
	v_pk_mul_f32 v[138:139], v[136:137], v[136:137]
	v_add_f32_e32 v135, v134, v135
	v_add_f32_e32 v131, v130, v131
	v_mov_b32_e32 v134, v138
	v_mov_b32_e32 v130, v139
	v_mov_b32_e32 v126, v96
	v_mov_b32_e32 v104, v97
	v_pk_add_f32 v[130:131], v[134:135], v[130:131]
	v_pk_add_f32 v[96:97], v[126:127], v[104:105]
	s_waitcnt vmcnt(2)
	v_and_b32_e32 v133, 0xffff0000, v72
	v_pk_add_f32 v[96:97], v[130:131], v[96:97]
	v_lshlrev_b32_e32 v130, 16, v73
	v_add_f32_e32 v96, v96, v97
	v_and_b32_e32 v131, 0xffff0000, v73
	s_nop 0
	v_add_f32_dpp v96, v96, v96 quad_perm:[1,0,3,2] row_mask:0xf bank_mask:0xf bound_ctrl:1
	s_nop 1
	v_add_f32_dpp v96, v96, v96 quad_perm:[2,3,0,1] row_mask:0xf bank_mask:0xf bound_ctrl:1
	v_fmamk_f32 v96, v96, 0x3c800000, v123
	v_mul_f32_e32 v97, 0x4f800000, v96
	v_cmp_gt_f32_e32 vcc, s26, v96
	s_nop 1
	v_cndmask_b32_e32 v96, v96, v97, vcc
	v_sqrt_f32_e32 v97, v96
	s_nop 0
	v_add_u32_e32 v104, -1, v97
	v_fma_f32 v105, -v104, v97, v96
	v_cmp_ge_f32_e64 s[0:1], 0, v105
	v_add_u32_e32 v105, 1, v97
	s_nop 0
	v_cndmask_b32_e64 v104, v97, v104, s[0:1]
	v_fma_f32 v97, -v105, v97, v96
	v_cmp_lt_f32_e64 s[0:1], 0, v97
	s_nop 1
	v_cndmask_b32_e64 v97, v104, v105, s[0:1]
	v_mul_f32_e32 v104, 0x37800000, v97
	v_cndmask_b32_e32 v97, v97, v104, vcc
	v_cmp_class_f32_e32 vcc, v96, v124
	s_nop 1
	v_cndmask_b32_e32 v96, v97, v96, vcc
	s_nop 0
	v_rcp_f32_e32 v126, v96
	s_nop 0
	v_pk_mul_f32 v[96:97], v[110:111], v[126:127] op_sel_hi:[1,0]
	v_lshlrev_b32_e32 v110, 16, v53
	v_and_b32_e32 v111, 0xffff0000, v53
	v_pk_mul_f32 v[104:105], v[108:109], v[126:127] op_sel_hi:[1,0]
	v_lshlrev_b32_e32 v127, 16, v72
	v_lshlrev_b32_e32 v108, 16, v52
	v_and_b32_e32 v109, 0xffff0000, v52
	v_sub_f32_e32 v131, v131, v111
	v_sub_f32_e32 v130, v130, v110
	v_pk_fma_f32 v[96:97], v[14:15], v[96:97], v[30:31]
	v_sub_f32_e32 v135, v133, v109
	v_sub_f32_e32 v134, v127, v108
	v_pk_fma_f32 v[110:111], v[46:47], v[130:131], v[110:111]
	v_pk_fma_f32 v[104:105], v[12:13], v[104:105], v[28:29]
	v_pk_fma_f32 v[108:109], v[44:45], v[134:135], v[108:109]
	s_waitcnt lgkmcnt(0)
; DI void chunk_scan(const float* const* in, unsigned char* ws, float* y, LAS unsigned char* lds, LAS unsigned* ctr  , int b, int hd, int wave) {
;     ...
;         GN_ISSUE(vcA, vpA, ggA, 0); GN_ISSUE(vcB, vpB, ggB, 1);
;         for (int c = 0; c < CS_NCHUNK; c += 2) {
;             GN_CHUNK(vcA, vpA, ggA, c);     if (c + 2 < CS_NCHUNK) GN_ISSUE(vcA, vpA, ggA, c + 2);
;             GN_CHUNK(vcB, vpB, ggB, c + 1); if (c + 3 < CS_NCHUNK) GN_ISSUE(vcB, vpB, ggB, c + 3);
	v_pk_fma_f32 v[96:97], v[110:111], v[118:119], v[96:97] op_sel_hi:[1,0,1]
	v_lshlrev_b32_e32 v110, 16, v61
	v_and_b32_e32 v111, 0xffff0000, v61
	v_pk_fma_f32 v[104:105], v[108:109], v[118:119], v[104:105] op_sel_hi:[1,0,1]
	v_lshlrev_b32_e32 v108, 16, v60
	v_and_b32_e32 v109, 0xffff0000, v60
	v_pk_mul_f32 v[96:97], v[96:97], v[110:111]
	v_pk_mul_f32 v[108:109], v[104:105], v[108:109]
	v_bfe_u32 v104, v97, 16, 1
	v_add3_u32 v97, v97, v104, s28
	v_bfe_u32 v104, v96, 16, 1
	v_add3_u32 v96, v96, v104, s28
	v_lshrrev_b32_e32 v96, 16, v96
	v_and_or_b32 v105, v97, s27, v96
	v_bfe_u32 v97, v108, 16, 1
	v_bfe_u32 v96, v109, 16, 1
	v_add3_u32 v97, v108, v97, s28
	v_add3_u32 v96, v109, v96, s28
	v_lshrrev_b32_e32 v97, 16, v97
	v_and_or_b32 v104, v96, s27, v97
	v_pk_mul_f32 v[96:97], v[106:107], v[126:127] op_sel_hi:[1,0]
	v_pk_mul_f32 v[106:107], v[128:129], v[126:127] op_sel_hi:[1,0]
	v_lshlrev_b32_e32 v128, 16, v75
	v_and_b32_e32 v129, 0xffff0000, v75
	v_lshlrev_b32_e32 v110, 16, v55
	v_and_b32_e32 v111, 0xffff0000, v55
	v_lshlrev_b32_e32 v127, 16, v74
	v_and_b32_e32 v130, 0xffff0000, v74
	v_lshlrev_b32_e32 v108, 16, v54
	v_and_b32_e32 v109, 0xffff0000, v54
	v_sub_f32_e32 v129, v129, v111
	v_sub_f32_e32 v128, v128, v110
	v_pk_fma_f32 v[96:97], v[10:11], v[96:97], v[26:27]
	v_sub_f32_e32 v131, v130, v109
	v_sub_f32_e32 v130, v127, v108
	v_pk_fma_f32 v[110:111], v[42:43], v[128:129], v[110:111]
	v_pk_fma_f32 v[106:107], v[8:9], v[106:107], v[24:25]
	v_pk_fma_f32 v[108:109], v[40:41], v[130:131], v[108:109]
	v_pk_fma_f32 v[96:97], v[110:111], v[118:119], v[96:97] op_sel_hi:[1,0,1]
	v_lshlrev_b32_e32 v110, 16, v63
	v_and_b32_e32 v111, 0xffff0000, v63
	v_pk_fma_f32 v[106:107], v[108:109], v[118:119], v[106:107] op_sel_hi:[1,0,1]
	v_lshlrev_b32_e32 v108, 16, v62
	v_and_b32_e32 v109, 0xffff0000, v62
	v_pk_mul_f32 v[96:97], v[96:97], v[110:111]
	v_pk_mul_f32 v[108:109], v[106:107], v[108:109]
	v_bfe_u32 v106, v97, 16, 1
	v_add3_u32 v97, v97, v106, s28
	v_bfe_u32 v106, v96, 16, 1
	v_add3_u32 v96, v96, v106, s28
	v_lshrrev_b32_e32 v96, 16, v96
	v_and_or_b32 v107, v97, s27, v96
	v_bfe_u32 v97, v108, 16, 1
	v_bfe_u32 v96, v109, 16, 1
	v_add3_u32 v97, v108, v97, s28
	v_add3_u32 v96, v109, v96, s28
	v_lshrrev_b32_e32 v97, 16, v97
	v_lshlrev_b32_e32 v110, 16, v69
	v_and_b32_e32 v111, 0xffff0000, v69
	v_lshlrev_b32_e32 v108, 16, v49
	v_and_b32_e32 v109, 0xffff0000, v49
	v_and_or_b32 v106, v96, s27, v97
	v_pk_mul_f32 v[96:97], v[102:103], v[126:127] op_sel_hi:[1,0]
	v_pk_mul_f32 v[100:101], v[100:101], v[126:127] op_sel_hi:[1,0]
	v_lshlrev_b32_e32 v127, 16, v68
	v_and_b32_e32 v128, 0xffff0000, v68
	v_lshlrev_b32_e32 v102, 16, v48
	v_and_b32_e32 v103, 0xffff0000, v48
	v_sub_f32_e32 v111, v111, v109
	v_sub_f32_e32 v110, v110, v108
	v_pk_fma_f32 v[96:97], v[6:7], v[96:97], v[22:23]
	v_sub_f32_e32 v129, v128, v103
	v_sub_f32_e32 v128, v127, v102
	v_pk_fma_f32 v[108:109], v[38:39], v[110:111], v[108:109]
	v_pk_fma_f32 v[100:101], v[4:5], v[100:101], v[20:21]
	v_pk_fma_f32 v[102:103], v[36:37], v[128:129], v[102:103]
	v_pk_fma_f32 v[96:97], v[108:109], v[118:119], v[96:97] op_sel_hi:[1,0,1]
	v_lshlrev_b32_e32 v108, 16, v57
	v_and_b32_e32 v109, 0xffff0000, v57
	v_pk_fma_f32 v[100:101], v[102:103], v[118:119], v[100:101] op_sel_hi:[1,0,1]
	v_lshlrev_b32_e32 v102, 16, v56
	v_and_b32_e32 v103, 0xffff0000, v56
	v_pk_mul_f32 v[96:97], v[96:97], v[108:109]
	v_pk_mul_f32 v[100:101], v[100:101], v[102:103]
	v_bfe_u32 v102, v97, 16, 1
	v_add3_u32 v97, v97, v102, s28
	v_bfe_u32 v102, v96, 16, 1
	v_add3_u32 v96, v96, v102, s28
	v_lshrrev_b32_e32 v96, 16, v96
	v_and_or_b32 v97, v97, s27, v96
	v_bfe_u32 v96, v101, 16, 1
	v_add3_u32 v96, v101, v96, s28
	v_bfe_u32 v101, v100, 16, 1
	v_add3_u32 v100, v100, v101, s28
	v_lshrrev_b32_e32 v100, 16, v100
	v_and_or_b32 v96, v96, s27, v100
	v_pk_mul_f32 v[100:101], v[136:137], v[126:127] op_sel_hi:[1,0]
	v_pk_mul_f32 v[98:99], v[98:99], v[126:127] op_sel_hi:[1,0]
	v_lshlrev_b32_e32 v110, 16, v70
	v_and_b32_e32 v111, 0xffff0000, v70
	v_lshlrev_b32_e32 v126, 16, v71
	v_and_b32_e32 v127, 0xffff0000, v71
	v_lshlrev_b32_e32 v102, 16, v50
	v_and_b32_e32 v103, 0xffff0000, v50
	v_lshlrev_b32_e32 v108, 16, v51
	v_and_b32_e32 v109, 0xffff0000, v51
	v_sub_f32_e32 v111, v111, v103
	v_sub_f32_e32 v110, v110, v102
	v_sub_f32_e32 v127, v127, v109
	v_sub_f32_e32 v126, v126, v108
	v_pk_fma_f32 v[98:99], v[2:3], v[98:99], v[18:19]
	v_pk_fma_f32 v[100:101], v[0:1], v[100:101], v[16:17]
	v_pk_fma_f32 v[108:109], v[34:35], v[126:127], v[108:109]
	v_pk_fma_f32 v[102:103], v[32:33], v[110:111], v[102:103]
	v_pk_fma_f32 v[98:99], v[108:109], v[118:119], v[98:99] op_sel_hi:[1,0,1]
	v_pk_fma_f32 v[100:101], v[102:103], v[118:119], v[100:101] op_sel_hi:[1,0,1]
	v_lshlrev_b32_e32 v102, 16, v58
	v_and_b32_e32 v103, 0xffff0000, v58
	v_lshlrev_b32_e32 v108, 16, v59
	v_and_b32_e32 v109, 0xffff0000, v59
	v_pk_mul_f32 v[108:109], v[98:99], v[108:109]
	v_pk_mul_f32 v[98:99], v[100:101], v[102:103]
	s_and_b64 vcc, exec, s[14:15]
	v_bfe_u32 v100, v99, 16, 1
	v_add3_u32 v99, v99, v100, s28
	v_bfe_u32 v100, v98, 16, 1
	v_add3_u32 v98, v98, v100, s28
	v_lshrrev_b32_e32 v98, 16, v98
	v_bfe_u32 v100, v108, 16, 1
	v_and_or_b32 v98, v99, s27, v98
	v_bfe_u32 v99, v109, 16, 1
	v_add3_u32 v100, v108, v100, s28
	v_add3_u32 v99, v109, v99, s28
	v_lshrrev_b32_e32 v100, 16, v100
	v_and_or_b32 v99, v99, s27, v100
	v_add_u32_e32 v100, s31, v112
	v_ashrrev_i32_e32 v101, 31, v100
	v_lshlrev_b64 v[100:101], 12, v[100:101]
	v_lshl_add_u64 v[100:101], v[116:117], 0, v[100:101]
	global_store_dwordx4 v[100:101], v[104:107], off sc1
	global_store_dwordx4 v[100:101], v[96:99], off offset:16 sc1
	s_cbranch_vccnz .LBB0_2159
	v_lshl_add_u32 v68, s30, 4, v120
	v_add_u32_e32 v48, s74, v68
	v_ashrrev_i32_e32 v49, 31, v48
	v_lshlrev_b64 v[56:57], 12, v[48:49]
	v_lshl_or_b32 v56, v119, 1, v56
	v_lshl_add_u64 v[96:97], s[2:3], 0, v[56:57]
	v_lshl_add_u64 v[60:61], s[18:19], 0, v[56:57]
	global_load_dwordx4 v[48:51], v[96:97], off offset:16
	global_load_dwordx4 v[52:55], v[96:97], off
	global_load_dwordx4 v[56:59], v[60:61], off offset:16
	s_nop 0
	global_load_dwordx4 v[60:63], v[60:61], off
	v_mov_b32_e32 v75, 0
	v_cmp_lt_i32_e32 vcc, 0, v68
	v_mov_b32_e32 v74, 0
	v_mov_b32_e32 v73, 0
	v_mov_b32_e32 v72, 0
	v_mov_b32_e32 v71, 0
	v_mov_b32_e32 v70, 0
	v_mov_b32_e32 v69, 0
	v_mov_b32_e32 v68, 0
	s_and_saveexec_b64 s[0:1], vcc
	s_cbranch_execz .LBB0_2158
	global_load_dwordx4 v[68:71], v[96:97], off offset:-4080
	global_load_dwordx4 v[72:75], v[96:97], off offset:-4096

.LBB0_2170:
	s_or_b64 exec, exec, s[0:1]
	s_waitcnt lgkmcnt(1)
	v_mov_b32_e32 v126, v108
	v_mov_b32_e32 v127, v100
	v_mov_b32_e32 v128, v109
	v_mov_b32_e32 v129, v101
	v_pk_add_f32 v[126:127], v[126:127], v[128:129]
	v_mov_b32_e32 v128, v110
	v_mov_b32_e32 v129, v102
	v_mov_b32_e32 v130, v111
	v_mov_b32_e32 v131, v103
	v_pk_add_f32 v[128:129], v[128:129], v[130:131]
	v_mov_b32_e32 v130, v105
	v_pk_add_f32 v[126:127], v[126:127], v[128:129]
	v_mov_b32_e32 v128, v104
	v_mov_b32_e32 v129, v96
	v_mov_b32_e32 v131, v97
	v_pk_add_f32 v[128:129], v[128:129], v[130:131]
	v_mov_b32_e32 v130, v106
	v_mov_b32_e32 v131, v98
	v_mov_b32_e32 v134, v107
	v_mov_b32_e32 v135, v99
	v_pk_add_f32 v[130:131], v[130:131], v[134:135]
	s_cmpk_gt_u32 s29, 0x1fc
	v_pk_add_f32 v[128:129], v[128:129], v[130:131]
	s_nop 0
	v_pk_add_f32 v[126:127], v[126:127], v[128:129]
	s_nop 0
	v_add_f32_e32 v126, v126, v127
	s_nop 1
	v_add_f32_dpp v126, v126, v126 quad_perm:[1,0,3,2] row_mask:0xf bank_mask:0xf bound_ctrl:1
	s_nop 1
	v_add_f32_dpp v133, v126, v126 quad_perm:[2,3,0,1] row_mask:0xf bank_mask:0xf bound_ctrl:1
	v_fmamk_f32 v109, v133, 0xbc800000, v109
	v_fmamk_f32 v108, v133, 0xbc800000, v108
	v_fmamk_f32 v111, v133, 0xbc800000, v111
	v_fmac_f32_e32 v110, 0xbc800000, v133
	v_pk_mul_f32 v[126:127], v[110:111], v[110:111]
	v_pk_mul_f32 v[128:129], v[108:109], v[108:109]
	v_fmamk_f32 v107, v133, 0xbc800000, v107
	v_pk_mov_b32 v[130:131], v[128:129], v[126:127] op_sel:[1,0]
	v_mov_b32_e32 v129, v127
	v_pk_add_f32 v[126:127], v[130:131], v[128:129]
	v_fmamk_f32 v129, v133, 0xbc800000, v105
	v_fmamk_f32 v128, v133, 0xbc800000, v104
	v_fmac_f32_e32 v106, 0xbc800000, v133
	v_pk_mul_f32 v[104:105], v[106:107], v[106:107]
	v_pk_mul_f32 v[130:131], v[128:129], v[128:129]
	v_fmamk_f32 v101, v133, 0xbc800000, v101
	v_pk_mov_b32 v[134:135], v[130:131], v[104:105] op_sel:[1,0]
	v_mov_b32_e32 v131, v105
	v_pk_add_f32 v[104:105], v[134:135], v[130:131]
	v_fmamk_f32 v100, v133, 0xbc800000, v100
	v_fmamk_f32 v103, v133, 0xbc800000, v103
	v_fmac_f32_e32 v102, 0xbc800000, v133
	v_fmamk_f32 v137, v133, 0xbc800000, v97
	v_fmamk_f32 v136, v133, 0xbc800000, v96
	v_fmamk_f32 v99, v133, 0xbc800000, v99
	v_fmac_f32_e32 v98, 0xbc800000, v133
	v_pk_add_f32 v[126:127], v[126:127], v[126:127] op_sel_hi:[0,1]
	v_pk_add_f32 v[104:105], v[104:105], v[104:105] op_sel_hi:[0,1]
	v_pk_mul_f32 v[130:131], v[102:103], v[102:103]
	v_pk_mul_f32 v[134:135], v[100:101], v[100:101]
	v_pk_mul_f32 v[96:97], v[98:99], v[98:99]
	v_pk_mul_f32 v[138:139], v[136:137], v[136:137]
	v_add_f32_e32 v135, v134, v135
	v_add_f32_e32 v131, v130, v131
	v_mov_b32_e32 v134, v138
	v_mov_b32_e32 v130, v139
	v_mov_b32_e32 v126, v96
	v_mov_b32_e32 v104, v97
	v_pk_add_f32 v[130:131], v[134:135], v[130:131]
	v_pk_add_f32 v[96:97], v[126:127], v[104:105]
	s_waitcnt vmcnt(2)
	v_and_b32_e32 v133, 0xffff0000, v92
	v_pk_add_f32 v[96:97], v[130:131], v[96:97]
	v_lshlrev_b32_e32 v130, 16, v93
	v_add_f32_e32 v96, v96, v97
	v_and_b32_e32 v131, 0xffff0000, v93
	s_nop 0
	v_add_f32_dpp v96, v96, v96 quad_perm:[1,0,3,2] row_mask:0xf bank_mask:0xf bound_ctrl:1
	s_nop 1
	v_add_f32_dpp v96, v96, v96 quad_perm:[2,3,0,1] row_mask:0xf bank_mask:0xf bound_ctrl:1
	v_fmamk_f32 v96, v96, 0x3c800000, v123
	v_mul_f32_e32 v97, 0x4f800000, v96
	v_cmp_gt_f32_e32 vcc, s26, v96
	s_nop 1
	v_cndmask_b32_e32 v96, v96, v97, vcc
	v_sqrt_f32_e32 v97, v96
	s_nop 0
	v_add_u32_e32 v104, -1, v97
	v_fma_f32 v105, -v104, v97, v96
	v_cmp_ge_f32_e64 s[0:1], 0, v105
	v_add_u32_e32 v105, 1, v97
	s_nop 0
	v_cndmask_b32_e64 v104, v97, v104, s[0:1]
	v_fma_f32 v97, -v105, v97, v96
	v_cmp_lt_f32_e64 s[0:1], 0, v97
	s_nop 1
	v_cndmask_b32_e64 v97, v104, v105, s[0:1]
	v_mul_f32_e32 v104, 0x37800000, v97
	v_cndmask_b32_e32 v97, v97, v104, vcc
	v_cmp_class_f32_e32 vcc, v96, v124
	s_nop 1
	v_cndmask_b32_e32 v96, v97, v96, vcc
	v_div_scale_f32 v97, s[0:1], v96, v96, 1.0
	v_rcp_f32_e32 v104, v97
	s_nop 0
	v_fma_f32 v105, -v97, v104, 1.0
	v_fmac_f32_e32 v104, v105, v104
	v_div_scale_f32 v105, vcc, 1.0, v96, 1.0
	v_mul_f32_e32 v126, v105, v104
	v_fma_f32 v127, -v97, v126, v105
	v_fmac_f32_e32 v126, v127, v104
	v_fma_f32 v97, -v97, v126, v105
	v_div_fmas_f32 v97, v97, v104, v126
	v_div_fixup_f32 v126, v97, v96, 1.0
	v_pk_mul_f32 v[96:97], v[110:111], v[126:127] op_sel_hi:[1,0]
	v_lshlrev_b32_e32 v110, 16, v81
	v_and_b32_e32 v111, 0xffff0000, v81
	v_pk_mul_f32 v[104:105], v[108:109], v[126:127] op_sel_hi:[1,0]
	v_lshlrev_b32_e32 v127, 16, v92
	v_lshlrev_b32_e32 v108, 16, v80
	v_and_b32_e32 v109, 0xffff0000, v80
	v_sub_f32_e32 v131, v131, v111
	v_sub_f32_e32 v130, v130, v110
	v_pk_fma_f32 v[96:97], v[14:15], v[96:97], v[30:31]
	v_sub_f32_e32 v135, v133, v109
	v_sub_f32_e32 v134, v127, v108
	v_pk_fma_f32 v[110:111], v[46:47], v[130:131], v[110:111]
	v_pk_fma_f32 v[104:105], v[12:13], v[104:105], v[28:29]
	v_pk_fma_f32 v[108:109], v[44:45], v[134:135], v[108:109]
	s_waitcnt lgkmcnt(0)
; DI void chunk_scan(const float* const* in, unsigned char* ws, float* y, LAS unsigned char* lds, LAS unsigned* ctr  , int b, int hd, int wave) {
;     ...
;         GN_ISSUE(vcA, vpA, ggA, 0); GN_ISSUE(vcB, vpB, ggB, 1);
;         for (int c = 0; c < CS_NCHUNK; c += 2) {
;             GN_CHUNK(vcA, vpA, ggA, c);     if (c + 2 < CS_NCHUNK) GN_ISSUE(vcA, vpA, ggA, c + 2);
;             GN_CHUNK(vcB, vpB, ggB, c + 1); if (c + 3 < CS_NCHUNK) GN_ISSUE(vcB, vpB, ggB, c + 3);
	v_pk_fma_f32 v[96:97], v[110:111], v[118:119], v[96:97] op_sel_hi:[1,0,1]
	v_lshlrev_b32_e32 v110, 16, v89
	v_and_b32_e32 v111, 0xffff0000, v89
	v_pk_fma_f32 v[104:105], v[108:109], v[118:119], v[104:105] op_sel_hi:[1,0,1]
	v_lshlrev_b32_e32 v108, 16, v88
	v_and_b32_e32 v109, 0xffff0000, v88
	v_pk_mul_f32 v[96:97], v[96:97], v[110:111]
	v_pk_mul_f32 v[108:109], v[104:105], v[108:109]
	v_bfe_u32 v104, v97, 16, 1
	v_add3_u32 v97, v97, v104, s28
	v_bfe_u32 v104, v96, 16, 1
	v_add3_u32 v96, v96, v104, s28
	v_lshrrev_b32_e32 v96, 16, v96
	v_and_or_b32 v105, v97, s27, v96
	v_bfe_u32 v97, v108, 16, 1
	v_bfe_u32 v96, v109, 16, 1
	v_add3_u32 v97, v108, v97, s28
	v_add3_u32 v96, v109, v96, s28
	v_lshrrev_b32_e32 v97, 16, v97
	v_and_or_b32 v104, v96, s27, v97
	v_pk_mul_f32 v[96:97], v[106:107], v[126:127] op_sel_hi:[1,0]
	v_pk_mul_f32 v[106:107], v[128:129], v[126:127] op_sel_hi:[1,0]
	v_lshlrev_b32_e32 v128, 16, v95
	v_and_b32_e32 v129, 0xffff0000, v95
	v_lshlrev_b32_e32 v110, 16, v83
	v_and_b32_e32 v111, 0xffff0000, v83
	v_lshlrev_b32_e32 v127, 16, v94
	v_and_b32_e32 v130, 0xffff0000, v94
	v_lshlrev_b32_e32 v108, 16, v82
	v_and_b32_e32 v109, 0xffff0000, v82
	v_sub_f32_e32 v129, v129, v111
	v_sub_f32_e32 v128, v128, v110
	v_pk_fma_f32 v[96:97], v[10:11], v[96:97], v[26:27]
	v_sub_f32_e32 v131, v130, v109
	v_sub_f32_e32 v130, v127, v108
	v_pk_fma_f32 v[110:111], v[42:43], v[128:129], v[110:111]
	v_pk_fma_f32 v[106:107], v[8:9], v[106:107], v[24:25]
	v_pk_fma_f32 v[108:109], v[40:41], v[130:131], v[108:109]
	v_pk_fma_f32 v[96:97], v[110:111], v[118:119], v[96:97] op_sel_hi:[1,0,1]
	v_lshlrev_b32_e32 v110, 16, v91
	v_and_b32_e32 v111, 0xffff0000, v91
	v_pk_fma_f32 v[106:107], v[108:109], v[118:119], v[106:107] op_sel_hi:[1,0,1]
	v_lshlrev_b32_e32 v108, 16, v90
	v_and_b32_e32 v109, 0xffff0000, v90
	v_pk_mul_f32 v[96:97], v[96:97], v[110:111]
	v_pk_mul_f32 v[108:109], v[106:107], v[108:109]
	v_bfe_u32 v106, v97, 16, 1
	v_add3_u32 v97, v97, v106, s28
	v_bfe_u32 v106, v96, 16, 1
	v_add3_u32 v96, v96, v106, s28
	v_lshrrev_b32_e32 v96, 16, v96
	v_and_or_b32 v107, v97, s27, v96
	v_bfe_u32 v97, v108, 16, 1
	v_bfe_u32 v96, v109, 16, 1
	v_add3_u32 v97, v108, v97, s28
	v_add3_u32 v96, v109, v96, s28
	v_lshrrev_b32_e32 v97, 16, v97
	v_lshlrev_b32_e32 v110, 16, v65
	v_and_b32_e32 v111, 0xffff0000, v65
	v_lshlrev_b32_e32 v108, 16, v77
	v_and_b32_e32 v109, 0xffff0000, v77
	v_and_or_b32 v106, v96, s27, v97
	v_pk_mul_f32 v[96:97], v[102:103], v[126:127] op_sel_hi:[1,0]
	v_pk_mul_f32 v[100:101], v[100:101], v[126:127] op_sel_hi:[1,0]
	v_lshlrev_b32_e32 v127, 16, v64
	v_and_b32_e32 v128, 0xffff0000, v64
	v_lshlrev_b32_e32 v102, 16, v76
	v_and_b32_e32 v103, 0xffff0000, v76
	v_sub_f32_e32 v111, v111, v109
	v_sub_f32_e32 v110, v110, v108
	v_pk_fma_f32 v[96:97], v[6:7], v[96:97], v[22:23]
	v_sub_f32_e32 v129, v128, v103
	v_sub_f32_e32 v128, v127, v102
	v_pk_fma_f32 v[108:109], v[38:39], v[110:111], v[108:109]
	v_pk_fma_f32 v[100:101], v[4:5], v[100:101], v[20:21]
	v_pk_fma_f32 v[102:103], v[36:37], v[128:129], v[102:103]
	v_pk_fma_f32 v[96:97], v[108:109], v[118:119], v[96:97] op_sel_hi:[1,0,1]
	v_lshlrev_b32_e32 v108, 16, v85
	v_and_b32_e32 v109, 0xffff0000, v85
	v_pk_fma_f32 v[100:101], v[102:103], v[118:119], v[100:101] op_sel_hi:[1,0,1]
	v_lshlrev_b32_e32 v102, 16, v84
	v_and_b32_e32 v103, 0xffff0000, v84
	v_pk_mul_f32 v[96:97], v[96:97], v[108:109]
	v_pk_mul_f32 v[100:101], v[100:101], v[102:103]
	v_bfe_u32 v102, v97, 16, 1
	v_add3_u32 v97, v97, v102, s28
	v_bfe_u32 v102, v96, 16, 1
	v_add3_u32 v96, v96, v102, s28
	v_lshrrev_b32_e32 v96, 16, v96
	v_and_or_b32 v97, v97, s27, v96
	v_bfe_u32 v96, v101, 16, 1
	v_add3_u32 v96, v101, v96, s28
	v_bfe_u32 v101, v100, 16, 1
	v_add3_u32 v100, v100, v101, s28
	v_lshrrev_b32_e32 v100, 16, v100
	v_and_or_b32 v96, v96, s27, v100
	v_pk_mul_f32 v[100:101], v[136:137], v[126:127] op_sel_hi:[1,0]
	v_pk_mul_f32 v[98:99], v[98:99], v[126:127] op_sel_hi:[1,0]
	v_lshlrev_b32_e32 v110, 16, v66
	v_and_b32_e32 v111, 0xffff0000, v66
	v_lshlrev_b32_e32 v126, 16, v67
	v_and_b32_e32 v127, 0xffff0000, v67
	v_lshlrev_b32_e32 v102, 16, v78
	v_and_b32_e32 v103, 0xffff0000, v78
	v_lshlrev_b32_e32 v108, 16, v79
	v_and_b32_e32 v109, 0xffff0000, v79
	v_sub_f32_e32 v111, v111, v103
	v_sub_f32_e32 v110, v110, v102
	v_sub_f32_e32 v127, v127, v109
	v_sub_f32_e32 v126, v126, v108
	v_pk_fma_f32 v[98:99], v[2:3], v[98:99], v[18:19]
	v_pk_fma_f32 v[100:101], v[0:1], v[100:101], v[16:17]
	v_pk_fma_f32 v[108:109], v[34:35], v[126:127], v[108:109]
	v_pk_fma_f32 v[102:103], v[32:33], v[110:111], v[102:103]
	v_pk_fma_f32 v[98:99], v[108:109], v[118:119], v[98:99] op_sel_hi:[1,0,1]
	v_pk_fma_f32 v[100:101], v[102:103], v[118:119], v[100:101] op_sel_hi:[1,0,1]
	v_lshlrev_b32_e32 v102, 16, v86
	v_and_b32_e32 v103, 0xffff0000, v86
	v_lshlrev_b32_e32 v108, 16, v87
	v_and_b32_e32 v109, 0xffff0000, v87
	v_pk_mul_f32 v[108:109], v[98:99], v[108:109]
	v_pk_mul_f32 v[98:99], v[100:101], v[102:103]
	s_nop 0
	v_bfe_u32 v100, v99, 16, 1
	v_add3_u32 v99, v99, v100, s28
	v_bfe_u32 v100, v98, 16, 1
	v_add3_u32 v98, v98, v100, s28
	v_lshrrev_b32_e32 v98, 16, v98
	v_bfe_u32 v100, v108, 16, 1
	v_and_or_b32 v98, v99, s27, v98
	v_bfe_u32 v99, v109, 16, 1
	v_add3_u32 v100, v108, v100, s28
	v_add3_u32 v99, v109, v99, s28
	v_lshrrev_b32_e32 v100, 16, v100
	v_and_or_b32 v99, v99, s27, v100
	v_add_u32_e32 v100, s31, v114
	v_ashrrev_i32_e32 v101, 31, v100
	v_lshlrev_b64 v[100:101], 12, v[100:101]
	v_lshl_add_u64 v[100:101], v[116:117], 0, v[100:101]
	global_store_dwordx4 v[100:101], v[104:107], off sc1
	global_store_dwordx4 v[100:101], v[96:99], off offset:16 sc1
	s_cbranch_scc1 .LBB0_2143
	v_add_u32_e32 v66, s31, v121
	v_add_u32_e32 v64, s74, v66
	v_ashrrev_i32_e32 v65, 31, v64
	v_lshlrev_b64 v[64:65], 12, v[64:65]
	v_lshl_or_b32 v64, v119, 1, v64
	v_lshl_add_u64 v[96:97], s[2:3], 0, v[64:65]
	v_lshl_add_u64 v[64:65], s[18:19], 0, v[64:65]
	global_load_dwordx4 v[76:79], v[96:97], off offset:16
	global_load_dwordx4 v[80:83], v[96:97], off
	global_load_dwordx4 v[84:87], v[64:65], off offset:16
	global_load_dwordx4 v[88:91], v[64:65], off
	v_mov_b32_e32 v95, 0
	v_cmp_lt_i32_e32 vcc, 0, v66
	v_mov_b32_e32 v94, 0
	v_mov_b32_e32 v93, 0
	v_mov_b32_e32 v92, 0
	v_mov_b32_e32 v67, 0
	v_mov_b32_e32 v66, 0
	v_mov_b32_e32 v65, 0
	v_mov_b32_e32 v64, 0
	s_and_saveexec_b64 s[0:1], vcc
	s_cbranch_execz .LBB0_2142
	global_load_dwordx4 v[64:67], v[96:97], off offset:-4080
	global_load_dwordx4 v[92:95], v[96:97], off offset:-4096
	s_branch .LBB0_2142

; DI v4u pack8(const f4& a, const f4& b) { v4u w; w.x = cvt_pk_bf16(a[0], a[1]); w.y = cvt_pk_bf16(a[2], a[3]); w.z = cvt_pk_bf16(b[0], b[1]); w.w = cvt_pk_bf16(b[2], b[3]); return w; }
; DI void unpack8(const v4u& w, f4& a, f4& b) { a[0] = bf_lo(w.x); a[1] = bf_hi(w.x); a[2] = bf_lo(w.y); a[3] = bf_hi(w.y); b[0] = bf_lo(w.z); b[1] = bf_hi(w.z); b[2] = bf_lo(w.w); b[3] = bf_hi(w.w); }
;     DI void operator()(f4 (&acc)[2][2][4][2], const Unit& u, int wr, int wc, int fr, int fq) const {
;     ...
;         const int which = u.pm >> 6, row0 = (u.pm & 63) * BM + wr * 64 + fr, col0 = (u.pn & 15) * BM + wc * 32 + 8 * fq;
;         const bf16* gsrc = gates + (which ? (size_t)M * D : (size_t)0);
; #pragma unroll
;         for (int ai = 0; ai < 2; ++ai) {
;             v4u gv[4][2];
; #pragma unroll
;             for (int m = 0; m < 4; ++m)
; #pragma unroll
;                 for (int bj = 0; bj < 2; ++bj) gv[m][bj] = *(const v4u*)(gsrc + (size_t)(row0 + ai * HALF + m * 16) * D + col0 + bj * HALF);
;             asm volatile("" ::: "memory");
; #pragma unroll
;             for (int m = 0; m < 4; ++m) { const int row = row0 + ai * HALF + m * 16;
; #pragma unroll
;                 for (int bj = 0; bj < 2; ++bj) { f4 g0, g1; unpack8(gv[m][bj], g0, g1);
;                     if (which == 0) { acc[ai][bj][m][0] = acc[ai][bj][m][0] * g0; acc[ai][bj][m][1] = acc[ai][bj][m][1] * g1; }
;                     else *(v4u*)(mout + (size_t)row * D + col0 + bj * HALF) = pack8(acc[ai][bj][m][0] * g0, acc[ai][bj][m][1] * g1); } }
.LBB0_2607:
	s_lshl_b32 s7, s12, 8
	s_lshl_b32 s6, s6, 8
	s_and_b32 s7, s7, 0x3f00
	s_and_b32 s6, s6, 0xf00
	v_mbcnt_lo_u32_b32 v2, -1, 0
	v_mbcnt_hi_u32_b32 v2, -1, v2
	s_add_i32 s7, s7, s41
	s_or_b32 s6, s6, s42
	v_and_or_b32 v0, v2, 15, s7
	v_ashrrev_i32_e32 v2, 1, v2
	s_cmp_gt_u32 s12, 63
	v_and_b32_e32 v2, -8, v2
	s_cselect_b64 s[24:25], -1, 0
	s_cmp_lt_u32 s12, 64
	v_add_u32_e32 v2, s6, v2
	s_cselect_b64 s[6:7], -1, 0
	s_and_b64 vcc, s[6:7], exec
	s_cselect_b32 s6, 0, 0x8000000
	s_add_u32 s6, s39, s6
	s_addc_u32 s7, s40, 0
	v_ashrrev_i32_e32 v3, 31, v2
	v_lshl_add_u64 v[184:185], v[2:3], 1, s[6:7]
	v_lshlrev_b64 v[64:65], 13, v[0:1]
	v_lshl_add_u64 v[66:67], v[184:185], 0, v[64:65]
	global_load_dwordx4 v[60:63], v[66:67], off
	global_load_dwordx4 v[88:91], v[66:67], off offset:256
	v_or_b32_e32 v66, 16, v0
	v_mov_b32_e32 v67, v1
	v_lshlrev_b64 v[190:191], 13, v[66:67]
	v_lshl_add_u64 v[66:67], v[184:185], 0, v[190:191]
	global_load_dwordx4 v[84:87], v[66:67], off
	global_load_dwordx4 v[120:123], v[66:67], off offset:256
	v_or_b32_e32 v66, 32, v0
	v_mov_b32_e32 v67, v1
	v_lshlrev_b64 v[188:189], 13, v[66:67]
	v_lshl_add_u64 v[66:67], v[184:185], 0, v[188:189]
	global_load_dwordx4 v[116:119], v[66:67], off
	global_load_dwordx4 v[144:147], v[66:67], off offset:256
	v_or_b32_e32 v66, 48, v0
	v_mov_b32_e32 v67, v1
	v_lshlrev_b64 v[186:187], 13, v[66:67]
	v_lshl_add_u64 v[66:67], v[184:185], 0, v[186:187]
	global_load_dwordx4 v[140:143], v[66:67], off
	global_load_dwordx4 v[164:167], v[66:67], off offset:256
	v_lshl_add_u64 v[64:65], s[8:9], 0, v[64:65]
	v_lshl_add_u64 v[192:193], v[2:3], 1, v[64:65]
	s_waitcnt vmcnt(0)
	v_lshlrev_b32_e32 v64, 16, v60
	v_and_b32_e32 v65, 0xffff0000, v60
	v_lshlrev_b32_e32 v60, 16, v61
	v_and_b32_e32 v61, 0xffff0000, v61
	v_lshlrev_b32_e32 v196, 16, v62
	v_and_b32_e32 v197, 0xffff0000, v62
	v_lshlrev_b32_e32 v62, 16, v63
	v_and_b32_e32 v63, 0xffff0000, v63
	v_pk_mul_f32 v[66:67], v[82:83], v[60:61]
	v_pk_mul_f32 v[64:65], v[80:81], v[64:65]
	v_pk_mul_f32 v[62:63], v[78:79], v[62:63]
	v_pk_mul_f32 v[60:61], v[76:77], v[196:197]
	s_cbranch_vccnz .LBB0_2609
	v_cvt_pk_bf16_f32 v64, v64, v65
	v_cvt_pk_bf16_f32 v65, v66, v67
	v_cvt_pk_bf16_f32 v66, v60, v61
	v_cvt_pk_bf16_f32 v67, v62, v63
	global_store_dwordx4 v[192:193], v[64:67], off sc1
	v_mov_b64_e32 v[60:61], v[76:77]
	v_mov_b64_e32 v[62:63], v[78:79]
	v_mov_b64_e32 v[64:65], v[80:81]
	v_mov_b64_e32 v[66:67], v[82:83]
.LBB0_2609:
	v_lshlrev_b32_e32 v76, 16, v88
	v_and_b32_e32 v77, 0xffff0000, v88
	v_lshlrev_b32_e32 v78, 16, v89
	v_and_b32_e32 v79, 0xffff0000, v89
	v_lshlrev_b32_e32 v80, 16, v90
	v_and_b32_e32 v81, 0xffff0000, v90
	v_lshlrev_b32_e32 v82, 16, v91
	v_and_b32_e32 v83, 0xffff0000, v91
	v_cndmask_b32_e64 v88, 0, 1, s[24:25]
	v_pk_mul_f32 v[78:79], v[162:163], v[78:79]
	v_pk_mul_f32 v[76:77], v[160:161], v[76:77]
	v_pk_mul_f32 v[82:83], v[158:159], v[82:83]
	v_cmp_ne_u32_e64 s[6:7], 1, v88
	s_andn2_b64 vcc, exec, s[24:25]
	v_pk_mul_f32 v[80:81], v[156:157], v[80:81]
	s_cbranch_vccnz .LBB0_2611
	v_cvt_pk_bf16_f32 v76, v76, v77
	v_cvt_pk_bf16_f32 v77, v78, v79
	v_cvt_pk_bf16_f32 v78, v80, v81
	v_cvt_pk_bf16_f32 v79, v82, v83
	global_store_dwordx4 v[192:193], v[76:79], off offset:256 sc1
	v_mov_b64_e32 v[80:81], v[156:157]
	v_mov_b64_e32 v[82:83], v[158:159]
	v_mov_b64_e32 v[76:77], v[160:161]
	v_mov_b64_e32 v[78:79], v[162:163]
.LBB0_2611:
	v_lshlrev_b32_e32 v88, 16, v84
	v_and_b32_e32 v89, 0xffff0000, v84
	v_lshlrev_b32_e32 v84, 16, v85
	v_and_b32_e32 v85, 0xffff0000, v85
	v_lshlrev_b32_e32 v156, 16, v86
	v_and_b32_e32 v157, 0xffff0000, v86
	v_lshlrev_b32_e32 v90, 16, v87
	v_and_b32_e32 v91, 0xffff0000, v87
	v_pk_mul_f32 v[86:87], v[106:107], v[84:85]
	v_pk_mul_f32 v[84:85], v[104:105], v[88:89]
	v_pk_mul_f32 v[88:89], v[100:101], v[156:157]
	v_lshl_add_u64 v[156:157], s[8:9], 0, v[190:191]
	v_pk_mul_f32 v[90:91], v[102:103], v[90:91]
	s_and_b64 vcc, exec, s[6:7]
	v_lshl_add_u64 v[156:157], v[2:3], 1, v[156:157]
	s_cbranch_vccnz .LBB0_2613
	v_cvt_pk_bf16_f32 v84, v84, v85
	v_cvt_pk_bf16_f32 v85, v86, v87
	v_cvt_pk_bf16_f32 v86, v88, v89
	v_cvt_pk_bf16_f32 v87, v90, v91
	global_store_dwordx4 v[156:157], v[84:87], off sc1
	v_mov_b64_e32 v[88:89], v[100:101]
	v_mov_b64_e32 v[90:91], v[102:103]
	v_mov_b64_e32 v[84:85], v[104:105]
	v_mov_b64_e32 v[86:87], v[106:107]
.LBB0_2613:
	v_lshlrev_b32_e32 v100, 16, v120
	v_and_b32_e32 v101, 0xffff0000, v120
	v_lshlrev_b32_e32 v102, 16, v121
	v_and_b32_e32 v103, 0xffff0000, v121
	v_lshlrev_b32_e32 v104, 16, v122
	v_and_b32_e32 v105, 0xffff0000, v122
	v_lshlrev_b32_e32 v106, 16, v123
	v_and_b32_e32 v107, 0xffff0000, v123
	v_pk_mul_f32 v[102:103], v[154:155], v[102:103]
	v_pk_mul_f32 v[100:101], v[152:153], v[100:101]
	v_pk_mul_f32 v[106:107], v[150:151], v[106:107]
	s_and_b64 vcc, exec, s[6:7]
	v_pk_mul_f32 v[104:105], v[148:149], v[104:105]
	s_cbranch_vccnz .LBB0_2615
	v_cvt_pk_bf16_f32 v100, v100, v101
	v_cvt_pk_bf16_f32 v101, v102, v103
	v_cvt_pk_bf16_f32 v102, v104, v105
	v_cvt_pk_bf16_f32 v103, v106, v107
	global_store_dwordx4 v[156:157], v[100:103], off offset:256 sc1
	v_mov_b64_e32 v[104:105], v[148:149]
	v_mov_b64_e32 v[106:107], v[150:151]
	v_mov_b64_e32 v[100:101], v[152:153]
	v_mov_b64_e32 v[102:103], v[154:155]
; DI v4u pack8(const f4& a, const f4& b) { v4u w; w.x = cvt_pk_bf16(a[0], a[1]); w.y = cvt_pk_bf16(a[2], a[3]); w.z = cvt_pk_bf16(b[0], b[1]); w.w = cvt_pk_bf16(b[2], b[3]); return w; }
; DI void unpack8(const v4u& w, f4& a, f4& b) { a[0] = bf_lo(w.x); a[1] = bf_hi(w.x); a[2] = bf_lo(w.y); a[3] = bf_hi(w.y); b[0] = bf_lo(w.z); b[1] = bf_hi(w.z); b[2] = bf_lo(w.w); b[3] = bf_hi(w.w); }
;     DI void operator()(f4 (&acc)[2][2][4][2], const Unit& u, int wr, int wc, int fr, int fq) const {
;     ...
;         for (int ai = 0; ai < 2; ++ai) {
;             v4u gv[4][2];
; #pragma unroll
;             for (int m = 0; m < 4; ++m)
; #pragma unroll
;                 for (int bj = 0; bj < 2; ++bj) gv[m][bj] = *(const v4u*)(gsrc + (size_t)(row0 + ai * HALF + m * 16) * D + col0 + bj * HALF);
;             asm volatile("" ::: "memory");
; #pragma unroll
;             for (int m = 0; m < 4; ++m) { const int row = row0 + ai * HALF + m * 16;
; #pragma unroll
;                 for (int bj = 0; bj < 2; ++bj) { f4 g0, g1; unpack8(gv[m][bj], g0, g1);
;                     if (which == 0) { acc[ai][bj][m][0] = acc[ai][bj][m][0] * g0; acc[ai][bj][m][1] = acc[ai][bj][m][1] * g1; }
;                     else *(v4u*)(mout + (size_t)row * D + col0 + bj * HALF) = pack8(acc[ai][bj][m][0] * g0, acc[ai][bj][m][1] * g1); } }
;             asm volatile("" ::: "memory");
;         }
.LBB0_2615:
	v_lshlrev_b32_e32 v120, 16, v116
	v_and_b32_e32 v121, 0xffff0000, v116
	v_lshlrev_b32_e32 v116, 16, v117
	v_and_b32_e32 v117, 0xffff0000, v117
	v_lshlrev_b32_e32 v148, 16, v118
	v_and_b32_e32 v149, 0xffff0000, v118
	v_lshlrev_b32_e32 v122, 16, v119
	v_and_b32_e32 v123, 0xffff0000, v119
	v_pk_mul_f32 v[118:119], v[138:139], v[116:117]
	v_pk_mul_f32 v[116:117], v[136:137], v[120:121]
	v_pk_mul_f32 v[120:121], v[132:133], v[148:149]
	v_lshl_add_u64 v[148:149], s[8:9], 0, v[188:189]
	v_pk_mul_f32 v[122:123], v[134:135], v[122:123]
	s_and_b64 vcc, exec, s[6:7]
	v_lshl_add_u64 v[148:149], v[2:3], 1, v[148:149]
	s_cbranch_vccnz .LBB0_2617
	v_cvt_pk_bf16_f32 v116, v116, v117
	v_cvt_pk_bf16_f32 v117, v118, v119
	v_cvt_pk_bf16_f32 v118, v120, v121
	v_cvt_pk_bf16_f32 v119, v122, v123
	global_store_dwordx4 v[148:149], v[116:119], off sc1
	v_mov_b64_e32 v[120:121], v[132:133]
	v_mov_b64_e32 v[122:123], v[134:135]
	v_mov_b64_e32 v[116:117], v[136:137]
	v_mov_b64_e32 v[118:119], v[138:139]
.LBB0_2617:
	v_lshlrev_b32_e32 v132, 16, v144
	v_and_b32_e32 v133, 0xffff0000, v144
	v_lshlrev_b32_e32 v134, 16, v145
	v_and_b32_e32 v135, 0xffff0000, v145
	v_lshlrev_b32_e32 v136, 16, v146
	v_and_b32_e32 v137, 0xffff0000, v146
	v_lshlrev_b32_e32 v138, 16, v147
	v_and_b32_e32 v139, 0xffff0000, v147
	v_pk_mul_f32 v[134:135], v[130:131], v[134:135]
	v_pk_mul_f32 v[132:133], v[128:129], v[132:133]
	v_pk_mul_f32 v[138:139], v[126:127], v[138:139]
	s_and_b64 vcc, exec, s[6:7]
	v_pk_mul_f32 v[136:137], v[124:125], v[136:137]
	s_cbranch_vccnz .LBB0_2619
	v_cvt_pk_bf16_f32 v132, v132, v133
	v_cvt_pk_bf16_f32 v133, v134, v135
	v_cvt_pk_bf16_f32 v134, v136, v137
	v_cvt_pk_bf16_f32 v135, v138, v139
	global_store_dwordx4 v[148:149], v[132:135], off offset:256 sc1
	v_mov_b64_e32 v[138:139], v[126:127]
	v_mov_b64_e32 v[136:137], v[124:125]
	v_mov_b64_e32 v[134:135], v[130:131]
	v_mov_b64_e32 v[132:133], v[128:129]
.LBB0_2619:
	v_lshlrev_b32_e32 v124, 16, v140
	v_and_b32_e32 v125, 0xffff0000, v140
	v_lshlrev_b32_e32 v126, 16, v141
	v_and_b32_e32 v127, 0xffff0000, v141
	v_lshlrev_b32_e32 v128, 16, v142
	v_and_b32_e32 v129, 0xffff0000, v142
	v_lshlrev_b32_e32 v130, 16, v143
	v_and_b32_e32 v131, 0xffff0000, v143
	v_pk_mul_f32 v[140:141], v[112:113], v[124:125]
	v_lshl_add_u64 v[124:125], s[8:9], 0, v[186:187]
	v_pk_mul_f32 v[142:143], v[114:115], v[126:127]
	v_pk_mul_f32 v[146:147], v[110:111], v[130:131]
	v_pk_mul_f32 v[144:145], v[108:109], v[128:129]
	s_and_b64 vcc, exec, s[6:7]
	v_lshl_add_u64 v[124:125], v[2:3], 1, v[124:125]
	s_cbranch_vccnz .LBB0_2621
	v_cvt_pk_bf16_f32 v126, v140, v141
	v_cvt_pk_bf16_f32 v127, v142, v143
	v_cvt_pk_bf16_f32 v128, v144, v145
	v_cvt_pk_bf16_f32 v129, v146, v147
	v_mov_b64_e32 v[146:147], v[110:111]
	v_mov_b64_e32 v[142:143], v[114:115]
	v_mov_b64_e32 v[144:145], v[108:109]
	v_mov_b64_e32 v[140:141], v[112:113]
	global_store_dwordx4 v[124:125], v[126:129], off sc1
.LBB0_2621:
	v_lshlrev_b32_e32 v108, 16, v164
	v_and_b32_e32 v109, 0xffff0000, v164
	v_lshlrev_b32_e32 v110, 16, v165
	v_and_b32_e32 v111, 0xffff0000, v165
	v_lshlrev_b32_e32 v112, 16, v166
	v_and_b32_e32 v113, 0xffff0000, v166
	v_lshlrev_b32_e32 v114, 16, v167
	v_and_b32_e32 v115, 0xffff0000, v167
	v_pk_mul_f32 v[110:111], v[98:99], v[110:111]
	v_pk_mul_f32 v[108:109], v[96:97], v[108:109]
	v_pk_mul_f32 v[114:115], v[94:95], v[114:115]
	s_and_b64 vcc, exec, s[6:7]
	v_pk_mul_f32 v[112:113], v[92:93], v[112:113]
	s_cbranch_vccnz .LBB0_2623
	v_cvt_pk_bf16_f32 v108, v108, v109
	v_cvt_pk_bf16_f32 v109, v110, v111
	v_cvt_pk_bf16_f32 v110, v112, v113
	v_cvt_pk_bf16_f32 v111, v114, v115
	global_store_dwordx4 v[124:125], v[108:111], off offset:256 sc1
	v_mov_b64_e32 v[114:115], v[94:95]
	v_mov_b64_e32 v[112:113], v[92:93]
	v_mov_b64_e32 v[110:111], v[98:99]
	v_mov_b64_e32 v[108:109], v[96:97]
.LBB0_2623:
	v_add_u32_e32 v92, 0x80, v0
	v_mov_b32_e32 v93, v1
	v_lshlrev_b64 v[96:97], 13, v[92:93]
	v_lshl_add_u64 v[98:99], v[184:185], 0, v[96:97]
	global_load_dwordx4 v[92:95], v[98:99], off
	global_load_dwordx4 v[128:131], v[98:99], off offset:256
	v_add_u32_e32 v98, 0x90, v0
	v_mov_b32_e32 v99, v1
	v_lshlrev_b64 v[190:191], 13, v[98:99]
	v_lshl_add_u64 v[98:99], v[184:185], 0, v[190:191]
	global_load_dwordx4 v[124:127], v[98:99], off
	global_load_dwordx4 v[156:159], v[98:99], off offset:256
	v_add_u32_e32 v98, 0xa0, v0
	v_mov_b32_e32 v99, v1
	v_lshlrev_b64 v[188:189], 13, v[98:99]
	v_add_u32_e32 v0, 0xb0, v0
	v_lshl_add_u64 v[98:99], v[184:185], 0, v[188:189]
	v_lshlrev_b64 v[186:187], 13, v[0:1]
	global_load_dwordx4 v[152:155], v[98:99], off
	global_load_dwordx4 v[164:167], v[98:99], off offset:256
	v_lshl_add_u64 v[98:99], v[184:185], 0, v[186:187]
	global_load_dwordx4 v[160:163], v[98:99], off
	global_load_dwordx4 v[148:151], v[98:99], off offset:256
	v_lshl_add_u64 v[184:185], s[8:9], 0, v[96:97]
	s_and_b64 vcc, exec, s[6:7]
	v_lshl_add_u64 v[184:185], v[2:3], 1, v[184:185]
	s_waitcnt vmcnt(7)
	v_lshlrev_b32_e32 v96, 16, v92
	v_and_b32_e32 v97, 0xffff0000, v92
	v_lshlrev_b32_e32 v92, 16, v93
	v_and_b32_e32 v93, 0xffff0000, v93
	v_lshlrev_b32_e32 v192, 16, v94
	v_and_b32_e32 v193, 0xffff0000, v94
	v_lshlrev_b32_e32 v94, 16, v95
	v_and_b32_e32 v95, 0xffff0000, v95
	v_pk_mul_f32 v[98:99], v[74:75], v[92:93]
	v_pk_mul_f32 v[96:97], v[72:73], v[96:97]
	v_pk_mul_f32 v[94:95], v[70:71], v[94:95]
	v_pk_mul_f32 v[92:93], v[68:69], v[192:193]
	s_cbranch_vccnz .LBB0_2625
	v_cvt_pk_bf16_f32 v96, v96, v97
	v_cvt_pk_bf16_f32 v97, v98, v99
	v_cvt_pk_bf16_f32 v98, v92, v93
	v_cvt_pk_bf16_f32 v99, v94, v95
	global_store_dwordx4 v[184:185], v[96:99], off sc1
	v_mov_b64_e32 v[94:95], v[70:71]
	v_mov_b64_e32 v[92:93], v[68:69]
	v_mov_b64_e32 v[98:99], v[74:75]
	v_mov_b64_e32 v[96:97], v[72:73]
; DI v4u pack8(const f4& a, const f4& b) { v4u w; w.x = cvt_pk_bf16(a[0], a[1]); w.y = cvt_pk_bf16(a[2], a[3]); w.z = cvt_pk_bf16(b[0], b[1]); w.w = cvt_pk_bf16(b[2], b[3]); return w; }
; DI void unpack8(const v4u& w, f4& a, f4& b) { a[0] = bf_lo(w.x); a[1] = bf_hi(w.x); a[2] = bf_lo(w.y); a[3] = bf_hi(w.y); b[0] = bf_lo(w.z); b[1] = bf_hi(w.z); b[2] = bf_lo(w.w); b[3] = bf_hi(w.w); }
;     DI void operator()(f4 (&acc)[2][2][4][2], const Unit& u, int wr, int wc, int fr, int fq) const {
;     ...
;         for (int ai = 0; ai < 2; ++ai) {
;             v4u gv[4][2];
; #pragma unroll
;             for (int m = 0; m < 4; ++m)
; #pragma unroll
;                 for (int bj = 0; bj < 2; ++bj) gv[m][bj] = *(const v4u*)(gsrc + (size_t)(row0 + ai * HALF + m * 16) * D + col0 + bj * HALF);
;             asm volatile("" ::: "memory");
; #pragma unroll
;             for (int m = 0; m < 4; ++m) { const int row = row0 + ai * HALF + m * 16;
; #pragma unroll
;                 for (int bj = 0; bj < 2; ++bj) { f4 g0, g1; unpack8(gv[m][bj], g0, g1);
;                     if (which == 0) { acc[ai][bj][m][0] = acc[ai][bj][m][0] * g0; acc[ai][bj][m][1] = acc[ai][bj][m][1] * g1; }
;                     else *(v4u*)(mout + (size_t)row * D + col0 + bj * HALF) = pack8(acc[ai][bj][m][0] * g0, acc[ai][bj][m][1] * g1); } }
;             asm volatile("" ::: "memory");
;         }
.LBB0_2625:
	s_waitcnt vmcnt(6)
	v_lshlrev_b32_e32 v68, 16, v128
	v_and_b32_e32 v69, 0xffff0000, v128
	v_lshlrev_b32_e32 v70, 16, v129
	v_and_b32_e32 v71, 0xffff0000, v129
	v_lshlrev_b32_e32 v72, 16, v130
	v_and_b32_e32 v73, 0xffff0000, v130
	v_lshlrev_b32_e32 v74, 16, v131
	v_and_b32_e32 v75, 0xffff0000, v131
	v_pk_mul_f32 v[70:71], v[58:59], v[70:71]
	v_pk_mul_f32 v[68:69], v[56:57], v[68:69]
	v_pk_mul_f32 v[74:75], v[54:55], v[74:75]
	s_and_b64 vcc, exec, s[6:7]
	v_pk_mul_f32 v[72:73], v[52:53], v[72:73]
	s_cbranch_vccnz .LBB0_2627
	v_cvt_pk_bf16_f32 v68, v68, v69
	v_cvt_pk_bf16_f32 v69, v70, v71
	v_cvt_pk_bf16_f32 v70, v72, v73
	v_cvt_pk_bf16_f32 v71, v74, v75
	global_store_dwordx4 v[184:185], v[68:71], off offset:256 sc1
	v_mov_b64_e32 v[74:75], v[54:55]
	v_mov_b64_e32 v[72:73], v[52:53]
	v_mov_b64_e32 v[70:71], v[58:59]
	v_mov_b64_e32 v[68:69], v[56:57]
.LBB0_2627:
	s_waitcnt vmcnt(5)
	v_lshlrev_b32_e32 v52, 16, v124
	v_and_b32_e32 v53, 0xffff0000, v124
	v_lshlrev_b32_e32 v54, 16, v125
	v_and_b32_e32 v55, 0xffff0000, v125
	v_lshlrev_b32_e32 v56, 16, v126
	v_and_b32_e32 v57, 0xffff0000, v126
	v_lshlrev_b32_e32 v58, 16, v127
	v_and_b32_e32 v59, 0xffff0000, v127
	v_pk_mul_f32 v[124:125], v[48:49], v[52:53]
	v_lshl_add_u64 v[52:53], s[8:9], 0, v[190:191]
	v_pk_mul_f32 v[126:127], v[50:51], v[54:55]
	v_pk_mul_f32 v[130:131], v[46:47], v[58:59]
	v_pk_mul_f32 v[128:129], v[44:45], v[56:57]
	s_and_b64 vcc, exec, s[6:7]
	v_lshl_add_u64 v[52:53], v[2:3], 1, v[52:53]
	s_cbranch_vccnz .LBB0_2629
	v_cvt_pk_bf16_f32 v54, v124, v125
	v_cvt_pk_bf16_f32 v55, v126, v127
	v_cvt_pk_bf16_f32 v56, v128, v129
	v_cvt_pk_bf16_f32 v57, v130, v131
	v_mov_b64_e32 v[130:131], v[46:47]
	v_mov_b64_e32 v[126:127], v[50:51]
	v_mov_b64_e32 v[128:129], v[44:45]
	v_mov_b64_e32 v[124:125], v[48:49]
	global_store_dwordx4 v[52:53], v[54:57], off sc1
.LBB0_2629:
	s_waitcnt vmcnt(4)
	v_lshlrev_b32_e32 v44, 16, v156
	v_and_b32_e32 v45, 0xffff0000, v156
	v_lshlrev_b32_e32 v46, 16, v157
	v_and_b32_e32 v47, 0xffff0000, v157
	v_lshlrev_b32_e32 v48, 16, v158
	v_and_b32_e32 v49, 0xffff0000, v158
	v_lshlrev_b32_e32 v50, 16, v159
	v_and_b32_e32 v51, 0xffff0000, v159
	v_pk_mul_f32 v[46:47], v[42:43], v[46:47]
	v_pk_mul_f32 v[44:45], v[40:41], v[44:45]
	v_pk_mul_f32 v[50:51], v[38:39], v[50:51]
	s_and_b64 vcc, exec, s[6:7]
	v_pk_mul_f32 v[48:49], v[36:37], v[48:49]
	s_cbranch_vccnz .LBB0_2631
	v_cvt_pk_bf16_f32 v44, v44, v45
	v_cvt_pk_bf16_f32 v45, v46, v47
	v_cvt_pk_bf16_f32 v46, v48, v49
	v_cvt_pk_bf16_f32 v47, v50, v51
	global_store_dwordx4 v[52:53], v[44:47], off offset:256 sc1
	v_mov_b64_e32 v[50:51], v[38:39]
	v_mov_b64_e32 v[48:49], v[36:37]
	v_mov_b64_e32 v[46:47], v[42:43]
	v_mov_b64_e32 v[44:45], v[40:41]
.LBB0_2631:
	s_waitcnt vmcnt(3)
	v_lshlrev_b32_e32 v36, 16, v152
	v_and_b32_e32 v37, 0xffff0000, v152
	v_lshlrev_b32_e32 v38, 16, v153
	v_and_b32_e32 v39, 0xffff0000, v153
	v_lshlrev_b32_e32 v40, 16, v154
	v_and_b32_e32 v41, 0xffff0000, v154
	v_lshlrev_b32_e32 v42, 16, v155
	v_and_b32_e32 v43, 0xffff0000, v155
	v_pk_mul_f32 v[152:153], v[32:33], v[36:37]
	v_lshl_add_u64 v[36:37], s[8:9], 0, v[188:189]
	v_pk_mul_f32 v[154:155], v[34:35], v[38:39]
	v_pk_mul_f32 v[158:159], v[30:31], v[42:43]
	v_pk_mul_f32 v[156:157], v[28:29], v[40:41]
	s_and_b64 vcc, exec, s[6:7]
	v_lshl_add_u64 v[36:37], v[2:3], 1, v[36:37]
	s_cbranch_vccnz .LBB0_2633
	v_cvt_pk_bf16_f32 v38, v152, v153
	v_cvt_pk_bf16_f32 v39, v154, v155
	v_cvt_pk_bf16_f32 v40, v156, v157
	v_cvt_pk_bf16_f32 v41, v158, v159
	v_mov_b64_e32 v[158:159], v[30:31]
	v_mov_b64_e32 v[154:155], v[34:35]
	v_mov_b64_e32 v[156:157], v[28:29]
	v_mov_b64_e32 v[152:153], v[32:33]
	global_store_dwordx4 v[36:37], v[38:41], off sc1
.LBB0_2633:
	s_waitcnt vmcnt(2)
	v_lshlrev_b32_e32 v28, 16, v164
	v_and_b32_e32 v29, 0xffff0000, v164
	v_lshlrev_b32_e32 v30, 16, v165
	v_and_b32_e32 v31, 0xffff0000, v165
	v_lshlrev_b32_e32 v32, 16, v166
	v_and_b32_e32 v33, 0xffff0000, v166
	v_lshlrev_b32_e32 v34, 16, v167
	v_and_b32_e32 v35, 0xffff0000, v167
	v_pk_mul_f32 v[30:31], v[26:27], v[30:31]
	v_pk_mul_f32 v[28:29], v[24:25], v[28:29]
	v_pk_mul_f32 v[34:35], v[22:23], v[34:35]
	s_and_b64 vcc, exec, s[6:7]
	v_pk_mul_f32 v[32:33], v[20:21], v[32:33]
	s_cbranch_vccnz .LBB0_2635
	v_cvt_pk_bf16_f32 v28, v28, v29
	v_cvt_pk_bf16_f32 v29, v30, v31
	v_cvt_pk_bf16_f32 v30, v32, v33
	v_cvt_pk_bf16_f32 v31, v34, v35
	global_store_dwordx4 v[36:37], v[28:31], off offset:256 sc1
	v_mov_b64_e32 v[34:35], v[22:23]
	v_mov_b64_e32 v[32:33], v[20:21]
	v_mov_b64_e32 v[30:31], v[26:27]
	v_mov_b64_e32 v[28:29], v[24:25]
.LBB0_2635:
	s_waitcnt vmcnt(1)
	v_lshlrev_b32_e32 v20, 16, v160
	v_and_b32_e32 v21, 0xffff0000, v160
	v_lshlrev_b32_e32 v22, 16, v161
	v_and_b32_e32 v23, 0xffff0000, v161
	v_lshlrev_b32_e32 v24, 16, v162
	v_and_b32_e32 v25, 0xffff0000, v162
	v_lshlrev_b32_e32 v26, 16, v163
	v_and_b32_e32 v27, 0xffff0000, v163
	v_pk_mul_f32 v[160:161], v[16:17], v[20:21]
	v_lshl_add_u64 v[20:21], s[8:9], 0, v[186:187]
	v_pk_mul_f32 v[162:163], v[18:19], v[22:23]
	v_pk_mul_f32 v[166:167], v[14:15], v[26:27]
	v_pk_mul_f32 v[164:165], v[12:13], v[24:25]
	s_and_b64 vcc, exec, s[6:7]
	v_lshl_add_u64 v[2:3], v[2:3], 1, v[20:21]
	s_cbranch_vccnz .LBB0_2637
	v_cvt_pk_bf16_f32 v20, v160, v161
	v_cvt_pk_bf16_f32 v21, v162, v163
	v_cvt_pk_bf16_f32 v22, v164, v165
	v_cvt_pk_bf16_f32 v23, v166, v167
	v_mov_b64_e32 v[166:167], v[14:15]
	v_mov_b64_e32 v[162:163], v[18:19]
	v_mov_b64_e32 v[164:165], v[12:13]
	v_mov_b64_e32 v[160:161], v[16:17]
	global_store_dwordx4 v[2:3], v[20:23], off sc1
.LBB0_2637:
	s_waitcnt vmcnt(0)
	v_lshlrev_b32_e32 v12, 16, v148
	v_and_b32_e32 v13, 0xffff0000, v148
	v_lshlrev_b32_e32 v14, 16, v149
	v_and_b32_e32 v15, 0xffff0000, v149
	v_lshlrev_b32_e32 v16, 16, v150
	v_and_b32_e32 v17, 0xffff0000, v150
	v_lshlrev_b32_e32 v18, 16, v151
	v_and_b32_e32 v19, 0xffff0000, v151
	v_pk_mul_f32 v[14:15], v[10:11], v[14:15]
	v_pk_mul_f32 v[12:13], v[8:9], v[12:13]
	v_pk_mul_f32 v[18:19], v[6:7], v[18:19]
	s_and_b64 vcc, exec, s[6:7]
	v_pk_mul_f32 v[16:17], v[4:5], v[16:17]
	s_cbranch_vccnz .LBB0_2639
	v_cvt_pk_bf16_f32 v12, v12, v13
	v_cvt_pk_bf16_f32 v13, v14, v15
	v_cvt_pk_bf16_f32 v14, v16, v17
	v_cvt_pk_bf16_f32 v15, v18, v19
	global_store_dwordx4 v[2:3], v[12:15], off offset:256 sc1
	v_mov_b64_e32 v[18:19], v[6:7]
	v_mov_b64_e32 v[16:17], v[4:5]
	v_mov_b64_e32 v[14:15], v[10:11]
	v_mov_b64_e32 v[12:13], v[8:9]

; DI v4u pack8(const f4& a, const f4& b) { v4u w; w.x = cvt_pk_bf16(a[0], a[1]); w.y = cvt_pk_bf16(a[2], a[3]); w.z = cvt_pk_bf16(b[0], b[1]); w.w = cvt_pk_bf16(b[2], b[3]); return w; }
; DI void unpack8(const v4u& w, f4& a, f4& b) { a[0] = bf_lo(w.x); a[1] = bf_hi(w.x); a[2] = bf_lo(w.y); a[3] = bf_hi(w.y); b[0] = bf_lo(w.z); b[1] = bf_hi(w.z); b[2] = bf_lo(w.w); b[3] = bf_hi(w.w); }
;     DI void operator()(f4 (&acc)[2][2][4][2], const Unit& u, int wr, int wc, int fr, int fq) const {
;     ...
;         const int row0 = u.pm * BM + wr * 64 + fr, col0 = u.pn * BM + wc * 32 + 8 * fq;
; #pragma unroll
;         for (int ai = 0; ai < 2; ++ai) {
;             f4 b0[4][2], b1[4][2];
;             if constexpr (SRCB) {
;                 v4u bb[4][2];
; #pragma unroll
;                 for (int m = 0; m < 4; ++m)
; #pragma unroll
;                     for (int bj = 0; bj < 2; ++bj) bb[m][bj] = *(const v4u*)(baseb + (size_t)(row0 + ai * HALF + m * 16) * D + col0 + bj * HALF);
;                 asm volatile("" ::: "memory");
; #pragma unroll
;                 for (int m = 0; m < 4; ++m)
; #pragma unroll
;                     for (int bj = 0; bj < 2; ++bj) unpack8(bb[m][bj], b0[m][bj], b1[m][bj]);
;             } else {
; #pragma unroll
;                 for (int m = 0; m < 4; ++m)
; #pragma unroll
;                     for (int bj = 0; bj < 2; ++bj) { const size_t off = (size_t)(row0 + ai * HALF + m * 16) * D + col0 + bj * HALF; b0[m][bj] = *(const f4*)(base + off); b1[m][bj] = *(const f4*)(base + off + 4); }
;                 asm volatile("" ::: "memory");
;             }
; #pragma unroll
;             for (int m = 0; m < 4; ++m) { const int row = row0 + ai * HALF + m * 16; float s = 0.f;
; #pragma unroll
;                 for (int bj = 0; bj < 2; ++bj) { const size_t off = (size_t)row * D + col0 + bj * HALF;
;                     const f4 h0 = b0[m][bj] + acc[ai][bj][m][0], h1 = b1[m][bj] + acc[ai][bj][m][1];
;                     *(v4u*)(outb + off) = pack8(h0, h1);
;                     s += (h0[0] * h0[0] + h0[1] * h0[1]) + (h0[2] * h0[2] + h0[3] * h0[3]) + (h1[0] * h1[0] + h1[1] * h1[1]) + (h1[2] * h1[2] + h1[3] * h1[3]); }
;                 s += __shfl_xor(s, 16); s += __shfl_xor(s, 32);
;                 if (fq == 0) atomicAdd(ss + row, s); }
.LBB0_2720:
	v_mbcnt_lo_u32_b32 v191, -1, 0
	v_mbcnt_hi_u32_b32 v191, -1, v191
	s_lshl_b32 s0, s0, 8
	v_ashrrev_i32_e32 v128, 1, v191
	s_lshl_b32 s1, s26, 8
	s_or_b32 s0, s0, s45
	v_and_b32_e32 v128, -8, v128
	s_add_i32 s1, s1, s44
	v_add_u32_e32 v168, s0, v128
	v_and_or_b32 v172, v191, 15, s1
	v_ashrrev_i32_e32 v169, 31, v168
	v_lshlrev_b64 v[200:201], 1, v[168:169]
	v_ashrrev_i32_e32 v173, 31, v172
	v_lshl_add_u64 v[170:171], s[6:7], 0, v[200:201]
	v_lshlrev_b64 v[202:203], 13, v[172:173]
	v_lshl_add_u64 v[128:129], v[170:171], 0, v[202:203]
	global_load_dwordx4 v[192:195], v[128:129], off
	global_load_dwordx4 v[196:199], v[128:129], off offset:256
	v_or_b32_e32 v182, 16, v172
	v_or_b32_e32 v178, 32, v172
	v_or_b32_e32 v174, 48, v172
	v_ashrrev_i32_e32 v183, 31, v182
	v_ashrrev_i32_e32 v179, 31, v178
	v_ashrrev_i32_e32 v175, 31, v174
	v_lshlrev_b64 v[184:185], 13, v[182:183]
	v_lshlrev_b64 v[180:181], 13, v[178:179]
	v_lshlrev_b64 v[176:177], 13, v[174:175]
	v_lshl_add_u64 v[128:129], v[170:171], 0, v[184:185]
	v_lshl_add_u64 v[130:131], v[170:171], 0, v[180:181]
	v_lshl_add_u64 v[204:205], v[170:171], 0, v[176:177]
	global_load_dwordx4 v[148:151], v[128:129], off
	global_load_dwordx4 v[144:147], v[128:129], off offset:256
	global_load_dwordx4 v[140:143], v[130:131], off
	global_load_dwordx4 v[136:139], v[130:131], off offset:256
	global_load_dwordx4 v[132:135], v[204:205], off
	s_nop 0
	global_load_dwordx4 v[128:131], v[204:205], off offset:256
	v_and_b32_e32 v205, 64, v190
	v_xor_b32_e32 v204, 16, v190
	v_add_u32_e32 v211, 64, v205
	v_lshl_add_u64 v[202:203], s[10:11], 0, v[202:203]
	v_cmp_lt_i32_e64 s[0:1], v204, v211
	v_lshl_add_u64 v[200:201], v[202:203], 0, v[200:201]
	v_cmp_gt_u32_e32 vcc, 16, v191
	v_cndmask_b32_e64 v191, v190, v204, s[0:1]
	v_lshlrev_b32_e32 v191, 2, v191
	v_xor_b32_e32 v210, 32, v190
	v_cmp_lt_i32_e64 s[0:1], v210, v211
	s_waitcnt vmcnt(0)
	v_lshlrev_b32_e32 v202, 16, v192
	v_and_b32_e32 v203, 0xffff0000, v192
	v_lshlrev_b32_e32 v192, 16, v193
	v_and_b32_e32 v193, 0xffff0000, v193
	v_lshlrev_b32_e32 v206, 16, v196
	v_and_b32_e32 v207, 0xffff0000, v196
	v_lshlrev_b32_e32 v196, 16, v197
	v_and_b32_e32 v197, 0xffff0000, v197
	v_lshlrev_b32_e32 v204, 16, v194
	v_and_b32_e32 v205, 0xffff0000, v194
	v_lshlrev_b32_e32 v194, 16, v195
	v_and_b32_e32 v195, 0xffff0000, v195
	v_lshlrev_b32_e32 v208, 16, v198
	v_and_b32_e32 v209, 0xffff0000, v198
	v_lshlrev_b32_e32 v198, 16, v199
	v_and_b32_e32 v199, 0xffff0000, v199
	v_pk_add_f32 v[126:127], v[126:127], v[192:193]
	v_pk_add_f32 v[124:125], v[124:125], v[202:203]
	v_pk_add_f32 v[118:119], v[118:119], v[196:197]
	v_pk_add_f32 v[116:117], v[116:117], v[206:207]
	v_pk_add_f32 v[122:123], v[122:123], v[194:195]
	v_pk_add_f32 v[120:121], v[120:121], v[204:205]
	v_pk_add_f32 v[192:193], v[114:115], v[198:199]
	v_pk_add_f32 v[194:195], v[112:113], v[208:209]
	v_mul_f32_e32 v114, v125, v125
	v_mul_f32_e32 v115, v127, v127
	v_mul_f32_e32 v196, v117, v117
	v_mul_f32_e32 v197, v119, v119
	v_cvt_pk_bf16_f32 v112, v124, v125
	v_mul_f32_e32 v125, v121, v121
	v_mul_f32_e32 v198, v195, v195
	v_fmac_f32_e32 v114, v124, v124
	v_fmac_f32_e32 v115, v126, v126
	v_fmac_f32_e32 v196, v116, v116
	v_fmac_f32_e32 v197, v118, v118
	v_cvt_pk_bf16_f32 v113, v126, v127
	v_mul_f32_e32 v127, v123, v123
	v_mul_f32_e32 v199, v193, v193
	v_fmac_f32_e32 v125, v120, v120
	v_fmac_f32_e32 v198, v194, v194
	v_add_f32_e32 v114, v114, v115
	v_add_f32_e32 v115, v196, v197
	v_fmac_f32_e32 v127, v122, v122
	v_fmac_f32_e32 v199, v192, v192
	v_add_f32_e32 v114, v125, v114
	v_add_f32_e32 v115, v198, v115
	v_add_f32_e32 v114, v127, v114
	v_add_f32_e32 v115, v199, v115
	v_add_f32_e32 v124, v114, v115
	ds_bpermute_b32 v125, v191, v124
	v_cvt_pk_bf16_f32 v114, v120, v121
	v_cvt_pk_bf16_f32 v115, v122, v123
	global_store_dwordx4 v[200:201], v[112:115], off sc1
	v_cvt_pk_bf16_f32 v116, v116, v117
	v_cvt_pk_bf16_f32 v117, v118, v119
	v_cvt_pk_bf16_f32 v118, v194, v195
	v_cvt_pk_bf16_f32 v119, v192, v193
	global_store_dwordx4 v[200:201], v[116:119], off offset:256 sc1
	s_nop 0
	v_cndmask_b32_e64 v112, v190, v210, s[0:1]
	s_waitcnt lgkmcnt(0)
	v_add_f32_e32 v113, v124, v125
	v_lshlrev_b32_e32 v112, 2, v112
	ds_bpermute_b32 v114, v112, v113
	s_and_saveexec_b64 s[0:1], vcc
	s_cbranch_execz .LBB0_2722
	v_lshl_add_u64 v[116:117], v[172:173], 2, s[12:13]
	s_waitcnt lgkmcnt(0)
	v_add_f32_e32 v113, v113, v114
	global_atomic_add_f32 v[116:117], v113, off
; DI v4u pack8(const f4& a, const f4& b) { v4u w; w.x = cvt_pk_bf16(a[0], a[1]); w.y = cvt_pk_bf16(a[2], a[3]); w.z = cvt_pk_bf16(b[0], b[1]); w.w = cvt_pk_bf16(b[2], b[3]); return w; }
;     DI void operator()(f4 (&acc)[2][2][4][2], const Unit& u, int wr, int wc, int fr, int fq) const {
;     ...
;             for (int m = 0; m < 4; ++m) { const int row = row0 + ai * HALF + m * 16; float s = 0.f;
; #pragma unroll
;                 for (int bj = 0; bj < 2; ++bj) { const size_t off = (size_t)row * D + col0 + bj * HALF;
;                     const f4 h0 = b0[m][bj] + acc[ai][bj][m][0], h1 = b1[m][bj] + acc[ai][bj][m][1];
;                     *(v4u*)(outb + off) = pack8(h0, h1);
;                     s += (h0[0] * h0[0] + h0[1] * h0[1]) + (h0[2] * h0[2] + h0[3] * h0[3]) + (h1[0] * h1[0] + h1[1] * h1[1]) + (h1[2] * h1[2] + h1[3] * h1[3]); }
;                 s += __shfl_xor(s, 16); s += __shfl_xor(s, 32);
;                 if (fq == 0) atomicAdd(ss + row, s); }
.LBB0_2722:
	s_or_b64 exec, exec, s[0:1]
	s_waitcnt lgkmcnt(0)
	v_lshlrev_b32_e32 v114, 16, v148
	v_and_b32_e32 v115, 0xffff0000, v148
	v_lshlrev_b32_e32 v116, 16, v149
	v_and_b32_e32 v117, 0xffff0000, v149
	v_lshlrev_b32_e32 v118, 16, v150
	v_and_b32_e32 v119, 0xffff0000, v150
	v_pk_add_f32 v[108:109], v[108:109], v[114:115]
	v_pk_add_f32 v[110:111], v[110:111], v[116:117]
	v_pk_add_f32 v[116:117], v[104:105], v[118:119]
	v_cvt_pk_bf16_f32 v104, v108, v109
	v_mul_f32_e32 v109, v109, v109
	v_fmac_f32_e32 v109, v108, v108
	v_mul_f32_e32 v108, v111, v111
	v_lshlrev_b32_e32 v122, 16, v144
	v_and_b32_e32 v123, 0xffff0000, v144
	v_lshlrev_b32_e32 v124, 16, v145
	v_and_b32_e32 v125, 0xffff0000, v145
	v_fmac_f32_e32 v108, v110, v110
	v_lshlrev_b32_e32 v120, 16, v151
	v_and_b32_e32 v121, 0xffff0000, v151
	v_lshlrev_b32_e32 v126, 16, v146
	v_and_b32_e32 v127, 0xffff0000, v146
	v_add_f32_e32 v108, v109, v108
	v_mul_f32_e32 v109, v117, v117
	v_pk_add_f32 v[102:103], v[102:103], v[124:125]
	v_pk_add_f32 v[100:101], v[100:101], v[122:123]
	v_pk_add_f32 v[114:115], v[106:107], v[120:121]
	v_cvt_pk_bf16_f32 v105, v110, v111
	v_fmac_f32_e32 v109, v116, v116
	v_pk_add_f32 v[110:111], v[96:97], v[126:127]
	v_mul_f32_e32 v96, v101, v101
	v_mul_f32_e32 v97, v103, v103
	v_add_f32_e32 v108, v109, v108
	v_mul_f32_e32 v109, v115, v115
	v_fmac_f32_e32 v96, v100, v100
	v_fmac_f32_e32 v97, v102, v102
	v_lshlrev_b32_e32 v144, 16, v147
	v_and_b32_e32 v145, 0xffff0000, v147
	v_fmac_f32_e32 v109, v114, v114
	v_add_f32_e32 v96, v96, v97
	v_mul_f32_e32 v97, v111, v111
	v_add_f32_e32 v113, v109, v108
	v_pk_add_f32 v[108:109], v[98:99], v[144:145]
	v_fmac_f32_e32 v97, v110, v110
	v_add_f32_e32 v96, v97, v96
	v_mul_f32_e32 v97, v109, v109
	v_fmac_f32_e32 v97, v108, v108
	v_add_f32_e32 v96, v97, v96
	v_add_f32_e32 v99, v113, v96
	ds_bpermute_b32 v113, v191, v99
	v_lshl_add_u64 v[96:97], s[10:11], 0, v[184:185]
	v_cvt_pk_bf16_f32 v106, v116, v117
	v_cvt_pk_bf16_f32 v107, v114, v115
	v_lshl_add_u64 v[114:115], v[168:169], 1, v[96:97]
	s_waitcnt lgkmcnt(0)
	v_add_f32_e32 v96, v99, v113
	ds_bpermute_b32 v97, v112, v96
	global_store_dwordx4 v[114:115], v[104:107], off sc1
	v_cvt_pk_bf16_f32 v98, v100, v101
	v_cvt_pk_bf16_f32 v99, v102, v103
	v_cvt_pk_bf16_f32 v100, v110, v111
	v_cvt_pk_bf16_f32 v101, v108, v109
	global_store_dwordx4 v[114:115], v[98:101], off offset:256 sc1
	s_and_saveexec_b64 s[0:1], vcc
	s_cbranch_execz .LBB0_2724
	v_lshl_add_u64 v[98:99], v[182:183], 2, s[12:13]
	s_waitcnt lgkmcnt(0)
	v_add_f32_e32 v96, v96, v97
	global_atomic_add_f32 v[98:99], v96, off
.LBB0_2724:
	s_or_b64 exec, exec, s[0:1]
	v_lshlrev_b32_e32 v96, 16, v140
	s_waitcnt lgkmcnt(0)
	v_and_b32_e32 v97, 0xffff0000, v140
	v_lshlrev_b32_e32 v98, 16, v141
	v_and_b32_e32 v99, 0xffff0000, v141
	v_lshlrev_b32_e32 v100, 16, v142
	v_and_b32_e32 v101, 0xffff0000, v142
	v_pk_add_f32 v[92:93], v[92:93], v[96:97]
	v_pk_add_f32 v[94:95], v[94:95], v[98:99]
	v_pk_add_f32 v[98:99], v[88:89], v[100:101]
	v_cvt_pk_bf16_f32 v88, v92, v93
	v_mul_f32_e32 v93, v93, v93
	v_fmac_f32_e32 v93, v92, v92
	v_mul_f32_e32 v92, v95, v95
	v_lshlrev_b32_e32 v104, 16, v136
	v_and_b32_e32 v105, 0xffff0000, v136
	v_lshlrev_b32_e32 v106, 16, v137
	v_and_b32_e32 v107, 0xffff0000, v137
	v_fmac_f32_e32 v92, v94, v94
	v_lshlrev_b32_e32 v102, 16, v143
	v_and_b32_e32 v103, 0xffff0000, v143
	v_lshlrev_b32_e32 v108, 16, v138
	v_and_b32_e32 v109, 0xffff0000, v138
	v_add_f32_e32 v92, v93, v92
	v_mul_f32_e32 v93, v99, v99
	v_pk_add_f32 v[86:87], v[86:87], v[106:107]
	v_pk_add_f32 v[84:85], v[84:85], v[104:105]
	v_pk_add_f32 v[96:97], v[90:91], v[102:103]
	v_cvt_pk_bf16_f32 v89, v94, v95
	v_fmac_f32_e32 v93, v98, v98
	v_pk_add_f32 v[94:95], v[80:81], v[108:109]
	v_mul_f32_e32 v80, v85, v85
	v_mul_f32_e32 v81, v87, v87
	v_add_f32_e32 v92, v93, v92
	v_mul_f32_e32 v93, v97, v97
	v_fmac_f32_e32 v80, v84, v84
	v_fmac_f32_e32 v81, v86, v86
	v_lshlrev_b32_e32 v110, 16, v139
	v_and_b32_e32 v111, 0xffff0000, v139
	v_fmac_f32_e32 v93, v96, v96
	v_add_f32_e32 v80, v80, v81
	v_mul_f32_e32 v81, v95, v95
	v_cvt_pk_bf16_f32 v90, v98, v99
	v_cvt_pk_bf16_f32 v91, v96, v97
	v_add_f32_e32 v96, v93, v92
	v_pk_add_f32 v[92:93], v[82:83], v[110:111]
	v_fmac_f32_e32 v81, v94, v94
	v_add_f32_e32 v80, v81, v80
	v_mul_f32_e32 v81, v93, v93
	v_fmac_f32_e32 v81, v92, v92
	v_add_f32_e32 v80, v81, v80
	v_add_f32_e32 v83, v96, v80
	ds_bpermute_b32 v98, v191, v83
	v_lshl_add_u64 v[80:81], s[10:11], 0, v[180:181]
	v_lshl_add_u64 v[96:97], v[168:169], 1, v[80:81]
	global_store_dwordx4 v[96:97], v[88:91], off sc1
	v_cvt_pk_bf16_f32 v82, v84, v85
	s_waitcnt lgkmcnt(0)
	v_add_f32_e32 v80, v83, v98
	ds_bpermute_b32 v81, v112, v80
	v_cvt_pk_bf16_f32 v83, v86, v87
	v_cvt_pk_bf16_f32 v84, v94, v95
	v_cvt_pk_bf16_f32 v85, v92, v93
	global_store_dwordx4 v[96:97], v[82:85], off offset:256 sc1
	s_and_saveexec_b64 s[0:1], vcc
	s_cbranch_execz .LBB0_2726
	v_lshl_add_u64 v[82:83], v[178:179], 2, s[12:13]
	s_waitcnt lgkmcnt(0)
	v_add_f32_e32 v80, v80, v81
	global_atomic_add_f32 v[82:83], v80, off
; DI v4u pack8(const f4& a, const f4& b) { v4u w; w.x = cvt_pk_bf16(a[0], a[1]); w.y = cvt_pk_bf16(a[2], a[3]); w.z = cvt_pk_bf16(b[0], b[1]); w.w = cvt_pk_bf16(b[2], b[3]); return w; }
;     DI void operator()(f4 (&acc)[2][2][4][2], const Unit& u, int wr, int wc, int fr, int fq) const {
;     ...
;         for (int ai = 0; ai < 2; ++ai) {
;             f4 b0[4][2], b1[4][2];
;             if constexpr (SRCB) {
;                 v4u bb[4][2];
; #pragma unroll
;                 for (int m = 0; m < 4; ++m)
; #pragma unroll
;                     for (int bj = 0; bj < 2; ++bj) bb[m][bj] = *(const v4u*)(baseb + (size_t)(row0 + ai * HALF + m * 16) * D + col0 + bj * HALF);
;     ...
;             for (int m = 0; m < 4; ++m) { const int row = row0 + ai * HALF + m * 16; float s = 0.f;
; #pragma unroll
;                 for (int bj = 0; bj < 2; ++bj) { const size_t off = (size_t)row * D + col0 + bj * HALF;
;                     const f4 h0 = b0[m][bj] + acc[ai][bj][m][0], h1 = b1[m][bj] + acc[ai][bj][m][1];
;                     *(v4u*)(outb + off) = pack8(h0, h1);
;                     s += (h0[0] * h0[0] + h0[1] * h0[1]) + (h0[2] * h0[2] + h0[3] * h0[3]) + (h1[0] * h1[0] + h1[1] * h1[1]) + (h1[2] * h1[2] + h1[3] * h1[3]); }
;                 s += __shfl_xor(s, 16); s += __shfl_xor(s, 32);
;                 if (fq == 0) atomicAdd(ss + row, s); }
.LBB0_2726:
	s_or_b64 exec, exec, s[0:1]
	v_lshlrev_b32_e32 v80, 16, v132
	s_waitcnt lgkmcnt(0)
	v_and_b32_e32 v81, 0xffff0000, v132
	v_lshlrev_b32_e32 v82, 16, v133
	v_and_b32_e32 v83, 0xffff0000, v133
	v_lshlrev_b32_e32 v84, 16, v134
	v_and_b32_e32 v85, 0xffff0000, v134
	v_pk_add_f32 v[76:77], v[76:77], v[80:81]
	v_pk_add_f32 v[78:79], v[78:79], v[82:83]
	v_pk_add_f32 v[82:83], v[72:73], v[84:85]
	v_cvt_pk_bf16_f32 v72, v76, v77
	v_mul_f32_e32 v77, v77, v77
	v_fmac_f32_e32 v77, v76, v76
	v_mul_f32_e32 v76, v79, v79
	v_lshlrev_b32_e32 v88, 16, v128
	v_and_b32_e32 v89, 0xffff0000, v128
	v_lshlrev_b32_e32 v90, 16, v129
	v_and_b32_e32 v91, 0xffff0000, v129
	v_fmac_f32_e32 v76, v78, v78
	v_lshlrev_b32_e32 v86, 16, v135
	v_and_b32_e32 v87, 0xffff0000, v135
	v_lshlrev_b32_e32 v92, 16, v130
	v_and_b32_e32 v93, 0xffff0000, v130
	v_add_f32_e32 v76, v77, v76
	v_mul_f32_e32 v77, v83, v83
	v_pk_add_f32 v[70:71], v[70:71], v[90:91]
	v_pk_add_f32 v[68:69], v[68:69], v[88:89]
	v_pk_add_f32 v[80:81], v[74:75], v[86:87]
	v_cvt_pk_bf16_f32 v73, v78, v79
	v_fmac_f32_e32 v77, v82, v82
	v_pk_add_f32 v[78:79], v[64:65], v[92:93]
	v_mul_f32_e32 v64, v69, v69
	v_mul_f32_e32 v65, v71, v71
	v_add_f32_e32 v76, v77, v76
	v_mul_f32_e32 v77, v81, v81
	v_fmac_f32_e32 v64, v68, v68
	v_fmac_f32_e32 v65, v70, v70
	v_lshlrev_b32_e32 v94, 16, v131
	v_and_b32_e32 v95, 0xffff0000, v131
	v_fmac_f32_e32 v77, v80, v80
	v_add_f32_e32 v64, v64, v65
	v_mul_f32_e32 v65, v79, v79
	v_cvt_pk_bf16_f32 v74, v82, v83
	v_cvt_pk_bf16_f32 v75, v80, v81
	v_add_f32_e32 v80, v77, v76
	v_pk_add_f32 v[76:77], v[66:67], v[94:95]
	v_fmac_f32_e32 v65, v78, v78
	v_add_f32_e32 v64, v65, v64
	v_mul_f32_e32 v65, v77, v77
	v_fmac_f32_e32 v65, v76, v76
	v_add_f32_e32 v64, v65, v64
	v_add_f32_e32 v67, v80, v64
	ds_bpermute_b32 v82, v191, v67
	v_lshl_add_u64 v[64:65], s[10:11], 0, v[176:177]
	v_lshl_add_u64 v[80:81], v[168:169], 1, v[64:65]
	global_store_dwordx4 v[80:81], v[72:75], off sc1
	v_cvt_pk_bf16_f32 v66, v68, v69
	s_waitcnt lgkmcnt(0)
	v_add_f32_e32 v64, v67, v82
	ds_bpermute_b32 v65, v112, v64
	v_cvt_pk_bf16_f32 v67, v70, v71
	v_cvt_pk_bf16_f32 v68, v78, v79
	v_cvt_pk_bf16_f32 v69, v76, v77
	global_store_dwordx4 v[80:81], v[66:69], off offset:256 sc1
	s_and_saveexec_b64 s[0:1], vcc
	s_cbranch_execz .LBB0_2728
	v_lshl_add_u64 v[66:67], v[174:175], 2, s[12:13]
	s_waitcnt lgkmcnt(0)
	v_add_f32_e32 v64, v64, v65
	global_atomic_add_f32 v[66:67], v64, off
.LBB0_2728:
	s_or_b64 exec, exec, s[0:1]
	v_add_u32_e32 v100, 0x80, v172
	v_ashrrev_i32_e32 v101, 31, v100
	v_lshlrev_b64 v[110:111], 13, v[100:101]
	s_waitcnt lgkmcnt(0)
	v_lshl_add_u64 v[64:65], v[170:171], 0, v[110:111]
	global_load_dwordx4 v[102:105], v[64:65], off
	global_load_dwordx4 v[106:109], v[64:65], off offset:256
	v_add_u32_e32 v96, 0x90, v172
	v_add_u32_e32 v92, 0xa0, v172
	v_add_u32_e32 v88, 0xb0, v172
	v_ashrrev_i32_e32 v97, 31, v96
	v_ashrrev_i32_e32 v93, 31, v92
	v_ashrrev_i32_e32 v89, 31, v88
	v_lshlrev_b64 v[98:99], 13, v[96:97]
	v_lshlrev_b64 v[94:95], 13, v[92:93]
	v_lshlrev_b64 v[90:91], 13, v[88:89]
	v_lshl_add_u64 v[64:65], v[170:171], 0, v[98:99]
	v_lshl_add_u64 v[66:67], v[170:171], 0, v[94:95]
	v_lshl_add_u64 v[114:115], v[170:171], 0, v[90:91]
	global_load_dwordx4 v[84:87], v[64:65], off
	global_load_dwordx4 v[80:83], v[64:65], off offset:256
	global_load_dwordx4 v[76:79], v[66:67], off
	global_load_dwordx4 v[72:75], v[66:67], off offset:256
	global_load_dwordx4 v[68:71], v[114:115], off
	s_nop 0
	global_load_dwordx4 v[64:67], v[114:115], off offset:256
	s_waitcnt vmcnt(7)
	v_lshlrev_b32_e32 v114, 16, v102
	v_and_b32_e32 v115, 0xffff0000, v102
	v_lshlrev_b32_e32 v102, 16, v103
	v_and_b32_e32 v103, 0xffff0000, v103
	s_waitcnt vmcnt(6)
	v_lshlrev_b32_e32 v118, 16, v106
	v_and_b32_e32 v119, 0xffff0000, v106
	v_lshlrev_b32_e32 v106, 16, v107
	v_and_b32_e32 v107, 0xffff0000, v107
	v_lshlrev_b32_e32 v116, 16, v104
	v_and_b32_e32 v117, 0xffff0000, v104
	v_lshlrev_b32_e32 v104, 16, v105
	v_and_b32_e32 v105, 0xffff0000, v105
	v_lshlrev_b32_e32 v120, 16, v108
	v_and_b32_e32 v121, 0xffff0000, v108
	v_pk_add_f32 v[62:63], v[62:63], v[102:103]
	v_pk_add_f32 v[60:61], v[60:61], v[114:115]
	v_pk_add_f32 v[54:55], v[54:55], v[106:107]
	v_pk_add_f32 v[52:53], v[52:53], v[118:119]
	v_lshlrev_b32_e32 v108, 16, v109
	v_and_b32_e32 v109, 0xffff0000, v109
	v_pk_add_f32 v[58:59], v[58:59], v[104:105]
	v_pk_add_f32 v[56:57], v[56:57], v[116:117]
	v_pk_add_f32 v[104:105], v[48:49], v[120:121]
	v_cvt_pk_bf16_f32 v48, v60, v61
	v_cvt_pk_bf16_f32 v49, v62, v63
	v_mul_f32_e32 v61, v61, v61
	v_mul_f32_e32 v63, v63, v63
	v_mul_f32_e32 v106, v53, v53
	v_mul_f32_e32 v107, v55, v55
	v_pk_add_f32 v[102:103], v[50:51], v[108:109]
	v_cvt_pk_bf16_f32 v50, v56, v57
	v_cvt_pk_bf16_f32 v51, v58, v59
	v_mul_f32_e32 v57, v57, v57
	v_mul_f32_e32 v59, v59, v59
	v_mul_f32_e32 v108, v105, v105
	v_fmac_f32_e32 v61, v60, v60
	v_fmac_f32_e32 v63, v62, v62
	v_fmac_f32_e32 v106, v52, v52
	v_fmac_f32_e32 v107, v54, v54
	v_mul_f32_e32 v109, v103, v103
	v_fmac_f32_e32 v57, v56, v56
	v_fmac_f32_e32 v59, v58, v58
	v_fmac_f32_e32 v108, v104, v104
	v_add_f32_e32 v56, v61, v63
	v_add_f32_e32 v58, v106, v107
	v_fmac_f32_e32 v109, v102, v102
	v_add_f32_e32 v56, v57, v56
	v_add_f32_e32 v57, v108, v58
	v_add_f32_e32 v56, v59, v56
	v_add_f32_e32 v57, v109, v57
	v_add_f32_e32 v58, v56, v57
	ds_bpermute_b32 v59, v191, v58
	v_lshl_add_u64 v[56:57], s[10:11], 0, v[110:111]
	v_lshl_add_u64 v[56:57], v[168:169], 1, v[56:57]
	global_store_dwordx4 v[56:57], v[48:51], off sc1
	s_waitcnt lgkmcnt(0)
	s_nop 0
	v_add_f32_e32 v48, v58, v59
	ds_bpermute_b32 v49, v112, v48
	v_cvt_pk_bf16_f32 v50, v52, v53
	v_cvt_pk_bf16_f32 v51, v54, v55
	v_cvt_pk_bf16_f32 v52, v104, v105
	v_cvt_pk_bf16_f32 v53, v102, v103
	global_store_dwordx4 v[56:57], v[50:53], off offset:256 sc1
	s_and_saveexec_b64 s[0:1], vcc
	s_cbranch_execz .LBB0_2730
	v_lshl_add_u64 v[50:51], v[100:101], 2, s[12:13]
	s_waitcnt lgkmcnt(0)
	v_add_f32_e32 v48, v48, v49
	global_atomic_add_f32 v[50:51], v48, off
; DI v4u pack8(const f4& a, const f4& b) { v4u w; w.x = cvt_pk_bf16(a[0], a[1]); w.y = cvt_pk_bf16(a[2], a[3]); w.z = cvt_pk_bf16(b[0], b[1]); w.w = cvt_pk_bf16(b[2], b[3]); return w; }
;     DI void operator()(f4 (&acc)[2][2][4][2], const Unit& u, int wr, int wc, int fr, int fq) const {
;     ...
;             for (int m = 0; m < 4; ++m) { const int row = row0 + ai * HALF + m * 16; float s = 0.f;
; #pragma unroll
;                 for (int bj = 0; bj < 2; ++bj) { const size_t off = (size_t)row * D + col0 + bj * HALF;
;                     const f4 h0 = b0[m][bj] + acc[ai][bj][m][0], h1 = b1[m][bj] + acc[ai][bj][m][1];
;                     *(v4u*)(outb + off) = pack8(h0, h1);
;                     s += (h0[0] * h0[0] + h0[1] * h0[1]) + (h0[2] * h0[2] + h0[3] * h0[3]) + (h1[0] * h1[0] + h1[1] * h1[1]) + (h1[2] * h1[2] + h1[3] * h1[3]); }
;                 s += __shfl_xor(s, 16); s += __shfl_xor(s, 32);
;                 if (fq == 0) atomicAdd(ss + row, s); }
.LBB0_2730:
	s_or_b64 exec, exec, s[0:1]
	s_waitcnt vmcnt(7)
	v_lshlrev_b32_e32 v48, 16, v84
	s_waitcnt lgkmcnt(0)
	v_and_b32_e32 v49, 0xffff0000, v84
	v_lshlrev_b32_e32 v50, 16, v85
	v_and_b32_e32 v51, 0xffff0000, v85
	v_lshlrev_b32_e32 v52, 16, v86
	v_and_b32_e32 v53, 0xffff0000, v86
	v_pk_add_f32 v[44:45], v[44:45], v[48:49]
	v_pk_add_f32 v[46:47], v[46:47], v[50:51]
	v_pk_add_f32 v[50:51], v[40:41], v[52:53]
	v_cvt_pk_bf16_f32 v40, v44, v45
	v_mul_f32_e32 v45, v45, v45
	v_fmac_f32_e32 v45, v44, v44
	v_mul_f32_e32 v44, v47, v47
	s_waitcnt vmcnt(6)
	v_lshlrev_b32_e32 v56, 16, v80
	v_and_b32_e32 v57, 0xffff0000, v80
	v_lshlrev_b32_e32 v58, 16, v81
	v_and_b32_e32 v59, 0xffff0000, v81
	v_fmac_f32_e32 v44, v46, v46
	v_lshlrev_b32_e32 v54, 16, v87
	v_and_b32_e32 v55, 0xffff0000, v87
	v_lshlrev_b32_e32 v60, 16, v82
	v_and_b32_e32 v61, 0xffff0000, v82
	v_add_f32_e32 v44, v45, v44
	v_mul_f32_e32 v45, v51, v51
	v_pk_add_f32 v[38:39], v[38:39], v[58:59]
	v_pk_add_f32 v[36:37], v[36:37], v[56:57]
	v_pk_add_f32 v[48:49], v[42:43], v[54:55]
	v_cvt_pk_bf16_f32 v41, v46, v47
	v_fmac_f32_e32 v45, v50, v50
	v_pk_add_f32 v[46:47], v[32:33], v[60:61]
	v_mul_f32_e32 v32, v37, v37
	v_mul_f32_e32 v33, v39, v39
	v_add_f32_e32 v44, v45, v44
	v_mul_f32_e32 v45, v49, v49
	v_fmac_f32_e32 v32, v36, v36
	v_fmac_f32_e32 v33, v38, v38
	v_lshlrev_b32_e32 v62, 16, v83
	v_and_b32_e32 v63, 0xffff0000, v83
	v_fmac_f32_e32 v45, v48, v48
	v_add_f32_e32 v32, v32, v33
	v_mul_f32_e32 v33, v47, v47
	v_cvt_pk_bf16_f32 v42, v50, v51
	v_cvt_pk_bf16_f32 v43, v48, v49
	v_add_f32_e32 v48, v45, v44
	v_pk_add_f32 v[44:45], v[34:35], v[62:63]
	v_fmac_f32_e32 v33, v46, v46
	v_add_f32_e32 v32, v33, v32
	v_mul_f32_e32 v33, v45, v45
	v_fmac_f32_e32 v33, v44, v44
	v_add_f32_e32 v32, v33, v32
	v_add_f32_e32 v35, v48, v32
	ds_bpermute_b32 v50, v191, v35
	v_lshl_add_u64 v[32:33], s[10:11], 0, v[98:99]
	v_lshl_add_u64 v[48:49], v[168:169], 1, v[32:33]
	global_store_dwordx4 v[48:49], v[40:43], off sc1
	v_cvt_pk_bf16_f32 v34, v36, v37
	s_waitcnt lgkmcnt(0)
	v_add_f32_e32 v32, v35, v50
	ds_bpermute_b32 v33, v112, v32
	v_cvt_pk_bf16_f32 v35, v38, v39
	v_cvt_pk_bf16_f32 v36, v46, v47
	v_cvt_pk_bf16_f32 v37, v44, v45
	global_store_dwordx4 v[48:49], v[34:37], off offset:256 sc1
	s_and_saveexec_b64 s[0:1], vcc
	s_cbranch_execz .LBB0_2732
	v_lshl_add_u64 v[34:35], v[96:97], 2, s[12:13]
	s_waitcnt lgkmcnt(0)
	v_add_f32_e32 v32, v32, v33
	global_atomic_add_f32 v[34:35], v32, off
; DI v4u pack8(const f4& a, const f4& b) { v4u w; w.x = cvt_pk_bf16(a[0], a[1]); w.y = cvt_pk_bf16(a[2], a[3]); w.z = cvt_pk_bf16(b[0], b[1]); w.w = cvt_pk_bf16(b[2], b[3]); return w; }
;     DI void operator()(f4 (&acc)[2][2][4][2], const Unit& u, int wr, int wc, int fr, int fq) const {
;     ...
;             for (int m = 0; m < 4; ++m) { const int row = row0 + ai * HALF + m * 16; float s = 0.f;
; #pragma unroll
;                 for (int bj = 0; bj < 2; ++bj) { const size_t off = (size_t)row * D + col0 + bj * HALF;
;                     const f4 h0 = b0[m][bj] + acc[ai][bj][m][0], h1 = b1[m][bj] + acc[ai][bj][m][1];
;                     *(v4u*)(outb + off) = pack8(h0, h1);
;                     s += (h0[0] * h0[0] + h0[1] * h0[1]) + (h0[2] * h0[2] + h0[3] * h0[3]) + (h1[0] * h1[0] + h1[1] * h1[1]) + (h1[2] * h1[2] + h1[3] * h1[3]); }
;                 s += __shfl_xor(s, 16); s += __shfl_xor(s, 32);
;                 if (fq == 0) atomicAdd(ss + row, s); }
;             asm volatile("" ::: "memory");
.LBB0_2732:
	s_or_b64 exec, exec, s[0:1]
	s_waitcnt vmcnt(7)
	v_lshlrev_b32_e32 v32, 16, v76
	s_waitcnt lgkmcnt(0)
	v_and_b32_e32 v33, 0xffff0000, v76
	v_lshlrev_b32_e32 v34, 16, v77
	v_and_b32_e32 v35, 0xffff0000, v77
	v_lshlrev_b32_e32 v36, 16, v78
	v_and_b32_e32 v37, 0xffff0000, v78
	v_pk_add_f32 v[28:29], v[28:29], v[32:33]
	v_pk_add_f32 v[30:31], v[30:31], v[34:35]
	v_pk_add_f32 v[34:35], v[24:25], v[36:37]
	v_cvt_pk_bf16_f32 v24, v28, v29
	v_mul_f32_e32 v29, v29, v29
	v_fmac_f32_e32 v29, v28, v28
	v_mul_f32_e32 v28, v31, v31
	s_waitcnt vmcnt(6)
	v_lshlrev_b32_e32 v40, 16, v72
	v_and_b32_e32 v41, 0xffff0000, v72
	v_lshlrev_b32_e32 v42, 16, v73
	v_and_b32_e32 v43, 0xffff0000, v73
	v_fmac_f32_e32 v28, v30, v30
	v_lshlrev_b32_e32 v38, 16, v79
	v_and_b32_e32 v39, 0xffff0000, v79
	v_lshlrev_b32_e32 v44, 16, v74
	v_and_b32_e32 v45, 0xffff0000, v74
	v_add_f32_e32 v28, v29, v28
	v_mul_f32_e32 v29, v35, v35
	v_pk_add_f32 v[22:23], v[22:23], v[42:43]
	v_pk_add_f32 v[20:21], v[20:21], v[40:41]
	v_pk_add_f32 v[32:33], v[26:27], v[38:39]
	v_cvt_pk_bf16_f32 v25, v30, v31
	v_fmac_f32_e32 v29, v34, v34
	v_pk_add_f32 v[30:31], v[16:17], v[44:45]
	v_mul_f32_e32 v16, v21, v21
	v_mul_f32_e32 v17, v23, v23
	v_add_f32_e32 v28, v29, v28
	v_mul_f32_e32 v29, v33, v33
	v_fmac_f32_e32 v16, v20, v20
	v_fmac_f32_e32 v17, v22, v22
	v_lshlrev_b32_e32 v46, 16, v75
	v_and_b32_e32 v47, 0xffff0000, v75
	v_fmac_f32_e32 v29, v32, v32
	v_add_f32_e32 v16, v16, v17
	v_mul_f32_e32 v17, v31, v31
	v_cvt_pk_bf16_f32 v26, v34, v35
	v_cvt_pk_bf16_f32 v27, v32, v33
	v_add_f32_e32 v32, v29, v28
	v_pk_add_f32 v[28:29], v[18:19], v[46:47]
	v_fmac_f32_e32 v17, v30, v30
	v_add_f32_e32 v16, v17, v16
	v_mul_f32_e32 v17, v29, v29
	v_fmac_f32_e32 v17, v28, v28
	v_add_f32_e32 v16, v17, v16
	v_add_f32_e32 v19, v32, v16
	ds_bpermute_b32 v34, v191, v19
	v_lshl_add_u64 v[16:17], s[10:11], 0, v[94:95]
	v_lshl_add_u64 v[32:33], v[168:169], 1, v[16:17]
	global_store_dwordx4 v[32:33], v[24:27], off sc1
	v_cvt_pk_bf16_f32 v18, v20, v21
	s_waitcnt lgkmcnt(0)
	v_add_f32_e32 v16, v19, v34
	ds_bpermute_b32 v17, v112, v16
	v_cvt_pk_bf16_f32 v19, v22, v23
	v_cvt_pk_bf16_f32 v20, v30, v31
	v_cvt_pk_bf16_f32 v21, v28, v29
	global_store_dwordx4 v[32:33], v[18:21], off offset:256 sc1
	s_and_saveexec_b64 s[0:1], vcc
	s_cbranch_execz .LBB0_2734
	v_lshl_add_u64 v[18:19], v[92:93], 2, s[12:13]
	s_waitcnt lgkmcnt(0)
	v_add_f32_e32 v16, v16, v17
	global_atomic_add_f32 v[18:19], v16, off
.LBB0_2734:
	s_or_b64 exec, exec, s[0:1]
	s_waitcnt vmcnt(7)
	v_lshlrev_b32_e32 v16, 16, v68
	s_waitcnt lgkmcnt(0)
	v_and_b32_e32 v17, 0xffff0000, v68
	v_lshlrev_b32_e32 v18, 16, v69
	v_and_b32_e32 v19, 0xffff0000, v69
	v_lshlrev_b32_e32 v20, 16, v70
	v_and_b32_e32 v21, 0xffff0000, v70
	v_pk_add_f32 v[12:13], v[12:13], v[16:17]
	v_pk_add_f32 v[14:15], v[14:15], v[18:19]
	v_pk_add_f32 v[18:19], v[8:9], v[20:21]
	v_cvt_pk_bf16_f32 v8, v12, v13
	v_mul_f32_e32 v13, v13, v13
	v_fmac_f32_e32 v13, v12, v12
	v_mul_f32_e32 v12, v15, v15
	s_waitcnt vmcnt(6)
	v_lshlrev_b32_e32 v24, 16, v64
	v_and_b32_e32 v25, 0xffff0000, v64
	v_lshlrev_b32_e32 v26, 16, v65
	v_and_b32_e32 v27, 0xffff0000, v65
	v_fmac_f32_e32 v12, v14, v14
	v_lshlrev_b32_e32 v22, 16, v71
	v_and_b32_e32 v23, 0xffff0000, v71
	v_lshlrev_b32_e32 v28, 16, v66
	v_and_b32_e32 v29, 0xffff0000, v66
	v_add_f32_e32 v12, v13, v12
	v_mul_f32_e32 v13, v19, v19
	v_pk_add_f32 v[6:7], v[6:7], v[26:27]
	v_pk_add_f32 v[4:5], v[4:5], v[24:25]
	v_pk_add_f32 v[16:17], v[10:11], v[22:23]
	v_cvt_pk_bf16_f32 v9, v14, v15
	v_fmac_f32_e32 v13, v18, v18
	v_pk_add_f32 v[14:15], v[0:1], v[28:29]
	v_mul_f32_e32 v0, v5, v5
	v_mul_f32_e32 v1, v7, v7
	v_add_f32_e32 v12, v13, v12
	v_mul_f32_e32 v13, v17, v17
	v_fmac_f32_e32 v0, v4, v4
	v_fmac_f32_e32 v1, v6, v6
	v_lshlrev_b32_e32 v30, 16, v67
	v_and_b32_e32 v31, 0xffff0000, v67
	v_fmac_f32_e32 v13, v16, v16
	v_add_f32_e32 v0, v0, v1
	v_mul_f32_e32 v1, v15, v15
	v_cvt_pk_bf16_f32 v10, v18, v19
	v_cvt_pk_bf16_f32 v11, v16, v17
	v_add_f32_e32 v16, v13, v12
	v_pk_add_f32 v[12:13], v[2:3], v[30:31]
	v_fmac_f32_e32 v1, v14, v14
	v_add_f32_e32 v0, v1, v0
	v_mul_f32_e32 v1, v13, v13
	v_fmac_f32_e32 v1, v12, v12
	v_add_f32_e32 v0, v1, v0
	v_add_f32_e32 v3, v16, v0
	ds_bpermute_b32 v18, v191, v3
	v_lshl_add_u64 v[0:1], s[10:11], 0, v[90:91]
	v_lshl_add_u64 v[16:17], v[168:169], 1, v[0:1]
	global_store_dwordx4 v[16:17], v[8:11], off sc1
	v_cvt_pk_bf16_f32 v2, v4, v5
	s_waitcnt lgkmcnt(0)
	v_add_f32_e32 v0, v3, v18
	ds_bpermute_b32 v1, v112, v0
	v_cvt_pk_bf16_f32 v3, v6, v7
	v_cvt_pk_bf16_f32 v4, v14, v15
	v_cvt_pk_bf16_f32 v5, v12, v13
	global_store_dwordx4 v[16:17], v[2:5], off offset:256 sc1
	s_and_saveexec_b64 s[0:1], vcc
	s_cbranch_execz .LBB0_2736
	v_lshl_add_u64 v[2:3], v[88:89], 2, s[12:13]
	s_waitcnt lgkmcnt(0)
	v_add_f32_e32 v0, v0, v1
	global_atomic_add_f32 v[2:3], v0, off

; DI float sigmoidf_(float z) { return 1.0f / (1.0f + __expf(-z)); }
; DI v4u pack8(const f4& a, const f4& b) { v4u w; w.x = cvt_pk_bf16(a[0], a[1]); w.y = cvt_pk_bf16(a[2], a[3]); w.z = cvt_pk_bf16(b[0], b[1]); w.w = cvt_pk_bf16(b[2], b[3]); return w; }
;     DI void operator()(f4 (&acc)[2][2][4][2], const Unit& u, int wr, int wc, int fr, int fq) const {
;     ...
;         const int row0 = u.pm * BM + wr * 64 + fr, col0 = u.pn * HALF + wc * 32 + 8 * fq;
;         float rr[2][4];
; #pragma unroll
;         for (int ai = 0; ai < 2; ++ai)
; #pragma unroll
;             for (int m = 0; m < 4; ++m) rr[ai][m] = ss[row0 + ai * HALF + m * 16];
; #pragma unroll
;         for (int ai = 0; ai < 2; ++ai)
; #pragma unroll
;             for (int m = 0; m < 4; ++m) { const int row = row0 + ai * HALF + m * 16; const float r = __builtin_amdgcn_rsqf(rr[ai][m] * (1.0f / D) + RMS_EPS);
;                 f4 o0, o1;
; #pragma unroll
;                 for (int e = 0; e < 4; ++e) { const float a0 = acc[ai][0][m][0][e] * r, a1 = acc[ai][0][m][1][e] * r;
;                     o0[e] = a0 * sigmoidf_(a0) * (acc[ai][1][m][0][e] * r); o1[e] = a1 * sigmoidf_(a1) * (acc[ai][1][m][1][e] * r); }
;                 *(v4u*)(uout + (size_t)row * DFF + col0) = pack8(o0, o1); }
.LBB0_2813:
	s_lshl_b32 s0, s0, 8
	s_add_i32 s0, s0, s36
	v_mbcnt_lo_u32_b32 v144, -1, 0
	v_mbcnt_hi_u32_b32 v144, -1, v144
	v_and_or_b32 v148, v144, 15, s0
	v_ashrrev_i32_e32 v149, 31, v148
	v_lshl_add_u64 v[146:147], v[148:149], 2, s[10:11]
	global_load_dword v155, v[146:147], off
	global_load_dword v156, v[146:147], off offset:64
	global_load_dword v157, v[146:147], off offset:128
	global_load_dword v158, v[146:147], off offset:192
	global_load_dword v159, v[146:147], off offset:512
	global_load_dword v160, v[146:147], off offset:576
	global_load_dword v161, v[146:147], off offset:640
	global_load_dword v162, v[146:147], off offset:704
	s_lshl_b32 s0, s1, 7
	s_or_b32 s0, s0, s37
	v_ashrrev_i32_e32 v145, 1, v144
	v_and_b32_e32 v145, -8, v145
	v_add_u32_e32 v164, s0, v145
	v_ashrrev_i32_e32 v165, 31, v164
	v_lshlrev_b64 v[164:165], 1, v[164:165]
	v_lshl_add_u64 v[164:165], v[164:165], 0, s[14:15]
	s_waitcnt vmcnt(0)
	v_fmamk_f32 v166, v155, 0x39800000, v154
	v_rsq_f32_e32 v167, v166
	v_pk_mul_f32 v[120:121], v[124:125], v[120:121]
	v_pk_mul_f32 v[122:123], v[126:127], v[122:123]
	v_pk_mul_f32 v[112:113], v[116:117], v[112:113]
	v_pk_mul_f32 v[114:115], v[118:119], v[114:115]
	v_mul_f32_e32 v168, 0xbfb8aa3b, v167
	v_mov_b32_e32 v149, v148
	v_pk_mul_f32 v[124:125], v[124:125], v[168:169] op_sel_hi:[1,0]
	v_pk_mul_f32 v[126:127], v[126:127], v[168:169] op_sel_hi:[1,0]
	v_pk_mul_f32 v[116:117], v[116:117], v[168:169] op_sel_hi:[1,0]
	v_pk_mul_f32 v[118:119], v[118:119], v[168:169] op_sel_hi:[1,0]
	v_exp_f32_e32 v124, v124
	v_exp_f32_e32 v125, v125
	v_exp_f32_e32 v126, v126
	v_exp_f32_e32 v127, v127
	v_exp_f32_e32 v116, v116
	v_exp_f32_e32 v117, v117
	v_exp_f32_e32 v118, v118
	v_exp_f32_e32 v119, v119
	v_mad_i64_i32 v[170:171], s[0:1], v149, s52, v[164:165]
	v_pk_fma_f32 v[124:125], v[124:125], v[166:167], v[166:167] op_sel_hi:[1,0,0]
	v_pk_fma_f32 v[126:127], v[126:127], v[166:167], v[166:167] op_sel_hi:[1,0,0]
	v_pk_fma_f32 v[116:117], v[116:117], v[166:167], v[166:167] op_sel_hi:[1,0,0]
	v_pk_fma_f32 v[118:119], v[118:119], v[166:167], v[166:167] op_sel_hi:[1,0,0]
	v_rcp_f32_e32 v124, v124
	v_rcp_f32_e32 v125, v125
	v_rcp_f32_e32 v126, v126
	v_rcp_f32_e32 v127, v127
	v_rcp_f32_e32 v116, v116
	v_rcp_f32_e32 v117, v117
	v_rcp_f32_e32 v118, v118
	v_rcp_f32_e32 v119, v119
	s_nop 0
	v_pk_mul_f32 v[120:121], v[120:121], v[124:125]
	v_pk_mul_f32 v[122:123], v[122:123], v[126:127]
	v_pk_mul_f32 v[112:113], v[112:113], v[116:117]
	v_pk_mul_f32 v[114:115], v[114:115], v[118:119]
	v_cvt_pk_bf16_f32 v124, v120, v121
	v_cvt_pk_bf16_f32 v125, v122, v123
	v_cvt_pk_bf16_f32 v126, v112, v113
	v_cvt_pk_bf16_f32 v127, v114, v115
	global_store_dwordx4 v[170:171], v[124:127], off sc1
	v_fmamk_f32 v166, v156, 0x39800000, v154
	v_rsq_f32_e32 v167, v166
	v_pk_mul_f32 v[104:105], v[108:109], v[104:105]
	v_pk_mul_f32 v[106:107], v[110:111], v[106:107]
	v_pk_mul_f32 v[96:97], v[100:101], v[96:97]
	v_pk_mul_f32 v[98:99], v[102:103], v[98:99]
	v_mul_f32_e32 v168, 0xbfb8aa3b, v167
	v_add_u32_e32 v149, 0x10, v148
	v_pk_mul_f32 v[108:109], v[108:109], v[168:169] op_sel_hi:[1,0]
	v_pk_mul_f32 v[110:111], v[110:111], v[168:169] op_sel_hi:[1,0]
	v_pk_mul_f32 v[100:101], v[100:101], v[168:169] op_sel_hi:[1,0]
	v_pk_mul_f32 v[102:103], v[102:103], v[168:169] op_sel_hi:[1,0]
	v_exp_f32_e32 v108, v108
	v_exp_f32_e32 v109, v109
	v_exp_f32_e32 v110, v110
	v_exp_f32_e32 v111, v111
	v_exp_f32_e32 v100, v100
	v_exp_f32_e32 v101, v101
	v_exp_f32_e32 v102, v102
	v_exp_f32_e32 v103, v103
	v_mad_i64_i32 v[170:171], s[0:1], v149, s52, v[164:165]
	v_pk_fma_f32 v[108:109], v[108:109], v[166:167], v[166:167] op_sel_hi:[1,0,0]
	v_pk_fma_f32 v[110:111], v[110:111], v[166:167], v[166:167] op_sel_hi:[1,0,0]
	v_pk_fma_f32 v[100:101], v[100:101], v[166:167], v[166:167] op_sel_hi:[1,0,0]
	v_pk_fma_f32 v[102:103], v[102:103], v[166:167], v[166:167] op_sel_hi:[1,0,0]
	v_rcp_f32_e32 v108, v108
	v_rcp_f32_e32 v109, v109
	v_rcp_f32_e32 v110, v110
	v_rcp_f32_e32 v111, v111
	v_rcp_f32_e32 v100, v100
	v_rcp_f32_e32 v101, v101
	v_rcp_f32_e32 v102, v102
	v_rcp_f32_e32 v103, v103
	s_nop 0
	v_pk_mul_f32 v[104:105], v[104:105], v[108:109]
	v_pk_mul_f32 v[106:107], v[106:107], v[110:111]
	v_pk_mul_f32 v[96:97], v[96:97], v[100:101]
	v_pk_mul_f32 v[98:99], v[98:99], v[102:103]
	v_cvt_pk_bf16_f32 v108, v104, v105
	v_cvt_pk_bf16_f32 v109, v106, v107
	v_cvt_pk_bf16_f32 v110, v96, v97
	v_cvt_pk_bf16_f32 v111, v98, v99
	global_store_dwordx4 v[170:171], v[108:111], off sc1
	v_fmamk_f32 v166, v157, 0x39800000, v154
	v_rsq_f32_e32 v167, v166
	v_pk_mul_f32 v[88:89], v[92:93], v[88:89]
	v_pk_mul_f32 v[90:91], v[94:95], v[90:91]
	v_pk_mul_f32 v[80:81], v[84:85], v[80:81]
	v_pk_mul_f32 v[82:83], v[86:87], v[82:83]
	v_mul_f32_e32 v168, 0xbfb8aa3b, v167
	v_add_u32_e32 v149, 0x20, v148
	v_pk_mul_f32 v[92:93], v[92:93], v[168:169] op_sel_hi:[1,0]
	v_pk_mul_f32 v[94:95], v[94:95], v[168:169] op_sel_hi:[1,0]
	v_pk_mul_f32 v[84:85], v[84:85], v[168:169] op_sel_hi:[1,0]
	v_pk_mul_f32 v[86:87], v[86:87], v[168:169] op_sel_hi:[1,0]
	v_exp_f32_e32 v92, v92
	v_exp_f32_e32 v93, v93
	v_exp_f32_e32 v94, v94
	v_exp_f32_e32 v95, v95
	v_exp_f32_e32 v84, v84
	v_exp_f32_e32 v85, v85
	v_exp_f32_e32 v86, v86
	v_exp_f32_e32 v87, v87
	v_mad_i64_i32 v[170:171], s[0:1], v149, s52, v[164:165]
	v_pk_fma_f32 v[92:93], v[92:93], v[166:167], v[166:167] op_sel_hi:[1,0,0]
	v_pk_fma_f32 v[94:95], v[94:95], v[166:167], v[166:167] op_sel_hi:[1,0,0]
	v_pk_fma_f32 v[84:85], v[84:85], v[166:167], v[166:167] op_sel_hi:[1,0,0]
	v_pk_fma_f32 v[86:87], v[86:87], v[166:167], v[166:167] op_sel_hi:[1,0,0]
	v_rcp_f32_e32 v92, v92
	v_rcp_f32_e32 v93, v93
; DI float sigmoidf_(float z) { return 1.0f / (1.0f + __expf(-z)); }
; DI v4u pack8(const f4& a, const f4& b) { v4u w; w.x = cvt_pk_bf16(a[0], a[1]); w.y = cvt_pk_bf16(a[2], a[3]); w.z = cvt_pk_bf16(b[0], b[1]); w.w = cvt_pk_bf16(b[2], b[3]); return w; }
;     DI void operator()(f4 (&acc)[2][2][4][2], const Unit& u, int wr, int wc, int fr, int fq) const {
;     ...
;         const int row0 = u.pm * BM + wr * 64 + fr, col0 = u.pn * HALF + wc * 32 + 8 * fq;
;         float rr[2][4];
; #pragma unroll
;         for (int ai = 0; ai < 2; ++ai)
; #pragma unroll
;             for (int m = 0; m < 4; ++m) rr[ai][m] = ss[row0 + ai * HALF + m * 16];
; #pragma unroll
;         for (int ai = 0; ai < 2; ++ai)
; #pragma unroll
;             for (int m = 0; m < 4; ++m) { const int row = row0 + ai * HALF + m * 16; const float r = __builtin_amdgcn_rsqf(rr[ai][m] * (1.0f / D) + RMS_EPS);
;                 f4 o0, o1;
; #pragma unroll
;                 for (int e = 0; e < 4; ++e) { const float a0 = acc[ai][0][m][0][e] * r, a1 = acc[ai][0][m][1][e] * r;
;                     o0[e] = a0 * sigmoidf_(a0) * (acc[ai][1][m][0][e] * r); o1[e] = a1 * sigmoidf_(a1) * (acc[ai][1][m][1][e] * r); }
;                 *(v4u*)(uout + (size_t)row * DFF + col0) = pack8(o0, o1); }
	v_rcp_f32_e32 v94, v94
	v_rcp_f32_e32 v95, v95
	v_rcp_f32_e32 v84, v84
	v_rcp_f32_e32 v85, v85
	v_rcp_f32_e32 v86, v86
	v_rcp_f32_e32 v87, v87
	s_nop 0
	v_pk_mul_f32 v[88:89], v[88:89], v[92:93]
	v_pk_mul_f32 v[90:91], v[90:91], v[94:95]
	v_pk_mul_f32 v[80:81], v[80:81], v[84:85]
	v_pk_mul_f32 v[82:83], v[82:83], v[86:87]
	v_cvt_pk_bf16_f32 v92, v88, v89
	v_cvt_pk_bf16_f32 v93, v90, v91
	v_cvt_pk_bf16_f32 v94, v80, v81
	v_cvt_pk_bf16_f32 v95, v82, v83
	global_store_dwordx4 v[170:171], v[92:95], off sc1
	v_fmamk_f32 v166, v158, 0x39800000, v154
	v_rsq_f32_e32 v167, v166
	v_pk_mul_f32 v[72:73], v[76:77], v[72:73]
	v_pk_mul_f32 v[74:75], v[78:79], v[74:75]
	v_pk_mul_f32 v[64:65], v[68:69], v[64:65]
	v_pk_mul_f32 v[66:67], v[70:71], v[66:67]
	v_mul_f32_e32 v168, 0xbfb8aa3b, v167
	v_add_u32_e32 v149, 0x30, v148
	v_pk_mul_f32 v[76:77], v[76:77], v[168:169] op_sel_hi:[1,0]
	v_pk_mul_f32 v[78:79], v[78:79], v[168:169] op_sel_hi:[1,0]
	v_pk_mul_f32 v[68:69], v[68:69], v[168:169] op_sel_hi:[1,0]
	v_pk_mul_f32 v[70:71], v[70:71], v[168:169] op_sel_hi:[1,0]
	v_exp_f32_e32 v76, v76
	v_exp_f32_e32 v77, v77
	v_exp_f32_e32 v78, v78
	v_exp_f32_e32 v79, v79
	v_exp_f32_e32 v68, v68
	v_exp_f32_e32 v69, v69
	v_exp_f32_e32 v70, v70
	v_exp_f32_e32 v71, v71
	v_mad_i64_i32 v[170:171], s[0:1], v149, s52, v[164:165]
	v_pk_fma_f32 v[76:77], v[76:77], v[166:167], v[166:167] op_sel_hi:[1,0,0]
	v_pk_fma_f32 v[78:79], v[78:79], v[166:167], v[166:167] op_sel_hi:[1,0,0]
	v_pk_fma_f32 v[68:69], v[68:69], v[166:167], v[166:167] op_sel_hi:[1,0,0]
	v_pk_fma_f32 v[70:71], v[70:71], v[166:167], v[166:167] op_sel_hi:[1,0,0]
	v_rcp_f32_e32 v76, v76
	v_rcp_f32_e32 v77, v77
	v_rcp_f32_e32 v78, v78
	v_rcp_f32_e32 v79, v79
	v_rcp_f32_e32 v68, v68
	v_rcp_f32_e32 v69, v69
	v_rcp_f32_e32 v70, v70
	v_rcp_f32_e32 v71, v71
	s_nop 0
	v_pk_mul_f32 v[72:73], v[72:73], v[76:77]
	v_pk_mul_f32 v[74:75], v[74:75], v[78:79]
	v_pk_mul_f32 v[64:65], v[64:65], v[68:69]
	v_pk_mul_f32 v[66:67], v[66:67], v[70:71]
	v_cvt_pk_bf16_f32 v76, v72, v73
	v_cvt_pk_bf16_f32 v77, v74, v75
	v_cvt_pk_bf16_f32 v78, v64, v65
	v_cvt_pk_bf16_f32 v79, v66, v67
	global_store_dwordx4 v[170:171], v[76:79], off sc1
	v_fmamk_f32 v166, v159, 0x39800000, v154
	v_rsq_f32_e32 v167, v166
	v_pk_mul_f32 v[56:57], v[60:61], v[56:57]
	v_pk_mul_f32 v[58:59], v[62:63], v[58:59]
	v_pk_mul_f32 v[48:49], v[52:53], v[48:49]
	v_pk_mul_f32 v[50:51], v[54:55], v[50:51]
	v_mul_f32_e32 v168, 0xbfb8aa3b, v167
	v_add_u32_e32 v149, 0x80, v148
	v_pk_mul_f32 v[60:61], v[60:61], v[168:169] op_sel_hi:[1,0]
	v_pk_mul_f32 v[62:63], v[62:63], v[168:169] op_sel_hi:[1,0]
	v_pk_mul_f32 v[52:53], v[52:53], v[168:169] op_sel_hi:[1,0]
	v_pk_mul_f32 v[54:55], v[54:55], v[168:169] op_sel_hi:[1,0]
	v_exp_f32_e32 v60, v60
	v_exp_f32_e32 v61, v61
	v_exp_f32_e32 v62, v62
	v_exp_f32_e32 v63, v63
	v_exp_f32_e32 v52, v52
	v_exp_f32_e32 v53, v53
	v_exp_f32_e32 v54, v54
	v_exp_f32_e32 v55, v55
	v_mad_i64_i32 v[170:171], s[0:1], v149, s52, v[164:165]
	v_pk_fma_f32 v[60:61], v[60:61], v[166:167], v[166:167] op_sel_hi:[1,0,0]
	v_pk_fma_f32 v[62:63], v[62:63], v[166:167], v[166:167] op_sel_hi:[1,0,0]
	v_pk_fma_f32 v[52:53], v[52:53], v[166:167], v[166:167] op_sel_hi:[1,0,0]
	v_pk_fma_f32 v[54:55], v[54:55], v[166:167], v[166:167] op_sel_hi:[1,0,0]
	v_rcp_f32_e32 v60, v60
	v_rcp_f32_e32 v61, v61
	v_rcp_f32_e32 v62, v62
	v_rcp_f32_e32 v63, v63
	v_rcp_f32_e32 v52, v52
	v_rcp_f32_e32 v53, v53
	v_rcp_f32_e32 v54, v54
	v_rcp_f32_e32 v55, v55
	s_nop 0
	v_pk_mul_f32 v[56:57], v[56:57], v[60:61]
	v_pk_mul_f32 v[58:59], v[58:59], v[62:63]
	v_pk_mul_f32 v[48:49], v[48:49], v[52:53]
	v_pk_mul_f32 v[50:51], v[50:51], v[54:55]
	v_cvt_pk_bf16_f32 v60, v56, v57
	v_cvt_pk_bf16_f32 v61, v58, v59
	v_cvt_pk_bf16_f32 v62, v48, v49
	v_cvt_pk_bf16_f32 v63, v50, v51
	global_store_dwordx4 v[170:171], v[60:63], off sc1
	v_fmamk_f32 v166, v160, 0x39800000, v154
	v_rsq_f32_e32 v167, v166
	v_pk_mul_f32 v[40:41], v[44:45], v[40:41]
	v_pk_mul_f32 v[42:43], v[46:47], v[42:43]
	v_pk_mul_f32 v[32:33], v[36:37], v[32:33]
	v_pk_mul_f32 v[34:35], v[38:39], v[34:35]
	v_mul_f32_e32 v168, 0xbfb8aa3b, v167
	v_add_u32_e32 v149, 0x90, v148
	v_pk_mul_f32 v[44:45], v[44:45], v[168:169] op_sel_hi:[1,0]
	v_pk_mul_f32 v[46:47], v[46:47], v[168:169] op_sel_hi:[1,0]
	v_pk_mul_f32 v[36:37], v[36:37], v[168:169] op_sel_hi:[1,0]
	v_pk_mul_f32 v[38:39], v[38:39], v[168:169] op_sel_hi:[1,0]
	v_exp_f32_e32 v44, v44
	v_exp_f32_e32 v45, v45
	v_exp_f32_e32 v46, v46
; DI float sigmoidf_(float z) { return 1.0f / (1.0f + __expf(-z)); }
; DI v4u pack8(const f4& a, const f4& b) { v4u w; w.x = cvt_pk_bf16(a[0], a[1]); w.y = cvt_pk_bf16(a[2], a[3]); w.z = cvt_pk_bf16(b[0], b[1]); w.w = cvt_pk_bf16(b[2], b[3]); return w; }
;     DI void operator()(f4 (&acc)[2][2][4][2], const Unit& u, int wr, int wc, int fr, int fq) const {
;     ...
;         const int row0 = u.pm * BM + wr * 64 + fr, col0 = u.pn * HALF + wc * 32 + 8 * fq;
;         float rr[2][4];
; #pragma unroll
;         for (int ai = 0; ai < 2; ++ai)
; #pragma unroll
;             for (int m = 0; m < 4; ++m) rr[ai][m] = ss[row0 + ai * HALF + m * 16];
; #pragma unroll
;         for (int ai = 0; ai < 2; ++ai)
; #pragma unroll
;             for (int m = 0; m < 4; ++m) { const int row = row0 + ai * HALF + m * 16; const float r = __builtin_amdgcn_rsqf(rr[ai][m] * (1.0f / D) + RMS_EPS);
;                 f4 o0, o1;
; #pragma unroll
;                 for (int e = 0; e < 4; ++e) { const float a0 = acc[ai][0][m][0][e] * r, a1 = acc[ai][0][m][1][e] * r;
;                     o0[e] = a0 * sigmoidf_(a0) * (acc[ai][1][m][0][e] * r); o1[e] = a1 * sigmoidf_(a1) * (acc[ai][1][m][1][e] * r); }
;                 *(v4u*)(uout + (size_t)row * DFF + col0) = pack8(o0, o1); }
;     }
	v_exp_f32_e32 v47, v47
	v_exp_f32_e32 v36, v36
	v_exp_f32_e32 v37, v37
	v_exp_f32_e32 v38, v38
	v_exp_f32_e32 v39, v39
	v_mad_i64_i32 v[170:171], s[0:1], v149, s52, v[164:165]
	v_pk_fma_f32 v[44:45], v[44:45], v[166:167], v[166:167] op_sel_hi:[1,0,0]
	v_pk_fma_f32 v[46:47], v[46:47], v[166:167], v[166:167] op_sel_hi:[1,0,0]
	v_pk_fma_f32 v[36:37], v[36:37], v[166:167], v[166:167] op_sel_hi:[1,0,0]
	v_pk_fma_f32 v[38:39], v[38:39], v[166:167], v[166:167] op_sel_hi:[1,0,0]
	v_rcp_f32_e32 v44, v44
	v_rcp_f32_e32 v45, v45
	v_rcp_f32_e32 v46, v46
	v_rcp_f32_e32 v47, v47
	v_rcp_f32_e32 v36, v36
	v_rcp_f32_e32 v37, v37
	v_rcp_f32_e32 v38, v38
	v_rcp_f32_e32 v39, v39
	s_nop 0
	v_pk_mul_f32 v[40:41], v[40:41], v[44:45]
	v_pk_mul_f32 v[42:43], v[42:43], v[46:47]
	v_pk_mul_f32 v[32:33], v[32:33], v[36:37]
	v_pk_mul_f32 v[34:35], v[34:35], v[38:39]
	v_cvt_pk_bf16_f32 v44, v40, v41
	v_cvt_pk_bf16_f32 v45, v42, v43
	v_cvt_pk_bf16_f32 v46, v32, v33
	v_cvt_pk_bf16_f32 v47, v34, v35
	global_store_dwordx4 v[170:171], v[44:47], off sc1
	v_fmamk_f32 v166, v161, 0x39800000, v154
	v_rsq_f32_e32 v167, v166
	v_pk_mul_f32 v[24:25], v[28:29], v[24:25]
	v_pk_mul_f32 v[26:27], v[30:31], v[26:27]
	v_pk_mul_f32 v[16:17], v[20:21], v[16:17]
	v_pk_mul_f32 v[18:19], v[22:23], v[18:19]
	v_mul_f32_e32 v168, 0xbfb8aa3b, v167
	v_add_u32_e32 v149, 0xa0, v148
	v_pk_mul_f32 v[28:29], v[28:29], v[168:169] op_sel_hi:[1,0]
	v_pk_mul_f32 v[30:31], v[30:31], v[168:169] op_sel_hi:[1,0]
	v_pk_mul_f32 v[20:21], v[20:21], v[168:169] op_sel_hi:[1,0]
	v_pk_mul_f32 v[22:23], v[22:23], v[168:169] op_sel_hi:[1,0]
	v_exp_f32_e32 v28, v28
	v_exp_f32_e32 v29, v29
	v_exp_f32_e32 v30, v30
	v_exp_f32_e32 v31, v31
	v_exp_f32_e32 v20, v20
	v_exp_f32_e32 v21, v21
	v_exp_f32_e32 v22, v22
	v_exp_f32_e32 v23, v23
	v_mad_i64_i32 v[170:171], s[0:1], v149, s52, v[164:165]
	v_pk_fma_f32 v[28:29], v[28:29], v[166:167], v[166:167] op_sel_hi:[1,0,0]
	v_pk_fma_f32 v[30:31], v[30:31], v[166:167], v[166:167] op_sel_hi:[1,0,0]
	v_pk_fma_f32 v[20:21], v[20:21], v[166:167], v[166:167] op_sel_hi:[1,0,0]
	v_pk_fma_f32 v[22:23], v[22:23], v[166:167], v[166:167] op_sel_hi:[1,0,0]
	v_rcp_f32_e32 v28, v28
	v_rcp_f32_e32 v29, v29
	v_rcp_f32_e32 v30, v30
	v_rcp_f32_e32 v31, v31
	v_rcp_f32_e32 v20, v20
	v_rcp_f32_e32 v21, v21
	v_rcp_f32_e32 v22, v22
	v_rcp_f32_e32 v23, v23
	s_nop 0
	v_pk_mul_f32 v[24:25], v[24:25], v[28:29]
	v_pk_mul_f32 v[26:27], v[26:27], v[30:31]
	v_pk_mul_f32 v[16:17], v[16:17], v[20:21]
	v_pk_mul_f32 v[18:19], v[18:19], v[22:23]
	v_cvt_pk_bf16_f32 v28, v24, v25
	v_cvt_pk_bf16_f32 v29, v26, v27
	v_cvt_pk_bf16_f32 v30, v16, v17
	v_cvt_pk_bf16_f32 v31, v18, v19
	global_store_dwordx4 v[170:171], v[28:31], off sc1
	v_fmamk_f32 v166, v162, 0x39800000, v154
	v_rsq_f32_e32 v167, v166
	v_pk_mul_f32 v[8:9], v[12:13], v[8:9]
	v_pk_mul_f32 v[10:11], v[14:15], v[10:11]
	v_pk_mul_f32 v[0:1], v[4:5], v[0:1]
	v_pk_mul_f32 v[2:3], v[6:7], v[2:3]
	v_mul_f32_e32 v168, 0xbfb8aa3b, v167
	v_add_u32_e32 v149, 0xb0, v148
	v_pk_mul_f32 v[12:13], v[12:13], v[168:169] op_sel_hi:[1,0]
	v_pk_mul_f32 v[14:15], v[14:15], v[168:169] op_sel_hi:[1,0]
	v_pk_mul_f32 v[4:5], v[4:5], v[168:169] op_sel_hi:[1,0]
	v_pk_mul_f32 v[6:7], v[6:7], v[168:169] op_sel_hi:[1,0]
	v_exp_f32_e32 v12, v12
	v_exp_f32_e32 v13, v13
	v_exp_f32_e32 v14, v14
	v_exp_f32_e32 v15, v15
	v_exp_f32_e32 v4, v4
	v_exp_f32_e32 v5, v5
	v_exp_f32_e32 v6, v6
	v_exp_f32_e32 v7, v7
	v_mad_i64_i32 v[170:171], s[0:1], v149, s52, v[164:165]
	v_pk_fma_f32 v[12:13], v[12:13], v[166:167], v[166:167] op_sel_hi:[1,0,0]
	v_pk_fma_f32 v[14:15], v[14:15], v[166:167], v[166:167] op_sel_hi:[1,0,0]
	v_pk_fma_f32 v[4:5], v[4:5], v[166:167], v[166:167] op_sel_hi:[1,0,0]
	v_pk_fma_f32 v[6:7], v[6:7], v[166:167], v[166:167] op_sel_hi:[1,0,0]
	v_rcp_f32_e32 v12, v12
	v_rcp_f32_e32 v13, v13
	v_rcp_f32_e32 v14, v14
	v_rcp_f32_e32 v15, v15
	v_rcp_f32_e32 v4, v4
	v_rcp_f32_e32 v5, v5
	v_rcp_f32_e32 v6, v6
	v_rcp_f32_e32 v7, v7
	s_nop 0
	v_pk_mul_f32 v[8:9], v[8:9], v[12:13]
	v_pk_mul_f32 v[10:11], v[10:11], v[14:15]
	v_pk_mul_f32 v[0:1], v[0:1], v[4:5]
	v_pk_mul_f32 v[2:3], v[2:3], v[6:7]
	s_andn2_b64 vcc, exec, s[4:5]
	s_mov_b64 s[0:1], -1
	v_cvt_pk_bf16_f32 v12, v8, v9
	v_cvt_pk_bf16_f32 v13, v10, v11
	v_cvt_pk_bf16_f32 v14, v0, v1
	v_cvt_pk_bf16_f32 v15, v2, v3
	global_store_dwordx4 v[170:171], v[12:15], off sc1
	s_cbranch_vccnz .LBB0_2802
	s_andn2_b64 vcc, exec, s[12:13]
	s_cbranch_vccnz .LBB0_2801
	s_barrier
	s_branch .LBB0_2801

; DI float sigmoidf_(float z) { return 1.0f / (1.0f + __expf(-z)); }
; DI v4u pack8(const f4& a, const f4& b) { v4u w; w.x = cvt_pk_bf16(a[0], a[1]); w.y = cvt_pk_bf16(a[2], a[3]); w.z = cvt_pk_bf16(b[0], b[1]); w.w = cvt_pk_bf16(b[2], b[3]); return w; }
;     DI void operator()(f4 (&acc)[2][2][4][2], const Unit& u, int wr, int wc, int fr, int fq) const {
;     ...
;         const int row0 = u.pm * BM + wr * 64 + fr, col0 = u.pn * HALF + wc * 32 + 8 * fq;
;         float rr[2][4];
; #pragma unroll
;         for (int ai = 0; ai < 2; ++ai)
; #pragma unroll
;             for (int m = 0; m < 4; ++m) rr[ai][m] = ss[row0 + ai * HALF + m * 16];
; #pragma unroll
;         for (int ai = 0; ai < 2; ++ai)
; #pragma unroll
;             for (int m = 0; m < 4; ++m) { const int row = row0 + ai * HALF + m * 16; const float r = __builtin_amdgcn_rsqf(rr[ai][m] * (1.0f / D) + RMS_EPS);
;                 f4 o0, o1;
; #pragma unroll
;                 for (int e = 0; e < 4; ++e) { const float a0 = acc[ai][0][m][0][e] * r, a1 = acc[ai][0][m][1][e] * r;
;                     o0[e] = a0 * sigmoidf_(a0) * (acc[ai][1][m][0][e] * r); o1[e] = a1 * sigmoidf_(a1) * (acc[ai][1][m][1][e] * r); }
;                 *(v4u*)(uout + (size_t)row * DFF + col0) = pack8(o0, o1); }
.LBB0_2829:
	s_lshl_b32 s0, s0, 8
	s_add_i32 s0, s0, s36
	v_mbcnt_lo_u32_b32 v144, -1, 0
	v_mbcnt_hi_u32_b32 v144, -1, v144
	v_and_or_b32 v148, v144, 15, s0
	v_ashrrev_i32_e32 v149, 31, v148
	v_lshl_add_u64 v[146:147], v[148:149], 2, s[10:11]
	global_load_dword v155, v[146:147], off
	global_load_dword v156, v[146:147], off offset:64
	global_load_dword v157, v[146:147], off offset:128
	global_load_dword v158, v[146:147], off offset:192
	global_load_dword v159, v[146:147], off offset:512
	global_load_dword v160, v[146:147], off offset:576
	global_load_dword v161, v[146:147], off offset:640
	global_load_dword v162, v[146:147], off offset:704
	s_lshl_b32 s0, s1, 7
	s_or_b32 s0, s0, s37
	v_ashrrev_i32_e32 v145, 1, v144
	v_and_b32_e32 v145, -8, v145
	v_add_u32_e32 v164, s0, v145
	v_ashrrev_i32_e32 v165, 31, v164
	v_lshlrev_b64 v[164:165], 1, v[164:165]
	v_lshl_add_u64 v[164:165], v[164:165], 0, s[14:15]
	s_waitcnt vmcnt(0)
	v_fmamk_f32 v166, v155, 0x39800000, v154
	v_rsq_f32_e32 v167, v166
	v_pk_mul_f32 v[120:121], v[124:125], v[120:121]
	v_pk_mul_f32 v[122:123], v[126:127], v[122:123]
	v_pk_mul_f32 v[112:113], v[116:117], v[112:113]
	v_pk_mul_f32 v[114:115], v[118:119], v[114:115]
	v_mul_f32_e32 v168, 0xbfb8aa3b, v167
	v_mov_b32_e32 v149, v148
	v_pk_mul_f32 v[124:125], v[124:125], v[168:169] op_sel_hi:[1,0]
	v_pk_mul_f32 v[126:127], v[126:127], v[168:169] op_sel_hi:[1,0]
	v_pk_mul_f32 v[116:117], v[116:117], v[168:169] op_sel_hi:[1,0]
	v_pk_mul_f32 v[118:119], v[118:119], v[168:169] op_sel_hi:[1,0]
	v_exp_f32_e32 v124, v124
	v_exp_f32_e32 v125, v125
	v_exp_f32_e32 v126, v126
	v_exp_f32_e32 v127, v127
	v_exp_f32_e32 v116, v116
	v_exp_f32_e32 v117, v117
	v_exp_f32_e32 v118, v118
	v_exp_f32_e32 v119, v119
	v_mad_i64_i32 v[170:171], s[0:1], v149, s53, v[164:165]
	v_pk_fma_f32 v[124:125], v[124:125], v[166:167], v[166:167] op_sel_hi:[1,0,0]
	v_pk_fma_f32 v[126:127], v[126:127], v[166:167], v[166:167] op_sel_hi:[1,0,0]
	v_pk_fma_f32 v[116:117], v[116:117], v[166:167], v[166:167] op_sel_hi:[1,0,0]
	v_pk_fma_f32 v[118:119], v[118:119], v[166:167], v[166:167] op_sel_hi:[1,0,0]
	v_rcp_f32_e32 v124, v124
	v_rcp_f32_e32 v125, v125
	v_rcp_f32_e32 v126, v126
	v_rcp_f32_e32 v127, v127
	v_rcp_f32_e32 v116, v116
	v_rcp_f32_e32 v117, v117
	v_rcp_f32_e32 v118, v118
	v_rcp_f32_e32 v119, v119
	s_nop 0
	v_pk_mul_f32 v[120:121], v[120:121], v[124:125]
	v_pk_mul_f32 v[122:123], v[122:123], v[126:127]
	v_pk_mul_f32 v[112:113], v[112:113], v[116:117]
	v_pk_mul_f32 v[114:115], v[114:115], v[118:119]
	v_cvt_pk_bf16_f32 v124, v120, v121
	v_cvt_pk_bf16_f32 v125, v122, v123
	v_cvt_pk_bf16_f32 v126, v112, v113
	v_cvt_pk_bf16_f32 v127, v114, v115
	global_store_dwordx4 v[170:171], v[124:127], off sc1
	v_fmamk_f32 v166, v156, 0x39800000, v154
	v_rsq_f32_e32 v167, v166
	v_pk_mul_f32 v[104:105], v[108:109], v[104:105]
	v_pk_mul_f32 v[106:107], v[110:111], v[106:107]
	v_pk_mul_f32 v[96:97], v[100:101], v[96:97]
	v_pk_mul_f32 v[98:99], v[102:103], v[98:99]
	v_mul_f32_e32 v168, 0xbfb8aa3b, v167
	v_add_u32_e32 v149, 0x10, v148
	v_pk_mul_f32 v[108:109], v[108:109], v[168:169] op_sel_hi:[1,0]
	v_pk_mul_f32 v[110:111], v[110:111], v[168:169] op_sel_hi:[1,0]
	v_pk_mul_f32 v[100:101], v[100:101], v[168:169] op_sel_hi:[1,0]
	v_pk_mul_f32 v[102:103], v[102:103], v[168:169] op_sel_hi:[1,0]
	v_exp_f32_e32 v108, v108
	v_exp_f32_e32 v109, v109
	v_exp_f32_e32 v110, v110
	v_exp_f32_e32 v111, v111
	v_exp_f32_e32 v100, v100
	v_exp_f32_e32 v101, v101
	v_exp_f32_e32 v102, v102
	v_exp_f32_e32 v103, v103
	v_mad_i64_i32 v[170:171], s[0:1], v149, s53, v[164:165]
	v_pk_fma_f32 v[108:109], v[108:109], v[166:167], v[166:167] op_sel_hi:[1,0,0]
	v_pk_fma_f32 v[110:111], v[110:111], v[166:167], v[166:167] op_sel_hi:[1,0,0]
	v_pk_fma_f32 v[100:101], v[100:101], v[166:167], v[166:167] op_sel_hi:[1,0,0]
	v_pk_fma_f32 v[102:103], v[102:103], v[166:167], v[166:167] op_sel_hi:[1,0,0]
	v_rcp_f32_e32 v108, v108
	v_rcp_f32_e32 v109, v109
	v_rcp_f32_e32 v110, v110
	v_rcp_f32_e32 v111, v111
	v_rcp_f32_e32 v100, v100
	v_rcp_f32_e32 v101, v101
	v_rcp_f32_e32 v102, v102
	v_rcp_f32_e32 v103, v103
	s_nop 0
	v_pk_mul_f32 v[104:105], v[104:105], v[108:109]
	v_pk_mul_f32 v[106:107], v[106:107], v[110:111]
	v_pk_mul_f32 v[96:97], v[96:97], v[100:101]
	v_pk_mul_f32 v[98:99], v[98:99], v[102:103]
	v_cvt_pk_bf16_f32 v108, v104, v105
	v_cvt_pk_bf16_f32 v109, v106, v107
	v_cvt_pk_bf16_f32 v110, v96, v97
	v_cvt_pk_bf16_f32 v111, v98, v99
	global_store_dwordx4 v[170:171], v[108:111], off sc1
	v_fmamk_f32 v166, v157, 0x39800000, v154
	v_rsq_f32_e32 v167, v166
	v_pk_mul_f32 v[88:89], v[92:93], v[88:89]
	v_pk_mul_f32 v[90:91], v[94:95], v[90:91]
	v_pk_mul_f32 v[80:81], v[84:85], v[80:81]
	v_pk_mul_f32 v[82:83], v[86:87], v[82:83]
	v_mul_f32_e32 v168, 0xbfb8aa3b, v167
	v_add_u32_e32 v149, 0x20, v148
	v_pk_mul_f32 v[92:93], v[92:93], v[168:169] op_sel_hi:[1,0]
	v_pk_mul_f32 v[94:95], v[94:95], v[168:169] op_sel_hi:[1,0]
	v_pk_mul_f32 v[84:85], v[84:85], v[168:169] op_sel_hi:[1,0]
	v_pk_mul_f32 v[86:87], v[86:87], v[168:169] op_sel_hi:[1,0]
	v_exp_f32_e32 v92, v92
	v_exp_f32_e32 v93, v93
	v_exp_f32_e32 v94, v94
	v_exp_f32_e32 v95, v95
	v_exp_f32_e32 v84, v84
	v_exp_f32_e32 v85, v85
	v_exp_f32_e32 v86, v86
	v_exp_f32_e32 v87, v87
	v_mad_i64_i32 v[170:171], s[0:1], v149, s53, v[164:165]
	v_pk_fma_f32 v[92:93], v[92:93], v[166:167], v[166:167] op_sel_hi:[1,0,0]
	v_pk_fma_f32 v[94:95], v[94:95], v[166:167], v[166:167] op_sel_hi:[1,0,0]
	v_pk_fma_f32 v[84:85], v[84:85], v[166:167], v[166:167] op_sel_hi:[1,0,0]
	v_pk_fma_f32 v[86:87], v[86:87], v[166:167], v[166:167] op_sel_hi:[1,0,0]
	v_rcp_f32_e32 v92, v92
	v_rcp_f32_e32 v93, v93
; DI float sigmoidf_(float z) { return 1.0f / (1.0f + __expf(-z)); }
; DI v4u pack8(const f4& a, const f4& b) { v4u w; w.x = cvt_pk_bf16(a[0], a[1]); w.y = cvt_pk_bf16(a[2], a[3]); w.z = cvt_pk_bf16(b[0], b[1]); w.w = cvt_pk_bf16(b[2], b[3]); return w; }
;     DI void operator()(f4 (&acc)[2][2][4][2], const Unit& u, int wr, int wc, int fr, int fq) const {
;     ...
;         const int row0 = u.pm * BM + wr * 64 + fr, col0 = u.pn * HALF + wc * 32 + 8 * fq;
;         float rr[2][4];
; #pragma unroll
;         for (int ai = 0; ai < 2; ++ai)
; #pragma unroll
;             for (int m = 0; m < 4; ++m) rr[ai][m] = ss[row0 + ai * HALF + m * 16];
; #pragma unroll
;         for (int ai = 0; ai < 2; ++ai)
; #pragma unroll
;             for (int m = 0; m < 4; ++m) { const int row = row0 + ai * HALF + m * 16; const float r = __builtin_amdgcn_rsqf(rr[ai][m] * (1.0f / D) + RMS_EPS);
;                 f4 o0, o1;
; #pragma unroll
;                 for (int e = 0; e < 4; ++e) { const float a0 = acc[ai][0][m][0][e] * r, a1 = acc[ai][0][m][1][e] * r;
;                     o0[e] = a0 * sigmoidf_(a0) * (acc[ai][1][m][0][e] * r); o1[e] = a1 * sigmoidf_(a1) * (acc[ai][1][m][1][e] * r); }
;                 *(v4u*)(uout + (size_t)row * DFF + col0) = pack8(o0, o1); }
	v_rcp_f32_e32 v94, v94
	v_rcp_f32_e32 v95, v95
	v_rcp_f32_e32 v84, v84
	v_rcp_f32_e32 v85, v85
	v_rcp_f32_e32 v86, v86
	v_rcp_f32_e32 v87, v87
	s_nop 0
	v_pk_mul_f32 v[88:89], v[88:89], v[92:93]
	v_pk_mul_f32 v[90:91], v[90:91], v[94:95]
	v_pk_mul_f32 v[80:81], v[80:81], v[84:85]
	v_pk_mul_f32 v[82:83], v[82:83], v[86:87]
	v_cvt_pk_bf16_f32 v92, v88, v89
	v_cvt_pk_bf16_f32 v93, v90, v91
	v_cvt_pk_bf16_f32 v94, v80, v81
	v_cvt_pk_bf16_f32 v95, v82, v83
	global_store_dwordx4 v[170:171], v[92:95], off sc1
	v_fmamk_f32 v166, v158, 0x39800000, v154
	v_rsq_f32_e32 v167, v166
	v_pk_mul_f32 v[72:73], v[76:77], v[72:73]
	v_pk_mul_f32 v[74:75], v[78:79], v[74:75]
	v_pk_mul_f32 v[64:65], v[68:69], v[64:65]
	v_pk_mul_f32 v[66:67], v[70:71], v[66:67]
	v_mul_f32_e32 v168, 0xbfb8aa3b, v167
	v_add_u32_e32 v149, 0x30, v148
	v_pk_mul_f32 v[76:77], v[76:77], v[168:169] op_sel_hi:[1,0]
	v_pk_mul_f32 v[78:79], v[78:79], v[168:169] op_sel_hi:[1,0]
	v_pk_mul_f32 v[68:69], v[68:69], v[168:169] op_sel_hi:[1,0]
	v_pk_mul_f32 v[70:71], v[70:71], v[168:169] op_sel_hi:[1,0]
	v_exp_f32_e32 v76, v76
	v_exp_f32_e32 v77, v77
	v_exp_f32_e32 v78, v78
	v_exp_f32_e32 v79, v79
	v_exp_f32_e32 v68, v68
	v_exp_f32_e32 v69, v69
	v_exp_f32_e32 v70, v70
	v_exp_f32_e32 v71, v71
	v_mad_i64_i32 v[170:171], s[0:1], v149, s53, v[164:165]
	v_pk_fma_f32 v[76:77], v[76:77], v[166:167], v[166:167] op_sel_hi:[1,0,0]
	v_pk_fma_f32 v[78:79], v[78:79], v[166:167], v[166:167] op_sel_hi:[1,0,0]
	v_pk_fma_f32 v[68:69], v[68:69], v[166:167], v[166:167] op_sel_hi:[1,0,0]
	v_pk_fma_f32 v[70:71], v[70:71], v[166:167], v[166:167] op_sel_hi:[1,0,0]
	v_rcp_f32_e32 v76, v76
	v_rcp_f32_e32 v77, v77
	v_rcp_f32_e32 v78, v78
	v_rcp_f32_e32 v79, v79
	v_rcp_f32_e32 v68, v68
	v_rcp_f32_e32 v69, v69
	v_rcp_f32_e32 v70, v70
	v_rcp_f32_e32 v71, v71
	s_nop 0
	v_pk_mul_f32 v[72:73], v[72:73], v[76:77]
	v_pk_mul_f32 v[74:75], v[74:75], v[78:79]
	v_pk_mul_f32 v[64:65], v[64:65], v[68:69]
	v_pk_mul_f32 v[66:67], v[66:67], v[70:71]
	v_cvt_pk_bf16_f32 v76, v72, v73
	v_cvt_pk_bf16_f32 v77, v74, v75
	v_cvt_pk_bf16_f32 v78, v64, v65
	v_cvt_pk_bf16_f32 v79, v66, v67
	global_store_dwordx4 v[170:171], v[76:79], off sc1
	v_fmamk_f32 v166, v159, 0x39800000, v154
	v_rsq_f32_e32 v167, v166
	v_pk_mul_f32 v[56:57], v[60:61], v[56:57]
	v_pk_mul_f32 v[58:59], v[62:63], v[58:59]
	v_pk_mul_f32 v[48:49], v[52:53], v[48:49]
	v_pk_mul_f32 v[50:51], v[54:55], v[50:51]
	v_mul_f32_e32 v168, 0xbfb8aa3b, v167
	v_add_u32_e32 v149, 0x80, v148
	v_pk_mul_f32 v[60:61], v[60:61], v[168:169] op_sel_hi:[1,0]
	v_pk_mul_f32 v[62:63], v[62:63], v[168:169] op_sel_hi:[1,0]
	v_pk_mul_f32 v[52:53], v[52:53], v[168:169] op_sel_hi:[1,0]
	v_pk_mul_f32 v[54:55], v[54:55], v[168:169] op_sel_hi:[1,0]
	v_exp_f32_e32 v60, v60
	v_exp_f32_e32 v61, v61
	v_exp_f32_e32 v62, v62
	v_exp_f32_e32 v63, v63
	v_exp_f32_e32 v52, v52
	v_exp_f32_e32 v53, v53
	v_exp_f32_e32 v54, v54
	v_exp_f32_e32 v55, v55
	v_mad_i64_i32 v[170:171], s[0:1], v149, s53, v[164:165]
	v_pk_fma_f32 v[60:61], v[60:61], v[166:167], v[166:167] op_sel_hi:[1,0,0]
	v_pk_fma_f32 v[62:63], v[62:63], v[166:167], v[166:167] op_sel_hi:[1,0,0]
	v_pk_fma_f32 v[52:53], v[52:53], v[166:167], v[166:167] op_sel_hi:[1,0,0]
	v_pk_fma_f32 v[54:55], v[54:55], v[166:167], v[166:167] op_sel_hi:[1,0,0]
	v_rcp_f32_e32 v60, v60
	v_rcp_f32_e32 v61, v61
	v_rcp_f32_e32 v62, v62
	v_rcp_f32_e32 v63, v63
	v_rcp_f32_e32 v52, v52
	v_rcp_f32_e32 v53, v53
	v_rcp_f32_e32 v54, v54
	v_rcp_f32_e32 v55, v55
	s_nop 0
	v_pk_mul_f32 v[56:57], v[56:57], v[60:61]
	v_pk_mul_f32 v[58:59], v[58:59], v[62:63]
	v_pk_mul_f32 v[48:49], v[48:49], v[52:53]
	v_pk_mul_f32 v[50:51], v[50:51], v[54:55]
	v_cvt_pk_bf16_f32 v60, v56, v57
	v_cvt_pk_bf16_f32 v61, v58, v59
	v_cvt_pk_bf16_f32 v62, v48, v49
	v_cvt_pk_bf16_f32 v63, v50, v51
	global_store_dwordx4 v[170:171], v[60:63], off sc1
	v_fmamk_f32 v166, v160, 0x39800000, v154
	v_rsq_f32_e32 v167, v166
	v_pk_mul_f32 v[40:41], v[44:45], v[40:41]
	v_pk_mul_f32 v[42:43], v[46:47], v[42:43]
	v_pk_mul_f32 v[32:33], v[36:37], v[32:33]
	v_pk_mul_f32 v[34:35], v[38:39], v[34:35]
	v_mul_f32_e32 v168, 0xbfb8aa3b, v167
	v_add_u32_e32 v149, 0x90, v148
	v_pk_mul_f32 v[44:45], v[44:45], v[168:169] op_sel_hi:[1,0]
	v_pk_mul_f32 v[46:47], v[46:47], v[168:169] op_sel_hi:[1,0]
	v_pk_mul_f32 v[36:37], v[36:37], v[168:169] op_sel_hi:[1,0]
	v_pk_mul_f32 v[38:39], v[38:39], v[168:169] op_sel_hi:[1,0]
	v_exp_f32_e32 v44, v44
	v_exp_f32_e32 v45, v45
	v_exp_f32_e32 v46, v46
; DI float sigmoidf_(float z) { return 1.0f / (1.0f + __expf(-z)); }
; DI v4u pack8(const f4& a, const f4& b) { v4u w; w.x = cvt_pk_bf16(a[0], a[1]); w.y = cvt_pk_bf16(a[2], a[3]); w.z = cvt_pk_bf16(b[0], b[1]); w.w = cvt_pk_bf16(b[2], b[3]); return w; }
;     DI void operator()(f4 (&acc)[2][2][4][2], const Unit& u, int wr, int wc, int fr, int fq) const {
;     ...
;         const int row0 = u.pm * BM + wr * 64 + fr, col0 = u.pn * HALF + wc * 32 + 8 * fq;
;         float rr[2][4];
; #pragma unroll
;         for (int ai = 0; ai < 2; ++ai)
; #pragma unroll
;             for (int m = 0; m < 4; ++m) rr[ai][m] = ss[row0 + ai * HALF + m * 16];
; #pragma unroll
;         for (int ai = 0; ai < 2; ++ai)
; #pragma unroll
;             for (int m = 0; m < 4; ++m) { const int row = row0 + ai * HALF + m * 16; const float r = __builtin_amdgcn_rsqf(rr[ai][m] * (1.0f / D) + RMS_EPS);
;                 f4 o0, o1;
; #pragma unroll
;                 for (int e = 0; e < 4; ++e) { const float a0 = acc[ai][0][m][0][e] * r, a1 = acc[ai][0][m][1][e] * r;
;                     o0[e] = a0 * sigmoidf_(a0) * (acc[ai][1][m][0][e] * r); o1[e] = a1 * sigmoidf_(a1) * (acc[ai][1][m][1][e] * r); }
;                 *(v4u*)(uout + (size_t)row * DFF + col0) = pack8(o0, o1); }
;     }
	v_exp_f32_e32 v47, v47
	v_exp_f32_e32 v36, v36
	v_exp_f32_e32 v37, v37
	v_exp_f32_e32 v38, v38
	v_exp_f32_e32 v39, v39
	v_mad_i64_i32 v[170:171], s[0:1], v149, s53, v[164:165]
	v_pk_fma_f32 v[44:45], v[44:45], v[166:167], v[166:167] op_sel_hi:[1,0,0]
	v_pk_fma_f32 v[46:47], v[46:47], v[166:167], v[166:167] op_sel_hi:[1,0,0]
	v_pk_fma_f32 v[36:37], v[36:37], v[166:167], v[166:167] op_sel_hi:[1,0,0]
	v_pk_fma_f32 v[38:39], v[38:39], v[166:167], v[166:167] op_sel_hi:[1,0,0]
	v_rcp_f32_e32 v44, v44
	v_rcp_f32_e32 v45, v45
	v_rcp_f32_e32 v46, v46
	v_rcp_f32_e32 v47, v47
	v_rcp_f32_e32 v36, v36
	v_rcp_f32_e32 v37, v37
	v_rcp_f32_e32 v38, v38
	v_rcp_f32_e32 v39, v39
	s_nop 0
	v_pk_mul_f32 v[40:41], v[40:41], v[44:45]
	v_pk_mul_f32 v[42:43], v[42:43], v[46:47]
	v_pk_mul_f32 v[32:33], v[32:33], v[36:37]
	v_pk_mul_f32 v[34:35], v[34:35], v[38:39]
	v_cvt_pk_bf16_f32 v44, v40, v41
	v_cvt_pk_bf16_f32 v45, v42, v43
	v_cvt_pk_bf16_f32 v46, v32, v33
	v_cvt_pk_bf16_f32 v47, v34, v35
	global_store_dwordx4 v[170:171], v[44:47], off sc1
	v_fmamk_f32 v166, v161, 0x39800000, v154
	v_rsq_f32_e32 v167, v166
	v_pk_mul_f32 v[24:25], v[28:29], v[24:25]
	v_pk_mul_f32 v[26:27], v[30:31], v[26:27]
	v_pk_mul_f32 v[16:17], v[20:21], v[16:17]
	v_pk_mul_f32 v[18:19], v[22:23], v[18:19]
	v_mul_f32_e32 v168, 0xbfb8aa3b, v167
	v_add_u32_e32 v149, 0xa0, v148
	v_pk_mul_f32 v[28:29], v[28:29], v[168:169] op_sel_hi:[1,0]
	v_pk_mul_f32 v[30:31], v[30:31], v[168:169] op_sel_hi:[1,0]
	v_pk_mul_f32 v[20:21], v[20:21], v[168:169] op_sel_hi:[1,0]
	v_pk_mul_f32 v[22:23], v[22:23], v[168:169] op_sel_hi:[1,0]
	v_exp_f32_e32 v28, v28
	v_exp_f32_e32 v29, v29
	v_exp_f32_e32 v30, v30
	v_exp_f32_e32 v31, v31
	v_exp_f32_e32 v20, v20
	v_exp_f32_e32 v21, v21
	v_exp_f32_e32 v22, v22
	v_exp_f32_e32 v23, v23
	v_mad_i64_i32 v[170:171], s[0:1], v149, s53, v[164:165]
	v_pk_fma_f32 v[28:29], v[28:29], v[166:167], v[166:167] op_sel_hi:[1,0,0]
	v_pk_fma_f32 v[30:31], v[30:31], v[166:167], v[166:167] op_sel_hi:[1,0,0]
	v_pk_fma_f32 v[20:21], v[20:21], v[166:167], v[166:167] op_sel_hi:[1,0,0]
	v_pk_fma_f32 v[22:23], v[22:23], v[166:167], v[166:167] op_sel_hi:[1,0,0]
	v_rcp_f32_e32 v28, v28
	v_rcp_f32_e32 v29, v29
	v_rcp_f32_e32 v30, v30
	v_rcp_f32_e32 v31, v31
	v_rcp_f32_e32 v20, v20
	v_rcp_f32_e32 v21, v21
	v_rcp_f32_e32 v22, v22
	v_rcp_f32_e32 v23, v23
	s_nop 0
	v_pk_mul_f32 v[24:25], v[24:25], v[28:29]
	v_pk_mul_f32 v[26:27], v[26:27], v[30:31]
	v_pk_mul_f32 v[16:17], v[16:17], v[20:21]
	v_pk_mul_f32 v[18:19], v[18:19], v[22:23]
	v_cvt_pk_bf16_f32 v28, v24, v25
	v_cvt_pk_bf16_f32 v29, v26, v27
	v_cvt_pk_bf16_f32 v30, v16, v17
	v_cvt_pk_bf16_f32 v31, v18, v19
	global_store_dwordx4 v[170:171], v[28:31], off sc1
	v_fmamk_f32 v166, v162, 0x39800000, v154
	v_rsq_f32_e32 v167, v166
	v_pk_mul_f32 v[8:9], v[12:13], v[8:9]
	v_pk_mul_f32 v[10:11], v[14:15], v[10:11]
	v_pk_mul_f32 v[0:1], v[4:5], v[0:1]
	v_pk_mul_f32 v[2:3], v[6:7], v[2:3]
	v_mul_f32_e32 v168, 0xbfb8aa3b, v167
	v_add_u32_e32 v149, 0xb0, v148
	v_pk_mul_f32 v[12:13], v[12:13], v[168:169] op_sel_hi:[1,0]
	v_pk_mul_f32 v[14:15], v[14:15], v[168:169] op_sel_hi:[1,0]
	v_pk_mul_f32 v[4:5], v[4:5], v[168:169] op_sel_hi:[1,0]
	v_pk_mul_f32 v[6:7], v[6:7], v[168:169] op_sel_hi:[1,0]
	v_exp_f32_e32 v12, v12
	v_exp_f32_e32 v13, v13
	v_exp_f32_e32 v14, v14
	v_exp_f32_e32 v15, v15
	v_exp_f32_e32 v4, v4
	v_exp_f32_e32 v5, v5
	v_exp_f32_e32 v6, v6
	v_exp_f32_e32 v7, v7
	v_mad_i64_i32 v[170:171], s[0:1], v149, s53, v[164:165]
	v_pk_fma_f32 v[12:13], v[12:13], v[166:167], v[166:167] op_sel_hi:[1,0,0]
	v_pk_fma_f32 v[14:15], v[14:15], v[166:167], v[166:167] op_sel_hi:[1,0,0]
	v_pk_fma_f32 v[4:5], v[4:5], v[166:167], v[166:167] op_sel_hi:[1,0,0]
	v_pk_fma_f32 v[6:7], v[6:7], v[166:167], v[166:167] op_sel_hi:[1,0,0]
	v_rcp_f32_e32 v12, v12
	v_rcp_f32_e32 v13, v13
	v_rcp_f32_e32 v14, v14
	v_rcp_f32_e32 v15, v15
	v_rcp_f32_e32 v4, v4
	v_rcp_f32_e32 v5, v5
	v_rcp_f32_e32 v6, v6
	v_rcp_f32_e32 v7, v7
	s_nop 0
	v_pk_mul_f32 v[8:9], v[8:9], v[12:13]
	v_pk_mul_f32 v[10:11], v[10:11], v[14:15]
	v_pk_mul_f32 v[0:1], v[0:1], v[4:5]
	v_pk_mul_f32 v[2:3], v[2:3], v[6:7]
	s_andn2_b64 vcc, exec, s[4:5]
	s_mov_b64 s[0:1], -1
	v_cvt_pk_bf16_f32 v12, v8, v9
	v_cvt_pk_bf16_f32 v13, v10, v11
	v_cvt_pk_bf16_f32 v14, v0, v1
	v_cvt_pk_bf16_f32 v15, v2, v3
	global_store_dwordx4 v[170:171], v[12:15], off sc1
	s_cbranch_vccnz .LBB0_2822
	s_andn2_b64 vcc, exec, s[12:13]
	s_cbranch_vccnz .LBB0_2821
	s_barrier
	s_branch .LBB0_2821

; __device__ __forceinline__ int lane_opaque() { int l; asm volatile("v_mbcnt_lo_u32_b32 %0, -1, 0\n\tv_mbcnt_hi_u32_b32 %0, -1, %0" : "=v"(l)); return l; }
; DI v4u pack8(const f4& a, const f4& b) { v4u w; w.x = cvt_pk_bf16(a[0], a[1]); w.y = cvt_pk_bf16(a[2], a[3]); w.z = cvt_pk_bf16(b[0], b[1]); w.w = cvt_pk_bf16(b[2], b[3]); return w; }
;     DI void operator()(f4 (&acc)[2][2][4][2], const Unit& u, int wr, int wc, int fr, int fq) const {
;         { const int ln_ = lane_opaque(); fr = ln_ & 15; fq = ln_ >> 4; }
;         const int row0 = u.pm * BM + wr * 64 + fr, col0 = u.pn * BM + wc * 32 + 8 * fq;
; #pragma unroll
;         for (int ai = 0; ai < 2; ++ai)
; #pragma unroll
;             for (int m = 0; m < 4; ++m)
; #pragma unroll
;                 for (int bj = 0; bj < 2; ++bj) *(v4u*)(o + (size_t)(row0 + ai * HALF + m * 16) * ld + col0 + bj * HALF) = pack8(acc[ai][bj][m][0], acc[ai][bj][m][1]);
;     }
.LBB0_2855:
	s_lshl_b32 s30, s59, 8
	v_mbcnt_lo_u32_b32 v149, -1, 0
	v_mbcnt_hi_u32_b32 v149, -1, v149
	s_add_i32 s30, s30, s36
	v_and_or_b32 v148, v149, 15, s30
	s_lshl_b32 s30, s62, 8
	v_ashrrev_i32_e32 v149, 1, v149
	s_or_b32 s30, s30, s37
	v_and_b32_e32 v149, -8, v149
	v_add_u32_e32 v150, s30, v149
	v_ashrrev_i32_e32 v149, 31, v148
	v_ashrrev_i32_e32 v151, 31, v150
	v_cvt_pk_bf16_f32 v120, v120, v121
	v_cvt_pk_bf16_f32 v121, v122, v123
	v_cvt_pk_bf16_f32 v122, v124, v125
	v_lshlrev_b64 v[124:125], 13, v[148:149]
	v_cvt_pk_bf16_f32 v123, v126, v127
	v_lshl_add_u64 v[124:125], s[12:13], 0, v[124:125]
	v_lshlrev_b64 v[126:127], 1, v[150:151]
	v_lshl_add_u64 v[124:125], v[124:125], 0, v[126:127]
	global_store_dwordx4 v[124:125], v[120:123], off sc1
	v_cvt_pk_bf16_f32 v116, v116, v117
	v_cvt_pk_bf16_f32 v117, v118, v119
	v_cvt_pk_bf16_f32 v118, v112, v113
	v_or_b32_e32 v112, 16, v148
	v_ashrrev_i32_e32 v113, 31, v112
	v_cvt_pk_bf16_f32 v119, v114, v115
	global_store_dwordx4 v[124:125], v[116:119], off offset:256 sc1
	v_cvt_pk_bf16_f32 v108, v108, v109
	v_cvt_pk_bf16_f32 v109, v110, v111
	v_cvt_pk_bf16_f32 v110, v104, v105
	v_lshlrev_b64 v[104:105], 13, v[112:113]
	v_lshl_add_u64 v[104:105], s[12:13], 0, v[104:105]
	v_lshl_add_u64 v[104:105], v[104:105], 0, v[126:127]
	v_cvt_pk_bf16_f32 v111, v106, v107
	global_store_dwordx4 v[104:105], v[108:111], off sc1
	v_cvt_pk_bf16_f32 v100, v100, v101
	v_cvt_pk_bf16_f32 v101, v102, v103
	v_cvt_pk_bf16_f32 v102, v96, v97
	v_or_b32_e32 v96, 32, v148
	v_ashrrev_i32_e32 v97, 31, v96
	v_cvt_pk_bf16_f32 v103, v98, v99
	global_store_dwordx4 v[104:105], v[100:103], off offset:256 sc1
	v_cvt_pk_bf16_f32 v92, v92, v93
	v_cvt_pk_bf16_f32 v93, v94, v95
	v_cvt_pk_bf16_f32 v94, v88, v89
	v_lshlrev_b64 v[88:89], 13, v[96:97]
	v_lshl_add_u64 v[88:89], s[12:13], 0, v[88:89]
	v_lshl_add_u64 v[88:89], v[88:89], 0, v[126:127]
	v_cvt_pk_bf16_f32 v95, v90, v91
	global_store_dwordx4 v[88:89], v[92:95], off sc1
	v_cvt_pk_bf16_f32 v84, v84, v85
	v_cvt_pk_bf16_f32 v85, v86, v87
	v_cvt_pk_bf16_f32 v86, v80, v81
	v_or_b32_e32 v80, 48, v148
	v_ashrrev_i32_e32 v81, 31, v80
	v_cvt_pk_bf16_f32 v87, v82, v83
	global_store_dwordx4 v[88:89], v[84:87], off offset:256 sc1
	v_cvt_pk_bf16_f32 v76, v76, v77
	v_cvt_pk_bf16_f32 v77, v78, v79
	v_cvt_pk_bf16_f32 v78, v72, v73
	v_lshlrev_b64 v[72:73], 13, v[80:81]
	v_lshl_add_u64 v[72:73], s[12:13], 0, v[72:73]
	v_lshl_add_u64 v[72:73], v[72:73], 0, v[126:127]
	v_cvt_pk_bf16_f32 v79, v74, v75
	global_store_dwordx4 v[72:73], v[76:79], off sc1
	v_cvt_pk_bf16_f32 v68, v68, v69
	v_cvt_pk_bf16_f32 v69, v70, v71
	v_cvt_pk_bf16_f32 v70, v64, v65
	v_cvt_pk_bf16_f32 v71, v66, v67
	global_store_dwordx4 v[72:73], v[68:71], off offset:256 sc1
	v_cvt_pk_bf16_f32 v60, v60, v61
	v_cvt_pk_bf16_f32 v61, v62, v63
	v_cvt_pk_bf16_f32 v62, v56, v57
	v_cvt_pk_bf16_f32 v63, v58, v59
	v_add_co_u32_e32 v58, vcc, s56, v124
	v_lshl_add_u64 v[56:57], v[124:125], 0, s[20:21]
	s_nop 0
	v_addc_co_u32_e32 v59, vcc, 0, v125, vcc
	global_store_dwordx4 v[58:59], v[60:63], off sc1
	v_cvt_pk_bf16_f32 v52, v52, v53
	v_cvt_pk_bf16_f32 v53, v54, v55
	v_cvt_pk_bf16_f32 v54, v48, v49
	v_cvt_pk_bf16_f32 v55, v50, v51
	global_store_dwordx4 v[56:57], v[52:55], off offset:256 sc1
	v_cvt_pk_bf16_f32 v44, v44, v45
	v_cvt_pk_bf16_f32 v45, v46, v47
	v_cvt_pk_bf16_f32 v46, v40, v41
	v_cvt_pk_bf16_f32 v47, v42, v43
	v_add_co_u32_e32 v42, vcc, s57, v124
	v_lshl_add_u64 v[40:41], v[124:125], 0, s[22:23]
	s_nop 0
	v_addc_co_u32_e32 v43, vcc, 0, v125, vcc
	global_store_dwordx4 v[42:43], v[44:47], off sc1
	v_cvt_pk_bf16_f32 v36, v36, v37
	v_cvt_pk_bf16_f32 v37, v38, v39
	v_cvt_pk_bf16_f32 v38, v32, v33
	v_cvt_pk_bf16_f32 v39, v34, v35
	global_store_dwordx4 v[40:41], v[36:39], off offset:256 sc1
	v_cvt_pk_bf16_f32 v28, v28, v29
	v_cvt_pk_bf16_f32 v29, v30, v31
	v_cvt_pk_bf16_f32 v30, v24, v25
	v_cvt_pk_bf16_f32 v31, v26, v27
	v_add_co_u32_e32 v26, vcc, s58, v124
	v_lshl_add_u64 v[24:25], v[124:125], 0, s[24:25]
	s_nop 0
	v_addc_co_u32_e32 v27, vcc, 0, v125, vcc
	global_store_dwordx4 v[26:27], v[28:31], off sc1
	v_cvt_pk_bf16_f32 v20, v20, v21
	v_cvt_pk_bf16_f32 v21, v22, v23
	v_cvt_pk_bf16_f32 v22, v16, v17
	v_cvt_pk_bf16_f32 v23, v18, v19
	global_store_dwordx4 v[24:25], v[20:23], off offset:256 sc1
	v_cvt_pk_bf16_f32 v12, v12, v13
	v_cvt_pk_bf16_f32 v13, v14, v15
	v_cvt_pk_bf16_f32 v14, v8, v9
	v_cvt_pk_bf16_f32 v15, v10, v11
	v_add_co_u32_e32 v10, vcc, 0x160000, v124
	v_lshl_add_u64 v[8:9], v[124:125], 0, s[26:27]
	s_nop 0
	v_addc_co_u32_e32 v11, vcc, 0, v125, vcc
	s_and_b64 vcc, exec, s[4:5]
	s_mov_b64 s[4:5], -1
	global_store_dwordx4 v[10:11], v[12:15], off sc1
	v_cvt_pk_bf16_f32 v4, v4, v5
	v_cvt_pk_bf16_f32 v5, v6, v7
	v_cvt_pk_bf16_f32 v6, v0, v1
	v_cvt_pk_bf16_f32 v7, v2, v3
	global_store_dwordx4 v[8:9], v[4:7], off offset:256 sc1
	s_cbranch_vccnz .LBB0_2839
	s_andn2_b64 vcc, exec, s[10:11]
	s_cbranch_vccnz .LBB0_2838
	s_barrier
	s_branch .LBB0_2838

; DI v4u pack8(const f4& a, const f4& b) { v4u w; w.x = cvt_pk_bf16(a[0], a[1]); w.y = cvt_pk_bf16(a[2], a[3]); w.z = cvt_pk_bf16(b[0], b[1]); w.w = cvt_pk_bf16(b[2], b[3]); return w; }
; DI void unpack8(const v4u& w, f4& a, f4& b) { a[0] = bf_lo(w.x); a[1] = bf_hi(w.x); a[2] = bf_lo(w.y); a[3] = bf_hi(w.y); b[0] = bf_lo(w.z); b[1] = bf_hi(w.z); b[2] = bf_lo(w.w); b[3] = bf_hi(w.w); }
;     DI void operator()(f4 (&acc)[2][2][4][2], const Unit& u, int wr, int wc, int fr, int fq) const {
;     ...
;         const int row0 = u.pm * BM + wr * 64 + fr, col0 = u.pn * BM + wc * 32 + 8 * fq;
; #pragma unroll
;         for (int ai = 0; ai < 2; ++ai) {
;             f4 b0[4][2], b1[4][2];
;             if constexpr (SRCB) {
;                 v4u bb[4][2];
; #pragma unroll
;                 for (int m = 0; m < 4; ++m)
; #pragma unroll
;                     for (int bj = 0; bj < 2; ++bj) bb[m][bj] = *(const v4u*)(baseb + (size_t)(row0 + ai * HALF + m * 16) * D + col0 + bj * HALF);
;                 asm volatile("" ::: "memory");
; #pragma unroll
;                 for (int m = 0; m < 4; ++m)
; #pragma unroll
;                     for (int bj = 0; bj < 2; ++bj) unpack8(bb[m][bj], b0[m][bj], b1[m][bj]);
;             } else {
; #pragma unroll
;                 for (int m = 0; m < 4; ++m)
; #pragma unroll
;                     for (int bj = 0; bj < 2; ++bj) { const size_t off = (size_t)(row0 + ai * HALF + m * 16) * D + col0 + bj * HALF; b0[m][bj] = *(const f4*)(base + off); b1[m][bj] = *(const f4*)(base + off + 4); }
;                 asm volatile("" ::: "memory");
;             }
; #pragma unroll
;             for (int m = 0; m < 4; ++m) { const int row = row0 + ai * HALF + m * 16; float s = 0.f;
; #pragma unroll
;                 for (int bj = 0; bj < 2; ++bj) { const size_t off = (size_t)row * D + col0 + bj * HALF;
;                     const f4 h0 = b0[m][bj] + acc[ai][bj][m][0], h1 = b1[m][bj] + acc[ai][bj][m][1];
;                     *(v4u*)(outb + off) = pack8(h0, h1);
;                     s += (h0[0] * h0[0] + h0[1] * h0[1]) + (h0[2] * h0[2] + h0[3] * h0[3]) + (h1[0] * h1[0] + h1[1] * h1[1]) + (h1[2] * h1[2] + h1[3] * h1[3]); }
;                 s += __shfl_xor(s, 16); s += __shfl_xor(s, 32);
;                 if (fq == 0) atomicAdd(ss + row, s); }
.LBB0_2938:
	s_lshl_b32 s0, s50, 8
	s_add_i32 s0, s0, s39
	v_mbcnt_lo_u32_b32 v191, -1, 0
	v_mbcnt_hi_u32_b32 v191, -1, v191
	v_xor_b32_e32 v210, 32, v190
	v_and_or_b32 v172, v191, 15, s0
	s_lshl_b32 s0, s49, 8
	v_ashrrev_i32_e32 v128, 1, v191
	s_or_b32 s0, s0, s40
	v_and_b32_e32 v128, -8, v128
	v_add_u32_e32 v168, s0, v128
	v_ashrrev_i32_e32 v169, 31, v168
	v_lshlrev_b64 v[200:201], 1, v[168:169]
	v_ashrrev_i32_e32 v173, 31, v172
	v_lshl_add_u64 v[170:171], s[8:9], 0, v[200:201]
	v_lshlrev_b64 v[202:203], 13, v[172:173]
	v_lshl_add_u64 v[128:129], v[170:171], 0, v[202:203]
	global_load_dwordx4 v[192:195], v[128:129], off
	global_load_dwordx4 v[196:199], v[128:129], off offset:256
	v_or_b32_e32 v182, 16, v172
	v_or_b32_e32 v178, 32, v172
	v_or_b32_e32 v174, 48, v172
	v_ashrrev_i32_e32 v183, 31, v182
	v_ashrrev_i32_e32 v179, 31, v178
	v_ashrrev_i32_e32 v175, 31, v174
	v_lshlrev_b64 v[184:185], 13, v[182:183]
	v_lshlrev_b64 v[180:181], 13, v[178:179]
	v_lshlrev_b64 v[176:177], 13, v[174:175]
	v_lshl_add_u64 v[128:129], v[170:171], 0, v[184:185]
	v_lshl_add_u64 v[130:131], v[170:171], 0, v[180:181]
	v_lshl_add_u64 v[204:205], v[170:171], 0, v[176:177]
	global_load_dwordx4 v[148:151], v[128:129], off
	global_load_dwordx4 v[144:147], v[128:129], off offset:256
	global_load_dwordx4 v[140:143], v[130:131], off
	global_load_dwordx4 v[136:139], v[130:131], off offset:256
	global_load_dwordx4 v[132:135], v[204:205], off
	s_nop 0
	global_load_dwordx4 v[128:131], v[204:205], off offset:256
	v_and_b32_e32 v205, 64, v190
	v_xor_b32_e32 v204, 16, v190
	v_add_u32_e32 v211, 64, v205
	v_lshl_add_u64 v[202:203], s[10:11], 0, v[202:203]
	v_cmp_lt_i32_e64 s[0:1], v204, v211
	v_lshl_add_u64 v[200:201], v[202:203], 0, v[200:201]
	v_cmp_gt_u32_e32 vcc, 16, v191
	v_cndmask_b32_e64 v191, v190, v204, s[0:1]
	v_lshlrev_b32_e32 v191, 2, v191
	v_cmp_lt_i32_e64 s[0:1], v210, v211
	s_waitcnt vmcnt(0)
	v_lshlrev_b32_e32 v202, 16, v192
	v_and_b32_e32 v203, 0xffff0000, v192
	v_lshlrev_b32_e32 v192, 16, v193
	v_and_b32_e32 v193, 0xffff0000, v193
	v_lshlrev_b32_e32 v206, 16, v196
	v_and_b32_e32 v207, 0xffff0000, v196
	v_lshlrev_b32_e32 v196, 16, v197
	v_and_b32_e32 v197, 0xffff0000, v197
	v_lshlrev_b32_e32 v204, 16, v194
	v_and_b32_e32 v205, 0xffff0000, v194
	v_lshlrev_b32_e32 v194, 16, v195
	v_and_b32_e32 v195, 0xffff0000, v195
	v_lshlrev_b32_e32 v208, 16, v198
	v_and_b32_e32 v209, 0xffff0000, v198
	v_lshlrev_b32_e32 v198, 16, v199
	v_and_b32_e32 v199, 0xffff0000, v199
	v_pk_add_f32 v[126:127], v[126:127], v[192:193]
	v_pk_add_f32 v[124:125], v[124:125], v[202:203]
	v_pk_add_f32 v[118:119], v[118:119], v[196:197]
	v_pk_add_f32 v[116:117], v[116:117], v[206:207]
	v_pk_add_f32 v[122:123], v[122:123], v[194:195]
	v_pk_add_f32 v[120:121], v[120:121], v[204:205]
	v_pk_add_f32 v[192:193], v[114:115], v[198:199]
	v_pk_add_f32 v[194:195], v[112:113], v[208:209]
	v_mul_f32_e32 v114, v125, v125
	v_mul_f32_e32 v115, v127, v127
	v_mul_f32_e32 v196, v117, v117
	v_mul_f32_e32 v197, v119, v119
	v_cvt_pk_bf16_f32 v112, v124, v125
	v_mul_f32_e32 v125, v121, v121
	v_mul_f32_e32 v198, v195, v195
	v_fmac_f32_e32 v114, v124, v124
	v_fmac_f32_e32 v115, v126, v126
	v_fmac_f32_e32 v196, v116, v116
	v_fmac_f32_e32 v197, v118, v118
	v_cvt_pk_bf16_f32 v113, v126, v127
	v_mul_f32_e32 v127, v123, v123
	v_mul_f32_e32 v199, v193, v193
	v_fmac_f32_e32 v125, v120, v120
	v_fmac_f32_e32 v198, v194, v194
	v_add_f32_e32 v114, v114, v115
	v_add_f32_e32 v115, v196, v197
	v_fmac_f32_e32 v127, v122, v122
	v_fmac_f32_e32 v199, v192, v192
	v_add_f32_e32 v114, v125, v114
	v_add_f32_e32 v115, v198, v115
	v_add_f32_e32 v114, v127, v114
	v_add_f32_e32 v115, v199, v115
	v_add_f32_e32 v124, v114, v115
	ds_bpermute_b32 v125, v191, v124
	v_cvt_pk_bf16_f32 v114, v120, v121
	v_cvt_pk_bf16_f32 v115, v122, v123
	global_store_dwordx4 v[200:201], v[112:115], off sc1
	v_cvt_pk_bf16_f32 v116, v116, v117
	v_cvt_pk_bf16_f32 v117, v118, v119
	v_cvt_pk_bf16_f32 v118, v194, v195
	v_cvt_pk_bf16_f32 v119, v192, v193
	global_store_dwordx4 v[200:201], v[116:119], off offset:256 sc1
	s_nop 0
	v_cndmask_b32_e64 v112, v190, v210, s[0:1]
	s_waitcnt lgkmcnt(0)
	v_add_f32_e32 v113, v124, v125
	v_lshlrev_b32_e32 v112, 2, v112
	ds_bpermute_b32 v114, v112, v113
	s_and_saveexec_b64 s[0:1], vcc
	s_cbranch_execz .LBB0_2940
	v_lshl_add_u64 v[116:117], v[172:173], 2, s[12:13]
	s_waitcnt lgkmcnt(0)
	v_add_f32_e32 v113, v113, v114
	global_atomic_add_f32 v[116:117], v113, off

; DI float sigmoidf_(float z) { return 1.0f / (1.0f + __expf(-z)); }
; DI v4u pack8(const f4& a, const f4& b) { v4u w; w.x = cvt_pk_bf16(a[0], a[1]); w.y = cvt_pk_bf16(a[2], a[3]); w.z = cvt_pk_bf16(b[0], b[1]); w.w = cvt_pk_bf16(b[2], b[3]); return w; }
; DI void unpack8(const v4u& w, f4& a, f4& b) { a[0] = bf_lo(w.x); a[1] = bf_hi(w.x); a[2] = bf_lo(w.y); a[3] = bf_hi(w.y); b[0] = bf_lo(w.z); b[1] = bf_hi(w.z); b[2] = bf_lo(w.w); b[3] = bf_hi(w.w); }
;     DI void operator()(f4 (&acc)[2][2][4][2], const Unit& u, int wr, int wc, int fr, int fq) const {
;     ...
;         const int row0 = u.pm * BM + wr * 64 + fr, col0 = u.pn * BM + wc * 32 + 8 * fq;
;         float rr[2][4];
; #pragma unroll
;         for (int ai = 0; ai < 2; ++ai)
; #pragma unroll
;             for (int m = 0; m < 4; ++m) rr[ai][m] = ss_in[row0 + ai * HALF + m * 16];
; #pragma unroll
;         for (int ai = 0; ai < 2; ++ai)
; #pragma unroll
;             for (int mp = 0; mp < 2; ++mp) {
;                 v4u pv[2][2], hv[2][2];
; #pragma unroll
;                 for (int mm = 0; mm < 2; ++mm)
; #pragma unroll
;                     for (int bj = 0; bj < 2; ++bj) { const size_t off = (size_t)(row0 + ai * HALF + (2 * mp + mm) * 16) * D + col0 + bj * HALF;
;                         pv[mm][bj] = *(const v4u*)(pp + off); hv[mm][bj] = *(const v4u*)(hb + off); }
;                 asm volatile("" ::: "memory");
; #pragma unroll
;                 for (int mm = 0; mm < 2; ++mm) { const int m = 2 * mp + mm, row = row0 + ai * HALF + m * 16; const float r = __builtin_amdgcn_rsqf(rr[ai][m] * (1.0f / D) + RMS_EPS); float s = 0.f;
; #pragma unroll
;                     for (int bj = 0; bj < 2; ++bj) { const size_t off = (size_t)row * D + col0 + bj * HALF;
;                         f4 p0, p1; unpack8(pv[mm][bj], p0, p1);
;                         f4 h0, h1; unpack8(hv[mm][bj], h0, h1);
; #pragma unroll
;                         for (int t = 0; t < 4; ++t) { h0[t] += sigmoidf_(acc[ai][bj][m][0][t] * r) * p0[t]; h1[t] += sigmoidf_(acc[ai][bj][m][1][t] * r) * p1[t]; }
;                         *(v4u*)(h3b + off) = pack8(h0, h1);
;                         s += (h0[0] * h0[0] + h0[1] * h0[1]) + (h0[2] * h0[2] + h0[3] * h0[3]) + (h1[0] * h1[0] + h1[1] * h1[1]) + (h1[2] * h1[2] + h1[3] * h1[3]); }
.LBB0_3033:
	s_lshl_b32 s1, s6, 8
	s_add_i32 s1, s1, s47
	v_mbcnt_lo_u32_b32 v134, -1, 0
	v_mbcnt_hi_u32_b32 v134, -1, v134
	s_lshl_b32 s0, s0, 8
	v_and_or_b32 v170, v134, 15, s1
	v_ashrrev_i32_e32 v128, 1, v134
	v_ashrrev_i32_e32 v171, 31, v170
	v_and_b32_e32 v130, -8, v128
	v_lshl_add_u64 v[128:129], v[170:171], 2, s[16:17]
	global_load_dword v193, v[128:129], off
	s_or_b32 s0, s0, s48
	v_add_u32_e32 v168, s0, v130
	v_ashrrev_i32_e32 v169, 31, v168
	v_lshlrev_b64 v[130:131], 12, v[170:171]
	v_lshl_add_u64 v[130:131], v[130:131], 0, v[168:169]
	v_lshlrev_b64 v[130:131], 1, v[130:131]
	v_lshl_add_u64 v[132:133], s[14:15], 0, v[130:131]
	v_lshl_add_u64 v[130:131], s[8:9], 0, v[130:131]
	global_load_dwordx4 v[194:197], v[132:133], off
	global_load_dwordx4 v[198:201], v[130:131], off
	v_or_b32_e32 v176, 16, v170
	v_or_b32_e32 v174, 32, v170
	v_or_b32_e32 v172, 48, v170
	v_ashrrev_i32_e32 v177, 31, v176
	v_ashrrev_i32_e32 v175, 31, v174
	v_ashrrev_i32_e32 v173, 31, v172
	v_cmp_gt_u32_e64 s[6:7], 16, v134
	v_lshl_add_u64 v[134:135], v[176:177], 2, s[16:17]
	v_lshl_add_u64 v[136:137], v[174:175], 2, s[16:17]
	v_lshl_add_u64 v[138:139], v[172:173], 2, s[16:17]
	global_load_dword v189, v[128:129], off offset:512
	global_load_dword v188, v[128:129], off offset:576
	global_load_dword v187, v[128:129], off offset:640
	global_load_dword v192, v[134:135], off
	global_load_dword v191, v[136:137], off
	global_load_dword v190, v[138:139], off
	global_load_dword v186, v[128:129], off offset:704
	global_load_dwordx4 v[148:151], v[132:133], off offset:256
	global_load_dwordx4 v[144:147], v[130:131], off offset:256
	v_lshlrev_b64 v[140:141], 12, v[176:177]
	v_lshl_add_u64 v[128:129], v[140:141], 0, v[168:169]
	v_lshlrev_b64 v[128:129], 1, v[128:129]
	v_lshl_add_u64 v[130:131], s[14:15], 0, v[128:129]
	v_lshl_add_u64 v[128:129], s[8:9], 0, v[128:129]
	global_load_dwordx4 v[140:143], v[130:131], off
	global_load_dwordx4 v[132:135], v[130:131], off offset:256
	global_load_dwordx4 v[136:139], v[128:129], off
	s_nop 0
	global_load_dwordx4 v[128:131], v[128:129], off offset:256
	v_lshlrev_b64 v[178:179], 13, v[170:171]
	s_waitcnt vmcnt(0)
	v_fmamk_f32 v193, v193, 0x39800000, v184
	v_rsq_f32_e32 v193, v193
	v_lshlrev_b32_e32 v204, 16, v196
	v_mul_f32_e32 v124, v124, v193
	v_mul_f32_e32 v120, v120, v193
	v_mul_f32_e32 v124, 0xbfb8aa3b, v124
	v_mul_f32_e32 v120, 0xbfb8aa3b, v120
	v_exp_f32_e32 v124, v124
	v_exp_f32_e32 v120, v120
	v_mul_f32_e32 v125, v125, v193
	v_mul_f32_e32 v125, 0xbfb8aa3b, v125
	v_add_f32_e32 v124, 1.0, v124
	v_add_f32_e32 v120, 1.0, v120
	v_exp_f32_e32 v125, v125
	s_nop 0
	v_add_f32_e32 v125, 1.0, v125
	v_rcp_f32_e32 v124, v124
	v_mul_f32_e32 v121, v121, v193
	v_lshlrev_b32_e32 v208, 16, v200
	v_rcp_f32_e32 v120, v120
	v_mul_f32_e32 v121, 0xbfb8aa3b, v121
	v_fmac_f32_e32 v208, v120, v204
	v_exp_f32_e32 v121, v121
	v_lshlrev_b32_e32 v202, 16, v194
	v_lshlrev_b32_e32 v206, 16, v198
	v_fmac_f32_e32 v206, v124, v202
	v_add_f32_e32 v121, 1.0, v121
	v_rcp_f32_e32 v120, v125
	v_mul_f32_e32 v125, v126, v193
	v_mul_f32_e32 v125, 0xbfb8aa3b, v125
	v_and_b32_e32 v194, 0xffff0000, v194
	v_and_b32_e32 v198, 0xffff0000, v198
	v_exp_f32_e32 v125, v125
	v_fmac_f32_e32 v198, v120, v194
	v_add_f32_e32 v125, 1.0, v125
	v_mul_f32_e32 v122, v122, v193
	v_mul_f32_e32 v122, 0xbfb8aa3b, v122
	v_and_b32_e32 v196, 0xffff0000, v196
	v_and_b32_e32 v200, 0xffff0000, v200
	v_rcp_f32_e32 v120, v121
	v_exp_f32_e32 v122, v122
	v_fmac_f32_e32 v200, v120, v196
	v_add_f32_e32 v122, 1.0, v122
	v_lshlrev_b32_e32 v203, 16, v195
	v_lshlrev_b32_e32 v207, 16, v199
	v_rcp_f32_e32 v120, v125
	v_mul_f32_e32 v125, v127, v193
	v_fmac_f32_e32 v207, v120, v203
	v_mul_f32_e32 v125, 0xbfb8aa3b, v125
	v_exp_f32_e32 v125, v125
	s_nop 0
	v_add_f32_e32 v124, 1.0, v125
	v_rcp_f32_e32 v120, v122
	v_mul_f32_e32 v122, v123, v193
	v_mul_f32_e32 v122, 0xbfb8aa3b, v122
	v_lshlrev_b32_e32 v205, 16, v197
	v_lshlrev_b32_e32 v209, 16, v201
	v_exp_f32_e32 v122, v122
	v_fmac_f32_e32 v209, v120, v205
	v_add_f32_e32 v122, 1.0, v122
	v_and_b32_e32 v195, 0xffff0000, v195
	v_and_b32_e32 v199, 0xffff0000, v199
	v_rcp_f32_e32 v120, v124
	s_nop 0
	v_fmac_f32_e32 v199, v120, v195
	v_mul_f32_e32 v116, v116, v193
	v_mul_f32_e32 v116, 0xbfb8aa3b, v116
	v_exp_f32_e32 v116, v116
	v_and_b32_e32 v197, 0xffff0000, v197
	v_and_b32_e32 v201, 0xffff0000, v201
	v_rcp_f32_e32 v120, v122
	v_add_f32_e32 v116, 1.0, v116
	v_fmac_f32_e32 v201, v120, v197
	v_cvt_pk_bf16_f32 v120, v206, v198
	v_mul_f32_e32 v124, v198, v198
	v_cvt_pk_bf16_f32 v121, v207, v199
	v_mul_f32_e32 v125, v199, v199
	v_fmac_f32_e32 v124, v206, v206
	v_fmac_f32_e32 v125, v207, v207
	v_add_f32_e32 v124, v124, v125
	v_mul_f32_e32 v125, v200, v200
	v_mul_f32_e32 v112, v112, v193
	v_fmac_f32_e32 v125, v208, v208
	v_mul_f32_e32 v112, 0xbfb8aa3b, v112
	v_cvt_pk_bf16_f32 v122, v208, v200
	v_cvt_pk_bf16_f32 v123, v209, v201
	v_add_f32_e32 v124, v125, v124
	v_mul_f32_e32 v125, v201, v201
	v_exp_f32_e32 v112, v112
	s_nop 0
	v_add_f32_e32 v112, 1.0, v112
	v_mul_f32_e32 v117, v117, v193
	v_fmac_f32_e32 v125, v209, v209
	v_mul_f32_e32 v117, 0xbfb8aa3b, v117
	v_add_f32_e32 v124, v125, v124
	v_lshlrev_b32_e32 v125, 16, v148
	v_lshlrev_b32_e32 v195, 16, v144
	v_rcp_f32_e32 v116, v116
	v_exp_f32_e32 v117, v117
	v_fmac_f32_e32 v195, v116, v125
	v_add_f32_e32 v117, 1.0, v117
	v_mul_f32_e32 v113, v113, v193
	v_and_b32_e32 v126, 0xffff0000, v148
	v_lshlrev_b32_e32 v127, 16, v149
	v_and_b32_e32 v148, 0xffff0000, v149
	v_lshlrev_b32_e32 v149, 16, v150
	v_lshlrev_b32_e32 v197, 16, v146
	v_rcp_f32_e32 v112, v112
	v_mul_f32_e32 v113, 0xbfb8aa3b, v113
	v_fmac_f32_e32 v197, v112, v149
; DI float sigmoidf_(float z) { return 1.0f / (1.0f + __expf(-z)); }
; DI v4u pack8(const f4& a, const f4& b) { v4u w; w.x = cvt_pk_bf16(a[0], a[1]); w.y = cvt_pk_bf16(a[2], a[3]); w.z = cvt_pk_bf16(b[0], b[1]); w.w = cvt_pk_bf16(b[2], b[3]); return w; }
; DI void unpack8(const v4u& w, f4& a, f4& b) { a[0] = bf_lo(w.x); a[1] = bf_hi(w.x); a[2] = bf_lo(w.y); a[3] = bf_hi(w.y); b[0] = bf_lo(w.z); b[1] = bf_hi(w.z); b[2] = bf_lo(w.w); b[3] = bf_hi(w.w); }
;     DI void operator()(f4 (&acc)[2][2][4][2], const Unit& u, int wr, int wc, int fr, int fq) const {
;     ...
;                 for (int mm = 0; mm < 2; ++mm) { const int m = 2 * mp + mm, row = row0 + ai * HALF + m * 16; const float r = __builtin_amdgcn_rsqf(rr[ai][m] * (1.0f / D) + RMS_EPS); float s = 0.f;
; #pragma unroll
;                     for (int bj = 0; bj < 2; ++bj) { const size_t off = (size_t)row * D + col0 + bj * HALF;
;                         f4 p0, p1; unpack8(pv[mm][bj], p0, p1);
;                         f4 h0, h1; unpack8(hv[mm][bj], h0, h1);
; #pragma unroll
;                         for (int t = 0; t < 4; ++t) { h0[t] += sigmoidf_(acc[ai][bj][m][0][t] * r) * p0[t]; h1[t] += sigmoidf_(acc[ai][bj][m][1][t] * r) * p1[t]; }
;                         *(v4u*)(h3b + off) = pack8(h0, h1);
;                         s += (h0[0] * h0[0] + h0[1] * h0[1]) + (h0[2] * h0[2] + h0[3] * h0[3]) + (h1[0] * h1[0] + h1[1] * h1[1]) + (h1[2] * h1[2] + h1[3] * h1[3]); }
;                     s += __shfl_xor(s, 16); s += __shfl_xor(s, 32);
;                     if (fq == 0) atomicAdd(ss_out + row, s); }
	v_exp_f32_e32 v113, v113
	s_nop 0
	v_add_f32_e32 v113, 1.0, v113
	v_rcp_f32_e32 v112, v117
	v_mul_f32_e32 v117, v118, v193
	v_mul_f32_e32 v117, 0xbfb8aa3b, v117
	v_and_b32_e32 v144, 0xffff0000, v144
	v_exp_f32_e32 v117, v117
	v_fmac_f32_e32 v144, v112, v126
	v_add_f32_e32 v117, 1.0, v117
	v_mul_f32_e32 v114, v114, v193
	v_mul_f32_e32 v114, 0xbfb8aa3b, v114
	v_and_b32_e32 v150, 0xffff0000, v150
	v_and_b32_e32 v146, 0xffff0000, v146
	v_rcp_f32_e32 v112, v113
	v_exp_f32_e32 v114, v114
	v_fmac_f32_e32 v146, v112, v150
	v_add_f32_e32 v114, 1.0, v114
	v_lshlrev_b32_e32 v196, 16, v145
	v_rcp_f32_e32 v112, v117
	v_mul_f32_e32 v117, v119, v193
	v_fmac_f32_e32 v196, v112, v127
	v_mul_f32_e32 v117, 0xbfb8aa3b, v117
	v_exp_f32_e32 v117, v117
	s_nop 0
	v_add_f32_e32 v116, 1.0, v117
	v_rcp_f32_e32 v112, v114
	v_mul_f32_e32 v114, v115, v193
	v_mul_f32_e32 v114, 0xbfb8aa3b, v114
	v_lshlrev_b32_e32 v194, 16, v151
	v_lshlrev_b32_e32 v200, 16, v147
	v_exp_f32_e32 v114, v114
	v_fmac_f32_e32 v200, v112, v194
	v_add_f32_e32 v114, 1.0, v114
	v_and_b32_e32 v145, 0xffff0000, v145
	v_rcp_f32_e32 v112, v116
	s_nop 0
	v_fmac_f32_e32 v145, v112, v148
	v_and_b32_e32 v151, 0xffff0000, v151
	v_and_b32_e32 v147, 0xffff0000, v147
	v_rcp_f32_e32 v112, v114
	s_nop 0
	v_fmac_f32_e32 v147, v112, v151
	v_mul_f32_e32 v112, v144, v144
	v_mul_f32_e32 v113, v145, v145
	v_fmac_f32_e32 v112, v195, v195
	v_fmac_f32_e32 v113, v196, v196
	v_add_f32_e32 v112, v112, v113
	v_mul_f32_e32 v113, v146, v146
	v_fmac_f32_e32 v113, v197, v197
	v_add_f32_e32 v112, v113, v112
	v_mul_f32_e32 v113, v147, v147
	v_fmac_f32_e32 v113, v200, v200
	v_add_f32_e32 v112, v113, v112
	v_and_b32_e32 v113, 64, v185
	v_add_f32_e32 v115, v124, v112
	v_xor_b32_e32 v112, 16, v185
	v_add_u32_e32 v116, 64, v113
	v_cmp_lt_i32_e32 vcc, v112, v116
	s_nop 1
	v_cndmask_b32_e32 v112, v185, v112, vcc
	v_lshlrev_b32_e32 v124, 2, v112
	ds_bpermute_b32 v117, v124, v115
	v_lshl_add_u64 v[112:113], s[12:13], 0, v[178:179]
	v_lshl_add_u64 v[118:119], v[168:169], 1, v[112:113]
	v_xor_b32_e32 v113, 32, v185
	v_cmp_lt_i32_e32 vcc, v113, v116
	global_store_dwordx4 v[118:119], v[120:123], off sc1
	s_waitcnt lgkmcnt(0)
	v_add_f32_e32 v112, v115, v117
	v_cndmask_b32_e32 v113, v185, v113, vcc
	v_lshlrev_b32_e32 v122, 2, v113
	ds_bpermute_b32 v113, v122, v112
	v_cvt_pk_bf16_f32 v114, v195, v144
	v_cvt_pk_bf16_f32 v115, v196, v145
	v_cvt_pk_bf16_f32 v116, v197, v146
	v_cvt_pk_bf16_f32 v117, v200, v147
	global_store_dwordx4 v[118:119], v[114:117], off offset:256 sc1
	s_and_saveexec_b64 s[0:1], s[6:7]
	s_cbranch_execz .LBB0_3035
	v_lshl_add_u64 v[114:115], v[170:171], 2, s[18:19]
	s_waitcnt lgkmcnt(0)
	v_add_f32_e32 v112, v112, v113
	global_atomic_add_f32 v[114:115], v112, off
.LBB0_3035:
	s_or_b64 exec, exec, s[0:1]
	v_fmamk_f32 v112, v192, 0x39800000, v184
	v_rsq_f32_e32 v114, v112
	v_lshlrev_b32_e32 v115, 16, v140
	v_and_b32_e32 v116, 0xffff0000, v140
	v_lshlrev_b32_e32 v117, 16, v141
	v_mul_f32_e32 v108, v108, v114
	v_mul_f32_e32 v108, 0xbfb8aa3b, v108
	v_exp_f32_e32 v108, v108
	v_and_b32_e32 v118, 0xffff0000, v141
	v_mul_f32_e32 v104, v104, v114
	v_mul_f32_e32 v104, 0xbfb8aa3b, v104
	v_add_f32_e32 v108, 1.0, v108
	v_lshlrev_b32_e32 v121, 16, v143
	v_and_b32_e32 v123, 0xffff0000, v143
	v_exp_f32_e32 v104, v104
	s_nop 0
	v_add_f32_e32 v104, 1.0, v104
	v_mul_f32_e32 v109, v109, v114
	v_mul_f32_e32 v109, 0xbfb8aa3b, v109
	v_lshlrev_b32_e32 v125, 16, v136
	v_rcp_f32_e32 v108, v108
	v_exp_f32_e32 v109, v109
	v_fmac_f32_e32 v125, v108, v115
	v_add_f32_e32 v109, 1.0, v109
	v_mul_f32_e32 v105, v105, v114
	v_lshlrev_b32_e32 v119, 16, v142
	v_and_b32_e32 v126, 0xffff0000, v136
	v_lshlrev_b32_e32 v127, 16, v137
	v_and_b32_e32 v136, 0xffff0000, v137
	v_lshlrev_b32_e32 v137, 16, v138
	v_rcp_f32_e32 v104, v104
	v_mul_f32_e32 v105, 0xbfb8aa3b, v105
	v_fmac_f32_e32 v137, v104, v119
	v_exp_f32_e32 v105, v105
	s_nop 0
	v_add_f32_e32 v105, 1.0, v105
	v_rcp_f32_e32 v104, v109
	v_mul_f32_e32 v109, v110, v114
	v_mul_f32_e32 v109, 0xbfb8aa3b, v109
	v_exp_f32_e32 v109, v109
	v_fmac_f32_e32 v126, v104, v116
	v_add_f32_e32 v109, 1.0, v109
	v_mul_f32_e32 v106, v106, v114
	v_mul_f32_e32 v106, 0xbfb8aa3b, v106
	v_and_b32_e32 v120, 0xffff0000, v142
	v_and_b32_e32 v138, 0xffff0000, v138
	v_rcp_f32_e32 v104, v105
	v_exp_f32_e32 v106, v106
	v_fmac_f32_e32 v138, v104, v120
	v_add_f32_e32 v106, 1.0, v106
	v_rcp_f32_e32 v104, v109
	v_mul_f32_e32 v109, v111, v114
	v_fmac_f32_e32 v127, v104, v117
	v_mul_f32_e32 v109, 0xbfb8aa3b, v109
	v_exp_f32_e32 v109, v109
	s_nop 0
	v_add_f32_e32 v108, 1.0, v109
	v_rcp_f32_e32 v104, v106
	v_mul_f32_e32 v106, v107, v114
	v_mul_f32_e32 v106, 0xbfb8aa3b, v106
	v_lshlrev_b32_e32 v142, 16, v139
	v_exp_f32_e32 v106, v106
	v_fmac_f32_e32 v142, v104, v121
	v_add_f32_e32 v106, 1.0, v106
	v_rcp_f32_e32 v104, v108
	s_nop 0
	v_fmac_f32_e32 v136, v104, v118
	v_mul_f32_e32 v100, v100, v114
	v_mul_f32_e32 v100, 0xbfb8aa3b, v100
	v_exp_f32_e32 v100, v100
	v_and_b32_e32 v139, 0xffff0000, v139
	v_rcp_f32_e32 v104, v106
	v_mul_f32_e32 v108, v126, v126
	v_mul_f32_e32 v109, v136, v136
	v_add_f32_e32 v100, 1.0, v100
	v_fmac_f32_e32 v139, v104, v123
	v_cvt_pk_bf16_f32 v104, v125, v126
	v_cvt_pk_bf16_f32 v105, v127, v136
	v_fmac_f32_e32 v108, v125, v125
	v_fmac_f32_e32 v109, v127, v127
	v_add_f32_e32 v108, v108, v109
	v_mul_f32_e32 v109, v138, v138
	v_lshlrev_b32_e32 v120, 16, v128
	v_and_b32_e32 v121, 0xffff0000, v128
	v_fmac_f32_e32 v109, v137, v137
	v_add_f32_e32 v108, v109, v108
	v_mul_f32_e32 v109, v139, v139
	v_mul_f32_e32 v96, v96, v114
	v_fmac_f32_e32 v109, v142, v142
	v_mul_f32_e32 v96, 0xbfb8aa3b, v96
	v_add_f32_e32 v108, v109, v108
; DI float sigmoidf_(float z) { return 1.0f / (1.0f + __expf(-z)); }
; DI v4u pack8(const f4& a, const f4& b) { v4u w; w.x = cvt_pk_bf16(a[0], a[1]); w.y = cvt_pk_bf16(a[2], a[3]); w.z = cvt_pk_bf16(b[0], b[1]); w.w = cvt_pk_bf16(b[2], b[3]); return w; }
; DI void unpack8(const v4u& w, f4& a, f4& b) { a[0] = bf_lo(w.x); a[1] = bf_hi(w.x); a[2] = bf_lo(w.y); a[3] = bf_hi(w.y); b[0] = bf_lo(w.z); b[1] = bf_hi(w.z); b[2] = bf_lo(w.w); b[3] = bf_hi(w.w); }
;     DI void operator()(f4 (&acc)[2][2][4][2], const Unit& u, int wr, int wc, int fr, int fq) const {
;     ...
;                     for (int bj = 0; bj < 2; ++bj) { const size_t off = (size_t)(row0 + ai * HALF + (2 * mp + mm) * 16) * D + col0 + bj * HALF;
;                         pv[mm][bj] = *(const v4u*)(pp + off); hv[mm][bj] = *(const v4u*)(hb + off); }
;     ...
;                 for (int mm = 0; mm < 2; ++mm) { const int m = 2 * mp + mm, row = row0 + ai * HALF + m * 16; const float r = __builtin_amdgcn_rsqf(rr[ai][m] * (1.0f / D) + RMS_EPS); float s = 0.f;
; #pragma unroll
;                     for (int bj = 0; bj < 2; ++bj) { const size_t off = (size_t)row * D + col0 + bj * HALF;
;                         f4 p0, p1; unpack8(pv[mm][bj], p0, p1);
;                         f4 h0, h1; unpack8(hv[mm][bj], h0, h1);
; #pragma unroll
;                         for (int t = 0; t < 4; ++t) { h0[t] += sigmoidf_(acc[ai][bj][m][0][t] * r) * p0[t]; h1[t] += sigmoidf_(acc[ai][bj][m][1][t] * r) * p1[t]; }
;                         *(v4u*)(h3b + off) = pack8(h0, h1);
;                         s += (h0[0] * h0[0] + h0[1] * h0[1]) + (h0[2] * h0[2] + h0[3] * h0[3]) + (h1[0] * h1[0] + h1[1] * h1[1]) + (h1[2] * h1[2] + h1[3] * h1[3]); }
;                     s += __shfl_xor(s, 16); s += __shfl_xor(s, 32);
;                     if (fq == 0) atomicAdd(ss_out + row, s); }
	v_lshlrev_b32_e32 v109, 16, v132
	v_and_b32_e32 v110, 0xffff0000, v132
	v_exp_f32_e32 v96, v96
	v_lshlrev_b32_e32 v111, 16, v133
	v_and_b32_e32 v115, 0xffff0000, v133
	v_lshlrev_b32_e32 v116, 16, v134
	v_and_b32_e32 v117, 0xffff0000, v134
	v_add_f32_e32 v96, 1.0, v96
	v_mul_f32_e32 v101, v101, v114
	v_mul_f32_e32 v101, 0xbfb8aa3b, v101
	v_rcp_f32_e32 v100, v100
	v_exp_f32_e32 v101, v101
	v_fmac_f32_e32 v120, v100, v109
	v_add_f32_e32 v101, 1.0, v101
	v_mul_f32_e32 v97, v97, v114
	v_lshlrev_b32_e32 v126, 16, v130
	v_rcp_f32_e32 v96, v96
	v_mul_f32_e32 v97, 0xbfb8aa3b, v97
	v_fmac_f32_e32 v126, v96, v116
	v_exp_f32_e32 v97, v97
	s_nop 0
	v_add_f32_e32 v97, 1.0, v97
	v_rcp_f32_e32 v96, v101
	v_mul_f32_e32 v101, v102, v114
	v_mul_f32_e32 v101, 0xbfb8aa3b, v101
	v_exp_f32_e32 v101, v101
	v_fmac_f32_e32 v121, v96, v110
	v_add_f32_e32 v101, 1.0, v101
	v_mul_f32_e32 v98, v98, v114
	v_mul_f32_e32 v98, 0xbfb8aa3b, v98
	v_lshlrev_b32_e32 v123, 16, v129
	v_and_b32_e32 v125, 0xffff0000, v129
	v_and_b32_e32 v129, 0xffff0000, v130
	v_rcp_f32_e32 v96, v97
	v_exp_f32_e32 v98, v98
	v_fmac_f32_e32 v129, v96, v117
	v_add_f32_e32 v98, 1.0, v98
	v_rcp_f32_e32 v96, v101
	v_mul_f32_e32 v101, v103, v114
	v_fmac_f32_e32 v123, v96, v111
	v_mul_f32_e32 v101, 0xbfb8aa3b, v101
	v_exp_f32_e32 v101, v101
	s_nop 0
	v_add_f32_e32 v100, 1.0, v101
	v_rcp_f32_e32 v96, v98
	v_mul_f32_e32 v98, v99, v114
	v_mul_f32_e32 v98, 0xbfb8aa3b, v98
	v_lshlrev_b32_e32 v118, 16, v135
	v_lshlrev_b32_e32 v130, 16, v131
	v_exp_f32_e32 v98, v98
	v_fmac_f32_e32 v130, v96, v118
	v_add_f32_e32 v98, 1.0, v98
	v_rcp_f32_e32 v96, v100
	s_nop 0
	v_fmac_f32_e32 v125, v96, v115
	v_and_b32_e32 v119, 0xffff0000, v135
	v_and_b32_e32 v131, 0xffff0000, v131
	v_rcp_f32_e32 v96, v98
	s_nop 0
	v_fmac_f32_e32 v131, v96, v119
	v_mul_f32_e32 v96, v121, v121
	v_mul_f32_e32 v97, v125, v125
	v_fmac_f32_e32 v96, v120, v120
	v_fmac_f32_e32 v97, v123, v123
	v_add_f32_e32 v96, v96, v97
	v_mul_f32_e32 v97, v129, v129
	v_fmac_f32_e32 v97, v126, v126
	v_add_f32_e32 v96, v97, v96
	v_mul_f32_e32 v97, v131, v131
	v_fmac_f32_e32 v97, v130, v130
	v_add_f32_e32 v96, v97, v96
	v_add_f32_e32 v99, v108, v96
	ds_bpermute_b32 v100, v124, v99
	s_waitcnt lgkmcnt(1)
	v_lshlrev_b64 v[112:113], 13, v[176:177]
	v_lshl_add_u64 v[96:97], s[12:13], 0, v[112:113]
	v_lshl_add_u64 v[102:103], v[168:169], 1, v[96:97]
	v_cvt_pk_bf16_f32 v106, v137, v138
	s_waitcnt lgkmcnt(0)
	v_add_f32_e32 v96, v99, v100
	ds_bpermute_b32 v97, v122, v96
	v_cvt_pk_bf16_f32 v107, v142, v139
	global_store_dwordx4 v[102:103], v[104:107], off sc1
	v_cvt_pk_bf16_f32 v98, v120, v121
	v_cvt_pk_bf16_f32 v99, v123, v125
	v_cvt_pk_bf16_f32 v100, v126, v129
	v_cvt_pk_bf16_f32 v101, v130, v131
	global_store_dwordx4 v[102:103], v[98:101], off offset:256 sc1
	s_and_saveexec_b64 s[0:1], s[6:7]
	s_cbranch_execz .LBB0_3037
	v_lshl_add_u64 v[98:99], v[176:177], 2, s[18:19]
	s_waitcnt lgkmcnt(0)
	v_add_f32_e32 v96, v96, v97
	global_atomic_add_f32 v[98:99], v96, off
.LBB0_3037:
	s_or_b64 exec, exec, s[0:1]
	s_waitcnt lgkmcnt(0)
	v_lshlrev_b64 v[96:97], 12, v[174:175]
	v_lshl_add_u64 v[96:97], v[96:97], 0, v[168:169]
	v_lshlrev_b64 v[96:97], 1, v[96:97]
	v_lshl_add_u64 v[98:99], s[14:15], 0, v[96:97]
	v_lshl_add_u64 v[96:97], s[8:9], 0, v[96:97]
	global_load_dwordx4 v[126:129], v[98:99], off
	global_load_dwordx4 v[130:133], v[96:97], off
	v_fmamk_f32 v102, v191, 0x39800000, v184
	v_rsq_f32_e32 v123, v102
	v_lshlrev_b64 v[100:101], 12, v[172:173]
	v_lshl_add_u64 v[100:101], v[100:101], 0, v[168:169]
	v_lshlrev_b64 v[100:101], 1, v[100:101]
	v_mul_f32_e32 v92, v92, v123
	v_mul_f32_e32 v88, v88, v123
	v_mul_f32_e32 v92, 0xbfb8aa3b, v92
	v_mul_f32_e32 v93, v93, v123
	v_mul_f32_e32 v88, 0xbfb8aa3b, v88
	v_exp_f32_e32 v92, v92
	v_mul_f32_e32 v93, 0xbfb8aa3b, v93
	v_exp_f32_e32 v88, v88
	v_exp_f32_e32 v93, v93
	v_add_f32_e32 v92, 1.0, v92
	v_lshl_add_u64 v[102:103], s[14:15], 0, v[100:101]
	v_lshl_add_u64 v[134:135], s[8:9], 0, v[100:101]
	v_add_f32_e32 v88, 1.0, v88
	global_load_dwordx4 v[116:119], v[98:99], off offset:256
	global_load_dwordx4 v[112:115], v[96:97], off offset:256
	global_load_dwordx4 v[108:111], v[102:103], off
	s_nop 0
	global_load_dwordx4 v[100:103], v[102:103], off offset:256
	s_nop 0
	global_load_dwordx4 v[104:107], v[134:135], off
	global_load_dwordx4 v[96:99], v[134:135], off offset:256
	v_add_f32_e32 v93, 1.0, v93
	v_mul_f32_e32 v89, v89, v123
	v_rcp_f32_e32 v92, v92
	v_mul_f32_e32 v89, 0xbfb8aa3b, v89
	v_rcp_f32_e32 v88, v88
	v_exp_f32_e32 v89, v89
	v_mul_f32_e32 v90, v90, v123
	v_mul_f32_e32 v90, 0xbfb8aa3b, v90
	v_exp_f32_e32 v90, v90
	v_add_f32_e32 v89, 1.0, v89
	v_mul_f32_e32 v84, v84, v123
	v_mul_f32_e32 v84, 0xbfb8aa3b, v84
	v_add_f32_e32 v90, 1.0, v90
	v_exp_f32_e32 v84, v84
	v_mul_f32_e32 v80, v80, v123
	v_mul_f32_e32 v80, 0xbfb8aa3b, v80
	v_add_f32_e32 v84, 1.0, v84
	v_exp_f32_e32 v80, v80
	v_mul_f32_e32 v85, v85, v123
	v_mul_f32_e32 v85, 0xbfb8aa3b, v85
	v_exp_f32_e32 v85, v85
	v_add_f32_e32 v80, 1.0, v80
	v_mul_f32_e32 v81, v81, v123
	v_mul_f32_e32 v81, 0xbfb8aa3b, v81
	v_add_f32_e32 v85, 1.0, v85
	v_exp_f32_e32 v81, v81
	v_mul_f32_e32 v82, v82, v123
	v_mul_f32_e32 v82, 0xbfb8aa3b, v82
	s_waitcnt vmcnt(7)
	v_lshlrev_b32_e32 v135, 16, v128
	s_waitcnt vmcnt(6)
; DI float sigmoidf_(float z) { return 1.0f / (1.0f + __expf(-z)); }
; DI v4u pack8(const f4& a, const f4& b) { v4u w; w.x = cvt_pk_bf16(a[0], a[1]); w.y = cvt_pk_bf16(a[2], a[3]); w.z = cvt_pk_bf16(b[0], b[1]); w.w = cvt_pk_bf16(b[2], b[3]); return w; }
; DI void unpack8(const v4u& w, f4& a, f4& b) { a[0] = bf_lo(w.x); a[1] = bf_hi(w.x); a[2] = bf_lo(w.y); a[3] = bf_hi(w.y); b[0] = bf_lo(w.z); b[1] = bf_hi(w.z); b[2] = bf_lo(w.w); b[3] = bf_hi(w.w); }
;     DI void operator()(f4 (&acc)[2][2][4][2], const Unit& u, int wr, int wc, int fr, int fq) const {
;     ...
; #pragma unroll
;                 for (int mm = 0; mm < 2; ++mm) { const int m = 2 * mp + mm, row = row0 + ai * HALF + m * 16; const float r = __builtin_amdgcn_rsqf(rr[ai][m] * (1.0f / D) + RMS_EPS); float s = 0.f;
; #pragma unroll
;                     for (int bj = 0; bj < 2; ++bj) { const size_t off = (size_t)row * D + col0 + bj * HALF;
;                         f4 p0, p1; unpack8(pv[mm][bj], p0, p1);
;                         f4 h0, h1; unpack8(hv[mm][bj], h0, h1);
; #pragma unroll
;                         for (int t = 0; t < 4; ++t) { h0[t] += sigmoidf_(acc[ai][bj][m][0][t] * r) * p0[t]; h1[t] += sigmoidf_(acc[ai][bj][m][1][t] * r) * p1[t]; }
;                         *(v4u*)(h3b + off) = pack8(h0, h1);
;                         s += (h0[0] * h0[0] + h0[1] * h0[1]) + (h0[2] * h0[2] + h0[3] * h0[3]) + (h1[0] * h1[0] + h1[1] * h1[1]) + (h1[2] * h1[2] + h1[3] * h1[3]); }
;                     s += __shfl_xor(s, 16); s += __shfl_xor(s, 32);
;                     if (fq == 0) atomicAdd(ss_out + row, s); }
	v_lshlrev_b32_e32 v141, 16, v132
	v_lshlrev_b32_e32 v125, 16, v126
	v_lshlrev_b32_e32 v138, 16, v130
	v_fmac_f32_e32 v141, v88, v135
	v_fmac_f32_e32 v138, v92, v125
	v_rcp_f32_e32 v88, v93
	v_mul_f32_e32 v93, v94, v123
	v_mul_f32_e32 v93, 0xbfb8aa3b, v93
	v_and_b32_e32 v126, 0xffff0000, v126
	v_and_b32_e32 v130, 0xffff0000, v130
	v_exp_f32_e32 v93, v93
	v_fmac_f32_e32 v130, v88, v126
	v_add_f32_e32 v93, 1.0, v93
	v_and_b32_e32 v128, 0xffff0000, v128
	v_and_b32_e32 v132, 0xffff0000, v132
	v_rcp_f32_e32 v88, v89
	s_nop 0
	v_fmac_f32_e32 v132, v88, v128
	v_lshlrev_b32_e32 v134, 16, v127
	v_lshlrev_b32_e32 v140, 16, v131
	v_rcp_f32_e32 v88, v93
	v_mul_f32_e32 v93, v95, v123
	v_fmac_f32_e32 v140, v88, v134
	v_mul_f32_e32 v93, 0xbfb8aa3b, v93
	v_exp_f32_e32 v93, v93
	s_nop 0
	v_add_f32_e32 v92, 1.0, v93
	v_rcp_f32_e32 v88, v90
	v_mul_f32_e32 v90, v91, v123
	v_mul_f32_e32 v90, 0xbfb8aa3b, v90
	v_lshlrev_b32_e32 v137, 16, v129
	v_lshlrev_b32_e32 v142, 16, v133
	v_exp_f32_e32 v90, v90
	v_fmac_f32_e32 v142, v88, v137
	v_add_f32_e32 v90, 1.0, v90
	v_and_b32_e32 v127, 0xffff0000, v127
	v_and_b32_e32 v131, 0xffff0000, v131
	v_rcp_f32_e32 v88, v92
	s_nop 0
	v_fmac_f32_e32 v131, v88, v127
	v_and_b32_e32 v129, 0xffff0000, v129
	v_and_b32_e32 v133, 0xffff0000, v133
	v_rcp_f32_e32 v88, v90
	s_nop 0
	v_fmac_f32_e32 v133, v88, v129
	v_cvt_pk_bf16_f32 v88, v138, v130
	v_mul_f32_e32 v92, v130, v130
	v_mul_f32_e32 v93, v131, v131
	v_fmac_f32_e32 v92, v138, v138
	v_fmac_f32_e32 v93, v140, v140
	v_cvt_pk_bf16_f32 v89, v140, v131
	v_cvt_pk_bf16_f32 v90, v141, v132
	v_add_f32_e32 v92, v92, v93
	v_mul_f32_e32 v93, v132, v132
	v_fmac_f32_e32 v93, v141, v141
	v_cvt_pk_bf16_f32 v91, v142, v133
	v_add_f32_e32 v92, v93, v92
	v_mul_f32_e32 v93, v133, v133
	v_fmac_f32_e32 v93, v142, v142
	v_add_f32_e32 v92, v93, v92
	s_waitcnt vmcnt(5)
	v_lshlrev_b32_e32 v93, 16, v116
	s_waitcnt vmcnt(4)
	v_lshlrev_b32_e32 v126, 16, v112
	v_rcp_f32_e32 v84, v84
	s_nop 0
	v_fmac_f32_e32 v126, v84, v93
	v_and_b32_e32 v94, 0xffff0000, v116
	v_lshlrev_b32_e32 v95, 16, v117
	v_and_b32_e32 v116, 0xffff0000, v117
	v_lshlrev_b32_e32 v117, 16, v118
	v_lshlrev_b32_e32 v128, 16, v114
	v_rcp_f32_e32 v80, v80
	s_nop 0
	v_fmac_f32_e32 v128, v80, v117
	v_add_f32_e32 v81, 1.0, v81
	v_rcp_f32_e32 v80, v85
	v_mul_f32_e32 v85, v86, v123
	v_mul_f32_e32 v85, 0xbfb8aa3b, v85
	v_and_b32_e32 v112, 0xffff0000, v112
	v_exp_f32_e32 v85, v85
	v_fmac_f32_e32 v112, v80, v94
	v_add_f32_e32 v85, 1.0, v85
	v_and_b32_e32 v118, 0xffff0000, v118
	v_and_b32_e32 v114, 0xffff0000, v114
	v_rcp_f32_e32 v80, v81
	v_exp_f32_e32 v82, v82
	v_fmac_f32_e32 v114, v80, v118
	v_add_f32_e32 v82, 1.0, v82
	v_lshlrev_b32_e32 v127, 16, v113
	v_rcp_f32_e32 v80, v85
	v_mul_f32_e32 v85, v87, v123
	v_fmac_f32_e32 v127, v80, v95
	v_mul_f32_e32 v85, 0xbfb8aa3b, v85
	v_exp_f32_e32 v85, v85
	s_nop 0
	v_add_f32_e32 v84, 1.0, v85
	v_rcp_f32_e32 v80, v82
	v_mul_f32_e32 v82, v83, v123
	v_mul_f32_e32 v82, 0xbfb8aa3b, v82
	v_lshlrev_b32_e32 v125, 16, v119
	v_lshlrev_b32_e32 v131, 16, v115
	v_exp_f32_e32 v82, v82
	v_fmac_f32_e32 v131, v80, v125
	v_add_f32_e32 v82, 1.0, v82
	v_and_b32_e32 v113, 0xffff0000, v113
	v_rcp_f32_e32 v80, v84
	s_nop 0
	v_fmac_f32_e32 v113, v80, v116
	v_and_b32_e32 v119, 0xffff0000, v119
	v_and_b32_e32 v115, 0xffff0000, v115
	v_rcp_f32_e32 v80, v82
	s_nop 0
	v_fmac_f32_e32 v115, v80, v119
	v_mul_f32_e32 v80, v112, v112
	v_mul_f32_e32 v81, v113, v113
	v_fmac_f32_e32 v80, v126, v126
	v_fmac_f32_e32 v81, v127, v127
	v_add_f32_e32 v80, v80, v81
	v_mul_f32_e32 v81, v114, v114
	v_fmac_f32_e32 v81, v128, v128
	v_add_f32_e32 v80, v81, v80
	v_mul_f32_e32 v81, v115, v115
	v_fmac_f32_e32 v81, v131, v131
	v_add_f32_e32 v80, v81, v80
	v_add_f32_e32 v83, v92, v80
	ds_bpermute_b32 v84, v124, v83
	v_lshlrev_b64 v[120:121], 13, v[174:175]
	v_lshl_add_u64 v[80:81], s[12:13], 0, v[120:121]
	v_lshl_add_u64 v[86:87], v[168:169], 1, v[80:81]
	global_store_dwordx4 v[86:87], v[88:91], off sc1
	s_waitcnt lgkmcnt(0)
	v_add_f32_e32 v80, v83, v84
	ds_bpermute_b32 v81, v122, v80
	v_cvt_pk_bf16_f32 v82, v126, v112
	v_cvt_pk_bf16_f32 v83, v127, v113
	v_cvt_pk_bf16_f32 v84, v128, v114
	v_cvt_pk_bf16_f32 v85, v131, v115
	global_store_dwordx4 v[86:87], v[82:85], off offset:256 sc1
	s_and_saveexec_b64 s[0:1], s[6:7]
	s_cbranch_execz .LBB0_3039
	v_lshl_add_u64 v[82:83], v[174:175], 2, s[18:19]
	s_waitcnt lgkmcnt(0)
	v_add_f32_e32 v80, v80, v81
	global_atomic_add_f32 v[82:83], v80, off
; DI float sigmoidf_(float z) { return 1.0f / (1.0f + __expf(-z)); }
; DI v4u pack8(const f4& a, const f4& b) { v4u w; w.x = cvt_pk_bf16(a[0], a[1]); w.y = cvt_pk_bf16(a[2], a[3]); w.z = cvt_pk_bf16(b[0], b[1]); w.w = cvt_pk_bf16(b[2], b[3]); return w; }
; DI void unpack8(const v4u& w, f4& a, f4& b) { a[0] = bf_lo(w.x); a[1] = bf_hi(w.x); a[2] = bf_lo(w.y); a[3] = bf_hi(w.y); b[0] = bf_lo(w.z); b[1] = bf_hi(w.z); b[2] = bf_lo(w.w); b[3] = bf_hi(w.w); }
;     DI void operator()(f4 (&acc)[2][2][4][2], const Unit& u, int wr, int wc, int fr, int fq) const {
;     ...
; #pragma unroll
;                 for (int mm = 0; mm < 2; ++mm) { const int m = 2 * mp + mm, row = row0 + ai * HALF + m * 16; const float r = __builtin_amdgcn_rsqf(rr[ai][m] * (1.0f / D) + RMS_EPS); float s = 0.f;
; #pragma unroll
;                     for (int bj = 0; bj < 2; ++bj) { const size_t off = (size_t)row * D + col0 + bj * HALF;
;                         f4 p0, p1; unpack8(pv[mm][bj], p0, p1);
;                         f4 h0, h1; unpack8(hv[mm][bj], h0, h1);
; #pragma unroll
;                         for (int t = 0; t < 4; ++t) { h0[t] += sigmoidf_(acc[ai][bj][m][0][t] * r) * p0[t]; h1[t] += sigmoidf_(acc[ai][bj][m][1][t] * r) * p1[t]; }
;                         *(v4u*)(h3b + off) = pack8(h0, h1);
;                         s += (h0[0] * h0[0] + h0[1] * h0[1]) + (h0[2] * h0[2] + h0[3] * h0[3]) + (h1[0] * h1[0] + h1[1] * h1[1]) + (h1[2] * h1[2] + h1[3] * h1[3]); }
;                     s += __shfl_xor(s, 16); s += __shfl_xor(s, 32);
;                     if (fq == 0) atomicAdd(ss_out + row, s); }
.LBB0_3039:
	s_or_b64 exec, exec, s[0:1]
	v_fmamk_f32 v80, v190, 0x39800000, v184
	v_rsq_f32_e32 v82, v80
	s_waitcnt vmcnt(3)
	v_lshlrev_b32_e32 v91, 16, v104
	v_and_b32_e32 v92, 0xffff0000, v104
	v_lshlrev_b32_e32 v93, 16, v105
	v_mul_f32_e32 v76, v76, v82
	v_mul_f32_e32 v76, 0xbfb8aa3b, v76
	v_exp_f32_e32 v76, v76
	v_and_b32_e32 v94, 0xffff0000, v105
	v_mul_f32_e32 v72, v72, v82
	v_mul_f32_e32 v72, 0xbfb8aa3b, v72
	v_add_f32_e32 v76, 1.0, v76
	v_lshlrev_b32_e32 v85, 16, v109
	v_and_b32_e32 v86, 0xffff0000, v109
	v_exp_f32_e32 v72, v72
	v_lshlrev_b32_e32 v87, 16, v110
	v_and_b32_e32 v88, 0xffff0000, v110
	v_lshlrev_b32_e32 v89, 16, v111
	v_and_b32_e32 v90, 0xffff0000, v111
	v_add_f32_e32 v72, 1.0, v72
	v_mul_f32_e32 v77, v77, v82
	v_mul_f32_e32 v77, 0xbfb8aa3b, v77
	v_lshlrev_b32_e32 v83, 16, v108
	v_rcp_f32_e32 v76, v76
	v_exp_f32_e32 v77, v77
	v_fmac_f32_e32 v91, v76, v83
	v_add_f32_e32 v77, 1.0, v77
	v_mul_f32_e32 v73, v73, v82
	v_lshlrev_b32_e32 v95, 16, v106
	v_rcp_f32_e32 v72, v72
	v_mul_f32_e32 v73, 0xbfb8aa3b, v73
	v_fmac_f32_e32 v95, v72, v87
	v_exp_f32_e32 v73, v73
	s_nop 0
	v_add_f32_e32 v73, 1.0, v73
	v_rcp_f32_e32 v72, v77
	v_mul_f32_e32 v77, v78, v82
	v_mul_f32_e32 v77, 0xbfb8aa3b, v77
	v_and_b32_e32 v84, 0xffff0000, v108
	v_exp_f32_e32 v77, v77
	v_fmac_f32_e32 v92, v72, v84
	v_add_f32_e32 v77, 1.0, v77
	v_mul_f32_e32 v74, v74, v82
	v_mul_f32_e32 v74, 0xbfb8aa3b, v74
	v_and_b32_e32 v106, 0xffff0000, v106
	v_rcp_f32_e32 v72, v73
	v_exp_f32_e32 v74, v74
	v_fmac_f32_e32 v106, v72, v88
	v_add_f32_e32 v74, 1.0, v74
	v_rcp_f32_e32 v72, v77
	v_mul_f32_e32 v77, v79, v82
	v_fmac_f32_e32 v93, v72, v85
	v_mul_f32_e32 v77, 0xbfb8aa3b, v77
	v_exp_f32_e32 v77, v77
	s_nop 0
	v_add_f32_e32 v76, 1.0, v77
	v_rcp_f32_e32 v72, v74
	v_mul_f32_e32 v74, v75, v82
	v_mul_f32_e32 v74, 0xbfb8aa3b, v74
	v_lshlrev_b32_e32 v108, 16, v107
	v_exp_f32_e32 v74, v74
	v_fmac_f32_e32 v108, v72, v89
	v_add_f32_e32 v74, 1.0, v74
	v_rcp_f32_e32 v72, v76
	s_nop 0
	v_fmac_f32_e32 v94, v72, v86
	v_mul_f32_e32 v68, v68, v82
	v_mul_f32_e32 v68, 0xbfb8aa3b, v68
	v_exp_f32_e32 v68, v68
	v_and_b32_e32 v107, 0xffff0000, v107
	v_rcp_f32_e32 v72, v74
	v_mul_f32_e32 v77, v94, v94
	v_add_f32_e32 v68, 1.0, v68
	v_fmac_f32_e32 v107, v72, v90
	v_cvt_pk_bf16_f32 v72, v91, v92
	v_cvt_pk_bf16_f32 v73, v93, v94
	v_fmac_f32_e32 v77, v93, v93
	v_mul_f32_e32 v76, v92, v92
	v_fmac_f32_e32 v76, v91, v91
	v_mul_f32_e32 v64, v64, v82
	v_add_f32_e32 v76, v76, v77
	v_mul_f32_e32 v77, v106, v106
	v_mul_f32_e32 v64, 0xbfb8aa3b, v64
	v_cvt_pk_bf16_f32 v74, v95, v106
	v_fmac_f32_e32 v77, v95, v95
	s_waitcnt vmcnt(2)
	v_lshlrev_b32_e32 v92, 16, v98
	v_and_b32_e32 v95, 0xffff0000, v98
	v_exp_f32_e32 v64, v64
	v_add_f32_e32 v76, v77, v76
	v_mul_f32_e32 v77, v107, v107
	v_fmac_f32_e32 v77, v108, v108
	v_lshlrev_b32_e32 v88, 16, v96
	v_and_b32_e32 v89, 0xffff0000, v96
	v_lshlrev_b32_e32 v90, 16, v97
	v_and_b32_e32 v91, 0xffff0000, v97
	v_lshlrev_b32_e32 v96, 16, v99
	v_and_b32_e32 v97, 0xffff0000, v99
	v_add_f32_e32 v76, v77, v76
	v_lshlrev_b32_e32 v77, 16, v100
	v_and_b32_e32 v78, 0xffff0000, v100
	v_add_f32_e32 v64, 1.0, v64
	v_mul_f32_e32 v69, v69, v82
	v_mul_f32_e32 v69, 0xbfb8aa3b, v69
	v_rcp_f32_e32 v68, v68
	v_exp_f32_e32 v69, v69
	v_fmac_f32_e32 v88, v68, v77
	v_add_f32_e32 v69, 1.0, v69
	v_mul_f32_e32 v65, v65, v82
	v_lshlrev_b32_e32 v84, 16, v102
	v_rcp_f32_e32 v64, v64
	v_mul_f32_e32 v65, 0xbfb8aa3b, v65
	v_fmac_f32_e32 v92, v64, v84
	v_exp_f32_e32 v65, v65
	s_nop 0
	v_add_f32_e32 v65, 1.0, v65
	v_rcp_f32_e32 v64, v69
	v_mul_f32_e32 v69, v70, v82
	v_mul_f32_e32 v69, 0xbfb8aa3b, v69
	v_exp_f32_e32 v69, v69
	v_fmac_f32_e32 v89, v64, v78
	v_add_f32_e32 v69, 1.0, v69
	v_mul_f32_e32 v66, v66, v82
	v_mul_f32_e32 v66, 0xbfb8aa3b, v66
	v_and_b32_e32 v85, 0xffff0000, v102
	v_rcp_f32_e32 v64, v65
	v_exp_f32_e32 v66, v66
	v_fmac_f32_e32 v95, v64, v85
	v_add_f32_e32 v66, 1.0, v66
	v_lshlrev_b32_e32 v79, 16, v101
	v_rcp_f32_e32 v64, v69
	v_mul_f32_e32 v69, v71, v82
	v_fmac_f32_e32 v90, v64, v79
	v_mul_f32_e32 v69, 0xbfb8aa3b, v69
	v_exp_f32_e32 v69, v69
	s_nop 0
	v_add_f32_e32 v68, 1.0, v69
	v_rcp_f32_e32 v64, v66
	v_mul_f32_e32 v66, v67, v82
	v_mul_f32_e32 v66, 0xbfb8aa3b, v66
	v_lshlrev_b32_e32 v86, 16, v103
	v_exp_f32_e32 v66, v66
	v_fmac_f32_e32 v96, v64, v86
	v_add_f32_e32 v66, 1.0, v66
	v_and_b32_e32 v83, 0xffff0000, v101
	v_rcp_f32_e32 v64, v68
	s_nop 0
	v_fmac_f32_e32 v91, v64, v83
	v_and_b32_e32 v87, 0xffff0000, v103
	v_rcp_f32_e32 v64, v66
	s_nop 0
	v_fmac_f32_e32 v97, v64, v87
	v_mul_f32_e32 v64, v89, v89
	v_mul_f32_e32 v65, v91, v91
	v_fmac_f32_e32 v64, v88, v88
	v_fmac_f32_e32 v65, v90, v90
	v_add_f32_e32 v64, v64, v65
	v_mul_f32_e32 v65, v95, v95
	v_fmac_f32_e32 v65, v92, v92
	v_add_f32_e32 v64, v65, v64
	v_mul_f32_e32 v65, v97, v97
	v_fmac_f32_e32 v65, v96, v96
	v_add_f32_e32 v64, v65, v64
	v_add_f32_e32 v67, v76, v64
	ds_bpermute_b32 v68, v124, v67
	s_waitcnt lgkmcnt(1)
	v_lshlrev_b64 v[80:81], 13, v[172:173]
	v_lshl_add_u64 v[64:65], s[12:13], 0, v[80:81]
	v_lshl_add_u64 v[70:71], v[168:169], 1, v[64:65]
	v_cvt_pk_bf16_f32 v75, v108, v107
	s_waitcnt lgkmcnt(0)
	v_add_f32_e32 v64, v67, v68
	ds_bpermute_b32 v65, v122, v64
	global_store_dwordx4 v[70:71], v[72:75], off sc1
	v_cvt_pk_bf16_f32 v66, v88, v89
	v_cvt_pk_bf16_f32 v67, v90, v91
	v_cvt_pk_bf16_f32 v68, v92, v95
	v_cvt_pk_bf16_f32 v69, v96, v97
	global_store_dwordx4 v[70:71], v[66:69], off offset:256 sc1
	s_and_saveexec_b64 s[0:1], s[6:7]
	s_cbranch_execz .LBB0_3041
	v_lshl_add_u64 v[66:67], v[172:173], 2, s[18:19]
	s_waitcnt lgkmcnt(0)
	v_add_f32_e32 v64, v64, v65
	global_atomic_add_f32 v[66:67], v64, off
; DI float sigmoidf_(float z) { return 1.0f / (1.0f + __expf(-z)); }
; DI v4u pack8(const f4& a, const f4& b) { v4u w; w.x = cvt_pk_bf16(a[0], a[1]); w.y = cvt_pk_bf16(a[2], a[3]); w.z = cvt_pk_bf16(b[0], b[1]); w.w = cvt_pk_bf16(b[2], b[3]); return w; }
; DI void unpack8(const v4u& w, f4& a, f4& b) { a[0] = bf_lo(w.x); a[1] = bf_hi(w.x); a[2] = bf_lo(w.y); a[3] = bf_hi(w.y); b[0] = bf_lo(w.z); b[1] = bf_hi(w.z); b[2] = bf_lo(w.w); b[3] = bf_hi(w.w); }
;     DI void operator()(f4 (&acc)[2][2][4][2], const Unit& u, int wr, int wc, int fr, int fq) const {
;     ...
;             for (int mp = 0; mp < 2; ++mp) {
;                 v4u pv[2][2], hv[2][2];
; #pragma unroll
;                 for (int mm = 0; mm < 2; ++mm)
; #pragma unroll
;                     for (int bj = 0; bj < 2; ++bj) { const size_t off = (size_t)(row0 + ai * HALF + (2 * mp + mm) * 16) * D + col0 + bj * HALF;
;                         pv[mm][bj] = *(const v4u*)(pp + off); hv[mm][bj] = *(const v4u*)(hb + off); }
;                 asm volatile("" ::: "memory");
; #pragma unroll
;                 for (int mm = 0; mm < 2; ++mm) { const int m = 2 * mp + mm, row = row0 + ai * HALF + m * 16; const float r = __builtin_amdgcn_rsqf(rr[ai][m] * (1.0f / D) + RMS_EPS); float s = 0.f;
; #pragma unroll
;                     for (int bj = 0; bj < 2; ++bj) { const size_t off = (size_t)row * D + col0 + bj * HALF;
;                         f4 p0, p1; unpack8(pv[mm][bj], p0, p1);
;                         f4 h0, h1; unpack8(hv[mm][bj], h0, h1);
; #pragma unroll
;                         for (int t = 0; t < 4; ++t) { h0[t] += sigmoidf_(acc[ai][bj][m][0][t] * r) * p0[t]; h1[t] += sigmoidf_(acc[ai][bj][m][1][t] * r) * p1[t]; }
;                         *(v4u*)(h3b + off) = pack8(h0, h1);
;                         s += (h0[0] * h0[0] + h0[1] * h0[1]) + (h0[2] * h0[2] + h0[3] * h0[3]) + (h1[0] * h1[0] + h1[1] * h1[1]) + (h1[2] * h1[2] + h1[3] * h1[3]); }
;                     s += __shfl_xor(s, 16); s += __shfl_xor(s, 32);
;                     if (fq == 0) atomicAdd(ss_out + row, s); }
.LBB0_3041:
	s_or_b64 exec, exec, s[0:1]
	v_add_u32_e32 v86, 0x80, v170
	v_ashrrev_i32_e32 v87, 31, v86
	s_waitcnt lgkmcnt(0)
	v_lshlrev_b64 v[64:65], 12, v[86:87]
	v_lshl_add_u64 v[64:65], v[64:65], 0, v[168:169]
	v_lshlrev_b64 v[64:65], 1, v[64:65]
	v_lshl_add_u64 v[66:67], s[14:15], 0, v[64:65]
	v_lshl_add_u64 v[64:65], s[8:9], 0, v[64:65]
	global_load_dwordx4 v[90:93], v[66:67], off
	global_load_dwordx4 v[94:97], v[64:65], off
	v_fmamk_f32 v68, v189, 0x39800000, v184
	v_rsq_f32_e32 v104, v68
	v_add_u32_e32 v84, 0x90, v170
	v_ashrrev_i32_e32 v85, 31, v84
	v_lshlrev_b64 v[68:69], 12, v[84:85]
	v_mul_f32_e32 v60, v60, v104
	v_mul_f32_e32 v56, v56, v104
	v_mul_f32_e32 v60, 0xbfb8aa3b, v60
	v_mul_f32_e32 v56, 0xbfb8aa3b, v56
	v_exp_f32_e32 v60, v60
	v_lshl_add_u64 v[68:69], v[68:69], 0, v[168:169]
	v_exp_f32_e32 v56, v56
	v_lshlrev_b64 v[68:69], 1, v[68:69]
	v_lshl_add_u64 v[70:71], s[14:15], 0, v[68:69]
	v_lshl_add_u64 v[102:103], s[8:9], 0, v[68:69]
	global_load_dwordx4 v[98:101], v[66:67], off offset:256
	global_load_dwordx4 v[80:83], v[64:65], off offset:256
	global_load_dwordx4 v[76:79], v[70:71], off
	s_nop 0
	global_load_dwordx4 v[68:71], v[70:71], off offset:256
	s_nop 0
	global_load_dwordx4 v[72:75], v[102:103], off
	global_load_dwordx4 v[64:67], v[102:103], off offset:256
	v_add_f32_e32 v60, 1.0, v60
	v_add_f32_e32 v56, 1.0, v56
	v_mul_f32_e32 v61, v61, v104
	v_mul_f32_e32 v61, 0xbfb8aa3b, v61
	v_exp_f32_e32 v61, v61
	s_nop 0
	v_add_f32_e32 v61, 1.0, v61
	v_rcp_f32_e32 v60, v60
	v_mul_f32_e32 v57, v57, v104
	v_rcp_f32_e32 v56, v56
	v_mul_f32_e32 v57, 0xbfb8aa3b, v57
	v_exp_f32_e32 v57, v57
	v_mul_f32_e32 v58, v58, v104
	v_mul_f32_e32 v58, 0xbfb8aa3b, v58
	v_exp_f32_e32 v58, v58
	v_add_f32_e32 v57, 1.0, v57
	v_mul_f32_e32 v52, v52, v104
	v_mul_f32_e32 v52, 0xbfb8aa3b, v52
	v_add_f32_e32 v58, 1.0, v58
	v_exp_f32_e32 v52, v52
	v_mul_f32_e32 v48, v48, v104
	v_mul_f32_e32 v48, 0xbfb8aa3b, v48
	v_add_f32_e32 v52, 1.0, v52
	v_exp_f32_e32 v48, v48
	v_mul_f32_e32 v53, v53, v104
	v_mul_f32_e32 v53, 0xbfb8aa3b, v53
	v_exp_f32_e32 v53, v53
	v_add_f32_e32 v48, 1.0, v48
	v_mul_f32_e32 v49, v49, v104
	v_mul_f32_e32 v49, 0xbfb8aa3b, v49
	v_add_f32_e32 v53, 1.0, v53
	v_exp_f32_e32 v49, v49
	v_mul_f32_e32 v50, v50, v104
	v_mul_f32_e32 v50, 0xbfb8aa3b, v50
	s_waitcnt vmcnt(7)
	v_lshlrev_b32_e32 v105, 16, v92
	s_waitcnt vmcnt(6)
	v_lshlrev_b32_e32 v111, 16, v96
	v_fmac_f32_e32 v111, v56, v105
	v_lshlrev_b32_e32 v102, 16, v90
	v_lshlrev_b32_e32 v107, 16, v94
	v_fmac_f32_e32 v107, v60, v102
	v_rcp_f32_e32 v56, v61
	v_mul_f32_e32 v61, v62, v104
	v_mul_f32_e32 v61, 0xbfb8aa3b, v61
	v_and_b32_e32 v90, 0xffff0000, v90
	v_and_b32_e32 v94, 0xffff0000, v94
	v_exp_f32_e32 v61, v61
	v_fmac_f32_e32 v94, v56, v90
	v_add_f32_e32 v61, 1.0, v61
	v_and_b32_e32 v92, 0xffff0000, v92
	v_and_b32_e32 v96, 0xffff0000, v96
	v_rcp_f32_e32 v56, v57
	s_nop 0
	v_fmac_f32_e32 v96, v56, v92
	v_lshlrev_b32_e32 v103, 16, v91
	v_lshlrev_b32_e32 v108, 16, v95
	v_rcp_f32_e32 v56, v61
	v_mul_f32_e32 v61, v63, v104
	v_fmac_f32_e32 v108, v56, v103
	v_mul_f32_e32 v61, 0xbfb8aa3b, v61
	v_exp_f32_e32 v61, v61
	s_nop 0
	v_add_f32_e32 v60, 1.0, v61
	v_rcp_f32_e32 v56, v58
	v_mul_f32_e32 v58, v59, v104
	v_mul_f32_e32 v58, 0xbfb8aa3b, v58
	v_lshlrev_b32_e32 v106, 16, v93
	v_lshlrev_b32_e32 v112, 16, v97
	v_exp_f32_e32 v58, v58
	v_fmac_f32_e32 v112, v56, v106
	v_add_f32_e32 v58, 1.0, v58
	v_and_b32_e32 v91, 0xffff0000, v91
	v_and_b32_e32 v95, 0xffff0000, v95
	v_rcp_f32_e32 v56, v60
	s_nop 0
	v_fmac_f32_e32 v95, v56, v91
	v_mul_f32_e32 v60, v94, v94
	v_mul_f32_e32 v61, v95, v95
	v_fmac_f32_e32 v60, v107, v107
	v_fmac_f32_e32 v61, v108, v108
	v_and_b32_e32 v93, 0xffff0000, v93
	v_and_b32_e32 v97, 0xffff0000, v97
	v_rcp_f32_e32 v56, v58
	v_add_f32_e32 v60, v60, v61
	v_mul_f32_e32 v61, v96, v96
	v_fmac_f32_e32 v97, v56, v93
	v_fmac_f32_e32 v61, v111, v111
	v_add_f32_e32 v60, v61, v60
	v_mul_f32_e32 v61, v97, v97
	v_fmac_f32_e32 v61, v112, v112
	v_add_f32_e32 v60, v61, v60
	s_waitcnt vmcnt(5)
	v_lshlrev_b32_e32 v61, 16, v98
	v_and_b32_e32 v62, 0xffff0000, v98
	v_lshlrev_b32_e32 v63, 16, v99
	v_and_b32_e32 v90, 0xffff0000, v99
	v_cvt_pk_bf16_f32 v56, v107, v94
	v_lshlrev_b32_e32 v93, 16, v101
	v_and_b32_e32 v94, 0xffff0000, v101
	v_cvt_pk_bf16_f32 v57, v108, v95
	s_waitcnt vmcnt(4)
	v_lshlrev_b32_e32 v95, 16, v80
	v_rcp_f32_e32 v52, v52
	s_nop 0
	v_fmac_f32_e32 v95, v52, v61
	v_cvt_pk_bf16_f32 v58, v111, v96
	v_cvt_pk_bf16_f32 v59, v112, v97
	v_lshlrev_b32_e32 v91, 16, v100
	v_lshlrev_b32_e32 v97, 16, v82
	v_rcp_f32_e32 v48, v48
	s_nop 0
	v_fmac_f32_e32 v97, v48, v91
	v_add_f32_e32 v49, 1.0, v49
	v_rcp_f32_e32 v48, v53
	v_mul_f32_e32 v53, v54, v104
	v_mul_f32_e32 v53, 0xbfb8aa3b, v53
	v_and_b32_e32 v80, 0xffff0000, v80
	v_exp_f32_e32 v53, v53
	v_fmac_f32_e32 v80, v48, v62
	v_add_f32_e32 v53, 1.0, v53
	v_and_b32_e32 v92, 0xffff0000, v100
	v_and_b32_e32 v82, 0xffff0000, v82
	v_rcp_f32_e32 v48, v49
	v_exp_f32_e32 v50, v50
	v_fmac_f32_e32 v82, v48, v92
	v_add_f32_e32 v50, 1.0, v50
	v_lshlrev_b32_e32 v96, 16, v81
	v_rcp_f32_e32 v48, v53
	v_mul_f32_e32 v53, v55, v104
	v_fmac_f32_e32 v96, v48, v63
	v_mul_f32_e32 v53, 0xbfb8aa3b, v53
	v_exp_f32_e32 v53, v53
	s_nop 0
	v_add_f32_e32 v52, 1.0, v53
	v_rcp_f32_e32 v48, v50
	v_mul_f32_e32 v50, v51, v104
	v_mul_f32_e32 v50, 0xbfb8aa3b, v50
	v_lshlrev_b32_e32 v100, 16, v83
	v_exp_f32_e32 v50, v50
	v_fmac_f32_e32 v100, v48, v93
	v_add_f32_e32 v50, 1.0, v50
	v_and_b32_e32 v81, 0xffff0000, v81
	v_rcp_f32_e32 v48, v52
	s_nop 0
	v_fmac_f32_e32 v81, v48, v90
	v_and_b32_e32 v83, 0xffff0000, v83
	v_rcp_f32_e32 v48, v50
	s_nop 0
	v_fmac_f32_e32 v83, v48, v94
	v_mul_f32_e32 v48, v80, v80
	v_mul_f32_e32 v49, v81, v81
	v_fmac_f32_e32 v48, v95, v95
	v_fmac_f32_e32 v49, v96, v96
	v_add_f32_e32 v48, v48, v49
	v_mul_f32_e32 v49, v82, v82
	v_fmac_f32_e32 v49, v97, v97
	v_add_f32_e32 v48, v49, v48
	v_mul_f32_e32 v49, v83, v83
	v_fmac_f32_e32 v49, v100, v100
	v_add_f32_e32 v48, v49, v48
	v_add_f32_e32 v51, v60, v48
	ds_bpermute_b32 v52, v124, v51
	v_lshlrev_b64 v[88:89], 13, v[86:87]
	v_lshl_add_u64 v[48:49], s[12:13], 0, v[88:89]
	v_lshl_add_u64 v[54:55], v[168:169], 1, v[48:49]
	global_store_dwordx4 v[54:55], v[56:59], off sc1
	s_waitcnt lgkmcnt(0)
	v_add_f32_e32 v48, v51, v52
	ds_bpermute_b32 v49, v122, v48
	v_cvt_pk_bf16_f32 v50, v95, v80
	v_cvt_pk_bf16_f32 v51, v96, v81
	v_cvt_pk_bf16_f32 v52, v97, v82
	v_cvt_pk_bf16_f32 v53, v100, v83
	global_store_dwordx4 v[54:55], v[50:53], off offset:256 sc1
	s_and_saveexec_b64 s[0:1], s[6:7]
	s_cbranch_execz .LBB0_3043
	v_lshl_add_u64 v[50:51], v[86:87], 2, s[18:19]
	s_waitcnt lgkmcnt(0)
	v_add_f32_e32 v48, v48, v49
	global_atomic_add_f32 v[50:51], v48, off
; DI float sigmoidf_(float z) { return 1.0f / (1.0f + __expf(-z)); }
; DI v4u pack8(const f4& a, const f4& b) { v4u w; w.x = cvt_pk_bf16(a[0], a[1]); w.y = cvt_pk_bf16(a[2], a[3]); w.z = cvt_pk_bf16(b[0], b[1]); w.w = cvt_pk_bf16(b[2], b[3]); return w; }
; DI void unpack8(const v4u& w, f4& a, f4& b) { a[0] = bf_lo(w.x); a[1] = bf_hi(w.x); a[2] = bf_lo(w.y); a[3] = bf_hi(w.y); b[0] = bf_lo(w.z); b[1] = bf_hi(w.z); b[2] = bf_lo(w.w); b[3] = bf_hi(w.w); }
;     DI void operator()(f4 (&acc)[2][2][4][2], const Unit& u, int wr, int wc, int fr, int fq) const {
;     ...
; #pragma unroll
;                 for (int mm = 0; mm < 2; ++mm) { const int m = 2 * mp + mm, row = row0 + ai * HALF + m * 16; const float r = __builtin_amdgcn_rsqf(rr[ai][m] * (1.0f / D) + RMS_EPS); float s = 0.f;
; #pragma unroll
;                     for (int bj = 0; bj < 2; ++bj) { const size_t off = (size_t)row * D + col0 + bj * HALF;
;                         f4 p0, p1; unpack8(pv[mm][bj], p0, p1);
;                         f4 h0, h1; unpack8(hv[mm][bj], h0, h1);
; #pragma unroll
;                         for (int t = 0; t < 4; ++t) { h0[t] += sigmoidf_(acc[ai][bj][m][0][t] * r) * p0[t]; h1[t] += sigmoidf_(acc[ai][bj][m][1][t] * r) * p1[t]; }
;                         *(v4u*)(h3b + off) = pack8(h0, h1);
;                         s += (h0[0] * h0[0] + h0[1] * h0[1]) + (h0[2] * h0[2] + h0[3] * h0[3]) + (h1[0] * h1[0] + h1[1] * h1[1]) + (h1[2] * h1[2] + h1[3] * h1[3]); }
;                     s += __shfl_xor(s, 16); s += __shfl_xor(s, 32);
;                     if (fq == 0) atomicAdd(ss_out + row, s); }
.LBB0_3043:
	s_or_b64 exec, exec, s[0:1]
	v_fmamk_f32 v48, v188, 0x39800000, v184
	v_rsq_f32_e32 v50, v48
	s_waitcnt vmcnt(3)
	v_lshlrev_b32_e32 v59, 16, v72
	v_and_b32_e32 v60, 0xffff0000, v72
	v_lshlrev_b32_e32 v61, 16, v73
	v_mul_f32_e32 v44, v44, v50
	v_mul_f32_e32 v44, 0xbfb8aa3b, v44
	v_exp_f32_e32 v44, v44
	v_and_b32_e32 v62, 0xffff0000, v73
	v_mul_f32_e32 v40, v40, v50
	v_mul_f32_e32 v40, 0xbfb8aa3b, v40
	v_add_f32_e32 v44, 1.0, v44
	v_lshlrev_b32_e32 v53, 16, v77
	v_and_b32_e32 v54, 0xffff0000, v77
	v_exp_f32_e32 v40, v40
	v_lshlrev_b32_e32 v55, 16, v78
	v_and_b32_e32 v56, 0xffff0000, v78
	v_lshlrev_b32_e32 v57, 16, v79
	v_and_b32_e32 v58, 0xffff0000, v79
	v_add_f32_e32 v40, 1.0, v40
	v_mul_f32_e32 v45, v45, v50
	v_mul_f32_e32 v45, 0xbfb8aa3b, v45
	v_lshlrev_b32_e32 v51, 16, v76
	v_rcp_f32_e32 v44, v44
	v_exp_f32_e32 v45, v45
	v_fmac_f32_e32 v59, v44, v51
	v_add_f32_e32 v45, 1.0, v45
	v_mul_f32_e32 v41, v41, v50
	v_lshlrev_b32_e32 v63, 16, v74
	v_rcp_f32_e32 v40, v40
	v_mul_f32_e32 v41, 0xbfb8aa3b, v41
	v_fmac_f32_e32 v63, v40, v55
	v_exp_f32_e32 v41, v41
	s_nop 0
	v_add_f32_e32 v41, 1.0, v41
	v_rcp_f32_e32 v40, v45
	v_mul_f32_e32 v45, v46, v50
	v_mul_f32_e32 v45, 0xbfb8aa3b, v45
	v_and_b32_e32 v52, 0xffff0000, v76
	v_exp_f32_e32 v45, v45
	v_fmac_f32_e32 v60, v40, v52
	v_add_f32_e32 v45, 1.0, v45
	v_mul_f32_e32 v42, v42, v50
	v_mul_f32_e32 v42, 0xbfb8aa3b, v42
	v_and_b32_e32 v74, 0xffff0000, v74
	v_rcp_f32_e32 v40, v41
	v_exp_f32_e32 v42, v42
	v_fmac_f32_e32 v74, v40, v56
	v_add_f32_e32 v42, 1.0, v42
	v_rcp_f32_e32 v40, v45
	v_mul_f32_e32 v45, v47, v50
	v_fmac_f32_e32 v61, v40, v53
	v_mul_f32_e32 v45, 0xbfb8aa3b, v45
	v_exp_f32_e32 v45, v45
	s_nop 0
	v_add_f32_e32 v44, 1.0, v45
	v_rcp_f32_e32 v40, v42
	v_mul_f32_e32 v42, v43, v50
	v_mul_f32_e32 v42, 0xbfb8aa3b, v42
	v_lshlrev_b32_e32 v76, 16, v75
	v_exp_f32_e32 v42, v42
	v_fmac_f32_e32 v76, v40, v57
	v_add_f32_e32 v42, 1.0, v42
	v_rcp_f32_e32 v40, v44
	s_nop 0
	v_fmac_f32_e32 v62, v40, v54
	v_mul_f32_e32 v36, v36, v50
	v_mul_f32_e32 v36, 0xbfb8aa3b, v36
	v_exp_f32_e32 v36, v36
	v_and_b32_e32 v75, 0xffff0000, v75
	v_rcp_f32_e32 v40, v42
	v_mul_f32_e32 v45, v62, v62
	v_add_f32_e32 v36, 1.0, v36
	v_fmac_f32_e32 v75, v40, v58
	v_cvt_pk_bf16_f32 v40, v59, v60
	v_cvt_pk_bf16_f32 v41, v61, v62
	v_fmac_f32_e32 v45, v61, v61
	v_mul_f32_e32 v44, v60, v60
	v_fmac_f32_e32 v44, v59, v59
	v_mul_f32_e32 v32, v32, v50
	v_add_f32_e32 v44, v44, v45
	v_mul_f32_e32 v45, v74, v74
	v_mul_f32_e32 v32, 0xbfb8aa3b, v32
	v_cvt_pk_bf16_f32 v42, v63, v74
	v_fmac_f32_e32 v45, v63, v63
	s_waitcnt vmcnt(2)
	v_lshlrev_b32_e32 v60, 16, v66
	v_and_b32_e32 v63, 0xffff0000, v66
	v_exp_f32_e32 v32, v32
	v_add_f32_e32 v44, v45, v44
	v_mul_f32_e32 v45, v75, v75
	v_fmac_f32_e32 v45, v76, v76
	v_lshlrev_b32_e32 v56, 16, v64
	v_and_b32_e32 v57, 0xffff0000, v64
	v_lshlrev_b32_e32 v58, 16, v65
	v_and_b32_e32 v59, 0xffff0000, v65
	v_lshlrev_b32_e32 v64, 16, v67
	v_and_b32_e32 v65, 0xffff0000, v67
	v_add_f32_e32 v44, v45, v44
	v_lshlrev_b32_e32 v45, 16, v68
	v_and_b32_e32 v46, 0xffff0000, v68
	v_add_f32_e32 v32, 1.0, v32
	v_mul_f32_e32 v37, v37, v50
	v_mul_f32_e32 v37, 0xbfb8aa3b, v37
	v_rcp_f32_e32 v36, v36
	v_exp_f32_e32 v37, v37
	v_fmac_f32_e32 v56, v36, v45
	v_add_f32_e32 v37, 1.0, v37
	v_mul_f32_e32 v33, v33, v50
	v_lshlrev_b32_e32 v52, 16, v70
	v_rcp_f32_e32 v32, v32
	v_mul_f32_e32 v33, 0xbfb8aa3b, v33
	v_fmac_f32_e32 v60, v32, v52
	v_exp_f32_e32 v33, v33
	s_nop 0
	v_add_f32_e32 v33, 1.0, v33
	v_rcp_f32_e32 v32, v37
	v_mul_f32_e32 v37, v38, v50
	v_mul_f32_e32 v37, 0xbfb8aa3b, v37
	v_exp_f32_e32 v37, v37
	v_fmac_f32_e32 v57, v32, v46
	v_add_f32_e32 v37, 1.0, v37
	v_mul_f32_e32 v34, v34, v50
	v_mul_f32_e32 v34, 0xbfb8aa3b, v34
	v_and_b32_e32 v53, 0xffff0000, v70
	v_rcp_f32_e32 v32, v33
	v_exp_f32_e32 v34, v34
	v_fmac_f32_e32 v63, v32, v53
	v_add_f32_e32 v34, 1.0, v34
	v_lshlrev_b32_e32 v47, 16, v69
	v_rcp_f32_e32 v32, v37
	v_mul_f32_e32 v37, v39, v50
	v_fmac_f32_e32 v58, v32, v47
	v_mul_f32_e32 v37, 0xbfb8aa3b, v37
	v_exp_f32_e32 v37, v37
	s_nop 0
	v_add_f32_e32 v36, 1.0, v37
	v_rcp_f32_e32 v32, v34
	v_mul_f32_e32 v34, v35, v50
	v_mul_f32_e32 v34, 0xbfb8aa3b, v34
	v_lshlrev_b32_e32 v54, 16, v71
	v_exp_f32_e32 v34, v34
	v_fmac_f32_e32 v64, v32, v54
	v_add_f32_e32 v34, 1.0, v34
	v_and_b32_e32 v51, 0xffff0000, v69
	v_rcp_f32_e32 v32, v36
	s_nop 0
	v_fmac_f32_e32 v59, v32, v51
	v_and_b32_e32 v55, 0xffff0000, v71
	v_rcp_f32_e32 v32, v34
	s_nop 0
	v_fmac_f32_e32 v65, v32, v55
	v_mul_f32_e32 v32, v57, v57
	v_mul_f32_e32 v33, v59, v59
	v_fmac_f32_e32 v32, v56, v56
	v_fmac_f32_e32 v33, v58, v58
	v_add_f32_e32 v32, v32, v33
	v_mul_f32_e32 v33, v63, v63
	v_fmac_f32_e32 v33, v60, v60
	v_add_f32_e32 v32, v33, v32
	v_mul_f32_e32 v33, v65, v65
	v_fmac_f32_e32 v33, v64, v64
	v_add_f32_e32 v32, v33, v32
	v_add_f32_e32 v35, v44, v32
	ds_bpermute_b32 v36, v124, v35
	s_waitcnt lgkmcnt(1)
	v_lshlrev_b64 v[48:49], 13, v[84:85]
	v_lshl_add_u64 v[32:33], s[12:13], 0, v[48:49]
	v_lshl_add_u64 v[38:39], v[168:169], 1, v[32:33]
	v_cvt_pk_bf16_f32 v43, v76, v75
	s_waitcnt lgkmcnt(0)
	v_add_f32_e32 v32, v35, v36
	ds_bpermute_b32 v33, v122, v32
	global_store_dwordx4 v[38:39], v[40:43], off sc1
	v_cvt_pk_bf16_f32 v34, v56, v57
	v_cvt_pk_bf16_f32 v35, v58, v59
	v_cvt_pk_bf16_f32 v36, v60, v63
	v_cvt_pk_bf16_f32 v37, v64, v65
	global_store_dwordx4 v[38:39], v[34:37], off offset:256 sc1
	s_and_saveexec_b64 s[0:1], s[6:7]
	s_cbranch_execz .LBB0_3045
	v_lshl_add_u64 v[34:35], v[84:85], 2, s[18:19]
	s_waitcnt lgkmcnt(0)
	v_add_f32_e32 v32, v32, v33
	global_atomic_add_f32 v[34:35], v32, off
; DI float sigmoidf_(float z) { return 1.0f / (1.0f + __expf(-z)); }
; DI v4u pack8(const f4& a, const f4& b) { v4u w; w.x = cvt_pk_bf16(a[0], a[1]); w.y = cvt_pk_bf16(a[2], a[3]); w.z = cvt_pk_bf16(b[0], b[1]); w.w = cvt_pk_bf16(b[2], b[3]); return w; }
; DI void unpack8(const v4u& w, f4& a, f4& b) { a[0] = bf_lo(w.x); a[1] = bf_hi(w.x); a[2] = bf_lo(w.y); a[3] = bf_hi(w.y); b[0] = bf_lo(w.z); b[1] = bf_hi(w.z); b[2] = bf_lo(w.w); b[3] = bf_hi(w.w); }
;     DI void operator()(f4 (&acc)[2][2][4][2], const Unit& u, int wr, int wc, int fr, int fq) const {
;     ...
;             for (int mp = 0; mp < 2; ++mp) {
;                 v4u pv[2][2], hv[2][2];
; #pragma unroll
;                 for (int mm = 0; mm < 2; ++mm)
; #pragma unroll
;                     for (int bj = 0; bj < 2; ++bj) { const size_t off = (size_t)(row0 + ai * HALF + (2 * mp + mm) * 16) * D + col0 + bj * HALF;
;                         pv[mm][bj] = *(const v4u*)(pp + off); hv[mm][bj] = *(const v4u*)(hb + off); }
;                 asm volatile("" ::: "memory");
; #pragma unroll
;                 for (int mm = 0; mm < 2; ++mm) { const int m = 2 * mp + mm, row = row0 + ai * HALF + m * 16; const float r = __builtin_amdgcn_rsqf(rr[ai][m] * (1.0f / D) + RMS_EPS); float s = 0.f;
; #pragma unroll
;                     for (int bj = 0; bj < 2; ++bj) { const size_t off = (size_t)row * D + col0 + bj * HALF;
;                         f4 p0, p1; unpack8(pv[mm][bj], p0, p1);
;                         f4 h0, h1; unpack8(hv[mm][bj], h0, h1);
; #pragma unroll
;                         for (int t = 0; t < 4; ++t) { h0[t] += sigmoidf_(acc[ai][bj][m][0][t] * r) * p0[t]; h1[t] += sigmoidf_(acc[ai][bj][m][1][t] * r) * p1[t]; }
;                         *(v4u*)(h3b + off) = pack8(h0, h1);
;                         s += (h0[0] * h0[0] + h0[1] * h0[1]) + (h0[2] * h0[2] + h0[3] * h0[3]) + (h1[0] * h1[0] + h1[1] * h1[1]) + (h1[2] * h1[2] + h1[3] * h1[3]); }
;                     s += __shfl_xor(s, 16); s += __shfl_xor(s, 32);
;                     if (fq == 0) atomicAdd(ss_out + row, s); }
.LBB0_3045:
	s_or_b64 exec, exec, s[0:1]
	v_add_u32_e32 v54, 0xa0, v170
	v_ashrrev_i32_e32 v55, 31, v54
	s_waitcnt lgkmcnt(0)
	v_lshlrev_b64 v[32:33], 12, v[54:55]
	v_lshl_add_u64 v[32:33], v[32:33], 0, v[168:169]
	v_lshlrev_b64 v[32:33], 1, v[32:33]
	v_lshl_add_u64 v[34:35], s[14:15], 0, v[32:33]
	v_lshl_add_u64 v[32:33], s[8:9], 0, v[32:33]
	global_load_dwordx4 v[58:61], v[34:35], off
	global_load_dwordx4 v[62:65], v[32:33], off
	v_fmamk_f32 v36, v187, 0x39800000, v184
	v_rsq_f32_e32 v72, v36
	v_add_u32_e32 v52, 0xb0, v170
	v_ashrrev_i32_e32 v53, 31, v52
	v_lshlrev_b64 v[36:37], 12, v[52:53]
	v_mul_f32_e32 v28, v28, v72
	v_mul_f32_e32 v24, v24, v72
	v_mul_f32_e32 v28, 0xbfb8aa3b, v28
	v_mul_f32_e32 v24, 0xbfb8aa3b, v24
	v_exp_f32_e32 v28, v28
	v_lshl_add_u64 v[36:37], v[36:37], 0, v[168:169]
	v_exp_f32_e32 v24, v24
	v_lshlrev_b64 v[36:37], 1, v[36:37]
	v_lshl_add_u64 v[38:39], s[14:15], 0, v[36:37]
	v_lshl_add_u64 v[70:71], s[8:9], 0, v[36:37]
	global_load_dwordx4 v[66:69], v[34:35], off offset:256
	global_load_dwordx4 v[48:51], v[32:33], off offset:256
	global_load_dwordx4 v[44:47], v[38:39], off
	s_nop 0
	global_load_dwordx4 v[36:39], v[38:39], off offset:256
	s_nop 0
	global_load_dwordx4 v[40:43], v[70:71], off
	global_load_dwordx4 v[32:35], v[70:71], off offset:256
	v_add_f32_e32 v28, 1.0, v28
	v_add_f32_e32 v24, 1.0, v24
	v_mul_f32_e32 v29, v29, v72
	v_mul_f32_e32 v29, 0xbfb8aa3b, v29
	v_exp_f32_e32 v29, v29
	s_nop 0
	v_add_f32_e32 v29, 1.0, v29
	v_rcp_f32_e32 v28, v28
	v_mul_f32_e32 v25, v25, v72
	v_rcp_f32_e32 v24, v24
	v_mul_f32_e32 v25, 0xbfb8aa3b, v25
	v_exp_f32_e32 v25, v25
	v_mul_f32_e32 v26, v26, v72
	v_mul_f32_e32 v26, 0xbfb8aa3b, v26
	v_exp_f32_e32 v26, v26
	v_add_f32_e32 v25, 1.0, v25
	v_mul_f32_e32 v20, v20, v72
	v_mul_f32_e32 v20, 0xbfb8aa3b, v20
	v_add_f32_e32 v26, 1.0, v26
	v_exp_f32_e32 v20, v20
	v_mul_f32_e32 v16, v16, v72
	v_mul_f32_e32 v16, 0xbfb8aa3b, v16
	v_add_f32_e32 v20, 1.0, v20
	v_exp_f32_e32 v16, v16
	v_mul_f32_e32 v21, v21, v72
	v_mul_f32_e32 v21, 0xbfb8aa3b, v21
	v_exp_f32_e32 v21, v21
	v_add_f32_e32 v16, 1.0, v16
	v_mul_f32_e32 v17, v17, v72
	v_mul_f32_e32 v17, 0xbfb8aa3b, v17
	v_add_f32_e32 v21, 1.0, v21
	v_exp_f32_e32 v17, v17
	v_mul_f32_e32 v18, v18, v72
	v_mul_f32_e32 v18, 0xbfb8aa3b, v18
	s_waitcnt vmcnt(7)
	v_lshlrev_b32_e32 v73, 16, v60
	s_waitcnt vmcnt(6)
	v_lshlrev_b32_e32 v79, 16, v64
	v_fmac_f32_e32 v79, v24, v73
	v_lshlrev_b32_e32 v70, 16, v58
	v_lshlrev_b32_e32 v75, 16, v62
	v_fmac_f32_e32 v75, v28, v70
	v_rcp_f32_e32 v24, v29
	v_mul_f32_e32 v29, v30, v72
	v_mul_f32_e32 v29, 0xbfb8aa3b, v29
	v_and_b32_e32 v58, 0xffff0000, v58
	v_and_b32_e32 v62, 0xffff0000, v62
	v_exp_f32_e32 v29, v29
	v_fmac_f32_e32 v62, v24, v58
	v_add_f32_e32 v29, 1.0, v29
	v_and_b32_e32 v60, 0xffff0000, v60
	v_and_b32_e32 v64, 0xffff0000, v64
	v_rcp_f32_e32 v24, v25
	s_nop 0
	v_fmac_f32_e32 v64, v24, v60
	v_lshlrev_b32_e32 v71, 16, v59
	v_lshlrev_b32_e32 v76, 16, v63
	v_rcp_f32_e32 v24, v29
	v_mul_f32_e32 v29, v31, v72
	v_fmac_f32_e32 v76, v24, v71
	v_mul_f32_e32 v29, 0xbfb8aa3b, v29
	v_exp_f32_e32 v29, v29
	s_nop 0
	v_add_f32_e32 v28, 1.0, v29
	v_rcp_f32_e32 v24, v26
	v_mul_f32_e32 v26, v27, v72
	v_mul_f32_e32 v26, 0xbfb8aa3b, v26
	v_lshlrev_b32_e32 v74, 16, v61
	v_lshlrev_b32_e32 v80, 16, v65
	v_exp_f32_e32 v26, v26
	v_fmac_f32_e32 v80, v24, v74
	v_add_f32_e32 v26, 1.0, v26
	v_and_b32_e32 v59, 0xffff0000, v59
	v_and_b32_e32 v63, 0xffff0000, v63
	v_rcp_f32_e32 v24, v28
	s_nop 0
	v_fmac_f32_e32 v63, v24, v59
	v_mul_f32_e32 v28, v62, v62
	v_mul_f32_e32 v29, v63, v63
	v_fmac_f32_e32 v28, v75, v75
	v_fmac_f32_e32 v29, v76, v76
	v_and_b32_e32 v61, 0xffff0000, v61
	v_and_b32_e32 v65, 0xffff0000, v65
	v_rcp_f32_e32 v24, v26
	v_add_f32_e32 v28, v28, v29
	v_mul_f32_e32 v29, v64, v64
	v_fmac_f32_e32 v65, v24, v61
	v_fmac_f32_e32 v29, v79, v79
	v_add_f32_e32 v28, v29, v28
	v_mul_f32_e32 v29, v65, v65
	v_fmac_f32_e32 v29, v80, v80
	v_add_f32_e32 v28, v29, v28
	s_waitcnt vmcnt(5)
	v_lshlrev_b32_e32 v29, 16, v66
	v_and_b32_e32 v30, 0xffff0000, v66
	v_lshlrev_b32_e32 v31, 16, v67
	v_and_b32_e32 v58, 0xffff0000, v67
	v_cvt_pk_bf16_f32 v24, v75, v62
	v_lshlrev_b32_e32 v61, 16, v69
	v_and_b32_e32 v62, 0xffff0000, v69
	v_cvt_pk_bf16_f32 v25, v76, v63
	s_waitcnt vmcnt(4)
	v_lshlrev_b32_e32 v63, 16, v48
	v_rcp_f32_e32 v20, v20
	s_nop 0
	v_fmac_f32_e32 v63, v20, v29
	v_cvt_pk_bf16_f32 v26, v79, v64
	v_cvt_pk_bf16_f32 v27, v80, v65
	v_lshlrev_b32_e32 v59, 16, v68
	v_lshlrev_b32_e32 v65, 16, v50
	v_rcp_f32_e32 v16, v16
	s_nop 0
	v_fmac_f32_e32 v65, v16, v59
	v_add_f32_e32 v17, 1.0, v17
	v_rcp_f32_e32 v16, v21
	v_mul_f32_e32 v21, v22, v72
	v_mul_f32_e32 v21, 0xbfb8aa3b, v21
	v_and_b32_e32 v48, 0xffff0000, v48
	v_exp_f32_e32 v21, v21
	v_fmac_f32_e32 v48, v16, v30
	v_add_f32_e32 v21, 1.0, v21
	v_and_b32_e32 v60, 0xffff0000, v68
	v_and_b32_e32 v50, 0xffff0000, v50
	v_rcp_f32_e32 v16, v17
	v_exp_f32_e32 v18, v18
	v_fmac_f32_e32 v50, v16, v60
	v_add_f32_e32 v18, 1.0, v18
	v_lshlrev_b32_e32 v64, 16, v49
	v_rcp_f32_e32 v16, v21
	v_mul_f32_e32 v21, v23, v72
	v_fmac_f32_e32 v64, v16, v31
	v_mul_f32_e32 v21, 0xbfb8aa3b, v21
	v_exp_f32_e32 v21, v21
	s_nop 0
	v_add_f32_e32 v20, 1.0, v21
	v_rcp_f32_e32 v16, v18
	v_mul_f32_e32 v18, v19, v72
	v_mul_f32_e32 v18, 0xbfb8aa3b, v18
	v_lshlrev_b32_e32 v68, 16, v51
	v_exp_f32_e32 v18, v18
	v_fmac_f32_e32 v68, v16, v61
	v_add_f32_e32 v18, 1.0, v18
	v_and_b32_e32 v49, 0xffff0000, v49
	v_rcp_f32_e32 v16, v20
	s_nop 0
	v_fmac_f32_e32 v49, v16, v58
	v_and_b32_e32 v51, 0xffff0000, v51
	v_rcp_f32_e32 v16, v18
	s_nop 0
	v_fmac_f32_e32 v51, v16, v62
	v_mul_f32_e32 v16, v48, v48
	v_mul_f32_e32 v17, v49, v49
	v_fmac_f32_e32 v16, v63, v63
	v_fmac_f32_e32 v17, v64, v64
	v_add_f32_e32 v16, v16, v17
	v_mul_f32_e32 v17, v50, v50
	v_fmac_f32_e32 v17, v65, v65
	v_add_f32_e32 v16, v17, v16
	v_mul_f32_e32 v17, v51, v51
	v_fmac_f32_e32 v17, v68, v68
	v_add_f32_e32 v16, v17, v16
	v_add_f32_e32 v19, v28, v16
	ds_bpermute_b32 v20, v124, v19
	v_lshlrev_b64 v[56:57], 13, v[54:55]
	v_lshl_add_u64 v[16:17], s[12:13], 0, v[56:57]
	v_lshl_add_u64 v[22:23], v[168:169], 1, v[16:17]
	global_store_dwordx4 v[22:23], v[24:27], off sc1
	s_waitcnt lgkmcnt(0)
	v_add_f32_e32 v16, v19, v20
	ds_bpermute_b32 v17, v122, v16
	v_cvt_pk_bf16_f32 v18, v63, v48
	v_cvt_pk_bf16_f32 v19, v64, v49
	v_cvt_pk_bf16_f32 v20, v65, v50
	v_cvt_pk_bf16_f32 v21, v68, v51
	global_store_dwordx4 v[22:23], v[18:21], off offset:256 sc1
	s_and_saveexec_b64 s[0:1], s[6:7]
	s_cbranch_execz .LBB0_3047
	v_lshl_add_u64 v[18:19], v[54:55], 2, s[18:19]
	s_waitcnt lgkmcnt(0)
	v_add_f32_e32 v16, v16, v17
	global_atomic_add_f32 v[18:19], v16, off
; DI float sigmoidf_(float z) { return 1.0f / (1.0f + __expf(-z)); }
; DI v4u pack8(const f4& a, const f4& b) { v4u w; w.x = cvt_pk_bf16(a[0], a[1]); w.y = cvt_pk_bf16(a[2], a[3]); w.z = cvt_pk_bf16(b[0], b[1]); w.w = cvt_pk_bf16(b[2], b[3]); return w; }
; DI void unpack8(const v4u& w, f4& a, f4& b) { a[0] = bf_lo(w.x); a[1] = bf_hi(w.x); a[2] = bf_lo(w.y); a[3] = bf_hi(w.y); b[0] = bf_lo(w.z); b[1] = bf_hi(w.z); b[2] = bf_lo(w.w); b[3] = bf_hi(w.w); }
;     DI void operator()(f4 (&acc)[2][2][4][2], const Unit& u, int wr, int wc, int fr, int fq) const {
;     ...
; #pragma unroll
;                 for (int mm = 0; mm < 2; ++mm) { const int m = 2 * mp + mm, row = row0 + ai * HALF + m * 16; const float r = __builtin_amdgcn_rsqf(rr[ai][m] * (1.0f / D) + RMS_EPS); float s = 0.f;
; #pragma unroll
;                     for (int bj = 0; bj < 2; ++bj) { const size_t off = (size_t)row * D + col0 + bj * HALF;
;                         f4 p0, p1; unpack8(pv[mm][bj], p0, p1);
;                         f4 h0, h1; unpack8(hv[mm][bj], h0, h1);
; #pragma unroll
;                         for (int t = 0; t < 4; ++t) { h0[t] += sigmoidf_(acc[ai][bj][m][0][t] * r) * p0[t]; h1[t] += sigmoidf_(acc[ai][bj][m][1][t] * r) * p1[t]; }
;                         *(v4u*)(h3b + off) = pack8(h0, h1);
;                         s += (h0[0] * h0[0] + h0[1] * h0[1]) + (h0[2] * h0[2] + h0[3] * h0[3]) + (h1[0] * h1[0] + h1[1] * h1[1]) + (h1[2] * h1[2] + h1[3] * h1[3]); }
;                     s += __shfl_xor(s, 16); s += __shfl_xor(s, 32);
;                     if (fq == 0) atomicAdd(ss_out + row, s); }
.LBB0_3047:
	s_or_b64 exec, exec, s[0:1]
	v_fmamk_f32 v16, v186, 0x39800000, v184
	v_rsq_f32_e32 v18, v16
	s_waitcnt vmcnt(3)
	v_lshlrev_b32_e32 v27, 16, v40
	v_and_b32_e32 v28, 0xffff0000, v40
	v_lshlrev_b32_e32 v29, 16, v41
	v_mul_f32_e32 v12, v12, v18
	v_mul_f32_e32 v12, 0xbfb8aa3b, v12
	v_exp_f32_e32 v12, v12
	v_and_b32_e32 v30, 0xffff0000, v41
	v_mul_f32_e32 v8, v8, v18
	v_mul_f32_e32 v8, 0xbfb8aa3b, v8
	v_add_f32_e32 v12, 1.0, v12
	v_lshlrev_b32_e32 v21, 16, v45
	v_and_b32_e32 v22, 0xffff0000, v45
	v_exp_f32_e32 v8, v8
	v_lshlrev_b32_e32 v23, 16, v46
	v_and_b32_e32 v24, 0xffff0000, v46
	v_lshlrev_b32_e32 v25, 16, v47
	v_and_b32_e32 v26, 0xffff0000, v47
	v_add_f32_e32 v8, 1.0, v8
	v_mul_f32_e32 v13, v13, v18
	v_mul_f32_e32 v13, 0xbfb8aa3b, v13
	v_lshlrev_b32_e32 v19, 16, v44
	v_rcp_f32_e32 v12, v12
	v_exp_f32_e32 v13, v13
	v_fmac_f32_e32 v27, v12, v19
	v_add_f32_e32 v13, 1.0, v13
	v_mul_f32_e32 v9, v9, v18
	v_lshlrev_b32_e32 v31, 16, v42
	v_rcp_f32_e32 v8, v8
	v_mul_f32_e32 v9, 0xbfb8aa3b, v9
	v_fmac_f32_e32 v31, v8, v23
	v_exp_f32_e32 v9, v9
	s_nop 0
	v_add_f32_e32 v9, 1.0, v9
	v_rcp_f32_e32 v8, v13
	v_mul_f32_e32 v13, v14, v18
	v_mul_f32_e32 v13, 0xbfb8aa3b, v13
	v_and_b32_e32 v20, 0xffff0000, v44
	v_exp_f32_e32 v13, v13
	v_fmac_f32_e32 v28, v8, v20
	v_add_f32_e32 v13, 1.0, v13
	v_mul_f32_e32 v10, v10, v18
	v_mul_f32_e32 v10, 0xbfb8aa3b, v10
	v_and_b32_e32 v42, 0xffff0000, v42
	v_rcp_f32_e32 v8, v9
	v_exp_f32_e32 v10, v10
	v_fmac_f32_e32 v42, v8, v24
	v_add_f32_e32 v10, 1.0, v10
	v_rcp_f32_e32 v8, v13
	v_mul_f32_e32 v13, v15, v18
	v_fmac_f32_e32 v29, v8, v21
	v_mul_f32_e32 v13, 0xbfb8aa3b, v13
	v_exp_f32_e32 v13, v13
	s_nop 0
	v_add_f32_e32 v12, 1.0, v13
	v_rcp_f32_e32 v8, v10
	v_mul_f32_e32 v10, v11, v18
	v_mul_f32_e32 v10, 0xbfb8aa3b, v10
	v_lshlrev_b32_e32 v44, 16, v43
	v_exp_f32_e32 v10, v10
	v_fmac_f32_e32 v44, v8, v25
	v_add_f32_e32 v10, 1.0, v10
	v_rcp_f32_e32 v8, v12
	s_nop 0
	v_fmac_f32_e32 v30, v8, v22
	v_mul_f32_e32 v4, v4, v18
	v_mul_f32_e32 v4, 0xbfb8aa3b, v4
	v_exp_f32_e32 v4, v4
	v_and_b32_e32 v43, 0xffff0000, v43
	v_rcp_f32_e32 v8, v10
	v_mul_f32_e32 v13, v30, v30
	v_add_f32_e32 v4, 1.0, v4
	v_fmac_f32_e32 v43, v8, v26
	v_cvt_pk_bf16_f32 v8, v27, v28
	v_cvt_pk_bf16_f32 v9, v29, v30
	v_fmac_f32_e32 v13, v29, v29
	v_mul_f32_e32 v12, v28, v28
	v_fmac_f32_e32 v12, v27, v27
	v_mul_f32_e32 v0, v0, v18
	v_add_f32_e32 v12, v12, v13
	v_mul_f32_e32 v13, v42, v42
	v_mul_f32_e32 v0, 0xbfb8aa3b, v0
	v_cvt_pk_bf16_f32 v10, v31, v42
	v_fmac_f32_e32 v13, v31, v31
	s_waitcnt vmcnt(2)
	v_lshlrev_b32_e32 v28, 16, v34
	v_and_b32_e32 v31, 0xffff0000, v34
	v_exp_f32_e32 v0, v0
	v_add_f32_e32 v12, v13, v12
	v_mul_f32_e32 v13, v43, v43
	v_fmac_f32_e32 v13, v44, v44
	v_lshlrev_b32_e32 v24, 16, v32
	v_and_b32_e32 v25, 0xffff0000, v32
	v_lshlrev_b32_e32 v26, 16, v33
	v_and_b32_e32 v27, 0xffff0000, v33
	v_lshlrev_b32_e32 v32, 16, v35
	v_and_b32_e32 v33, 0xffff0000, v35
	v_add_f32_e32 v12, v13, v12
	v_lshlrev_b32_e32 v13, 16, v36
	v_and_b32_e32 v14, 0xffff0000, v36
	v_add_f32_e32 v0, 1.0, v0
	v_mul_f32_e32 v5, v5, v18
	v_mul_f32_e32 v5, 0xbfb8aa3b, v5
	v_rcp_f32_e32 v4, v4
	v_exp_f32_e32 v5, v5
	v_fmac_f32_e32 v24, v4, v13
	v_add_f32_e32 v5, 1.0, v5
	v_mul_f32_e32 v1, v1, v18
	v_lshlrev_b32_e32 v20, 16, v38
	v_rcp_f32_e32 v0, v0
	v_mul_f32_e32 v1, 0xbfb8aa3b, v1
	v_fmac_f32_e32 v28, v0, v20
	v_exp_f32_e32 v1, v1
	s_nop 0
	v_add_f32_e32 v1, 1.0, v1
	v_rcp_f32_e32 v0, v5
	v_mul_f32_e32 v5, v6, v18
	v_mul_f32_e32 v5, 0xbfb8aa3b, v5
	v_exp_f32_e32 v5, v5
	v_fmac_f32_e32 v25, v0, v14
	v_add_f32_e32 v5, 1.0, v5
	v_mul_f32_e32 v2, v2, v18
	v_mul_f32_e32 v2, 0xbfb8aa3b, v2
	v_and_b32_e32 v21, 0xffff0000, v38
	v_rcp_f32_e32 v0, v1
	v_exp_f32_e32 v2, v2
	v_fmac_f32_e32 v31, v0, v21
	v_add_f32_e32 v2, 1.0, v2
	v_lshlrev_b32_e32 v15, 16, v37
	v_rcp_f32_e32 v0, v5
	v_mul_f32_e32 v5, v7, v18
	v_fmac_f32_e32 v26, v0, v15
	v_mul_f32_e32 v5, 0xbfb8aa3b, v5
	v_exp_f32_e32 v5, v5
	s_nop 0
	v_add_f32_e32 v4, 1.0, v5
	v_rcp_f32_e32 v0, v2
	v_mul_f32_e32 v2, v3, v18
	v_mul_f32_e32 v2, 0xbfb8aa3b, v2
	v_lshlrev_b32_e32 v22, 16, v39
	v_exp_f32_e32 v2, v2
	v_fmac_f32_e32 v32, v0, v22
	v_add_f32_e32 v2, 1.0, v2
	v_and_b32_e32 v19, 0xffff0000, v37
	v_rcp_f32_e32 v0, v4
	s_nop 0
	v_fmac_f32_e32 v27, v0, v19
	v_and_b32_e32 v23, 0xffff0000, v39
	v_rcp_f32_e32 v0, v2
	s_nop 0
	v_fmac_f32_e32 v33, v0, v23
	v_mul_f32_e32 v0, v25, v25
	v_mul_f32_e32 v1, v27, v27
	v_fmac_f32_e32 v0, v24, v24
	v_fmac_f32_e32 v1, v26, v26
	v_add_f32_e32 v0, v0, v1
	v_mul_f32_e32 v1, v31, v31
	v_fmac_f32_e32 v1, v28, v28
	v_add_f32_e32 v0, v1, v0
	v_mul_f32_e32 v1, v33, v33
	v_fmac_f32_e32 v1, v32, v32
	v_add_f32_e32 v0, v1, v0
	v_add_f32_e32 v3, v12, v0
	ds_bpermute_b32 v4, v124, v3
	s_waitcnt lgkmcnt(1)
	v_lshlrev_b64 v[16:17], 13, v[52:53]
	v_lshl_add_u64 v[0:1], s[12:13], 0, v[16:17]
	v_lshl_add_u64 v[6:7], v[168:169], 1, v[0:1]
	v_cvt_pk_bf16_f32 v11, v44, v43
	s_waitcnt lgkmcnt(0)
	v_add_f32_e32 v0, v3, v4
	ds_bpermute_b32 v1, v122, v0
	global_store_dwordx4 v[6:7], v[8:11], off sc1
	v_cvt_pk_bf16_f32 v2, v24, v25
	v_cvt_pk_bf16_f32 v3, v26, v27
	v_cvt_pk_bf16_f32 v4, v28, v31
	v_cvt_pk_bf16_f32 v5, v32, v33
	global_store_dwordx4 v[6:7], v[2:5], off offset:256 sc1
	s_and_saveexec_b64 s[0:1], s[6:7]
	s_cbranch_execz .LBB0_3049
	v_lshl_add_u64 v[2:3], v[52:53], 2, s[18:19]
	s_waitcnt lgkmcnt(0)
	v_add_f32_e32 v0, v0, v1
	global_atomic_add_f32 v[2:3], v0, off
